# unit prologues de-serialised (LRU halo loads, GLA staging ladders incl. following row loads, lambda rounds) on top of the P4 split and attention re-deal
# baseline (speedup 1.0000x reference)
; #define LAS __attribute__((address_space(3)))
; #define WSYNC() asm volatile("s_waitcnt lgkmcnt(0)" ::: "memory")
; __device__ __forceinline__ void gla_gates(const bf16* prow, const float* wg, const float* bg, int h, int lane, float (&bc)[32], LAS float* Wst) {
; #pragma unroll
;     for (int r = 0; r < 8; ++r) { const int i = r * 64 + lane; Wst[i] = wg[(i >> 5) * 128 + h * 32 + (i & 31)]; }
;     if (lane < 32) Wst[512 + lane] = bg[h * 32 + lane];
;     float glr[16]; unpack8(*(const u32x4*)(prow + C_GLR), glr); unpack8(*(const u32x4*)(prow + C_GLR + 8), glr + 8);
;     WSYNC();
; #pragma unroll
;     for (int d4 = 0; d4 < 8; ++d4) { f32x4 z = *(const LAS f32x4*)(Wst + 512 + 4 * d4);
; #pragma unroll
;         for (int r = 0; r < 16; ++r) { const f32x4 w = *(const LAS f32x4*)(Wst + r * 32 + 4 * d4); z += w * glr[r]; }
; __device__ __forceinline__ void gla_local_unit(int u, const bf16* proj, const float* wg, const float* bg, float* KV, float* DEC, LAS unsigned char* wl, int lane) {
;     const int b = u >> 8, h = (u >> 6) & 3, n = u & 63; const size_t row = (size_t)b * SEQ + n * 64 + lane; const bf16* prow = proj + row * PP;
;     LAS bf16* KstT = (LAS bf16*)wl; LAS bf16* VT = (LAS bf16*)(wl + 4352);
;     u32x4 kraw[4], vraw[8];
; #pragma unroll
;     for (int i = 0; i < 4; ++i) kraw[i] = *(const u32x4*)(prow + C_GK + h * 32 + 8 * i);
; #pragma unroll
;     for (int i = 0; i < 8; ++i) vraw[i] = *(const u32x4*)(prow + C_GV + h * 64 + 8 * i);
;     float bc[32]; gla_gates(prow, wg, bg, h, lane, bc, (LAS float*)(wl + 4352));
.LBB0_437:
	s_ashr_i32 s2, s59, 8
	s_ashr_i32 s3, s2, 31
	s_lshl_b64 s[2:3], s[2:3], 12
	s_and_b32 s18, s78, 0xfc0
	s_or_b32 s2, s2, s18
	s_bfe_u32 s21, s59, 0x20006
	v_or_b32_e32 v4, s2, v0
	v_mov_b64_e32 v[2:3], s[22:23]
	v_mad_u64_u32 v[50:51], s[18:19], v4, s88, v[2:3]
	v_mov_b32_e32 v2, 0x1400
	s_lshl_b32 s2, s21, 5
	v_mad_i32_i24 v51, s3, v2, v51
	s_lshl_b32 s34, s21, 6
	v_or_b32_e32 v52, s2, v65
	v_lshl_add_u64 v[2:3], v[50:51], 0, s[34:35]
	s_lshl_b32 s34, s21, 7
	v_or_b32_e32 v53, v52, v67
	v_or_b32_e32 v54, v52, v71
	global_load_dwordx4 v[34:37], v[2:3], off offset:304
	global_load_dwordx4 v[38:41], v[2:3], off offset:288
	global_load_dwordx4 v[42:45], v[2:3], off offset:272
	global_load_dwordx4 v[46:49], v[2:3], off offset:256
	v_lshl_add_u64 v[2:3], v[50:51], 0, s[34:35]
	v_lshlrev_b32_e32 v53, 2, v53
	v_lshlrev_b32_e32 v54, 2, v54
	global_load_dwordx4 v[30:33], v[2:3], off offset:512
	global_load_dwordx4 v[26:29], v[2:3], off offset:528
	global_load_dwordx4 v[22:25], v[2:3], off offset:544
	global_load_dwordx4 v[18:21], v[2:3], off offset:560
	global_load_dwordx4 v[14:17], v[2:3], off offset:576
	global_load_dwordx4 v[10:13], v[2:3], off offset:592
	global_load_dwordx4 v[6:9], v[2:3], off offset:608
	s_nop 0
	global_load_dwordx4 v[2:5], v[2:3], off offset:624
	s_nop 0
	global_load_dword v53, v53, s[26:27]
	s_nop 0
	global_load_dword v54, v54, s[26:27]
	v_or_b32_e32 v154, v52, v73
	v_or_b32_e32 v155, v52, v75
	v_or_b32_e32 v156, v52, v77
	v_or_b32_e32 v157, v52, v79
	v_or_b32_e32 v158, v52, v81
	v_or_b32_e32 v159, v52, v83
	v_lshlrev_b32_e32 v154, 2, v154
	v_lshlrev_b32_e32 v155, 2, v155
	v_lshlrev_b32_e32 v156, 2, v156
	v_lshlrev_b32_e32 v157, 2, v157
	v_lshlrev_b32_e32 v158, 2, v158
	v_lshlrev_b32_e32 v159, 2, v159
	s_nop 0
	global_load_dword v154, v154, s[26:27]
	s_nop 0
	global_load_dword v155, v155, s[26:27]
	s_nop 0
	global_load_dword v156, v156, s[26:27]
	s_nop 0
	global_load_dword v157, v157, s[26:27]
	s_nop 0
	global_load_dword v158, v158, s[26:27]
	s_nop 0
	global_load_dword v159, v159, s[26:27]
	v_lshl_add_u64 v[170:171], v[50:51], 0, s[42:43]
	v_add_co_u32_e32 v172, vcc, s39, v50
	s_nop 1
	v_addc_co_u32_e32 v173, vcc, 0, v51, vcc
	global_load_dwordx4 v[162:165], v[172:173], off offset:512
	global_load_dwordx4 v[166:169], v[170:171], off offset:16
	s_and_saveexec_b64 s[18:19], s[4:5]
	v_or_b32_e32 v160, s2, v0
	v_lshlrev_b32_e32 v160, 2, v160
	global_load_dword v160, v160, s[28:29]
	s_or_b64 exec, exec, s[18:19]
	s_waitcnt vmcnt(0)
	ds_write2st64_b32 v69, v53, v54 offset0:17 offset1:18
	ds_write2st64_b32 v69, v154, v155 offset0:19 offset1:20
	ds_write2st64_b32 v69, v156, v157 offset0:21 offset1:22
	ds_write2st64_b32 v69, v158, v159 offset0:23 offset1:24
	s_and_saveexec_b64 s[18:19], s[4:5]
	ds_write_b32 v69, v160 offset:6400
.LBB0_439:
	s_or_b64 exec, exec, s[18:19]
	v_mov_b32_e32 v103, s61
	s_waitcnt lgkmcnt(0)
	s_waitcnt vmcnt(1)
	v_lshlrev_b32_e32 v94, 16, v162
	v_and_b32_e32 v92, 0xffff0000, v162
	v_lshlrev_b32_e32 v90, 16, v163
	v_and_b32_e32 v88, 0xffff0000, v163
	v_lshlrev_b32_e32 v86, 16, v164
	v_and_b32_e32 v84, 0xffff0000, v164
	v_lshlrev_b32_e32 v82, 16, v165
	v_and_b32_e32 v80, 0xffff0000, v165
	s_waitcnt vmcnt(0)
	v_lshlrev_b32_e32 v78, 16, v166
	v_and_b32_e32 v76, 0xffff0000, v166
	v_lshlrev_b32_e32 v74, 16, v167
	v_and_b32_e32 v72, 0xffff0000, v167
	v_lshlrev_b32_e32 v70, 16, v168
	v_and_b32_e32 v68, 0xffff0000, v168
	v_lshlrev_b32_e32 v66, 16, v169
	v_and_b32_e32 v64, 0xffff0000, v169
	ds_read_b128 v[96:99], v103 offset:6400
	ds_read_b128 v[104:107], v103 offset:4352
	ds_read_b128 v[58:61], v103 offset:4368
	ds_read_b128 v[54:57], v103 offset:4384
	ds_read_b128 v[50:53], v103 offset:4400
	ds_read_b128 v[112:115], v103 offset:6448
	s_waitcnt lgkmcnt(4)
	v_pk_fma_f32 v[100:101], v[104:105], v[94:95], v[96:97] op_sel_hi:[1,0,1]
	v_pk_fma_f32 v[104:105], v[106:107], v[94:95], v[98:99] op_sel_hi:[1,0,1]
	ds_read_b128 v[96:99], v103 offset:4480
	s_waitcnt lgkmcnt(0)
	v_pk_fma_f32 v[104:105], v[92:93], v[98:99], v[104:105] op_sel_hi:[0,1,1]
	v_pk_fma_f32 v[100:101], v[92:93], v[96:97], v[100:101] op_sel_hi:[0,1,1]
	ds_read_b128 v[96:99], v103 offset:4608
	s_waitcnt lgkmcnt(0)
	v_pk_fma_f32 v[100:101], v[90:91], v[96:97], v[100:101] op_sel_hi:[0,1,1]
	v_pk_fma_f32 v[104:105], v[90:91], v[98:99], v[104:105] op_sel_hi:[0,1,1]
	ds_read_b128 v[96:99], v103 offset:4736
	s_waitcnt lgkmcnt(0)
	v_pk_fma_f32 v[104:105], v[88:89], v[98:99], v[104:105] op_sel_hi:[0,1,1]
	v_pk_fma_f32 v[100:101], v[88:89], v[96:97], v[100:101] op_sel_hi:[0,1,1]
	ds_read_b128 v[96:99], v103 offset:4864
	s_waitcnt lgkmcnt(0)
	v_pk_fma_f32 v[100:101], v[86:87], v[96:97], v[100:101] op_sel_hi:[0,1,1]
	v_pk_fma_f32 v[104:105], v[86:87], v[98:99], v[104:105] op_sel_hi:[0,1,1]
	ds_read_b128 v[96:99], v103 offset:4992
	s_waitcnt lgkmcnt(0)
	v_pk_fma_f32 v[104:105], v[84:85], v[98:99], v[104:105] op_sel_hi:[0,1,1]
	v_pk_fma_f32 v[100:101], v[84:85], v[96:97], v[100:101] op_sel_hi:[0,1,1]
	ds_read_b128 v[96:99], v103 offset:5120
	s_waitcnt lgkmcnt(0)
	v_pk_fma_f32 v[100:101], v[82:83], v[96:97], v[100:101] op_sel_hi:[0,1,1]
	v_pk_fma_f32 v[104:105], v[82:83], v[98:99], v[104:105] op_sel_hi:[0,1,1]
	ds_read_b128 v[96:99], v103 offset:5248
	s_waitcnt lgkmcnt(0)
	v_pk_fma_f32 v[104:105], v[80:81], v[98:99], v[104:105] op_sel_hi:[0,1,1]
	v_pk_fma_f32 v[100:101], v[80:81], v[96:97], v[100:101] op_sel_hi:[0,1,1]
	ds_read_b128 v[96:99], v103 offset:5376
	s_waitcnt lgkmcnt(0)
	v_pk_fma_f32 v[100:101], v[78:79], v[96:97], v[100:101] op_sel_hi:[0,1,1]
	v_pk_fma_f32 v[104:105], v[78:79], v[98:99], v[104:105] op_sel_hi:[0,1,1]
	ds_read_b128 v[96:99], v103 offset:5504
	s_waitcnt lgkmcnt(0)
; #define LAS __attribute__((address_space(3)))
; __device__ __forceinline__ void gla_gates(const bf16* prow, const float* wg, const float* bg, int h, int lane, float (&bc)[32], LAS float* Wst) {
;     ...
; #pragma unroll
;     for (int d4 = 0; d4 < 8; ++d4) { f32x4 z = *(const LAS f32x4*)(Wst + 512 + 4 * d4);
; #pragma unroll
;         for (int r = 0; r < 16; ++r) { const f32x4 w = *(const LAS f32x4*)(Wst + r * 32 + 4 * d4); z += w * glr[r]; }
; #pragma unroll
;         for (int e = 0; e < 4; ++e) bc[4 * d4 + e] = (fminf(z[e], 0.f) - __logf(1.f + __expf(-fabsf(z[e])))) * (1.f / 16.f); }
	v_pk_fma_f32 v[104:105], v[76:77], v[98:99], v[104:105] op_sel_hi:[0,1,1]
	v_pk_fma_f32 v[100:101], v[76:77], v[96:97], v[100:101] op_sel_hi:[0,1,1]
	ds_read_b128 v[96:99], v103 offset:5632
	s_waitcnt lgkmcnt(0)
	v_pk_fma_f32 v[100:101], v[74:75], v[96:97], v[100:101] op_sel_hi:[0,1,1]
	v_pk_fma_f32 v[104:105], v[74:75], v[98:99], v[104:105] op_sel_hi:[0,1,1]
	ds_read_b128 v[96:99], v103 offset:5760
	s_waitcnt lgkmcnt(0)
	v_pk_fma_f32 v[104:105], v[72:73], v[98:99], v[104:105] op_sel_hi:[0,1,1]
	v_pk_fma_f32 v[100:101], v[72:73], v[96:97], v[100:101] op_sel_hi:[0,1,1]
	ds_read_b128 v[96:99], v103 offset:5888
	s_waitcnt lgkmcnt(0)
	v_pk_fma_f32 v[100:101], v[70:71], v[96:97], v[100:101] op_sel_hi:[0,1,1]
	v_pk_fma_f32 v[104:105], v[70:71], v[98:99], v[104:105] op_sel_hi:[0,1,1]
	ds_read_b128 v[96:99], v103 offset:6016
	s_waitcnt lgkmcnt(0)
	v_pk_fma_f32 v[104:105], v[68:69], v[98:99], v[104:105] op_sel_hi:[0,1,1]
	v_pk_fma_f32 v[100:101], v[68:69], v[96:97], v[100:101] op_sel_hi:[0,1,1]
	ds_read_b128 v[96:99], v103 offset:6144
	s_waitcnt lgkmcnt(0)
	v_pk_fma_f32 v[100:101], v[66:67], v[96:97], v[100:101] op_sel_hi:[0,1,1]
	v_pk_fma_f32 v[104:105], v[66:67], v[98:99], v[104:105] op_sel_hi:[0,1,1]
	ds_read_b128 v[96:99], v103 offset:6272
	s_waitcnt lgkmcnt(0)
	v_pk_fma_f32 v[96:97], v[64:65], v[96:97], v[100:101] op_sel_hi:[0,1,1]
	v_mul_f32_e64 v93, |v96|, s97
	v_exp_f32_e32 v93, v93
	v_min_f32_e32 v91, 0, v96
	v_pk_fma_f32 v[104:105], v[64:65], v[98:99], v[104:105] op_sel_hi:[0,1,1]
	v_add_f32_e32 v93, 1.0, v93
	v_cmp_gt_f32_e32 vcc, s45, v93
	s_nop 1
	v_cndmask_b32_e64 v95, 0, 32, vcc
	v_ldexp_f32 v93, v93, v95
	v_log_f32_e32 v93, v93
	s_nop 0
	v_mul_f32_e32 v95, 0x3f317217, v93
	v_fma_f32 v95, v93, s31, -v95
	v_fmac_f32_e32 v95, 0x3377d1cf, v93
	v_fmac_f32_e32 v95, 0x3f317217, v93
	v_cmp_lt_f32_e64 s[18:19], |v93|, s44
	s_nop 1
	v_cndmask_b32_e64 v93, v93, v95, s[18:19]
	v_cndmask_b32_e32 v95, 0, v240, vcc
	v_sub_f32_e32 v93, v93, v95
	v_sub_f32_e32 v101, v91, v93
	v_mul_f32_e64 v93, |v97|, s97
	v_exp_f32_e32 v93, v93
	v_min_f32_e32 v91, 0, v97
	v_mul_f32_e32 v102, 0x3d800000, v101
	v_add_f32_e32 v93, 1.0, v93
	v_cmp_gt_f32_e32 vcc, s45, v93
	s_nop 1
	v_cndmask_b32_e64 v95, 0, 32, vcc
	v_ldexp_f32 v93, v93, v95
	v_log_f32_e32 v93, v93
	s_nop 0
	v_mul_f32_e32 v95, 0x3f317217, v93
	v_fma_f32 v95, v93, s31, -v95
	v_fmac_f32_e32 v95, 0x3377d1cf, v93
	v_fmac_f32_e32 v95, 0x3f317217, v93
	v_cmp_lt_f32_e64 s[18:19], |v93|, s44
	s_nop 1
	v_cndmask_b32_e64 v93, v93, v95, s[18:19]
	v_cndmask_b32_e32 v95, 0, v240, vcc
	v_sub_f32_e32 v93, v93, v95
	v_sub_f32_e32 v99, v91, v93
	v_mul_f32_e64 v93, |v104|, s97
	v_exp_f32_e32 v93, v93
	v_min_f32_e32 v91, 0, v104
	v_mul_f32_e32 v100, 0x3d800000, v99
	v_add_f32_e32 v93, 1.0, v93
	v_cmp_gt_f32_e32 vcc, s45, v93
	s_nop 1
	v_cndmask_b32_e64 v95, 0, 32, vcc
	v_ldexp_f32 v93, v93, v95
	v_log_f32_e32 v93, v93
	s_nop 0
	v_mul_f32_e32 v95, 0x3f317217, v93
	v_fma_f32 v95, v93, s31, -v95
	v_fmac_f32_e32 v95, 0x3377d1cf, v93
	v_fmac_f32_e32 v95, 0x3f317217, v93
	v_cmp_lt_f32_e64 s[18:19], |v93|, s44
	s_nop 1
	v_cndmask_b32_e64 v93, v93, v95, s[18:19]
	v_cndmask_b32_e32 v95, 0, v240, vcc
	v_sub_f32_e32 v93, v93, v95
	v_sub_f32_e32 v95, v91, v93
	v_mul_f32_e64 v93, |v105|, s97
	v_exp_f32_e32 v93, v93
	v_min_f32_e32 v91, 0, v105
	ds_read_b128 v[104:107], v103 offset:6416
	v_mul_f32_e32 v98, 0x3d800000, v95
	v_add_f32_e32 v93, 1.0, v93
	v_cmp_gt_f32_e32 vcc, s45, v93
	s_nop 1
	v_cndmask_b32_e64 v96, 0, 32, vcc
	v_ldexp_f32 v93, v93, v96
	v_log_f32_e32 v93, v93
	s_nop 0
	v_mul_f32_e32 v96, 0x3f317217, v93
	v_fma_f32 v96, v93, s31, -v96
	v_fmac_f32_e32 v96, 0x3377d1cf, v93
	v_fmac_f32_e32 v96, 0x3f317217, v93
	v_cmp_lt_f32_e64 s[18:19], |v93|, s44
	s_nop 1
	v_cndmask_b32_e64 v93, v93, v96, s[18:19]
	v_cndmask_b32_e32 v96, 0, v240, vcc
	v_sub_f32_e32 v93, v93, v96
	s_waitcnt lgkmcnt(0)
	v_pk_fma_f32 v[96:97], v[94:95], v[58:59], v[104:105] op_sel_hi:[0,1,1]
	v_pk_fma_f32 v[104:105], v[94:95], v[60:61], v[106:107] op_sel_hi:[0,1,1]
	ds_read_b128 v[58:61], v103 offset:4496
	v_sub_f32_e32 v91, v91, v93
	v_mul_f32_e32 v93, 0x3d800000, v91
	s_waitcnt lgkmcnt(0)
	v_pk_fma_f32 v[104:105], v[92:93], v[60:61], v[104:105] op_sel_hi:[0,1,1]
	v_pk_fma_f32 v[96:97], v[92:93], v[58:59], v[96:97] op_sel_hi:[0,1,1]
	ds_read_b128 v[58:61], v103 offset:4624
	s_waitcnt lgkmcnt(0)
	v_pk_fma_f32 v[96:97], v[90:91], v[58:59], v[96:97] op_sel_hi:[0,1,1]
	v_pk_fma_f32 v[104:105], v[90:91], v[60:61], v[104:105] op_sel_hi:[0,1,1]
	ds_read_b128 v[58:61], v103 offset:4752
	s_waitcnt lgkmcnt(0)
	v_pk_fma_f32 v[104:105], v[88:89], v[60:61], v[104:105] op_sel_hi:[0,1,1]
	v_pk_fma_f32 v[96:97], v[88:89], v[58:59], v[96:97] op_sel_hi:[0,1,1]
	ds_read_b128 v[58:61], v103 offset:4880
	s_waitcnt lgkmcnt(0)
	v_pk_fma_f32 v[96:97], v[86:87], v[58:59], v[96:97] op_sel_hi:[0,1,1]
	v_pk_fma_f32 v[104:105], v[86:87], v[60:61], v[104:105] op_sel_hi:[0,1,1]
	ds_read_b128 v[58:61], v103 offset:5008
	s_waitcnt lgkmcnt(0)
	v_pk_fma_f32 v[104:105], v[84:85], v[60:61], v[104:105] op_sel_hi:[0,1,1]
	v_pk_fma_f32 v[96:97], v[84:85], v[58:59], v[96:97] op_sel_hi:[0,1,1]
	ds_read_b128 v[58:61], v103 offset:5136
	s_waitcnt lgkmcnt(0)
	v_pk_fma_f32 v[96:97], v[82:83], v[58:59], v[96:97] op_sel_hi:[0,1,1]
	v_pk_fma_f32 v[104:105], v[82:83], v[60:61], v[104:105] op_sel_hi:[0,1,1]
	ds_read_b128 v[58:61], v103 offset:5264
	s_waitcnt lgkmcnt(0)
	v_pk_fma_f32 v[104:105], v[80:81], v[60:61], v[104:105] op_sel_hi:[0,1,1]
	v_pk_fma_f32 v[96:97], v[80:81], v[58:59], v[96:97] op_sel_hi:[0,1,1]
	ds_read_b128 v[58:61], v103 offset:5392
	s_waitcnt lgkmcnt(0)
; #define LAS __attribute__((address_space(3)))
; __device__ __forceinline__ void gla_gates(const bf16* prow, const float* wg, const float* bg, int h, int lane, float (&bc)[32], LAS float* Wst) {
;     ...
; #pragma unroll
;     for (int d4 = 0; d4 < 8; ++d4) { f32x4 z = *(const LAS f32x4*)(Wst + 512 + 4 * d4);
; #pragma unroll
;         for (int r = 0; r < 16; ++r) { const f32x4 w = *(const LAS f32x4*)(Wst + r * 32 + 4 * d4); z += w * glr[r]; }
; #pragma unroll
;         for (int e = 0; e < 4; ++e) bc[4 * d4 + e] = (fminf(z[e], 0.f) - __logf(1.f + __expf(-fabsf(z[e])))) * (1.f / 16.f); }
	v_pk_fma_f32 v[96:97], v[78:79], v[58:59], v[96:97] op_sel_hi:[0,1,1]
	v_pk_fma_f32 v[104:105], v[78:79], v[60:61], v[104:105] op_sel_hi:[0,1,1]
	ds_read_b128 v[58:61], v103 offset:5520
	s_waitcnt lgkmcnt(0)
	v_pk_fma_f32 v[104:105], v[76:77], v[60:61], v[104:105] op_sel_hi:[0,1,1]
	v_pk_fma_f32 v[96:97], v[76:77], v[58:59], v[96:97] op_sel_hi:[0,1,1]
	ds_read_b128 v[58:61], v103 offset:5648
	s_waitcnt lgkmcnt(0)
	v_pk_fma_f32 v[96:97], v[74:75], v[58:59], v[96:97] op_sel_hi:[0,1,1]
	v_pk_fma_f32 v[104:105], v[74:75], v[60:61], v[104:105] op_sel_hi:[0,1,1]
	ds_read_b128 v[58:61], v103 offset:5776
	s_waitcnt lgkmcnt(0)
	v_pk_fma_f32 v[104:105], v[72:73], v[60:61], v[104:105] op_sel_hi:[0,1,1]
	v_pk_fma_f32 v[96:97], v[72:73], v[58:59], v[96:97] op_sel_hi:[0,1,1]
	ds_read_b128 v[58:61], v103 offset:5904
	s_waitcnt lgkmcnt(0)
	v_pk_fma_f32 v[96:97], v[70:71], v[58:59], v[96:97] op_sel_hi:[0,1,1]
	v_pk_fma_f32 v[104:105], v[70:71], v[60:61], v[104:105] op_sel_hi:[0,1,1]
	ds_read_b128 v[58:61], v103 offset:6032
	s_waitcnt lgkmcnt(0)
	v_pk_fma_f32 v[104:105], v[68:69], v[60:61], v[104:105] op_sel_hi:[0,1,1]
	v_pk_fma_f32 v[96:97], v[68:69], v[58:59], v[96:97] op_sel_hi:[0,1,1]
	ds_read_b128 v[58:61], v103 offset:6160
	s_waitcnt lgkmcnt(0)
	v_pk_fma_f32 v[96:97], v[66:67], v[58:59], v[96:97] op_sel_hi:[0,1,1]
	v_pk_fma_f32 v[104:105], v[66:67], v[60:61], v[104:105] op_sel_hi:[0,1,1]
	ds_read_b128 v[58:61], v103 offset:6288
	s_waitcnt lgkmcnt(0)
	v_pk_fma_f32 v[58:59], v[64:65], v[58:59], v[96:97] op_sel_hi:[0,1,1]
	v_min_f32_e32 v96, 0, v58
	v_mul_f32_e64 v58, |v58|, s97
	v_exp_f32_e32 v58, v58
	v_pk_fma_f32 v[60:61], v[64:65], v[60:61], v[104:105] op_sel_hi:[0,1,1]
	v_add_f32_e32 v58, 1.0, v58
	v_cmp_gt_f32_e32 vcc, s45, v58
	s_nop 1
	v_cndmask_b32_e64 v97, 0, 32, vcc
	v_ldexp_f32 v58, v58, v97
	v_log_f32_e32 v58, v58
	s_nop 0
	v_mul_f32_e32 v97, 0x3f317217, v58
	v_fma_f32 v97, v58, s31, -v97
	v_fmac_f32_e32 v97, 0x3377d1cf, v58
	v_fmac_f32_e32 v97, 0x3f317217, v58
	v_cmp_lt_f32_e64 s[18:19], |v58|, s44
	s_nop 1
	v_cndmask_b32_e64 v58, v58, v97, s[18:19]
	v_cndmask_b32_e32 v97, 0, v240, vcc
	v_sub_f32_e32 v58, v58, v97
	v_sub_f32_e32 v110, v96, v58
	v_min_f32_e32 v58, 0, v59
	v_mul_f32_e64 v59, |v59|, s97
	v_exp_f32_e32 v59, v59
	v_mul_f32_e32 v111, 0x3d800000, v110
	v_add_f32_e32 v59, 1.0, v59
	v_cmp_gt_f32_e32 vcc, s45, v59
	s_nop 1
	v_cndmask_b32_e64 v96, 0, 32, vcc
	v_ldexp_f32 v59, v59, v96
	v_log_f32_e32 v59, v59
	s_nop 0
	v_mul_f32_e32 v96, 0x3f317217, v59
	v_fma_f32 v96, v59, s31, -v96
	v_fmac_f32_e32 v96, 0x3377d1cf, v59
	v_fmac_f32_e32 v96, 0x3f317217, v59
	v_cmp_lt_f32_e64 s[18:19], |v59|, s44
	s_nop 1
	v_cndmask_b32_e64 v59, v59, v96, s[18:19]
	v_cndmask_b32_e32 v96, 0, v240, vcc
	v_sub_f32_e32 v59, v59, v96
	v_sub_f32_e32 v108, v58, v59
	v_mul_f32_e64 v59, |v60|, s97
	v_exp_f32_e32 v59, v59
	v_min_f32_e32 v58, 0, v60
	v_mul_f32_e32 v109, 0x3d800000, v108
	v_add_f32_e32 v59, 1.0, v59
	v_cmp_gt_f32_e32 vcc, s45, v59
	s_nop 1
	v_cndmask_b32_e64 v60, 0, 32, vcc
	v_ldexp_f32 v59, v59, v60
	v_log_f32_e32 v59, v59
	s_nop 0
	v_mul_f32_e32 v60, 0x3f317217, v59
	v_fma_f32 v60, v59, s31, -v60
	v_fmac_f32_e32 v60, 0x3377d1cf, v59
	v_fmac_f32_e32 v60, 0x3f317217, v59
	v_cmp_lt_f32_e64 s[18:19], |v59|, s44
	s_nop 1
	v_cndmask_b32_e64 v59, v59, v60, s[18:19]
	v_cndmask_b32_e32 v60, 0, v240, vcc
	v_sub_f32_e32 v59, v59, v60
	v_sub_f32_e32 v106, v58, v59
	v_mul_f32_e64 v59, |v61|, s97
	v_exp_f32_e32 v59, v59
	v_min_f32_e32 v58, 0, v61
	v_mul_f32_e32 v107, 0x3d800000, v106
	v_add_f32_e32 v59, 1.0, v59
	v_cmp_gt_f32_e32 vcc, s45, v59
	s_nop 1
	v_cndmask_b32_e64 v60, 0, 32, vcc
	v_ldexp_f32 v59, v59, v60
	v_log_f32_e32 v59, v59
	s_nop 0
	v_mul_f32_e32 v60, 0x3f317217, v59
	v_fma_f32 v60, v59, s31, -v60
	v_fmac_f32_e32 v60, 0x3377d1cf, v59
	v_fmac_f32_e32 v60, 0x3f317217, v59
	v_cmp_lt_f32_e64 s[18:19], |v59|, s44
	s_nop 1
	v_cndmask_b32_e64 v59, v59, v60, s[18:19]
	v_cndmask_b32_e32 v60, 0, v240, vcc
	v_sub_f32_e32 v59, v59, v60
	v_sub_f32_e32 v104, v58, v59
	ds_read_b128 v[58:61], v103 offset:6432
	v_mul_f32_e32 v105, 0x3d800000, v104
	s_waitcnt lgkmcnt(0)
	v_pk_fma_f32 v[58:59], v[94:95], v[54:55], v[58:59] op_sel_hi:[0,1,1]
	v_pk_fma_f32 v[60:61], v[94:95], v[56:57], v[60:61] op_sel_hi:[0,1,1]
	ds_read_b128 v[54:57], v103 offset:4512
	s_waitcnt lgkmcnt(0)
	v_pk_fma_f32 v[60:61], v[92:93], v[56:57], v[60:61] op_sel_hi:[0,1,1]
	v_pk_fma_f32 v[58:59], v[92:93], v[54:55], v[58:59] op_sel_hi:[0,1,1]
	ds_read_b128 v[54:57], v103 offset:4640
	s_waitcnt lgkmcnt(0)
	v_pk_fma_f32 v[58:59], v[90:91], v[54:55], v[58:59] op_sel_hi:[0,1,1]
	v_pk_fma_f32 v[60:61], v[90:91], v[56:57], v[60:61] op_sel_hi:[0,1,1]
	ds_read_b128 v[54:57], v103 offset:4768
	s_waitcnt lgkmcnt(0)
	v_pk_fma_f32 v[60:61], v[88:89], v[56:57], v[60:61] op_sel_hi:[0,1,1]
	v_pk_fma_f32 v[58:59], v[88:89], v[54:55], v[58:59] op_sel_hi:[0,1,1]
	ds_read_b128 v[54:57], v103 offset:4896
	s_waitcnt lgkmcnt(0)
	v_pk_fma_f32 v[58:59], v[86:87], v[54:55], v[58:59] op_sel_hi:[0,1,1]
	v_pk_fma_f32 v[60:61], v[86:87], v[56:57], v[60:61] op_sel_hi:[0,1,1]
	ds_read_b128 v[54:57], v103 offset:5024
	s_waitcnt lgkmcnt(0)
	v_pk_fma_f32 v[60:61], v[84:85], v[56:57], v[60:61] op_sel_hi:[0,1,1]
	v_pk_fma_f32 v[58:59], v[84:85], v[54:55], v[58:59] op_sel_hi:[0,1,1]
	ds_read_b128 v[54:57], v103 offset:5152
	s_waitcnt lgkmcnt(0)
	v_pk_fma_f32 v[58:59], v[82:83], v[54:55], v[58:59] op_sel_hi:[0,1,1]
	v_pk_fma_f32 v[60:61], v[82:83], v[56:57], v[60:61] op_sel_hi:[0,1,1]
	ds_read_b128 v[54:57], v103 offset:5280
	s_waitcnt lgkmcnt(0)
; #define LAS __attribute__((address_space(3)))
; __device__ __forceinline__ void gla_gates(const bf16* prow, const float* wg, const float* bg, int h, int lane, float (&bc)[32], LAS float* Wst) {
;     ...
; #pragma unroll
;     for (int d4 = 0; d4 < 8; ++d4) { f32x4 z = *(const LAS f32x4*)(Wst + 512 + 4 * d4);
; #pragma unroll
;         for (int r = 0; r < 16; ++r) { const f32x4 w = *(const LAS f32x4*)(Wst + r * 32 + 4 * d4); z += w * glr[r]; }
; #pragma unroll
;         for (int e = 0; e < 4; ++e) bc[4 * d4 + e] = (fminf(z[e], 0.f) - __logf(1.f + __expf(-fabsf(z[e])))) * (1.f / 16.f); }
	v_pk_fma_f32 v[60:61], v[80:81], v[56:57], v[60:61] op_sel_hi:[0,1,1]
	v_pk_fma_f32 v[58:59], v[80:81], v[54:55], v[58:59] op_sel_hi:[0,1,1]
	ds_read_b128 v[54:57], v103 offset:5408
	s_waitcnt lgkmcnt(0)
	v_pk_fma_f32 v[58:59], v[78:79], v[54:55], v[58:59] op_sel_hi:[0,1,1]
	v_pk_fma_f32 v[60:61], v[78:79], v[56:57], v[60:61] op_sel_hi:[0,1,1]
	ds_read_b128 v[54:57], v103 offset:5536
	s_waitcnt lgkmcnt(0)
	v_pk_fma_f32 v[60:61], v[76:77], v[56:57], v[60:61] op_sel_hi:[0,1,1]
	v_pk_fma_f32 v[58:59], v[76:77], v[54:55], v[58:59] op_sel_hi:[0,1,1]
	ds_read_b128 v[54:57], v103 offset:5664
	s_waitcnt lgkmcnt(0)
	v_pk_fma_f32 v[58:59], v[74:75], v[54:55], v[58:59] op_sel_hi:[0,1,1]
	v_pk_fma_f32 v[60:61], v[74:75], v[56:57], v[60:61] op_sel_hi:[0,1,1]
	ds_read_b128 v[54:57], v103 offset:5792
	s_waitcnt lgkmcnt(0)
	v_pk_fma_f32 v[60:61], v[72:73], v[56:57], v[60:61] op_sel_hi:[0,1,1]
	v_pk_fma_f32 v[58:59], v[72:73], v[54:55], v[58:59] op_sel_hi:[0,1,1]
	ds_read_b128 v[54:57], v103 offset:5920
	s_waitcnt lgkmcnt(0)
	v_pk_fma_f32 v[58:59], v[70:71], v[54:55], v[58:59] op_sel_hi:[0,1,1]
	v_pk_fma_f32 v[60:61], v[70:71], v[56:57], v[60:61] op_sel_hi:[0,1,1]
	ds_read_b128 v[54:57], v103 offset:6048
	s_waitcnt lgkmcnt(0)
	v_pk_fma_f32 v[60:61], v[68:69], v[56:57], v[60:61] op_sel_hi:[0,1,1]
	v_pk_fma_f32 v[58:59], v[68:69], v[54:55], v[58:59] op_sel_hi:[0,1,1]
	ds_read_b128 v[54:57], v103 offset:6176
	s_waitcnt lgkmcnt(0)
	v_pk_fma_f32 v[58:59], v[66:67], v[54:55], v[58:59] op_sel_hi:[0,1,1]
	v_pk_fma_f32 v[60:61], v[66:67], v[56:57], v[60:61] op_sel_hi:[0,1,1]
	ds_read_b128 v[54:57], v103 offset:6304
	s_waitcnt lgkmcnt(0)
	v_pk_fma_f32 v[54:55], v[64:65], v[54:55], v[58:59] op_sel_hi:[0,1,1]
	v_min_f32_e32 v58, 0, v54
	v_mul_f32_e64 v54, |v54|, s97
	v_exp_f32_e32 v54, v54
	v_pk_fma_f32 v[56:57], v[64:65], v[56:57], v[60:61] op_sel_hi:[0,1,1]
	v_add_f32_e32 v54, 1.0, v54
	v_cmp_gt_f32_e32 vcc, s45, v54
	s_nop 1
	v_cndmask_b32_e64 v59, 0, 32, vcc
	v_ldexp_f32 v54, v54, v59
	v_log_f32_e32 v54, v54
	s_nop 0
	v_mul_f32_e32 v59, 0x3f317217, v54
	v_fma_f32 v59, v54, s31, -v59
	v_fmac_f32_e32 v59, 0x3377d1cf, v54
	v_fmac_f32_e32 v59, 0x3f317217, v54
	v_cmp_lt_f32_e64 s[18:19], |v54|, s44
	s_nop 1
	v_cndmask_b32_e64 v54, v54, v59, s[18:19]
	v_cndmask_b32_e32 v59, 0, v240, vcc
	v_sub_f32_e32 v54, v54, v59
	v_sub_f32_e32 v96, v58, v54
	v_min_f32_e32 v54, 0, v55
	v_mul_f32_e64 v55, |v55|, s97
	v_exp_f32_e32 v55, v55
	v_mul_f32_e32 v97, 0x3d800000, v96
	v_add_f32_e32 v55, 1.0, v55
	v_cmp_gt_f32_e32 vcc, s45, v55
	s_nop 1
	v_cndmask_b32_e64 v58, 0, 32, vcc
	v_ldexp_f32 v55, v55, v58
	v_log_f32_e32 v55, v55
	s_nop 0
	v_mul_f32_e32 v58, 0x3f317217, v55
	v_fma_f32 v58, v55, s31, -v58
	v_fmac_f32_e32 v58, 0x3377d1cf, v55
	v_fmac_f32_e32 v58, 0x3f317217, v55
	v_cmp_lt_f32_e64 s[18:19], |v55|, s44
	s_nop 1
	v_cndmask_b32_e64 v55, v55, v58, s[18:19]
	v_cndmask_b32_e32 v58, 0, v240, vcc
	v_sub_f32_e32 v55, v55, v58
	v_sub_f32_e32 v60, v54, v55
	v_mul_f32_e64 v55, |v56|, s97
	v_exp_f32_e32 v55, v55
	v_min_f32_e32 v54, 0, v56
	v_mul_f32_e32 v61, 0x3d800000, v60
	v_add_f32_e32 v55, 1.0, v55
	v_cmp_gt_f32_e32 vcc, s45, v55
	s_nop 1
	v_cndmask_b32_e64 v56, 0, 32, vcc
	v_ldexp_f32 v55, v55, v56
	v_log_f32_e32 v55, v55
	s_nop 0
	v_mul_f32_e32 v56, 0x3f317217, v55
	v_fma_f32 v56, v55, s31, -v56
	v_fmac_f32_e32 v56, 0x3377d1cf, v55
	v_fmac_f32_e32 v56, 0x3f317217, v55
	v_cmp_lt_f32_e64 s[18:19], |v55|, s44
	s_nop 1
	v_cndmask_b32_e64 v55, v55, v56, s[18:19]
	v_cndmask_b32_e32 v56, 0, v240, vcc
	v_sub_f32_e32 v55, v55, v56
	v_sub_f32_e32 v58, v54, v55
	v_mul_f32_e64 v55, |v57|, s97
	v_exp_f32_e32 v55, v55
	v_min_f32_e32 v54, 0, v57
	v_mul_f32_e32 v59, 0x3d800000, v58
	v_add_f32_e32 v55, 1.0, v55
	v_cmp_gt_f32_e32 vcc, s45, v55
	s_nop 1
	v_cndmask_b32_e64 v56, 0, 32, vcc
	v_ldexp_f32 v55, v55, v56
	v_log_f32_e32 v55, v55
	s_nop 0
	v_mul_f32_e32 v56, 0x3f317217, v55
	v_fma_f32 v56, v55, s31, -v56
	v_fmac_f32_e32 v56, 0x3377d1cf, v55
	v_fmac_f32_e32 v56, 0x3f317217, v55
	v_cmp_lt_f32_e64 s[18:19], |v55|, s44
	s_nop 1
	v_cndmask_b32_e64 v55, v55, v56, s[18:19]
	v_cndmask_b32_e32 v56, 0, v240, vcc
	v_sub_f32_e32 v55, v55, v56
	v_sub_f32_e32 v56, v54, v55
	v_pk_fma_f32 v[54:55], v[94:95], v[50:51], v[112:113] op_sel_hi:[0,1,1]
	v_pk_fma_f32 v[112:113], v[94:95], v[52:53], v[114:115] op_sel_hi:[0,1,1]
	ds_read_b128 v[50:53], v103 offset:4528
	v_mul_f32_e32 v57, 0x3d800000, v56
	s_waitcnt lgkmcnt(0)
	v_pk_fma_f32 v[112:113], v[92:93], v[52:53], v[112:113] op_sel_hi:[0,1,1]
	v_pk_fma_f32 v[54:55], v[92:93], v[50:51], v[54:55] op_sel_hi:[0,1,1]
	ds_read_b128 v[50:53], v103 offset:4656
	s_waitcnt lgkmcnt(0)
	v_pk_fma_f32 v[54:55], v[90:91], v[50:51], v[54:55] op_sel_hi:[0,1,1]
	v_pk_fma_f32 v[112:113], v[90:91], v[52:53], v[112:113] op_sel_hi:[0,1,1]
	ds_read_b128 v[50:53], v103 offset:4784
	s_waitcnt lgkmcnt(0)
	v_pk_fma_f32 v[112:113], v[88:89], v[52:53], v[112:113] op_sel_hi:[0,1,1]
	v_pk_fma_f32 v[54:55], v[88:89], v[50:51], v[54:55] op_sel_hi:[0,1,1]
	ds_read_b128 v[50:53], v103 offset:4912
	s_waitcnt lgkmcnt(0)
	v_pk_fma_f32 v[54:55], v[86:87], v[50:51], v[54:55] op_sel_hi:[0,1,1]
	v_pk_fma_f32 v[112:113], v[86:87], v[52:53], v[112:113] op_sel_hi:[0,1,1]
	ds_read_b128 v[50:53], v103 offset:5040
	s_waitcnt lgkmcnt(0)
	v_pk_fma_f32 v[112:113], v[84:85], v[52:53], v[112:113] op_sel_hi:[0,1,1]
	v_pk_fma_f32 v[54:55], v[84:85], v[50:51], v[54:55] op_sel_hi:[0,1,1]
	ds_read_b128 v[50:53], v103 offset:5168
	s_waitcnt lgkmcnt(0)
	v_pk_fma_f32 v[54:55], v[82:83], v[50:51], v[54:55] op_sel_hi:[0,1,1]
	v_pk_fma_f32 v[112:113], v[82:83], v[52:53], v[112:113] op_sel_hi:[0,1,1]
	ds_read_b128 v[50:53], v103 offset:5296
	s_waitcnt lgkmcnt(0)
; #define LAS __attribute__((address_space(3)))
; __device__ __forceinline__ void gla_gates(const bf16* prow, const float* wg, const float* bg, int h, int lane, float (&bc)[32], LAS float* Wst) {
;     ...
; #pragma unroll
;     for (int d4 = 0; d4 < 8; ++d4) { f32x4 z = *(const LAS f32x4*)(Wst + 512 + 4 * d4);
; #pragma unroll
;         for (int r = 0; r < 16; ++r) { const f32x4 w = *(const LAS f32x4*)(Wst + r * 32 + 4 * d4); z += w * glr[r]; }
; #pragma unroll
;         for (int e = 0; e < 4; ++e) bc[4 * d4 + e] = (fminf(z[e], 0.f) - __logf(1.f + __expf(-fabsf(z[e])))) * (1.f / 16.f); }
	v_pk_fma_f32 v[112:113], v[80:81], v[52:53], v[112:113] op_sel_hi:[0,1,1]
	v_pk_fma_f32 v[54:55], v[80:81], v[50:51], v[54:55] op_sel_hi:[0,1,1]
	ds_read_b128 v[50:53], v103 offset:5424
	s_waitcnt lgkmcnt(0)
	v_pk_fma_f32 v[54:55], v[78:79], v[50:51], v[54:55] op_sel_hi:[0,1,1]
	v_pk_fma_f32 v[112:113], v[78:79], v[52:53], v[112:113] op_sel_hi:[0,1,1]
	ds_read_b128 v[50:53], v103 offset:5552
	s_waitcnt lgkmcnt(0)
	v_pk_fma_f32 v[112:113], v[76:77], v[52:53], v[112:113] op_sel_hi:[0,1,1]
	v_pk_fma_f32 v[54:55], v[76:77], v[50:51], v[54:55] op_sel_hi:[0,1,1]
	ds_read_b128 v[50:53], v103 offset:5680
	s_waitcnt lgkmcnt(0)
	v_pk_fma_f32 v[54:55], v[74:75], v[50:51], v[54:55] op_sel_hi:[0,1,1]
	v_pk_fma_f32 v[112:113], v[74:75], v[52:53], v[112:113] op_sel_hi:[0,1,1]
	ds_read_b128 v[50:53], v103 offset:5808
	s_waitcnt lgkmcnt(0)
	v_pk_fma_f32 v[112:113], v[72:73], v[52:53], v[112:113] op_sel_hi:[0,1,1]
	v_pk_fma_f32 v[54:55], v[72:73], v[50:51], v[54:55] op_sel_hi:[0,1,1]
	ds_read_b128 v[50:53], v103 offset:5936
	s_waitcnt lgkmcnt(0)
	v_pk_fma_f32 v[54:55], v[70:71], v[50:51], v[54:55] op_sel_hi:[0,1,1]
	v_pk_fma_f32 v[112:113], v[70:71], v[52:53], v[112:113] op_sel_hi:[0,1,1]
	ds_read_b128 v[50:53], v103 offset:6064
	s_waitcnt lgkmcnt(0)
	v_pk_fma_f32 v[112:113], v[68:69], v[52:53], v[112:113] op_sel_hi:[0,1,1]
	v_pk_fma_f32 v[54:55], v[68:69], v[50:51], v[54:55] op_sel_hi:[0,1,1]
	ds_read_b128 v[50:53], v103 offset:6192
	s_waitcnt lgkmcnt(0)
	v_pk_fma_f32 v[54:55], v[66:67], v[50:51], v[54:55] op_sel_hi:[0,1,1]
	v_pk_fma_f32 v[112:113], v[66:67], v[52:53], v[112:113] op_sel_hi:[0,1,1]
	ds_read_b128 v[50:53], v103 offset:6320
	s_waitcnt lgkmcnt(0)
	v_pk_fma_f32 v[50:51], v[64:65], v[50:51], v[54:55] op_sel_hi:[0,1,1]
	v_min_f32_e32 v54, 0, v50
	v_mul_f32_e64 v50, |v50|, s97
	v_exp_f32_e32 v50, v50
	v_pk_fma_f32 v[52:53], v[64:65], v[52:53], v[112:113] op_sel_hi:[0,1,1]
	v_add_f32_e32 v50, 1.0, v50
	v_cmp_gt_f32_e32 vcc, s45, v50
	s_nop 1
	v_cndmask_b32_e64 v55, 0, 32, vcc
	v_ldexp_f32 v50, v50, v55
	v_log_f32_e32 v50, v50
	s_nop 0
	v_mul_f32_e32 v55, 0x3f317217, v50
	v_fma_f32 v55, v50, s31, -v55
	v_fmac_f32_e32 v55, 0x3377d1cf, v50
	v_fmac_f32_e32 v55, 0x3f317217, v50
	v_cmp_lt_f32_e64 s[18:19], |v50|, s44
	s_nop 1
	v_cndmask_b32_e64 v50, v50, v55, s[18:19]
	v_cndmask_b32_e32 v55, 0, v240, vcc
	v_sub_f32_e32 v50, v50, v55
	v_sub_f32_e32 v126, v54, v50
	v_min_f32_e32 v50, 0, v51
	v_mul_f32_e64 v51, |v51|, s97
	v_exp_f32_e32 v51, v51
	v_mul_f32_e32 v127, 0x3d800000, v126
	v_add_f32_e32 v51, 1.0, v51
	v_cmp_gt_f32_e32 vcc, s45, v51
	s_nop 1
	v_cndmask_b32_e64 v54, 0, 32, vcc
	v_ldexp_f32 v51, v51, v54
	v_log_f32_e32 v51, v51
	s_nop 0
	v_mul_f32_e32 v54, 0x3f317217, v51
	v_fma_f32 v54, v51, s31, -v54
	v_fmac_f32_e32 v54, 0x3377d1cf, v51
	v_fmac_f32_e32 v54, 0x3f317217, v51
	v_cmp_lt_f32_e64 s[18:19], |v51|, s44
	s_nop 1
	v_cndmask_b32_e64 v51, v51, v54, s[18:19]
	v_cndmask_b32_e32 v54, 0, v240, vcc
	v_sub_f32_e32 v51, v51, v54
	v_sub_f32_e32 v124, v50, v51
	v_mul_f32_e64 v51, |v52|, s97
	v_exp_f32_e32 v51, v51
	v_min_f32_e32 v50, 0, v52
	v_mul_f32_e32 v125, 0x3d800000, v124
	v_add_f32_e32 v51, 1.0, v51
	v_cmp_gt_f32_e32 vcc, s45, v51
	s_nop 1
	v_cndmask_b32_e64 v52, 0, 32, vcc
	v_ldexp_f32 v51, v51, v52
	v_log_f32_e32 v51, v51
	s_nop 0
	v_mul_f32_e32 v52, 0x3f317217, v51
	v_fma_f32 v52, v51, s31, -v52
	v_fmac_f32_e32 v52, 0x3377d1cf, v51
	v_fmac_f32_e32 v52, 0x3f317217, v51
	v_cmp_lt_f32_e64 s[18:19], |v51|, s44
	s_nop 1
	v_cndmask_b32_e64 v51, v51, v52, s[18:19]
	v_cndmask_b32_e32 v52, 0, v240, vcc
	v_sub_f32_e32 v51, v51, v52
	v_sub_f32_e32 v122, v50, v51
	v_mul_f32_e64 v51, |v53|, s97
	v_exp_f32_e32 v51, v51
	v_min_f32_e32 v50, 0, v53
	v_mul_f32_e32 v123, 0x3d800000, v122
	v_add_f32_e32 v51, 1.0, v51
	v_cmp_gt_f32_e32 vcc, s45, v51
	s_nop 1
	v_cndmask_b32_e64 v52, 0, 32, vcc
	v_ldexp_f32 v51, v51, v52
	v_log_f32_e32 v51, v51
	s_nop 0
	v_mul_f32_e32 v52, 0x3f317217, v51
	v_fma_f32 v52, v51, s31, -v52
	v_fmac_f32_e32 v52, 0x3377d1cf, v51
	v_fmac_f32_e32 v52, 0x3f317217, v51
	v_cmp_lt_f32_e64 s[18:19], |v51|, s44
	s_nop 1
	v_cndmask_b32_e64 v51, v51, v52, s[18:19]
	v_cndmask_b32_e32 v52, 0, v240, vcc
	v_sub_f32_e32 v51, v51, v52
	v_sub_f32_e32 v120, v50, v51
	ds_read_b128 v[50:53], v103 offset:6464
	ds_read_b128 v[112:115], v103 offset:4416
	v_mul_f32_e32 v121, 0x3d800000, v120
	s_waitcnt lgkmcnt(0)
	v_pk_fma_f32 v[54:55], v[94:95], v[112:113], v[50:51] op_sel_hi:[0,1,1]
	v_pk_fma_f32 v[112:113], v[94:95], v[114:115], v[52:53] op_sel_hi:[0,1,1]
	ds_read_b128 v[50:53], v103 offset:4544
	s_waitcnt lgkmcnt(0)
	v_pk_fma_f32 v[112:113], v[92:93], v[52:53], v[112:113] op_sel_hi:[0,1,1]
	v_pk_fma_f32 v[54:55], v[92:93], v[50:51], v[54:55] op_sel_hi:[0,1,1]
	ds_read_b128 v[50:53], v103 offset:4672
	s_waitcnt lgkmcnt(0)
	v_pk_fma_f32 v[54:55], v[90:91], v[50:51], v[54:55] op_sel_hi:[0,1,1]
	v_pk_fma_f32 v[112:113], v[90:91], v[52:53], v[112:113] op_sel_hi:[0,1,1]
	ds_read_b128 v[50:53], v103 offset:4800
	s_waitcnt lgkmcnt(0)
	v_pk_fma_f32 v[112:113], v[88:89], v[52:53], v[112:113] op_sel_hi:[0,1,1]
	v_pk_fma_f32 v[54:55], v[88:89], v[50:51], v[54:55] op_sel_hi:[0,1,1]
	ds_read_b128 v[50:53], v103 offset:4928
	s_waitcnt lgkmcnt(0)
	v_pk_fma_f32 v[54:55], v[86:87], v[50:51], v[54:55] op_sel_hi:[0,1,1]
	v_pk_fma_f32 v[112:113], v[86:87], v[52:53], v[112:113] op_sel_hi:[0,1,1]
	ds_read_b128 v[50:53], v103 offset:5056
	s_waitcnt lgkmcnt(0)
	v_pk_fma_f32 v[112:113], v[84:85], v[52:53], v[112:113] op_sel_hi:[0,1,1]
	v_pk_fma_f32 v[54:55], v[84:85], v[50:51], v[54:55] op_sel_hi:[0,1,1]
	ds_read_b128 v[50:53], v103 offset:5184
	s_waitcnt lgkmcnt(0)
; #define LAS __attribute__((address_space(3)))
; __device__ __forceinline__ void gla_gates(const bf16* prow, const float* wg, const float* bg, int h, int lane, float (&bc)[32], LAS float* Wst) {
;     ...
; #pragma unroll
;     for (int d4 = 0; d4 < 8; ++d4) { f32x4 z = *(const LAS f32x4*)(Wst + 512 + 4 * d4);
; #pragma unroll
;         for (int r = 0; r < 16; ++r) { const f32x4 w = *(const LAS f32x4*)(Wst + r * 32 + 4 * d4); z += w * glr[r]; }
; #pragma unroll
;         for (int e = 0; e < 4; ++e) bc[4 * d4 + e] = (fminf(z[e], 0.f) - __logf(1.f + __expf(-fabsf(z[e])))) * (1.f / 16.f); }
	v_pk_fma_f32 v[54:55], v[82:83], v[50:51], v[54:55] op_sel_hi:[0,1,1]
	v_pk_fma_f32 v[112:113], v[82:83], v[52:53], v[112:113] op_sel_hi:[0,1,1]
	ds_read_b128 v[50:53], v103 offset:5312
	s_waitcnt lgkmcnt(0)
	v_pk_fma_f32 v[112:113], v[80:81], v[52:53], v[112:113] op_sel_hi:[0,1,1]
	v_pk_fma_f32 v[54:55], v[80:81], v[50:51], v[54:55] op_sel_hi:[0,1,1]
	ds_read_b128 v[50:53], v103 offset:5440
	s_waitcnt lgkmcnt(0)
	v_pk_fma_f32 v[54:55], v[78:79], v[50:51], v[54:55] op_sel_hi:[0,1,1]
	v_pk_fma_f32 v[112:113], v[78:79], v[52:53], v[112:113] op_sel_hi:[0,1,1]
	ds_read_b128 v[50:53], v103 offset:5568
	s_waitcnt lgkmcnt(0)
	v_pk_fma_f32 v[112:113], v[76:77], v[52:53], v[112:113] op_sel_hi:[0,1,1]
	v_pk_fma_f32 v[54:55], v[76:77], v[50:51], v[54:55] op_sel_hi:[0,1,1]
	ds_read_b128 v[50:53], v103 offset:5696
	s_waitcnt lgkmcnt(0)
	v_pk_fma_f32 v[54:55], v[74:75], v[50:51], v[54:55] op_sel_hi:[0,1,1]
	v_pk_fma_f32 v[112:113], v[74:75], v[52:53], v[112:113] op_sel_hi:[0,1,1]
	ds_read_b128 v[50:53], v103 offset:5824
	s_waitcnt lgkmcnt(0)
	v_pk_fma_f32 v[112:113], v[72:73], v[52:53], v[112:113] op_sel_hi:[0,1,1]
	v_pk_fma_f32 v[54:55], v[72:73], v[50:51], v[54:55] op_sel_hi:[0,1,1]
	ds_read_b128 v[50:53], v103 offset:5952
	s_waitcnt lgkmcnt(0)
	v_pk_fma_f32 v[54:55], v[70:71], v[50:51], v[54:55] op_sel_hi:[0,1,1]
	v_pk_fma_f32 v[112:113], v[70:71], v[52:53], v[112:113] op_sel_hi:[0,1,1]
	ds_read_b128 v[50:53], v103 offset:6080
	s_waitcnt lgkmcnt(0)
	v_pk_fma_f32 v[112:113], v[68:69], v[52:53], v[112:113] op_sel_hi:[0,1,1]
	v_pk_fma_f32 v[54:55], v[68:69], v[50:51], v[54:55] op_sel_hi:[0,1,1]
	ds_read_b128 v[50:53], v103 offset:6208
	s_waitcnt lgkmcnt(0)
	v_pk_fma_f32 v[54:55], v[66:67], v[50:51], v[54:55] op_sel_hi:[0,1,1]
	v_pk_fma_f32 v[112:113], v[66:67], v[52:53], v[112:113] op_sel_hi:[0,1,1]
	ds_read_b128 v[50:53], v103 offset:6336
	s_waitcnt lgkmcnt(0)
	v_pk_fma_f32 v[50:51], v[64:65], v[50:51], v[54:55] op_sel_hi:[0,1,1]
	v_min_f32_e32 v54, 0, v50
	v_mul_f32_e64 v50, |v50|, s97
	v_exp_f32_e32 v50, v50
	v_pk_fma_f32 v[52:53], v[64:65], v[52:53], v[112:113] op_sel_hi:[0,1,1]
	v_add_f32_e32 v50, 1.0, v50
	v_cmp_gt_f32_e32 vcc, s45, v50
	s_nop 1
	v_cndmask_b32_e64 v55, 0, 32, vcc
	v_ldexp_f32 v50, v50, v55
	v_log_f32_e32 v50, v50
	s_nop 0
	v_mul_f32_e32 v55, 0x3f317217, v50
	v_fma_f32 v55, v50, s31, -v55
	v_fmac_f32_e32 v55, 0x3377d1cf, v50
	v_fmac_f32_e32 v55, 0x3f317217, v50
	v_cmp_lt_f32_e64 s[18:19], |v50|, s44
	s_nop 1
	v_cndmask_b32_e64 v50, v50, v55, s[18:19]
	v_cndmask_b32_e32 v55, 0, v240, vcc
	v_sub_f32_e32 v50, v50, v55
	v_sub_f32_e32 v118, v54, v50
	v_min_f32_e32 v50, 0, v51
	v_mul_f32_e64 v51, |v51|, s97
	v_exp_f32_e32 v51, v51
	v_mul_f32_e32 v119, 0x3d800000, v118
	v_add_f32_e32 v51, 1.0, v51
	v_cmp_gt_f32_e32 vcc, s45, v51
	s_nop 1
	v_cndmask_b32_e64 v54, 0, 32, vcc
	v_ldexp_f32 v51, v51, v54
	v_log_f32_e32 v51, v51
	s_nop 0
	v_mul_f32_e32 v54, 0x3f317217, v51
	v_fma_f32 v54, v51, s31, -v54
	v_fmac_f32_e32 v54, 0x3377d1cf, v51
	v_fmac_f32_e32 v54, 0x3f317217, v51
	v_cmp_lt_f32_e64 s[18:19], |v51|, s44
	s_nop 1
	v_cndmask_b32_e64 v51, v51, v54, s[18:19]
	v_cndmask_b32_e32 v54, 0, v240, vcc
	v_sub_f32_e32 v51, v51, v54
	v_sub_f32_e32 v116, v50, v51
	v_mul_f32_e64 v51, |v52|, s97
	v_exp_f32_e32 v51, v51
	v_min_f32_e32 v50, 0, v52
	v_mul_f32_e32 v117, 0x3d800000, v116
	v_add_f32_e32 v51, 1.0, v51
	v_cmp_gt_f32_e32 vcc, s45, v51
	s_nop 1
	v_cndmask_b32_e64 v52, 0, 32, vcc
	v_ldexp_f32 v51, v51, v52
	v_log_f32_e32 v51, v51
	s_nop 0
	v_mul_f32_e32 v52, 0x3f317217, v51
	v_fma_f32 v52, v51, s31, -v52
	v_fmac_f32_e32 v52, 0x3377d1cf, v51
	v_fmac_f32_e32 v52, 0x3f317217, v51
	v_cmp_lt_f32_e64 s[18:19], |v51|, s44
	s_nop 1
	v_cndmask_b32_e64 v51, v51, v52, s[18:19]
	v_cndmask_b32_e32 v52, 0, v240, vcc
	v_sub_f32_e32 v51, v51, v52
	v_sub_f32_e32 v114, v50, v51
	v_mul_f32_e64 v51, |v53|, s97
	v_exp_f32_e32 v51, v51
	v_min_f32_e32 v50, 0, v53
	v_mul_f32_e32 v115, 0x3d800000, v114
	v_add_f32_e32 v51, 1.0, v51
	v_cmp_gt_f32_e32 vcc, s45, v51
	s_nop 1
	v_cndmask_b32_e64 v52, 0, 32, vcc
	v_ldexp_f32 v51, v51, v52
	v_log_f32_e32 v51, v51
	s_nop 0
	v_mul_f32_e32 v52, 0x3f317217, v51
	v_fma_f32 v52, v51, s31, -v52
	v_fmac_f32_e32 v52, 0x3377d1cf, v51
	v_fmac_f32_e32 v52, 0x3f317217, v51
	v_cmp_lt_f32_e64 s[18:19], |v51|, s44
	s_nop 1
	v_cndmask_b32_e64 v51, v51, v52, s[18:19]
	v_cndmask_b32_e32 v52, 0, v240, vcc
	v_sub_f32_e32 v51, v51, v52
	v_sub_f32_e32 v112, v50, v51
	ds_read_b128 v[50:53], v103 offset:6480
	ds_read_b128 v[128:131], v103 offset:4432
	v_mul_f32_e32 v113, 0x3d800000, v112
	s_waitcnt lgkmcnt(0)
	v_pk_fma_f32 v[54:55], v[94:95], v[128:129], v[50:51] op_sel_hi:[0,1,1]
	v_pk_fma_f32 v[128:129], v[94:95], v[130:131], v[52:53] op_sel_hi:[0,1,1]
	ds_read_b128 v[50:53], v103 offset:4560
	s_waitcnt lgkmcnt(0)
	v_pk_fma_f32 v[128:129], v[92:93], v[52:53], v[128:129] op_sel_hi:[0,1,1]
	v_pk_fma_f32 v[54:55], v[92:93], v[50:51], v[54:55] op_sel_hi:[0,1,1]
	ds_read_b128 v[50:53], v103 offset:4688
	s_waitcnt lgkmcnt(0)
	v_pk_fma_f32 v[54:55], v[90:91], v[50:51], v[54:55] op_sel_hi:[0,1,1]
	v_pk_fma_f32 v[128:129], v[90:91], v[52:53], v[128:129] op_sel_hi:[0,1,1]
	ds_read_b128 v[50:53], v103 offset:4816
	s_waitcnt lgkmcnt(0)
	v_pk_fma_f32 v[128:129], v[88:89], v[52:53], v[128:129] op_sel_hi:[0,1,1]
	v_pk_fma_f32 v[54:55], v[88:89], v[50:51], v[54:55] op_sel_hi:[0,1,1]
	ds_read_b128 v[50:53], v103 offset:4944
	s_waitcnt lgkmcnt(0)
	v_pk_fma_f32 v[54:55], v[86:87], v[50:51], v[54:55] op_sel_hi:[0,1,1]
	v_pk_fma_f32 v[128:129], v[86:87], v[52:53], v[128:129] op_sel_hi:[0,1,1]
	ds_read_b128 v[50:53], v103 offset:5072
	s_waitcnt lgkmcnt(0)
; #define LAS __attribute__((address_space(3)))
; __device__ __forceinline__ void gla_gates(const bf16* prow, const float* wg, const float* bg, int h, int lane, float (&bc)[32], LAS float* Wst) {
;     ...
; #pragma unroll
;     for (int d4 = 0; d4 < 8; ++d4) { f32x4 z = *(const LAS f32x4*)(Wst + 512 + 4 * d4);
; #pragma unroll
;         for (int r = 0; r < 16; ++r) { const f32x4 w = *(const LAS f32x4*)(Wst + r * 32 + 4 * d4); z += w * glr[r]; }
; #pragma unroll
;         for (int e = 0; e < 4; ++e) bc[4 * d4 + e] = (fminf(z[e], 0.f) - __logf(1.f + __expf(-fabsf(z[e])))) * (1.f / 16.f); }
	v_pk_fma_f32 v[128:129], v[84:85], v[52:53], v[128:129] op_sel_hi:[0,1,1]
	v_pk_fma_f32 v[54:55], v[84:85], v[50:51], v[54:55] op_sel_hi:[0,1,1]
	ds_read_b128 v[50:53], v103 offset:5200
	s_waitcnt lgkmcnt(0)
	v_pk_fma_f32 v[54:55], v[82:83], v[50:51], v[54:55] op_sel_hi:[0,1,1]
	v_pk_fma_f32 v[128:129], v[82:83], v[52:53], v[128:129] op_sel_hi:[0,1,1]
	ds_read_b128 v[50:53], v103 offset:5328
	s_waitcnt lgkmcnt(0)
	v_pk_fma_f32 v[128:129], v[80:81], v[52:53], v[128:129] op_sel_hi:[0,1,1]
	v_pk_fma_f32 v[54:55], v[80:81], v[50:51], v[54:55] op_sel_hi:[0,1,1]
	ds_read_b128 v[50:53], v103 offset:5456
	s_waitcnt lgkmcnt(0)
	v_pk_fma_f32 v[54:55], v[78:79], v[50:51], v[54:55] op_sel_hi:[0,1,1]
	v_pk_fma_f32 v[128:129], v[78:79], v[52:53], v[128:129] op_sel_hi:[0,1,1]
	ds_read_b128 v[50:53], v103 offset:5584
	s_waitcnt lgkmcnt(0)
	v_pk_fma_f32 v[128:129], v[76:77], v[52:53], v[128:129] op_sel_hi:[0,1,1]
	v_pk_fma_f32 v[54:55], v[76:77], v[50:51], v[54:55] op_sel_hi:[0,1,1]
	ds_read_b128 v[50:53], v103 offset:5712
	s_waitcnt lgkmcnt(0)
	v_pk_fma_f32 v[54:55], v[74:75], v[50:51], v[54:55] op_sel_hi:[0,1,1]
	v_pk_fma_f32 v[128:129], v[74:75], v[52:53], v[128:129] op_sel_hi:[0,1,1]
	ds_read_b128 v[50:53], v103 offset:5840
	s_waitcnt lgkmcnt(0)
	v_pk_fma_f32 v[128:129], v[72:73], v[52:53], v[128:129] op_sel_hi:[0,1,1]
	v_pk_fma_f32 v[54:55], v[72:73], v[50:51], v[54:55] op_sel_hi:[0,1,1]
	ds_read_b128 v[50:53], v103 offset:5968
	s_waitcnt lgkmcnt(0)
	v_pk_fma_f32 v[54:55], v[70:71], v[50:51], v[54:55] op_sel_hi:[0,1,1]
	v_pk_fma_f32 v[128:129], v[70:71], v[52:53], v[128:129] op_sel_hi:[0,1,1]
	ds_read_b128 v[50:53], v103 offset:6096
	s_waitcnt lgkmcnt(0)
	v_pk_fma_f32 v[128:129], v[68:69], v[52:53], v[128:129] op_sel_hi:[0,1,1]
	v_pk_fma_f32 v[54:55], v[68:69], v[50:51], v[54:55] op_sel_hi:[0,1,1]
	ds_read_b128 v[50:53], v103 offset:6224
	s_waitcnt lgkmcnt(0)
	v_pk_fma_f32 v[54:55], v[66:67], v[50:51], v[54:55] op_sel_hi:[0,1,1]
	v_pk_fma_f32 v[128:129], v[66:67], v[52:53], v[128:129] op_sel_hi:[0,1,1]
	ds_read_b128 v[50:53], v103 offset:6352
	s_waitcnt lgkmcnt(0)
	v_pk_fma_f32 v[50:51], v[64:65], v[50:51], v[54:55] op_sel_hi:[0,1,1]
	v_min_f32_e32 v54, 0, v50
	v_mul_f32_e64 v50, |v50|, s97
	v_exp_f32_e32 v50, v50
	v_pk_fma_f32 v[52:53], v[64:65], v[52:53], v[128:129] op_sel_hi:[0,1,1]
	v_add_f32_e32 v50, 1.0, v50
	v_cmp_gt_f32_e32 vcc, s45, v50
	s_nop 1
	v_cndmask_b32_e64 v55, 0, 32, vcc
	v_ldexp_f32 v50, v50, v55
	v_log_f32_e32 v50, v50
	s_nop 0
	v_mul_f32_e32 v55, 0x3f317217, v50
	v_fma_f32 v55, v50, s31, -v55
	v_fmac_f32_e32 v55, 0x3377d1cf, v50
	v_fmac_f32_e32 v55, 0x3f317217, v50
	v_cmp_lt_f32_e64 s[18:19], |v50|, s44
	s_nop 1
	v_cndmask_b32_e64 v50, v50, v55, s[18:19]
	v_cndmask_b32_e32 v55, 0, v240, vcc
	v_sub_f32_e32 v50, v50, v55
	v_sub_f32_e32 v142, v54, v50
	v_min_f32_e32 v50, 0, v51
	v_mul_f32_e64 v51, |v51|, s97
	v_exp_f32_e32 v51, v51
	v_mul_f32_e32 v143, 0x3d800000, v142
	v_add_f32_e32 v51, 1.0, v51
	v_cmp_gt_f32_e32 vcc, s45, v51
	s_nop 1
	v_cndmask_b32_e64 v54, 0, 32, vcc
	v_ldexp_f32 v51, v51, v54
	v_log_f32_e32 v51, v51
	s_nop 0
	v_mul_f32_e32 v54, 0x3f317217, v51
	v_fma_f32 v54, v51, s31, -v54
	v_fmac_f32_e32 v54, 0x3377d1cf, v51
	v_fmac_f32_e32 v54, 0x3f317217, v51
	v_cmp_lt_f32_e64 s[18:19], |v51|, s44
	s_nop 1
	v_cndmask_b32_e64 v51, v51, v54, s[18:19]
	v_cndmask_b32_e32 v54, 0, v240, vcc
	v_sub_f32_e32 v51, v51, v54
	v_sub_f32_e32 v140, v50, v51
	v_mul_f32_e64 v51, |v52|, s97
	v_exp_f32_e32 v51, v51
	v_min_f32_e32 v50, 0, v52
	v_mul_f32_e32 v141, 0x3d800000, v140
	v_add_f32_e32 v51, 1.0, v51
	v_cmp_gt_f32_e32 vcc, s45, v51
	s_nop 1
	v_cndmask_b32_e64 v52, 0, 32, vcc
	v_ldexp_f32 v51, v51, v52
	v_log_f32_e32 v51, v51
	s_nop 0
	v_mul_f32_e32 v52, 0x3f317217, v51
	v_fma_f32 v52, v51, s31, -v52
	v_fmac_f32_e32 v52, 0x3377d1cf, v51
	v_fmac_f32_e32 v52, 0x3f317217, v51
	v_cmp_lt_f32_e64 s[18:19], |v51|, s44
	s_nop 1
	v_cndmask_b32_e64 v51, v51, v52, s[18:19]
	v_cndmask_b32_e32 v52, 0, v240, vcc
	v_sub_f32_e32 v51, v51, v52
	v_sub_f32_e32 v138, v50, v51
	v_mul_f32_e64 v51, |v53|, s97
	v_exp_f32_e32 v51, v51
	v_min_f32_e32 v50, 0, v53
	v_mul_f32_e32 v139, 0x3d800000, v138
	v_add_f32_e32 v51, 1.0, v51
	v_cmp_gt_f32_e32 vcc, s45, v51
	s_nop 1
	v_cndmask_b32_e64 v52, 0, 32, vcc
	v_ldexp_f32 v51, v51, v52
	v_log_f32_e32 v51, v51
	s_nop 0
	v_mul_f32_e32 v52, 0x3f317217, v51
	v_fma_f32 v52, v51, s31, -v52
	v_fmac_f32_e32 v52, 0x3377d1cf, v51
	v_fmac_f32_e32 v52, 0x3f317217, v51
	v_cmp_lt_f32_e64 s[18:19], |v51|, s44
	s_nop 1
	v_cndmask_b32_e64 v51, v51, v52, s[18:19]
	v_cndmask_b32_e32 v52, 0, v240, vcc
	v_sub_f32_e32 v51, v51, v52
	v_sub_f32_e32 v136, v50, v51
	ds_read_b128 v[50:53], v103 offset:6496
	ds_read_b128 v[128:131], v103 offset:4448
	v_mul_f32_e32 v137, 0x3d800000, v136
	s_waitcnt lgkmcnt(0)
	v_pk_fma_f32 v[54:55], v[94:95], v[128:129], v[50:51] op_sel_hi:[0,1,1]
	v_pk_fma_f32 v[128:129], v[94:95], v[130:131], v[52:53] op_sel_hi:[0,1,1]
	ds_read_b128 v[50:53], v103 offset:4576
	s_waitcnt lgkmcnt(0)
	v_pk_fma_f32 v[128:129], v[92:93], v[52:53], v[128:129] op_sel_hi:[0,1,1]
	v_pk_fma_f32 v[54:55], v[92:93], v[50:51], v[54:55] op_sel_hi:[0,1,1]
	ds_read_b128 v[50:53], v103 offset:4704
	s_waitcnt lgkmcnt(0)
	v_pk_fma_f32 v[54:55], v[90:91], v[50:51], v[54:55] op_sel_hi:[0,1,1]
	v_pk_fma_f32 v[128:129], v[90:91], v[52:53], v[128:129] op_sel_hi:[0,1,1]
	ds_read_b128 v[50:53], v103 offset:4832
	s_waitcnt lgkmcnt(0)
	v_pk_fma_f32 v[128:129], v[88:89], v[52:53], v[128:129] op_sel_hi:[0,1,1]
	v_pk_fma_f32 v[54:55], v[88:89], v[50:51], v[54:55] op_sel_hi:[0,1,1]
	ds_read_b128 v[50:53], v103 offset:4960
	s_waitcnt lgkmcnt(0)
; #define LAS __attribute__((address_space(3)))
; __device__ __forceinline__ void gla_gates(const bf16* prow, const float* wg, const float* bg, int h, int lane, float (&bc)[32], LAS float* Wst) {
;     ...
; #pragma unroll
;     for (int d4 = 0; d4 < 8; ++d4) { f32x4 z = *(const LAS f32x4*)(Wst + 512 + 4 * d4);
; #pragma unroll
;         for (int r = 0; r < 16; ++r) { const f32x4 w = *(const LAS f32x4*)(Wst + r * 32 + 4 * d4); z += w * glr[r]; }
; #pragma unroll
;         for (int e = 0; e < 4; ++e) bc[4 * d4 + e] = (fminf(z[e], 0.f) - __logf(1.f + __expf(-fabsf(z[e])))) * (1.f / 16.f); }
	v_pk_fma_f32 v[54:55], v[86:87], v[50:51], v[54:55] op_sel_hi:[0,1,1]
	v_pk_fma_f32 v[128:129], v[86:87], v[52:53], v[128:129] op_sel_hi:[0,1,1]
	ds_read_b128 v[50:53], v103 offset:5088
	s_waitcnt lgkmcnt(0)
	v_pk_fma_f32 v[128:129], v[84:85], v[52:53], v[128:129] op_sel_hi:[0,1,1]
	v_pk_fma_f32 v[54:55], v[84:85], v[50:51], v[54:55] op_sel_hi:[0,1,1]
	ds_read_b128 v[50:53], v103 offset:5216
	s_waitcnt lgkmcnt(0)
	v_pk_fma_f32 v[54:55], v[82:83], v[50:51], v[54:55] op_sel_hi:[0,1,1]
	v_pk_fma_f32 v[128:129], v[82:83], v[52:53], v[128:129] op_sel_hi:[0,1,1]
	ds_read_b128 v[50:53], v103 offset:5344
	s_waitcnt lgkmcnt(0)
	v_pk_fma_f32 v[128:129], v[80:81], v[52:53], v[128:129] op_sel_hi:[0,1,1]
	v_pk_fma_f32 v[54:55], v[80:81], v[50:51], v[54:55] op_sel_hi:[0,1,1]
	ds_read_b128 v[50:53], v103 offset:5472
	s_waitcnt lgkmcnt(0)
	v_pk_fma_f32 v[54:55], v[78:79], v[50:51], v[54:55] op_sel_hi:[0,1,1]
	v_pk_fma_f32 v[128:129], v[78:79], v[52:53], v[128:129] op_sel_hi:[0,1,1]
	ds_read_b128 v[50:53], v103 offset:5600
	s_waitcnt lgkmcnt(0)
	v_pk_fma_f32 v[128:129], v[76:77], v[52:53], v[128:129] op_sel_hi:[0,1,1]
	v_pk_fma_f32 v[54:55], v[76:77], v[50:51], v[54:55] op_sel_hi:[0,1,1]
	ds_read_b128 v[50:53], v103 offset:5728
	s_waitcnt lgkmcnt(0)
	v_pk_fma_f32 v[54:55], v[74:75], v[50:51], v[54:55] op_sel_hi:[0,1,1]
	v_pk_fma_f32 v[128:129], v[74:75], v[52:53], v[128:129] op_sel_hi:[0,1,1]
	ds_read_b128 v[50:53], v103 offset:5856
	s_waitcnt lgkmcnt(0)
	v_pk_fma_f32 v[128:129], v[72:73], v[52:53], v[128:129] op_sel_hi:[0,1,1]
	v_pk_fma_f32 v[54:55], v[72:73], v[50:51], v[54:55] op_sel_hi:[0,1,1]
	ds_read_b128 v[50:53], v103 offset:5984
	s_waitcnt lgkmcnt(0)
	v_pk_fma_f32 v[54:55], v[70:71], v[50:51], v[54:55] op_sel_hi:[0,1,1]
	v_pk_fma_f32 v[128:129], v[70:71], v[52:53], v[128:129] op_sel_hi:[0,1,1]
	ds_read_b128 v[50:53], v103 offset:6112
	s_waitcnt lgkmcnt(0)
	v_pk_fma_f32 v[128:129], v[68:69], v[52:53], v[128:129] op_sel_hi:[0,1,1]
	v_pk_fma_f32 v[54:55], v[68:69], v[50:51], v[54:55] op_sel_hi:[0,1,1]
	ds_read_b128 v[50:53], v103 offset:6240
	s_waitcnt lgkmcnt(0)
	v_pk_fma_f32 v[54:55], v[66:67], v[50:51], v[54:55] op_sel_hi:[0,1,1]
	v_pk_fma_f32 v[128:129], v[66:67], v[52:53], v[128:129] op_sel_hi:[0,1,1]
	ds_read_b128 v[50:53], v103 offset:6368
	s_waitcnt lgkmcnt(0)
	v_pk_fma_f32 v[50:51], v[64:65], v[50:51], v[54:55] op_sel_hi:[0,1,1]
	v_min_f32_e32 v54, 0, v50
	v_mul_f32_e64 v50, |v50|, s97
	v_exp_f32_e32 v50, v50
	v_pk_fma_f32 v[52:53], v[64:65], v[52:53], v[128:129] op_sel_hi:[0,1,1]
	v_add_f32_e32 v50, 1.0, v50
	v_cmp_gt_f32_e32 vcc, s45, v50
	s_nop 1
	v_cndmask_b32_e64 v55, 0, 32, vcc
	v_ldexp_f32 v50, v50, v55
	v_log_f32_e32 v50, v50
	s_nop 0
	v_mul_f32_e32 v55, 0x3f317217, v50
	v_fma_f32 v55, v50, s31, -v55
	v_fmac_f32_e32 v55, 0x3377d1cf, v50
	v_fmac_f32_e32 v55, 0x3f317217, v50
	v_cmp_lt_f32_e64 s[18:19], |v50|, s44
	s_nop 1
	v_cndmask_b32_e64 v50, v50, v55, s[18:19]
	v_cndmask_b32_e32 v55, 0, v240, vcc
	v_sub_f32_e32 v50, v50, v55
	v_sub_f32_e32 v134, v54, v50
	v_min_f32_e32 v50, 0, v51
	v_mul_f32_e64 v51, |v51|, s97
	v_exp_f32_e32 v51, v51
	v_mul_f32_e32 v135, 0x3d800000, v134
	v_add_f32_e32 v51, 1.0, v51
	v_cmp_gt_f32_e32 vcc, s45, v51
	s_nop 1
	v_cndmask_b32_e64 v54, 0, 32, vcc
	v_ldexp_f32 v51, v51, v54
	v_log_f32_e32 v51, v51
	s_nop 0
	v_mul_f32_e32 v54, 0x3f317217, v51
	v_fma_f32 v54, v51, s31, -v54
	v_fmac_f32_e32 v54, 0x3377d1cf, v51
	v_fmac_f32_e32 v54, 0x3f317217, v51
	v_cmp_lt_f32_e64 s[18:19], |v51|, s44
	s_nop 1
	v_cndmask_b32_e64 v51, v51, v54, s[18:19]
	v_cndmask_b32_e32 v54, 0, v240, vcc
	v_sub_f32_e32 v51, v51, v54
	v_sub_f32_e32 v132, v50, v51
	v_mul_f32_e64 v51, |v52|, s97
	v_exp_f32_e32 v51, v51
	v_min_f32_e32 v50, 0, v52
	v_mul_f32_e32 v133, 0x3d800000, v132
	v_add_f32_e32 v51, 1.0, v51
	v_cmp_gt_f32_e32 vcc, s45, v51
	s_nop 1
	v_cndmask_b32_e64 v52, 0, 32, vcc
	v_ldexp_f32 v51, v51, v52
	v_log_f32_e32 v51, v51
	s_nop 0
	v_mul_f32_e32 v52, 0x3f317217, v51
	v_fma_f32 v52, v51, s31, -v52
	v_fmac_f32_e32 v52, 0x3377d1cf, v51
	v_fmac_f32_e32 v52, 0x3f317217, v51
	v_cmp_lt_f32_e64 s[18:19], |v51|, s44
	s_nop 1
	v_cndmask_b32_e64 v51, v51, v52, s[18:19]
	v_cndmask_b32_e32 v52, 0, v240, vcc
	v_sub_f32_e32 v51, v51, v52
	v_sub_f32_e32 v130, v50, v51
	v_mul_f32_e64 v51, |v53|, s97
	v_exp_f32_e32 v51, v51
	v_min_f32_e32 v50, 0, v53
	v_mul_f32_e32 v131, 0x3d800000, v130
	v_add_f32_e32 v51, 1.0, v51
	v_cmp_gt_f32_e32 vcc, s45, v51
	s_nop 1
	v_cndmask_b32_e64 v52, 0, 32, vcc
	v_ldexp_f32 v51, v51, v52
	v_log_f32_e32 v51, v51
	s_nop 0
	v_mul_f32_e32 v52, 0x3f317217, v51
	v_fma_f32 v52, v51, s31, -v52
	v_fmac_f32_e32 v52, 0x3377d1cf, v51
	v_fmac_f32_e32 v52, 0x3f317217, v51
	v_cmp_lt_f32_e64 s[18:19], |v51|, s44
	s_nop 1
	v_cndmask_b32_e64 v51, v51, v52, s[18:19]
	v_cndmask_b32_e32 v52, 0, v240, vcc
	v_sub_f32_e32 v51, v51, v52
	v_sub_f32_e32 v128, v50, v51
	ds_read_b128 v[50:53], v103 offset:6512
	ds_read_b128 v[144:147], v103 offset:4464
	v_mul_f32_e32 v129, 0x3d800000, v128
	s_waitcnt lgkmcnt(0)
	v_pk_fma_f32 v[54:55], v[94:95], v[144:145], v[50:51] op_sel_hi:[0,1,1]
	v_pk_fma_f32 v[144:145], v[94:95], v[146:147], v[52:53] op_sel_hi:[0,1,1]
	ds_read_b128 v[50:53], v103 offset:4592
	s_waitcnt lgkmcnt(0)
	v_pk_fma_f32 v[144:145], v[92:93], v[52:53], v[144:145] op_sel_hi:[0,1,1]
	v_pk_fma_f32 v[54:55], v[92:93], v[50:51], v[54:55] op_sel_hi:[0,1,1]
	ds_read_b128 v[50:53], v103 offset:4720
	s_waitcnt lgkmcnt(0)
	v_pk_fma_f32 v[54:55], v[90:91], v[50:51], v[54:55] op_sel_hi:[0,1,1]
	v_pk_fma_f32 v[144:145], v[90:91], v[52:53], v[144:145] op_sel_hi:[0,1,1]
	ds_read_b128 v[50:53], v103 offset:4848
	s_waitcnt lgkmcnt(0)
; #define LAS __attribute__((address_space(3)))
; #define WSYNC() asm volatile("s_waitcnt lgkmcnt(0)" ::: "memory")
; __device__ __forceinline__ void gla_gates(const bf16* prow, const float* wg, const float* bg, int h, int lane, float (&bc)[32], LAS float* Wst) {
;     ...
;     for (int d4 = 0; d4 < 8; ++d4) { f32x4 z = *(const LAS f32x4*)(Wst + 512 + 4 * d4);
; #pragma unroll
;         for (int r = 0; r < 16; ++r) { const f32x4 w = *(const LAS f32x4*)(Wst + r * 32 + 4 * d4); z += w * glr[r]; }
; #pragma unroll
;         for (int e = 0; e < 4; ++e) bc[4 * d4 + e] = (fminf(z[e], 0.f) - __logf(1.f + __expf(-fabsf(z[e])))) * (1.f / 16.f); }
;     WSYNC();
; #pragma unroll
;     for (int d = 0; d < 32; ++d) { float v = bc[d];
; #pragma unroll
;         for (int off = 1; off < 64; off <<= 1) { const float t = __shfl_up(v, off); if (lane >= off) v += t; }
;         bc[d] = v; }
	v_pk_fma_f32 v[144:145], v[88:89], v[52:53], v[144:145] op_sel_hi:[0,1,1]
	v_pk_fma_f32 v[54:55], v[88:89], v[50:51], v[54:55] op_sel_hi:[0,1,1]
	ds_read_b128 v[50:53], v103 offset:4976
	s_waitcnt lgkmcnt(0)
	v_pk_fma_f32 v[54:55], v[86:87], v[50:51], v[54:55] op_sel_hi:[0,1,1]
	v_pk_fma_f32 v[144:145], v[86:87], v[52:53], v[144:145] op_sel_hi:[0,1,1]
	ds_read_b128 v[50:53], v103 offset:5104
	s_waitcnt lgkmcnt(0)
	v_pk_fma_f32 v[144:145], v[84:85], v[52:53], v[144:145] op_sel_hi:[0,1,1]
	v_pk_fma_f32 v[54:55], v[84:85], v[50:51], v[54:55] op_sel_hi:[0,1,1]
	ds_read_b128 v[50:53], v103 offset:5232
	s_waitcnt lgkmcnt(0)
	v_pk_fma_f32 v[54:55], v[82:83], v[50:51], v[54:55] op_sel_hi:[0,1,1]
	v_pk_fma_f32 v[144:145], v[82:83], v[52:53], v[144:145] op_sel_hi:[0,1,1]
	ds_read_b128 v[50:53], v103 offset:5360
	s_waitcnt lgkmcnt(0)
	v_pk_fma_f32 v[144:145], v[80:81], v[52:53], v[144:145] op_sel_hi:[0,1,1]
	v_pk_fma_f32 v[54:55], v[80:81], v[50:51], v[54:55] op_sel_hi:[0,1,1]
	ds_read_b128 v[50:53], v103 offset:5488
	s_waitcnt lgkmcnt(0)
	v_pk_fma_f32 v[54:55], v[78:79], v[50:51], v[54:55] op_sel_hi:[0,1,1]
	v_pk_fma_f32 v[144:145], v[78:79], v[52:53], v[144:145] op_sel_hi:[0,1,1]
	ds_read_b128 v[50:53], v103 offset:5616
	s_waitcnt lgkmcnt(0)
	v_pk_fma_f32 v[144:145], v[76:77], v[52:53], v[144:145] op_sel_hi:[0,1,1]
	v_pk_fma_f32 v[54:55], v[76:77], v[50:51], v[54:55] op_sel_hi:[0,1,1]
	ds_read_b128 v[50:53], v103 offset:5744
	s_waitcnt lgkmcnt(0)
	v_pk_fma_f32 v[54:55], v[74:75], v[50:51], v[54:55] op_sel_hi:[0,1,1]
	v_pk_fma_f32 v[144:145], v[74:75], v[52:53], v[144:145] op_sel_hi:[0,1,1]
	ds_read_b128 v[50:53], v103 offset:5872
	s_waitcnt lgkmcnt(0)
	v_pk_fma_f32 v[144:145], v[72:73], v[52:53], v[144:145] op_sel_hi:[0,1,1]
	v_pk_fma_f32 v[54:55], v[72:73], v[50:51], v[54:55] op_sel_hi:[0,1,1]
	ds_read_b128 v[50:53], v103 offset:6000
	s_waitcnt lgkmcnt(0)
	v_pk_fma_f32 v[54:55], v[70:71], v[50:51], v[54:55] op_sel_hi:[0,1,1]
	v_pk_fma_f32 v[144:145], v[70:71], v[52:53], v[144:145] op_sel_hi:[0,1,1]
	ds_read_b128 v[50:53], v103 offset:6128
	s_waitcnt lgkmcnt(0)
	v_pk_fma_f32 v[144:145], v[68:69], v[52:53], v[144:145] op_sel_hi:[0,1,1]
	v_pk_fma_f32 v[54:55], v[68:69], v[50:51], v[54:55] op_sel_hi:[0,1,1]
	ds_read_b128 v[50:53], v103 offset:6256
	s_waitcnt lgkmcnt(0)
	v_pk_fma_f32 v[54:55], v[66:67], v[50:51], v[54:55] op_sel_hi:[0,1,1]
	v_pk_fma_f32 v[144:145], v[66:67], v[52:53], v[144:145] op_sel_hi:[0,1,1]
	ds_read_b128 v[50:53], v103 offset:6384
	s_waitcnt lgkmcnt(0)
	s_waitcnt lgkmcnt(0)
	v_pk_fma_f32 v[50:51], v[64:65], v[50:51], v[54:55] op_sel_hi:[0,1,1]
	v_min_f32_e32 v54, 0, v50
	v_mul_f32_e64 v50, |v50|, s97
	v_exp_f32_e32 v50, v50
	v_pk_fma_f32 v[52:53], v[64:65], v[52:53], v[144:145] op_sel_hi:[0,1,1]
	v_lshlrev_b32_e32 v145, 16, v44
	v_add_f32_e32 v50, 1.0, v50
	v_cmp_gt_f32_e32 vcc, s45, v50
	s_nop 1
	v_cndmask_b32_e64 v55, 0, 32, vcc
	v_ldexp_f32 v50, v50, v55
	v_log_f32_e32 v50, v50
	s_nop 0
	v_mul_f32_e32 v55, 0x3f317217, v50
	v_fma_f32 v55, v50, s31, -v55
	v_fmac_f32_e32 v55, 0x3377d1cf, v50
	v_fmac_f32_e32 v55, 0x3f317217, v50
	v_cmp_lt_f32_e64 s[18:19], |v50|, s44
	s_nop 1
	v_cndmask_b32_e64 v50, v50, v55, s[18:19]
	v_cndmask_b32_e32 v55, 0, v240, vcc
	v_sub_f32_e32 v50, v50, v55
	v_sub_f32_e32 v103, v54, v50
	v_min_f32_e32 v50, 0, v51
	v_mul_f32_e64 v51, |v51|, s97
	v_exp_f32_e32 v51, v51
	v_mul_f32_e32 v144, 0x3d800000, v103
	v_add_f32_e32 v51, 1.0, v51
	v_cmp_gt_f32_e32 vcc, s45, v51
	s_nop 1
	v_cndmask_b32_e64 v54, 0, 32, vcc
	v_ldexp_f32 v51, v51, v54
	v_log_f32_e32 v51, v51
	s_nop 0
	v_mul_f32_e32 v54, 0x3f317217, v51
	v_fma_f32 v54, v51, s31, -v54
	v_fmac_f32_e32 v54, 0x3377d1cf, v51
	v_fmac_f32_e32 v54, 0x3f317217, v51
	v_cmp_lt_f32_e64 s[18:19], |v51|, s44
	s_nop 1
	v_cndmask_b32_e64 v51, v51, v54, s[18:19]
	v_cndmask_b32_e32 v54, 0, v240, vcc
	v_sub_f32_e32 v51, v51, v54
	v_sub_f32_e32 v82, v50, v51
	v_mul_f32_e64 v51, |v52|, s97
	v_exp_f32_e32 v51, v51
	v_min_f32_e32 v50, 0, v52
	v_mul_f32_e32 v84, 0x3d800000, v82
	v_add_f32_e32 v51, 1.0, v51
	v_cmp_gt_f32_e32 vcc, s45, v51
	s_nop 1
	v_cndmask_b32_e64 v52, 0, 32, vcc
	v_ldexp_f32 v51, v51, v52
	v_log_f32_e32 v51, v51
	s_nop 0
	v_mul_f32_e32 v52, 0x3f317217, v51
	v_fma_f32 v52, v51, s31, -v52
	v_fmac_f32_e32 v52, 0x3377d1cf, v51
	v_fmac_f32_e32 v52, 0x3f317217, v51
	v_cmp_lt_f32_e64 s[18:19], |v51|, s44
	s_nop 1
	v_cndmask_b32_e64 v51, v51, v52, s[18:19]
	v_cndmask_b32_e32 v52, 0, v240, vcc
	v_sub_f32_e32 v51, v51, v52
	v_sub_f32_e32 v76, v50, v51
	v_mul_f32_e64 v51, |v53|, s97
	v_exp_f32_e32 v51, v51
	v_min_f32_e32 v50, 0, v53
	v_mul_f32_e32 v78, 0x3d800000, v76
	v_add_f32_e32 v51, 1.0, v51
	v_cmp_gt_f32_e32 vcc, s45, v51
	s_nop 1
	v_cndmask_b32_e64 v52, 0, 32, vcc
	v_ldexp_f32 v51, v51, v52
	v_log_f32_e32 v51, v51
	s_nop 0
	v_mul_f32_e32 v52, 0x3f317217, v51
	v_fma_f32 v52, v51, s31, -v52
	v_fmac_f32_e32 v52, 0x3377d1cf, v51
	v_fmac_f32_e32 v52, 0x3f317217, v51
	v_cmp_lt_f32_e64 s[18:19], |v51|, s44
	s_nop 1
	v_cndmask_b32_e64 v51, v51, v52, s[18:19]
	v_cndmask_b32_e32 v52, 0, v240, vcc
	v_sub_f32_e32 v51, v51, v52
	v_sub_f32_e32 v70, v50, v51
	v_and_b32_e32 v50, 64, v241
	v_add_u32_e32 v51, -1, v241
	v_cmp_lt_i32_e32 vcc, v51, v50
	v_add_u32_e32 v52, -2, v241
	v_mul_f32_e32 v72, 0x3d800000, v70
	v_cndmask_b32_e32 v51, v51, v241, vcc
	v_lshlrev_b32_e32 v88, 2, v51
	ds_bpermute_b32 v51, v88, v102
	v_cmp_lt_i32_e32 vcc, v52, v50
	s_waitcnt lgkmcnt(0)
	v_fmac_f32_e32 v51, 0x3d800000, v101
	v_cndmask_b32_e32 v52, v52, v241, vcc
	v_cndmask_b32_e64 v51, v51, v102, s[6:7]
	v_lshlrev_b32_e32 v90, 2, v52
	ds_bpermute_b32 v52, v90, v51
	s_waitcnt lgkmcnt(0)
; __device__ __forceinline__ void gla_gates(const bf16* prow, const float* wg, const float* bg, int h, int lane, float (&bc)[32], LAS float* Wst) {
;     ...
; #pragma unroll
;     for (int d = 0; d < 32; ++d) { float v = bc[d];
; #pragma unroll
;         for (int off = 1; off < 64; off <<= 1) { const float t = __shfl_up(v, off); if (lane >= off) v += t; }
;         bc[d] = v; }
	v_add_f32_e32 v52, v51, v52
	v_cndmask_b32_e64 v51, v52, v51, s[8:9]
	v_add_u32_e32 v52, -4, v241
	v_cmp_lt_i32_e32 vcc, v52, v50
	s_nop 1
	v_cndmask_b32_e32 v52, v52, v241, vcc
	v_lshlrev_b32_e32 v94, 2, v52
	ds_bpermute_b32 v52, v94, v51
	s_waitcnt lgkmcnt(0)
	v_add_f32_e32 v52, v51, v52
	v_cndmask_b32_e64 v51, v52, v51, s[10:11]
	v_add_u32_e32 v52, -8, v241
	v_cmp_lt_i32_e32 vcc, v52, v50
	s_nop 1
	v_cndmask_b32_e32 v52, v52, v241, vcc
	v_lshlrev_b32_e32 v101, 2, v52
	ds_bpermute_b32 v52, v101, v51
	s_waitcnt lgkmcnt(0)
	v_add_f32_e32 v52, v51, v52
	v_cndmask_b32_e64 v51, v52, v51, s[12:13]
	v_add_u32_e32 v52, -16, v241
	v_cmp_lt_i32_e32 vcc, v52, v50
	s_nop 1
	v_cndmask_b32_e32 v52, v52, v241, vcc
	v_lshlrev_b32_e32 v102, 2, v52
	ds_bpermute_b32 v52, v102, v51
	s_waitcnt lgkmcnt(0)
	v_add_f32_e32 v52, v51, v52
	v_cndmask_b32_e64 v51, v52, v51, s[14:15]
	v_subrev_u32_e32 v52, 32, v241
	v_cmp_lt_i32_e32 vcc, v52, v50
	s_nop 1
	v_cndmask_b32_e32 v50, v52, v241, vcc
	v_lshlrev_b32_e32 v92, 2, v50
	ds_bpermute_b32 v50, v92, v51
	s_waitcnt lgkmcnt(0)
	v_add_f32_e32 v50, v51, v50
	v_cndmask_b32_e64 v74, v50, v51, s[4:5]
	ds_bpermute_b32 v51, v88, v100
	s_waitcnt lgkmcnt(0)
	v_fmac_f32_e32 v51, 0x3d800000, v99
	v_cndmask_b32_e64 v51, v51, v100, s[6:7]
	ds_bpermute_b32 v52, v90, v51
	s_waitcnt lgkmcnt(0)
	v_add_f32_e32 v52, v51, v52
	v_cndmask_b32_e64 v51, v52, v51, s[8:9]
	ds_bpermute_b32 v52, v94, v51
	s_waitcnt lgkmcnt(0)
	v_add_f32_e32 v52, v51, v52
	v_cndmask_b32_e64 v51, v52, v51, s[10:11]
	ds_bpermute_b32 v52, v101, v51
	s_waitcnt lgkmcnt(0)
	v_add_f32_e32 v52, v51, v52
	v_cndmask_b32_e64 v51, v52, v51, s[12:13]
	ds_bpermute_b32 v52, v102, v51
	s_waitcnt lgkmcnt(0)
	v_add_f32_e32 v52, v51, v52
	v_cndmask_b32_e64 v52, v52, v51, s[14:15]
	ds_bpermute_b32 v51, v92, v52
	s_waitcnt lgkmcnt(0)
	v_add_f32_e32 v51, v52, v51
	v_cndmask_b32_e64 v80, v51, v52, s[4:5]
	ds_bpermute_b32 v52, v88, v98
	s_waitcnt lgkmcnt(0)
	v_fmac_f32_e32 v52, 0x3d800000, v95
	v_cndmask_b32_e64 v52, v52, v98, s[6:7]
	ds_bpermute_b32 v53, v90, v52
	s_waitcnt lgkmcnt(0)
	v_add_f32_e32 v53, v52, v53
	v_cndmask_b32_e64 v52, v53, v52, s[8:9]
	ds_bpermute_b32 v53, v94, v52
	s_waitcnt lgkmcnt(0)
	v_add_f32_e32 v53, v52, v53
	v_cndmask_b32_e64 v52, v53, v52, s[10:11]
	ds_bpermute_b32 v53, v101, v52
	s_waitcnt lgkmcnt(0)
	v_add_f32_e32 v53, v52, v53
	v_cndmask_b32_e64 v52, v53, v52, s[12:13]
	ds_bpermute_b32 v53, v102, v52
	s_waitcnt lgkmcnt(0)
	v_add_f32_e32 v53, v52, v53
	v_cndmask_b32_e64 v53, v53, v52, s[14:15]
	ds_bpermute_b32 v52, v92, v53
	s_waitcnt lgkmcnt(0)
	v_add_f32_e32 v52, v53, v52
	v_cndmask_b32_e64 v95, v52, v53, s[4:5]
	ds_bpermute_b32 v53, v88, v93
	s_waitcnt lgkmcnt(0)
	v_fmac_f32_e32 v53, 0x3d800000, v91
	v_cndmask_b32_e64 v53, v53, v93, s[6:7]
	ds_bpermute_b32 v54, v90, v53
	s_waitcnt lgkmcnt(0)
	v_add_f32_e32 v54, v53, v54
	v_cndmask_b32_e64 v53, v54, v53, s[8:9]
	ds_bpermute_b32 v54, v94, v53
	s_waitcnt lgkmcnt(0)
	v_add_f32_e32 v54, v53, v54
	v_cndmask_b32_e64 v53, v54, v53, s[10:11]
	ds_bpermute_b32 v54, v101, v53
	s_waitcnt lgkmcnt(0)
	v_add_f32_e32 v54, v53, v54
	v_cndmask_b32_e64 v53, v54, v53, s[12:13]
	ds_bpermute_b32 v54, v102, v53
	s_waitcnt lgkmcnt(0)
	v_add_f32_e32 v54, v53, v54
	v_cndmask_b32_e64 v54, v54, v53, s[14:15]
	ds_bpermute_b32 v53, v92, v54
	s_waitcnt lgkmcnt(0)
	v_add_f32_e32 v53, v54, v53
	v_cndmask_b32_e64 v93, v53, v54, s[4:5]
	ds_bpermute_b32 v54, v88, v111
	s_waitcnt lgkmcnt(0)
	v_fmac_f32_e32 v54, 0x3d800000, v110
	v_cndmask_b32_e64 v54, v54, v111, s[6:7]
	ds_bpermute_b32 v55, v90, v54
	s_waitcnt lgkmcnt(0)
	v_add_f32_e32 v55, v54, v55
	v_cndmask_b32_e64 v54, v55, v54, s[8:9]
	ds_bpermute_b32 v55, v94, v54
	s_waitcnt lgkmcnt(0)
	v_add_f32_e32 v55, v54, v55
	v_cndmask_b32_e64 v54, v55, v54, s[10:11]
	ds_bpermute_b32 v55, v101, v54
	s_waitcnt lgkmcnt(0)
	v_add_f32_e32 v55, v54, v55
	v_cndmask_b32_e64 v54, v55, v54, s[12:13]
	ds_bpermute_b32 v55, v102, v54
	s_waitcnt lgkmcnt(0)
	v_add_f32_e32 v55, v54, v55
	v_cndmask_b32_e64 v55, v55, v54, s[14:15]
	ds_bpermute_b32 v54, v92, v55
	s_waitcnt lgkmcnt(0)
	v_add_f32_e32 v54, v55, v54
	v_cndmask_b32_e64 v98, v54, v55, s[4:5]
	ds_bpermute_b32 v55, v88, v109
	s_waitcnt lgkmcnt(0)
	v_fmac_f32_e32 v55, 0x3d800000, v108
	v_cndmask_b32_e64 v55, v55, v109, s[6:7]
	ds_bpermute_b32 v64, v90, v55
	s_waitcnt lgkmcnt(0)
	v_add_f32_e32 v64, v55, v64
	v_cndmask_b32_e64 v55, v64, v55, s[8:9]
	ds_bpermute_b32 v64, v94, v55
	s_waitcnt lgkmcnt(0)
	v_add_f32_e32 v64, v55, v64
	v_cndmask_b32_e64 v55, v64, v55, s[10:11]
	ds_bpermute_b32 v64, v101, v55
	s_waitcnt lgkmcnt(0)
	v_add_f32_e32 v64, v55, v64
	v_cndmask_b32_e64 v55, v64, v55, s[12:13]
	ds_bpermute_b32 v64, v102, v55
	s_waitcnt lgkmcnt(0)
	v_add_f32_e32 v64, v55, v64
	v_cndmask_b32_e64 v64, v64, v55, s[14:15]
	ds_bpermute_b32 v55, v92, v64
	s_waitcnt lgkmcnt(0)
	v_add_f32_e32 v55, v64, v55
	v_cndmask_b32_e64 v99, v55, v64, s[4:5]
	ds_bpermute_b32 v64, v88, v107
	s_waitcnt lgkmcnt(0)
	v_fmac_f32_e32 v64, 0x3d800000, v106
	v_cndmask_b32_e64 v64, v64, v107, s[6:7]
	ds_bpermute_b32 v66, v90, v64
	s_waitcnt lgkmcnt(0)
	v_add_f32_e32 v66, v64, v66
	v_cndmask_b32_e64 v64, v66, v64, s[8:9]
	ds_bpermute_b32 v66, v94, v64
	s_waitcnt lgkmcnt(0)
	v_add_f32_e32 v66, v64, v66
	v_cndmask_b32_e64 v64, v66, v64, s[10:11]
	ds_bpermute_b32 v66, v101, v64
	s_waitcnt lgkmcnt(0)
	v_add_f32_e32 v66, v64, v66
	v_cndmask_b32_e64 v64, v66, v64, s[12:13]
	ds_bpermute_b32 v66, v102, v64
	s_waitcnt lgkmcnt(0)
	v_add_f32_e32 v66, v64, v66
	v_cndmask_b32_e64 v66, v66, v64, s[14:15]
	ds_bpermute_b32 v64, v92, v66
	s_waitcnt lgkmcnt(0)
; __device__ __forceinline__ void gla_gates(const bf16* prow, const float* wg, const float* bg, int h, int lane, float (&bc)[32], LAS float* Wst) {
;     ...
; #pragma unroll
;     for (int d = 0; d < 32; ++d) { float v = bc[d];
; #pragma unroll
;         for (int off = 1; off < 64; off <<= 1) { const float t = __shfl_up(v, off); if (lane >= off) v += t; }
;         bc[d] = v; }
	v_add_f32_e32 v64, v66, v64
	v_cndmask_b32_e64 v100, v64, v66, s[4:5]
	ds_bpermute_b32 v66, v88, v105
	s_waitcnt lgkmcnt(0)
	v_fmac_f32_e32 v66, 0x3d800000, v104
	v_cndmask_b32_e64 v66, v66, v105, s[6:7]
	ds_bpermute_b32 v68, v90, v66
	s_waitcnt lgkmcnt(0)
	v_add_f32_e32 v68, v66, v68
	v_cndmask_b32_e64 v66, v68, v66, s[8:9]
	ds_bpermute_b32 v68, v94, v66
	s_waitcnt lgkmcnt(0)
	v_add_f32_e32 v68, v66, v68
	v_cndmask_b32_e64 v66, v68, v66, s[10:11]
	ds_bpermute_b32 v68, v101, v66
	s_waitcnt lgkmcnt(0)
	v_add_f32_e32 v68, v66, v68
	v_cndmask_b32_e64 v66, v68, v66, s[12:13]
	ds_bpermute_b32 v68, v102, v66
	s_waitcnt lgkmcnt(0)
	v_add_f32_e32 v68, v66, v68
	v_cndmask_b32_e64 v68, v68, v66, s[14:15]
	ds_bpermute_b32 v66, v92, v68
	s_waitcnt lgkmcnt(0)
	v_add_f32_e32 v66, v68, v66
	v_cndmask_b32_e64 v105, v66, v68, s[4:5]
	ds_bpermute_b32 v68, v88, v97
	s_waitcnt lgkmcnt(0)
	v_fmac_f32_e32 v68, 0x3d800000, v96
	v_cndmask_b32_e64 v68, v68, v97, s[6:7]
	ds_bpermute_b32 v86, v90, v68
	s_waitcnt lgkmcnt(0)
	v_add_f32_e32 v86, v68, v86
	v_cndmask_b32_e64 v68, v86, v68, s[8:9]
	ds_bpermute_b32 v86, v94, v68
	s_waitcnt lgkmcnt(0)
	v_add_f32_e32 v86, v68, v86
	v_cndmask_b32_e64 v68, v86, v68, s[10:11]
	ds_bpermute_b32 v86, v101, v68
	s_waitcnt lgkmcnt(0)
	v_add_f32_e32 v86, v68, v86
	v_cndmask_b32_e64 v68, v86, v68, s[12:13]
	ds_bpermute_b32 v86, v102, v68
	s_waitcnt lgkmcnt(0)
	v_add_f32_e32 v86, v68, v86
	v_cndmask_b32_e64 v86, v86, v68, s[14:15]
	ds_bpermute_b32 v68, v92, v86
	s_waitcnt lgkmcnt(0)
	v_add_f32_e32 v68, v86, v68
	v_cndmask_b32_e64 v106, v68, v86, s[4:5]
	ds_bpermute_b32 v86, v88, v61
	s_waitcnt lgkmcnt(0)
	v_fmac_f32_e32 v86, 0x3d800000, v60
	v_cndmask_b32_e64 v60, v86, v61, s[6:7]
	ds_bpermute_b32 v61, v90, v60
	s_waitcnt lgkmcnt(0)
	v_add_f32_e32 v61, v60, v61
	v_cndmask_b32_e64 v60, v61, v60, s[8:9]
	ds_bpermute_b32 v61, v94, v60
	s_waitcnt lgkmcnt(0)
	v_add_f32_e32 v61, v60, v61
	v_cndmask_b32_e64 v60, v61, v60, s[10:11]
	ds_bpermute_b32 v61, v101, v60
	s_waitcnt lgkmcnt(0)
	v_add_f32_e32 v61, v60, v61
	v_cndmask_b32_e64 v60, v61, v60, s[12:13]
	ds_bpermute_b32 v61, v102, v60
	s_waitcnt lgkmcnt(0)
	v_add_f32_e32 v61, v60, v61
	v_cndmask_b32_e64 v61, v61, v60, s[14:15]
	ds_bpermute_b32 v60, v92, v61
	s_waitcnt lgkmcnt(0)
	v_add_f32_e32 v60, v61, v60
	v_cndmask_b32_e64 v108, v60, v61, s[4:5]
	ds_bpermute_b32 v61, v88, v59
	s_waitcnt lgkmcnt(0)
	v_fmac_f32_e32 v61, 0x3d800000, v58
	v_cndmask_b32_e64 v58, v61, v59, s[6:7]
	ds_bpermute_b32 v59, v90, v58
	s_waitcnt lgkmcnt(0)
	v_add_f32_e32 v59, v58, v59
	v_cndmask_b32_e64 v58, v59, v58, s[8:9]
	ds_bpermute_b32 v59, v94, v58
	s_waitcnt lgkmcnt(0)
	v_add_f32_e32 v59, v58, v59
	v_cndmask_b32_e64 v58, v59, v58, s[10:11]
	ds_bpermute_b32 v59, v101, v58
	s_waitcnt lgkmcnt(0)
	v_add_f32_e32 v59, v58, v59
	v_cndmask_b32_e64 v58, v59, v58, s[12:13]
	ds_bpermute_b32 v59, v102, v58
	s_waitcnt lgkmcnt(0)
	v_add_f32_e32 v59, v58, v59
	v_cndmask_b32_e64 v59, v59, v58, s[14:15]
	ds_bpermute_b32 v58, v92, v59
	s_waitcnt lgkmcnt(0)
	v_add_f32_e32 v58, v59, v58
	v_cndmask_b32_e64 v110, v58, v59, s[4:5]
	ds_bpermute_b32 v59, v88, v57
	s_waitcnt lgkmcnt(0)
	v_fmac_f32_e32 v59, 0x3d800000, v56
	v_cndmask_b32_e64 v56, v59, v57, s[6:7]
	ds_bpermute_b32 v57, v90, v56
	s_waitcnt lgkmcnt(0)
	v_add_f32_e32 v57, v56, v57
	v_cndmask_b32_e64 v56, v57, v56, s[8:9]
	ds_bpermute_b32 v57, v94, v56
	s_waitcnt lgkmcnt(0)
	v_add_f32_e32 v57, v56, v57
	v_cndmask_b32_e64 v56, v57, v56, s[10:11]
	ds_bpermute_b32 v57, v101, v56
	s_waitcnt lgkmcnt(0)
	v_add_f32_e32 v57, v56, v57
	v_cndmask_b32_e64 v56, v57, v56, s[12:13]
	ds_bpermute_b32 v57, v102, v56
	s_waitcnt lgkmcnt(0)
	v_add_f32_e32 v57, v56, v57
	v_cndmask_b32_e64 v57, v57, v56, s[14:15]
	ds_bpermute_b32 v56, v92, v57
	s_waitcnt lgkmcnt(0)
	v_add_f32_e32 v56, v57, v56
	v_cndmask_b32_e64 v111, v56, v57, s[4:5]
	ds_bpermute_b32 v57, v88, v127
	s_waitcnt lgkmcnt(0)
	v_fmac_f32_e32 v57, 0x3d800000, v126
	v_cndmask_b32_e64 v57, v57, v127, s[6:7]
	ds_bpermute_b32 v59, v90, v57
	s_waitcnt lgkmcnt(0)
	v_add_f32_e32 v59, v57, v59
	v_cndmask_b32_e64 v57, v59, v57, s[8:9]
	ds_bpermute_b32 v59, v94, v57
	s_waitcnt lgkmcnt(0)
	v_add_f32_e32 v59, v57, v59
	v_cndmask_b32_e64 v57, v59, v57, s[10:11]
	ds_bpermute_b32 v59, v101, v57
	s_waitcnt lgkmcnt(0)
	v_add_f32_e32 v59, v57, v59
	v_cndmask_b32_e64 v57, v59, v57, s[12:13]
	ds_bpermute_b32 v59, v102, v57
	s_waitcnt lgkmcnt(0)
	v_add_f32_e32 v59, v57, v59
	v_cndmask_b32_e64 v59, v59, v57, s[14:15]
	ds_bpermute_b32 v57, v92, v59
	s_waitcnt lgkmcnt(0)
	v_add_f32_e32 v57, v59, v57
	v_cndmask_b32_e64 v126, v57, v59, s[4:5]
	ds_bpermute_b32 v59, v88, v125
	s_waitcnt lgkmcnt(0)
	v_fmac_f32_e32 v59, 0x3d800000, v124
	v_cndmask_b32_e64 v59, v59, v125, s[6:7]
	ds_bpermute_b32 v61, v90, v59
	s_waitcnt lgkmcnt(0)
	v_add_f32_e32 v61, v59, v61
	v_cndmask_b32_e64 v59, v61, v59, s[8:9]
	ds_bpermute_b32 v61, v94, v59
	s_waitcnt lgkmcnt(0)
	v_add_f32_e32 v61, v59, v61
	v_cndmask_b32_e64 v59, v61, v59, s[10:11]
	ds_bpermute_b32 v61, v101, v59
	s_waitcnt lgkmcnt(0)
	v_add_f32_e32 v61, v59, v61
	v_cndmask_b32_e64 v59, v61, v59, s[12:13]
	ds_bpermute_b32 v61, v102, v59
	s_waitcnt lgkmcnt(0)
	v_add_f32_e32 v61, v59, v61
	v_cndmask_b32_e64 v61, v61, v59, s[14:15]
	ds_bpermute_b32 v59, v92, v61
	s_waitcnt lgkmcnt(0)
	v_add_f32_e32 v59, v61, v59
	v_cndmask_b32_e64 v124, v59, v61, s[4:5]
	ds_bpermute_b32 v61, v88, v123
	s_waitcnt lgkmcnt(0)
	v_fmac_f32_e32 v61, 0x3d800000, v122
	v_cndmask_b32_e64 v61, v61, v123, s[6:7]
	ds_bpermute_b32 v86, v90, v61
	s_waitcnt lgkmcnt(0)
	v_add_f32_e32 v86, v61, v86
	v_cndmask_b32_e64 v61, v86, v61, s[8:9]
	ds_bpermute_b32 v86, v94, v61
	s_waitcnt lgkmcnt(0)
; #define WSYNC() asm volatile("s_waitcnt lgkmcnt(0)" ::: "memory")
; __device__ __forceinline__ void gla_gates(const bf16* prow, const float* wg, const float* bg, int h, int lane, float (&bc)[32], LAS float* Wst) {
;     ...
;         for (int e = 0; e < 4; ++e) bc[4 * d4 + e] = (fminf(z[e], 0.f) - __logf(1.f + __expf(-fabsf(z[e])))) * (1.f / 16.f); }
;     WSYNC();
; #pragma unroll
;     for (int d = 0; d < 32; ++d) { float v = bc[d];
; #pragma unroll
;         for (int off = 1; off < 64; off <<= 1) { const float t = __shfl_up(v, off); if (lane >= off) v += t; }
;         bc[d] = v; }
	v_add_f32_e32 v86, v61, v86
	v_cndmask_b32_e64 v61, v86, v61, s[10:11]
	ds_bpermute_b32 v86, v101, v61
	s_waitcnt lgkmcnt(0)
	v_add_f32_e32 v86, v61, v86
	v_cndmask_b32_e64 v61, v86, v61, s[12:13]
	ds_bpermute_b32 v86, v102, v61
	s_waitcnt lgkmcnt(0)
	v_add_f32_e32 v86, v61, v86
	v_cndmask_b32_e64 v86, v86, v61, s[14:15]
	ds_bpermute_b32 v61, v92, v86
	s_waitcnt lgkmcnt(0)
	v_add_f32_e32 v61, v86, v61
	v_cndmask_b32_e64 v122, v61, v86, s[4:5]
	ds_bpermute_b32 v86, v88, v121
	s_waitcnt lgkmcnt(0)
	v_fmac_f32_e32 v86, 0x3d800000, v120
	v_cndmask_b32_e64 v86, v86, v121, s[6:7]
	ds_bpermute_b32 v91, v90, v86
	s_waitcnt lgkmcnt(0)
	v_add_f32_e32 v91, v86, v91
	v_cndmask_b32_e64 v86, v91, v86, s[8:9]
	ds_bpermute_b32 v91, v94, v86
	s_waitcnt lgkmcnt(0)
	v_add_f32_e32 v91, v86, v91
	v_cndmask_b32_e64 v86, v91, v86, s[10:11]
	ds_bpermute_b32 v91, v101, v86
	s_waitcnt lgkmcnt(0)
	v_add_f32_e32 v91, v86, v91
	v_cndmask_b32_e64 v86, v91, v86, s[12:13]
	ds_bpermute_b32 v91, v102, v86
	s_waitcnt lgkmcnt(0)
	v_add_f32_e32 v91, v86, v91
	v_cndmask_b32_e64 v91, v91, v86, s[14:15]
	ds_bpermute_b32 v86, v92, v91
	s_waitcnt lgkmcnt(0)
	v_add_f32_e32 v86, v91, v86
	v_cndmask_b32_e64 v120, v86, v91, s[4:5]
	ds_bpermute_b32 v91, v88, v119
	s_waitcnt lgkmcnt(0)
	v_fmac_f32_e32 v91, 0x3d800000, v118
	v_cndmask_b32_e64 v91, v91, v119, s[6:7]
	ds_bpermute_b32 v96, v90, v91
	s_waitcnt lgkmcnt(0)
	v_add_f32_e32 v96, v91, v96
	v_cndmask_b32_e64 v91, v96, v91, s[8:9]
	ds_bpermute_b32 v96, v94, v91
	s_waitcnt lgkmcnt(0)
	v_add_f32_e32 v96, v91, v96
	v_cndmask_b32_e64 v91, v96, v91, s[10:11]
	ds_bpermute_b32 v96, v101, v91
	s_waitcnt lgkmcnt(0)
	v_add_f32_e32 v96, v91, v96
	v_cndmask_b32_e64 v91, v96, v91, s[12:13]
	ds_bpermute_b32 v96, v102, v91
	s_waitcnt lgkmcnt(0)
	v_add_f32_e32 v96, v91, v96
	v_cndmask_b32_e64 v96, v96, v91, s[14:15]
	ds_bpermute_b32 v91, v92, v96
	s_waitcnt lgkmcnt(0)
	v_add_f32_e32 v91, v96, v91
	v_cndmask_b32_e64 v118, v91, v96, s[4:5]
	ds_bpermute_b32 v96, v88, v117
	s_waitcnt lgkmcnt(0)
	v_fmac_f32_e32 v96, 0x3d800000, v116
	v_cndmask_b32_e64 v96, v96, v117, s[6:7]
	ds_bpermute_b32 v97, v90, v96
	s_waitcnt lgkmcnt(0)
	v_add_f32_e32 v97, v96, v97
	v_cndmask_b32_e64 v96, v97, v96, s[8:9]
	ds_bpermute_b32 v97, v94, v96
	s_waitcnt lgkmcnt(0)
	v_add_f32_e32 v97, v96, v97
	v_cndmask_b32_e64 v96, v97, v96, s[10:11]
	ds_bpermute_b32 v97, v101, v96
	s_waitcnt lgkmcnt(0)
	v_add_f32_e32 v97, v96, v97
	v_cndmask_b32_e64 v96, v97, v96, s[12:13]
	ds_bpermute_b32 v97, v102, v96
	s_waitcnt lgkmcnt(0)
	v_add_f32_e32 v97, v96, v97
	v_cndmask_b32_e64 v97, v97, v96, s[14:15]
	ds_bpermute_b32 v96, v92, v97
	s_waitcnt lgkmcnt(0)
	v_add_f32_e32 v96, v97, v96
	v_cndmask_b32_e64 v116, v96, v97, s[4:5]
	ds_bpermute_b32 v97, v88, v115
	s_waitcnt lgkmcnt(0)
	v_fmac_f32_e32 v97, 0x3d800000, v114
	v_cndmask_b32_e64 v97, v97, v115, s[6:7]
	ds_bpermute_b32 v104, v90, v97
	s_waitcnt lgkmcnt(0)
	v_add_f32_e32 v104, v97, v104
	v_cndmask_b32_e64 v97, v104, v97, s[8:9]
	ds_bpermute_b32 v104, v94, v97
	s_waitcnt lgkmcnt(0)
	v_add_f32_e32 v104, v97, v104
	v_cndmask_b32_e64 v97, v104, v97, s[10:11]
	ds_bpermute_b32 v104, v101, v97
	s_waitcnt lgkmcnt(0)
	v_add_f32_e32 v104, v97, v104
	v_cndmask_b32_e64 v97, v104, v97, s[12:13]
	ds_bpermute_b32 v104, v102, v97
	s_waitcnt lgkmcnt(0)
	v_add_f32_e32 v104, v97, v104
	v_cndmask_b32_e64 v104, v104, v97, s[14:15]
	ds_bpermute_b32 v97, v92, v104
	s_waitcnt lgkmcnt(0)
	v_add_f32_e32 v97, v104, v97
	v_cndmask_b32_e64 v119, v97, v104, s[4:5]
	ds_bpermute_b32 v104, v88, v113
	s_waitcnt lgkmcnt(0)
	v_fmac_f32_e32 v104, 0x3d800000, v112
	v_cndmask_b32_e64 v104, v104, v113, s[6:7]
	ds_bpermute_b32 v107, v90, v104
	s_waitcnt lgkmcnt(0)
	v_add_f32_e32 v107, v104, v107
	v_cndmask_b32_e64 v104, v107, v104, s[8:9]
	ds_bpermute_b32 v107, v94, v104
	s_waitcnt lgkmcnt(0)
	v_add_f32_e32 v107, v104, v107
	v_cndmask_b32_e64 v104, v107, v104, s[10:11]
	ds_bpermute_b32 v107, v101, v104
	s_waitcnt lgkmcnt(0)
	v_add_f32_e32 v107, v104, v107
	v_cndmask_b32_e64 v104, v107, v104, s[12:13]
	ds_bpermute_b32 v107, v102, v104
	s_waitcnt lgkmcnt(0)
	v_add_f32_e32 v107, v104, v107
	v_cndmask_b32_e64 v107, v107, v104, s[14:15]
	ds_bpermute_b32 v104, v92, v107
	s_waitcnt lgkmcnt(0)
	v_add_f32_e32 v104, v107, v104
	v_cndmask_b32_e64 v121, v104, v107, s[4:5]
	ds_bpermute_b32 v107, v88, v143
	s_waitcnt lgkmcnt(0)
	v_fmac_f32_e32 v107, 0x3d800000, v142
	v_cndmask_b32_e64 v107, v107, v143, s[6:7]
	ds_bpermute_b32 v109, v90, v107
	v_and_b32_e32 v142, 0xffff0000, v42
	v_lshlrev_b32_e32 v143, 16, v43
	s_waitcnt lgkmcnt(0)
	v_add_f32_e32 v109, v107, v109
	v_cndmask_b32_e64 v107, v109, v107, s[8:9]
	ds_bpermute_b32 v109, v94, v107
	s_waitcnt lgkmcnt(0)
	v_add_f32_e32 v109, v107, v109
	v_cndmask_b32_e64 v107, v109, v107, s[10:11]
	ds_bpermute_b32 v109, v101, v107
	s_waitcnt lgkmcnt(0)
	v_add_f32_e32 v109, v107, v109
	v_cndmask_b32_e64 v107, v109, v107, s[12:13]
	ds_bpermute_b32 v109, v102, v107
	s_waitcnt lgkmcnt(0)
	v_add_f32_e32 v109, v107, v109
	v_cndmask_b32_e64 v109, v109, v107, s[14:15]
	ds_bpermute_b32 v107, v92, v109
	s_waitcnt lgkmcnt(0)
	v_add_f32_e32 v107, v109, v107
	v_cndmask_b32_e64 v125, v107, v109, s[4:5]
	ds_bpermute_b32 v109, v88, v141
	s_waitcnt lgkmcnt(0)
	v_fmac_f32_e32 v109, 0x3d800000, v140
	v_cndmask_b32_e64 v109, v109, v141, s[6:7]
	ds_bpermute_b32 v112, v90, v109
	v_lshlrev_b32_e32 v141, 16, v42
	v_lshlrev_b32_e32 v42, 16, v34
	v_and_b32_e32 v140, 0xffff0000, v49
	s_waitcnt lgkmcnt(0)
	v_add_f32_e32 v112, v109, v112
	v_cndmask_b32_e64 v109, v112, v109, s[8:9]
	ds_bpermute_b32 v112, v94, v109
	s_waitcnt lgkmcnt(0)
; #define WSYNC() asm volatile("s_waitcnt lgkmcnt(0)" ::: "memory")
; __device__ __forceinline__ void gla_gates(const bf16* prow, const float* wg, const float* bg, int h, int lane, float (&bc)[32], LAS float* Wst) {
;     ...
;         for (int e = 0; e < 4; ++e) bc[4 * d4 + e] = (fminf(z[e], 0.f) - __logf(1.f + __expf(-fabsf(z[e])))) * (1.f / 16.f); }
;     WSYNC();
; #pragma unroll
;     for (int d = 0; d < 32; ++d) { float v = bc[d];
; #pragma unroll
;         for (int off = 1; off < 64; off <<= 1) { const float t = __shfl_up(v, off); if (lane >= off) v += t; }
;         bc[d] = v; }
	v_add_f32_e32 v112, v109, v112
	v_cndmask_b32_e64 v109, v112, v109, s[10:11]
	ds_bpermute_b32 v112, v101, v109
	s_waitcnt lgkmcnt(0)
	v_add_f32_e32 v112, v109, v112
	v_cndmask_b32_e64 v109, v112, v109, s[12:13]
	ds_bpermute_b32 v112, v102, v109
	s_waitcnt lgkmcnt(0)
	v_add_f32_e32 v112, v109, v112
	v_cndmask_b32_e64 v112, v112, v109, s[14:15]
	ds_bpermute_b32 v109, v92, v112
	s_waitcnt lgkmcnt(0)
	v_add_f32_e32 v109, v112, v109
	v_cndmask_b32_e64 v127, v109, v112, s[4:5]
	ds_bpermute_b32 v112, v88, v139
	s_waitcnt lgkmcnt(0)
	v_fmac_f32_e32 v112, 0x3d800000, v138
	v_cndmask_b32_e64 v112, v112, v139, s[6:7]
	ds_bpermute_b32 v113, v90, v112
	v_lshlrev_b32_e32 v139, 16, v49
	v_and_b32_e32 v49, 0xffff0000, v38
	s_waitcnt lgkmcnt(0)
	v_add_f32_e32 v113, v112, v113
	v_cndmask_b32_e64 v112, v113, v112, s[8:9]
	ds_bpermute_b32 v113, v94, v112
	s_waitcnt lgkmcnt(0)
	v_add_f32_e32 v113, v112, v113
	v_cndmask_b32_e64 v112, v113, v112, s[10:11]
	ds_bpermute_b32 v113, v101, v112
	s_waitcnt lgkmcnt(0)
	v_add_f32_e32 v113, v112, v113
	v_cndmask_b32_e64 v112, v113, v112, s[12:13]
	ds_bpermute_b32 v113, v102, v112
	s_waitcnt lgkmcnt(0)
	v_add_f32_e32 v113, v112, v113
	v_cndmask_b32_e64 v113, v113, v112, s[14:15]
	ds_bpermute_b32 v112, v92, v113
	s_waitcnt lgkmcnt(0)
	v_add_f32_e32 v112, v113, v112
	v_cndmask_b32_e64 v138, v112, v113, s[4:5]
	ds_bpermute_b32 v113, v88, v137
	s_waitcnt lgkmcnt(0)
	v_fmac_f32_e32 v113, 0x3d800000, v136
	v_cndmask_b32_e64 v113, v113, v137, s[6:7]
	ds_bpermute_b32 v114, v90, v113
	v_and_b32_e32 v137, 0xffff0000, v48
	s_waitcnt lgkmcnt(0)
	v_add_f32_e32 v114, v113, v114
	v_cndmask_b32_e64 v113, v114, v113, s[8:9]
	ds_bpermute_b32 v114, v94, v113
	s_waitcnt lgkmcnt(0)
	v_add_f32_e32 v114, v113, v114
	v_cndmask_b32_e64 v113, v114, v113, s[10:11]
	ds_bpermute_b32 v114, v101, v113
	s_waitcnt lgkmcnt(0)
	v_add_f32_e32 v114, v113, v114
	v_cndmask_b32_e64 v113, v114, v113, s[12:13]
	ds_bpermute_b32 v114, v102, v113
	s_waitcnt lgkmcnt(0)
	v_add_f32_e32 v114, v113, v114
	v_cndmask_b32_e64 v114, v114, v113, s[14:15]
	ds_bpermute_b32 v113, v92, v114
	s_waitcnt lgkmcnt(0)
	v_add_f32_e32 v113, v114, v113
	v_cndmask_b32_e64 v136, v113, v114, s[4:5]
	ds_bpermute_b32 v114, v88, v135
	s_waitcnt lgkmcnt(0)
	v_fmac_f32_e32 v114, 0x3d800000, v134
	v_cndmask_b32_e64 v114, v114, v135, s[6:7]
	ds_bpermute_b32 v115, v90, v114
	v_lshlrev_b32_e32 v135, 16, v48
	v_lshlrev_b32_e32 v48, 16, v39
	s_waitcnt lgkmcnt(0)
	v_add_f32_e32 v115, v114, v115
	v_cndmask_b32_e64 v114, v115, v114, s[8:9]
	ds_bpermute_b32 v115, v94, v114
	s_waitcnt lgkmcnt(0)
	v_add_f32_e32 v115, v114, v115
	v_cndmask_b32_e64 v114, v115, v114, s[10:11]
	ds_bpermute_b32 v115, v101, v114
	s_waitcnt lgkmcnt(0)
	v_add_f32_e32 v115, v114, v115
	v_cndmask_b32_e64 v114, v115, v114, s[12:13]
	ds_bpermute_b32 v115, v102, v114
	s_waitcnt lgkmcnt(0)
	v_add_f32_e32 v115, v114, v115
	v_cndmask_b32_e64 v115, v115, v114, s[14:15]
	ds_bpermute_b32 v114, v92, v115
	s_waitcnt lgkmcnt(0)
	v_add_f32_e32 v114, v115, v114
	v_cndmask_b32_e64 v134, v114, v115, s[4:5]
	ds_bpermute_b32 v115, v88, v133
	s_waitcnt lgkmcnt(0)
	v_fmac_f32_e32 v115, 0x3d800000, v132
	v_cndmask_b32_e64 v115, v115, v133, s[6:7]
	ds_bpermute_b32 v117, v90, v115
	v_and_b32_e32 v133, 0xffff0000, v47
	s_waitcnt lgkmcnt(0)
	v_add_f32_e32 v117, v115, v117
	v_cndmask_b32_e64 v115, v117, v115, s[8:9]
	ds_bpermute_b32 v117, v94, v115
	s_waitcnt lgkmcnt(0)
	v_add_f32_e32 v117, v115, v117
	v_cndmask_b32_e64 v115, v117, v115, s[10:11]
	ds_bpermute_b32 v117, v101, v115
	s_waitcnt lgkmcnt(0)
	v_add_f32_e32 v117, v115, v117
	v_cndmask_b32_e64 v115, v117, v115, s[12:13]
	ds_bpermute_b32 v117, v102, v115
	s_waitcnt lgkmcnt(0)
	v_add_f32_e32 v117, v115, v117
	v_cndmask_b32_e64 v117, v117, v115, s[14:15]
	ds_bpermute_b32 v115, v92, v117
	s_waitcnt lgkmcnt(0)
	v_add_f32_e32 v115, v117, v115
	v_cndmask_b32_e64 v132, v115, v117, s[4:5]
	ds_bpermute_b32 v117, v88, v131
	s_waitcnt lgkmcnt(0)
	v_fmac_f32_e32 v117, 0x3d800000, v130
	v_cndmask_b32_e64 v117, v117, v131, s[6:7]
	ds_bpermute_b32 v123, v90, v117
	ds_bpermute_b32 v131, v88, v84
	s_waitcnt lgkmcnt(1)
	v_add_f32_e32 v123, v117, v123
	v_cndmask_b32_e64 v117, v123, v117, s[8:9]
	ds_bpermute_b32 v123, v94, v117
	s_waitcnt lgkmcnt(1)
	v_fmac_f32_e32 v131, 0x3d800000, v82
	v_cndmask_b32_e64 v82, v131, v84, s[6:7]
	ds_bpermute_b32 v131, v88, v78
	ds_bpermute_b32 v84, v90, v82
	s_waitcnt lgkmcnt(2)
	v_add_f32_e32 v123, v117, v123
	v_cndmask_b32_e64 v117, v123, v117, s[10:11]
	ds_bpermute_b32 v123, v101, v117
	s_waitcnt lgkmcnt(2)
	v_fmac_f32_e32 v131, 0x3d800000, v76
	v_cndmask_b32_e64 v76, v131, v78, s[6:7]
	ds_bpermute_b32 v78, v90, v76
	s_waitcnt lgkmcnt(2)
	v_add_f32_e32 v84, v82, v84
	s_waitcnt lgkmcnt(1)
	v_add_f32_e32 v123, v117, v123
	v_cndmask_b32_e64 v117, v123, v117, s[12:13]
	ds_bpermute_b32 v123, v102, v117
	s_waitcnt lgkmcnt(1)
	v_add_f32_e32 v78, v76, v78
	v_cndmask_b32_e64 v82, v84, v82, s[8:9]
	v_cndmask_b32_e64 v76, v78, v76, s[8:9]
	ds_bpermute_b32 v84, v94, v82
	s_waitcnt lgkmcnt(1)
	v_add_f32_e32 v123, v117, v123
	v_cndmask_b32_e64 v123, v123, v117, s[14:15]
	ds_bpermute_b32 v117, v92, v123
	ds_bpermute_b32 v78, v94, v76
	s_waitcnt lgkmcnt(2)
	v_add_f32_e32 v84, v82, v84
	v_cndmask_b32_e64 v82, v84, v82, s[10:11]
	ds_bpermute_b32 v84, v101, v82
	s_waitcnt lgkmcnt(2)
	v_add_f32_e32 v117, v123, v117
	v_cndmask_b32_e64 v130, v117, v123, s[4:5]
	ds_bpermute_b32 v123, v88, v129
	s_waitcnt lgkmcnt(2)
	v_add_f32_e32 v78, v76, v78
	v_cndmask_b32_e64 v76, v78, v76, s[10:11]
	ds_bpermute_b32 v78, v101, v76
	s_waitcnt lgkmcnt(2)
	v_add_f32_e32 v84, v82, v84
	s_waitcnt lgkmcnt(1)
; __device__ __forceinline__ unsigned pk2(float lo, float hi) { const f32x2_ v = {lo, hi}; return __builtin_bit_cast(unsigned, __builtin_convertvector(v, bf16x2_)); }
; __device__ __forceinline__ void gla_gates(const bf16* prow, const float* wg, const float* bg, int h, int lane, float (&bc)[32], LAS float* Wst) {
;     ...
;     for (int d = 0; d < 32; ++d) { float v = bc[d];
; #pragma unroll
;         for (int off = 1; off < 64; off <<= 1) { const float t = __shfl_up(v, off); if (lane >= off) v += t; }
;         bc[d] = v; }
; __device__ __forceinline__ void gla_local_unit(int u, const bf16* proj, const float* wg, const float* bg, float* KV, float* DEC, LAS unsigned char* wl, int lane) {
;     ...
; #pragma unroll
;       for (int d = 0; d < 32; ++d) { const float bl = __shfl(bc[d], 63); KstT[d * 68 + lane] = (bf16)(pk2(k[d] * __expf(bl - bc[d]), 0.f) & 0xffffu); } }
	v_fmac_f32_e32 v123, 0x3d800000, v128
	v_cndmask_b32_e64 v123, v123, v129, s[6:7]
	ds_bpermute_b32 v129, v88, v144
	ds_bpermute_b32 v88, v88, v72
	ds_bpermute_b32 v128, v90, v123
	s_waitcnt lgkmcnt(3)
	v_add_f32_e32 v78, v76, v78
	v_cndmask_b32_e64 v82, v84, v82, s[12:13]
	s_waitcnt lgkmcnt(2)
	v_fmac_f32_e32 v129, 0x3d800000, v103
	s_waitcnt lgkmcnt(1)
	v_fmac_f32_e32 v88, 0x3d800000, v70
	v_cndmask_b32_e64 v103, v129, v144, s[6:7]
	v_cndmask_b32_e64 v70, v88, v72, s[6:7]
	ds_bpermute_b32 v129, v90, v103
	ds_bpermute_b32 v72, v90, v70
	s_waitcnt lgkmcnt(2)
	v_add_f32_e32 v128, v123, v128
	v_cndmask_b32_e64 v123, v128, v123, s[8:9]
	ds_bpermute_b32 v128, v94, v123
	s_waitcnt lgkmcnt(2)
	v_add_f32_e32 v129, v103, v129
	s_waitcnt lgkmcnt(1)
	v_add_f32_e32 v72, v70, v72
	v_cndmask_b32_e64 v103, v129, v103, s[8:9]
	v_cndmask_b32_e64 v70, v72, v70, s[8:9]
	ds_bpermute_b32 v129, v94, v103
	ds_bpermute_b32 v72, v94, v70
	s_waitcnt lgkmcnt(2)
	v_add_f32_e32 v128, v123, v128
	v_cndmask_b32_e64 v123, v128, v123, s[10:11]
	ds_bpermute_b32 v128, v101, v123
	s_waitcnt lgkmcnt(2)
	v_add_f32_e32 v129, v103, v129
	s_waitcnt lgkmcnt(1)
	v_add_f32_e32 v72, v70, v72
	v_cndmask_b32_e64 v103, v129, v103, s[10:11]
	v_cndmask_b32_e64 v70, v72, v70, s[10:11]
	ds_bpermute_b32 v129, v101, v103
	ds_bpermute_b32 v72, v101, v70
	s_waitcnt lgkmcnt(2)
	v_add_f32_e32 v128, v123, v128
	v_cndmask_b32_e64 v123, v128, v123, s[12:13]
	v_cndmask_b32_e64 v76, v78, v76, s[12:13]
	s_waitcnt lgkmcnt(1)
	v_add_f32_e32 v129, v103, v129
	s_waitcnt lgkmcnt(0)
	v_add_f32_e32 v72, v70, v72
	v_cndmask_b32_e64 v103, v129, v103, s[12:13]
	v_cndmask_b32_e64 v70, v72, v70, s[12:13]
	ds_bpermute_b32 v128, v102, v123
	ds_bpermute_b32 v129, v102, v103
	ds_bpermute_b32 v84, v102, v82
	ds_bpermute_b32 v78, v102, v76
	ds_bpermute_b32 v72, v102, v70
	s_waitcnt lgkmcnt(4)
	v_add_f32_e32 v128, v123, v128
	s_waitcnt lgkmcnt(3)
	v_add_f32_e32 v129, v103, v129
	s_waitcnt lgkmcnt(2)
	v_add_f32_e32 v84, v82, v84
	s_waitcnt lgkmcnt(1)
	v_add_f32_e32 v78, v76, v78
	s_waitcnt lgkmcnt(0)
	v_add_f32_e32 v72, v70, v72
	v_cndmask_b32_e64 v128, v128, v123, s[14:15]
	v_cndmask_b32_e64 v129, v129, v103, s[14:15]
	v_cndmask_b32_e64 v84, v84, v82, s[14:15]
	v_cndmask_b32_e64 v78, v78, v76, s[14:15]
	v_cndmask_b32_e64 v72, v72, v70, s[14:15]
	ds_bpermute_b32 v123, v92, v128
	ds_bpermute_b32 v103, v92, v129
	ds_bpermute_b32 v82, v92, v84
	ds_bpermute_b32 v76, v92, v78
	ds_bpermute_b32 v70, v92, v72
	v_lshlrev_b32_e32 v101, 16, v46
	v_and_b32_e32 v102, 0xffff0000, v46
	v_lshlrev_b32_e32 v131, 16, v47
	v_and_b32_e32 v144, 0xffff0000, v43
	v_and_b32_e32 v94, 0xffff0000, v44
	v_lshlrev_b32_e32 v92, 16, v45
	v_and_b32_e32 v90, 0xffff0000, v45
	v_and_b32_e32 v47, 0xffff0000, v39
	v_lshlrev_b32_e32 v46, 16, v40
	v_and_b32_e32 v45, 0xffff0000, v40
	v_lshlrev_b32_e32 v44, 16, v41
	v_and_b32_e32 v43, 0xffff0000, v41
	v_and_b32_e32 v41, 0xffff0000, v34
	v_lshlrev_b32_e32 v40, 16, v35
	v_and_b32_e32 v39, 0xffff0000, v35
	v_lshlrev_b32_e32 v35, 16, v37
	v_and_b32_e32 v34, 0xffff0000, v37
	ds_bpermute_b32 v37, v242, v74
	v_lshlrev_b32_e32 v88, 16, v38
	s_waitcnt lgkmcnt(5)
	v_add_f32_e32 v123, v128, v123
	v_cndmask_b32_e64 v128, v123, v128, s[4:5]
	s_waitcnt lgkmcnt(4)
	v_add_f32_e32 v103, v129, v103
	s_waitcnt lgkmcnt(0)
	v_sub_f32_e32 v37, v37, v74
	v_mul_f32_e32 v37, 0x3fb8aa3b, v37
	v_exp_f32_e32 v37, v37
	v_cndmask_b32_e64 v129, v103, v129, s[4:5]
	v_lshlrev_b32_e32 v38, 16, v36
	v_add_f32_e32 v82, v84, v82
	v_mul_f32_e32 v37, v37, v101
	v_cvt_pk_bf16_f32 v37, v37, s0
	ds_write_b16 v85, v37
	ds_bpermute_b32 v37, v242, v80
	v_cndmask_b32_e64 v84, v82, v84, s[4:5]
	v_and_b32_e32 v36, 0xffff0000, v36
	v_add_f32_e32 v76, v78, v76
	v_cndmask_b32_e64 v78, v76, v78, s[4:5]
	s_waitcnt lgkmcnt(0)
	v_sub_f32_e32 v37, v37, v80
	v_mul_f32_e32 v37, 0x3fb8aa3b, v37
	v_exp_f32_e32 v37, v37
	v_add_f32_e32 v70, v72, v70
	v_cndmask_b32_e64 v72, v70, v72, s[4:5]
	v_mul_f32_e32 v37, v37, v102
	v_cvt_pk_bf16_f32 v37, v37, s0
	ds_write_b16 v85, v37 offset:136
	ds_bpermute_b32 v37, v242, v95
	s_waitcnt lgkmcnt(0)
	v_sub_f32_e32 v37, v37, v95
	v_mul_f32_e32 v37, 0x3fb8aa3b, v37
	v_exp_f32_e32 v37, v37
	s_nop 0
	v_mul_f32_e32 v37, v37, v131
	v_cvt_pk_bf16_f32 v37, v37, s0
	ds_write_b16 v85, v37 offset:272
	ds_bpermute_b32 v37, v242, v93
	s_waitcnt lgkmcnt(0)
	v_sub_f32_e32 v37, v37, v93
	v_mul_f32_e32 v37, 0x3fb8aa3b, v37
	v_exp_f32_e32 v37, v37
	s_nop 0
	v_mul_f32_e32 v37, v37, v133
	v_cvt_pk_bf16_f32 v37, v37, s0
	ds_write_b16 v85, v37 offset:408
	ds_bpermute_b32 v37, v242, v98
	s_waitcnt lgkmcnt(0)
	v_sub_f32_e32 v37, v37, v98
	v_mul_f32_e32 v37, 0x3fb8aa3b, v37
	v_exp_f32_e32 v37, v37
	s_nop 0
	v_mul_f32_e32 v37, v37, v135
	v_cvt_pk_bf16_f32 v37, v37, s0
	ds_write_b16 v85, v37 offset:544
	ds_bpermute_b32 v37, v242, v99
	s_waitcnt lgkmcnt(0)
	v_sub_f32_e32 v37, v37, v99
	v_mul_f32_e32 v37, 0x3fb8aa3b, v37
	v_exp_f32_e32 v37, v37
	s_nop 0
	v_mul_f32_e32 v37, v37, v137
	v_cvt_pk_bf16_f32 v37, v37, s0
	ds_write_b16 v85, v37 offset:680
	ds_bpermute_b32 v37, v242, v100
	s_waitcnt lgkmcnt(0)
	v_sub_f32_e32 v37, v37, v100
	v_mul_f32_e32 v37, 0x3fb8aa3b, v37
	v_exp_f32_e32 v37, v37
	s_nop 0
	v_mul_f32_e32 v37, v37, v139
	v_cvt_pk_bf16_f32 v37, v37, s0
	ds_write_b16 v85, v37 offset:816
	ds_bpermute_b32 v37, v242, v105
	s_waitcnt lgkmcnt(0)
	v_sub_f32_e32 v37, v37, v105
	v_mul_f32_e32 v37, 0x3fb8aa3b, v37
	v_exp_f32_e32 v37, v37
	s_nop 0
	v_mul_f32_e32 v37, v37, v140
	v_cvt_pk_bf16_f32 v37, v37, s0
	ds_write_b16 v85, v37 offset:952
	ds_bpermute_b32 v37, v242, v106
	s_waitcnt lgkmcnt(0)
; __device__ __forceinline__ unsigned pk2(float lo, float hi) { const f32x2_ v = {lo, hi}; return __builtin_bit_cast(unsigned, __builtin_convertvector(v, bf16x2_)); }
; __device__ __forceinline__ void gla_local_unit(int u, const bf16* proj, const float* wg, const float* bg, float* KV, float* DEC, LAS unsigned char* wl, int lane) {
;     ...
; #pragma unroll
;       for (int d = 0; d < 32; ++d) { const float bl = __shfl(bc[d], 63); KstT[d * 68 + lane] = (bf16)(pk2(k[d] * __expf(bl - bc[d]), 0.f) & 0xffffu); } }
	v_sub_f32_e32 v37, v37, v106
	v_mul_f32_e32 v37, 0x3fb8aa3b, v37
	v_exp_f32_e32 v37, v37
	s_nop 0
	v_mul_f32_e32 v37, v37, v141
	v_cvt_pk_bf16_f32 v37, v37, s0
	ds_write_b16 v85, v37 offset:1088
	ds_bpermute_b32 v37, v242, v108
	s_waitcnt lgkmcnt(0)
	v_sub_f32_e32 v37, v37, v108
	v_mul_f32_e32 v37, 0x3fb8aa3b, v37
	v_exp_f32_e32 v37, v37
	s_nop 0
	v_mul_f32_e32 v37, v37, v142
	v_cvt_pk_bf16_f32 v37, v37, s0
	ds_write_b16 v85, v37 offset:1224
	ds_bpermute_b32 v37, v242, v110
	s_waitcnt lgkmcnt(0)
	v_sub_f32_e32 v37, v37, v110
	v_mul_f32_e32 v37, 0x3fb8aa3b, v37
	v_exp_f32_e32 v37, v37
	s_nop 0
	v_mul_f32_e32 v37, v37, v143
	v_cvt_pk_bf16_f32 v37, v37, s0
	ds_write_b16 v85, v37 offset:1360
	ds_bpermute_b32 v37, v242, v111
	s_waitcnt lgkmcnt(0)
	v_sub_f32_e32 v37, v37, v111
	v_mul_f32_e32 v37, 0x3fb8aa3b, v37
	v_exp_f32_e32 v37, v37
	s_nop 0
	v_mul_f32_e32 v37, v37, v144
	v_cvt_pk_bf16_f32 v37, v37, s0
	ds_write_b16 v85, v37 offset:1496
	ds_bpermute_b32 v37, v242, v126
	s_waitcnt lgkmcnt(0)
	v_sub_f32_e32 v37, v37, v126
	v_mul_f32_e32 v37, 0x3fb8aa3b, v37
	v_exp_f32_e32 v37, v37
	s_nop 0
	v_mul_f32_e32 v37, v37, v145
	v_cvt_pk_bf16_f32 v37, v37, s0
	ds_write_b16 v85, v37 offset:1632
	ds_bpermute_b32 v37, v242, v124
	s_waitcnt lgkmcnt(0)
	v_sub_f32_e32 v37, v37, v124
	v_mul_f32_e32 v37, 0x3fb8aa3b, v37
	v_exp_f32_e32 v37, v37
	s_nop 0
	v_mul_f32_e32 v37, v37, v94
	v_cvt_pk_bf16_f32 v37, v37, s0
	ds_write_b16 v85, v37 offset:1768
	ds_bpermute_b32 v37, v242, v122
	s_waitcnt lgkmcnt(0)
	v_sub_f32_e32 v37, v37, v122
	v_mul_f32_e32 v37, 0x3fb8aa3b, v37
	v_exp_f32_e32 v37, v37
	s_nop 0
	v_mul_f32_e32 v37, v37, v92
	v_cvt_pk_bf16_f32 v37, v37, s0
	ds_write_b16 v85, v37 offset:1904
	ds_bpermute_b32 v37, v242, v120
	s_waitcnt lgkmcnt(0)
	v_sub_f32_e32 v37, v37, v120
	v_mul_f32_e32 v37, 0x3fb8aa3b, v37
	v_exp_f32_e32 v37, v37
	s_nop 0
	v_mul_f32_e32 v37, v37, v90
	v_cvt_pk_bf16_f32 v37, v37, s0
	ds_write_b16 v85, v37 offset:2040
	ds_bpermute_b32 v37, v242, v118
	s_waitcnt lgkmcnt(0)
	v_sub_f32_e32 v37, v37, v118
	v_mul_f32_e32 v37, 0x3fb8aa3b, v37
	v_exp_f32_e32 v37, v37
	s_nop 0
	v_mul_f32_e32 v37, v37, v88
	v_cvt_pk_bf16_f32 v37, v37, s0
	ds_write_b16 v85, v37 offset:2176
	ds_bpermute_b32 v37, v242, v116
	s_waitcnt lgkmcnt(0)
	v_sub_f32_e32 v37, v37, v116
	v_mul_f32_e32 v37, 0x3fb8aa3b, v37
	v_exp_f32_e32 v37, v37
	s_nop 0
	v_mul_f32_e32 v37, v37, v49
	v_cvt_pk_bf16_f32 v37, v37, s0
	ds_write_b16 v85, v37 offset:2312
	ds_bpermute_b32 v37, v242, v119
	s_waitcnt lgkmcnt(0)
	v_sub_f32_e32 v37, v37, v119
	v_mul_f32_e32 v37, 0x3fb8aa3b, v37
	v_exp_f32_e32 v37, v37
	s_nop 0
	v_mul_f32_e32 v37, v37, v48
	v_cvt_pk_bf16_f32 v37, v37, s0
	ds_write_b16 v85, v37 offset:2448
	ds_bpermute_b32 v37, v242, v121
	v_add_u32_e32 v48, 0x1000, v89
	s_waitcnt lgkmcnt(0)
	v_sub_f32_e32 v37, v37, v121
	v_mul_f32_e32 v37, 0x3fb8aa3b, v37
	v_exp_f32_e32 v37, v37
	s_nop 0
	v_mul_f32_e32 v37, v37, v47
	v_cvt_pk_bf16_f32 v37, v37, s0
	ds_write_b16 v85, v37 offset:2584
	ds_bpermute_b32 v37, v242, v125
	v_add_u32_e32 v47, 0x2000, v87
	s_waitcnt lgkmcnt(0)
	v_sub_f32_e32 v37, v37, v125
	v_mul_f32_e32 v37, 0x3fb8aa3b, v37
	v_exp_f32_e32 v37, v37
	s_nop 0
	v_mul_f32_e32 v37, v37, v46
	v_cvt_pk_bf16_f32 v37, v37, s0
	ds_write_b16 v85, v37 offset:2720
	ds_bpermute_b32 v37, v242, v127
	v_add_u32_e32 v46, 0x1800, v87
	s_waitcnt lgkmcnt(0)
	v_sub_f32_e32 v37, v37, v127
	v_mul_f32_e32 v37, 0x3fb8aa3b, v37
	v_exp_f32_e32 v37, v37
	s_nop 0
	v_mul_f32_e32 v37, v37, v45
	v_cvt_pk_bf16_f32 v37, v37, s0
	ds_write_b16 v85, v37 offset:2856
	ds_bpermute_b32 v37, v242, v138
	s_waitcnt lgkmcnt(0)
	v_sub_f32_e32 v37, v37, v138
	v_mul_f32_e32 v37, 0x3fb8aa3b, v37
	v_exp_f32_e32 v37, v37
	s_nop 0
	v_mul_f32_e32 v37, v37, v44
	v_cvt_pk_bf16_f32 v37, v37, s0
	ds_write_b16 v85, v37 offset:2992
	ds_bpermute_b32 v37, v242, v136
	s_waitcnt lgkmcnt(0)
	v_sub_f32_e32 v37, v37, v136
	v_mul_f32_e32 v37, 0x3fb8aa3b, v37
	v_exp_f32_e32 v37, v37
	s_nop 0
	v_mul_f32_e32 v37, v37, v43
	v_cvt_pk_bf16_f32 v37, v37, s0
	ds_write_b16 v85, v37 offset:3128
	ds_bpermute_b32 v37, v242, v134
	s_waitcnt lgkmcnt(0)
	v_sub_f32_e32 v37, v37, v134
	v_mul_f32_e32 v37, 0x3fb8aa3b, v37
	v_exp_f32_e32 v37, v37
	s_nop 0
	v_mul_f32_e32 v37, v37, v42
	v_cvt_pk_bf16_f32 v37, v37, s0
	ds_write_b16 v85, v37 offset:3264
	ds_bpermute_b32 v37, v242, v132
	v_add_u32_e32 v42, 0x1000, v87
	s_waitcnt lgkmcnt(0)
	v_sub_f32_e32 v37, v37, v132
	v_mul_f32_e32 v37, 0x3fb8aa3b, v37
	v_exp_f32_e32 v37, v37
	s_nop 0
	v_mul_f32_e32 v37, v37, v41
	v_cvt_pk_bf16_f32 v37, v37, s0
	ds_write_b16 v85, v37 offset:3400
	ds_bpermute_b32 v37, v242, v130
	s_waitcnt lgkmcnt(0)
	v_sub_f32_e32 v37, v37, v130
	v_mul_f32_e32 v37, 0x3fb8aa3b, v37
	v_exp_f32_e32 v37, v37
	s_nop 0
	v_mul_f32_e32 v37, v37, v40
	v_cvt_pk_bf16_f32 v37, v37, s0
	ds_write_b16 v85, v37 offset:3536
	ds_bpermute_b32 v37, v242, v128
	s_waitcnt lgkmcnt(0)
	v_sub_f32_e32 v37, v37, v128
	v_mul_f32_e32 v37, 0x3fb8aa3b, v37
	v_exp_f32_e32 v37, v37
	s_nop 0
	v_mul_f32_e32 v37, v37, v39
	v_cvt_pk_bf16_f32 v37, v37, s0
	ds_write_b16 v85, v37 offset:3672
	ds_bpermute_b32 v37, v242, v129
	s_waitcnt lgkmcnt(0)
	v_sub_f32_e32 v37, v37, v129
	v_mul_f32_e32 v37, 0x3fb8aa3b, v37
	v_exp_f32_e32 v37, v37
	s_nop 0
	v_mul_f32_e32 v37, v37, v38
	v_cvt_pk_bf16_f32 v37, v37, s0
	ds_write_b16 v85, v37 offset:3808
	ds_bpermute_b32 v37, v242, v84
	v_add_u32_e32 v38, 0x800, v87
	s_waitcnt lgkmcnt(0)
	v_sub_f32_e32 v37, v37, v84
	v_mul_f32_e32 v37, 0x3fb8aa3b, v37
	v_exp_f32_e32 v37, v37
	s_nop 0
	v_mul_f32_e32 v36, v37, v36
	v_cvt_pk_bf16_f32 v36, v36, s0
	ds_write_b16 v85, v36 offset:3944
	ds_bpermute_b32 v36, v242, v78
	s_waitcnt lgkmcnt(0)
; __device__ __forceinline__ void gla_stage_vt(const u32x4 (&vraw)[8], LAS bf16* VT, int lane) {
; #pragma unroll
;     for (int i = 0; i < 8; ++i) { const u32x4 w = vraw[i]; const unsigned ww[4] = {w.x, w.y, w.z, w.w};
; #pragma unroll
;         for (int e = 0; e < 4; ++e) { VT[(8 * i + 2 * e) * 68 + lane] = (bf16)(ww[e] & 0xffffu); VT[(8 * i + 2 * e + 1) * 68 + lane] = (bf16)(ww[e] >> 16); } }
; }
; __device__ __forceinline__ void gla_local_unit(int u, const bf16* proj, const float* wg, const float* bg, float* KV, float* DEC, LAS unsigned char* wl, int lane) {
;     const int b = u >> 8, h = (u >> 6) & 3, n = u & 63; const size_t row = (size_t)b * SEQ + n * 64 + lane; const bf16* prow = proj + row * PP;
;     LAS bf16* KstT = (LAS bf16*)wl; LAS bf16* VT = (LAS bf16*)(wl + 4352);
;     u32x4 kraw[4], vraw[8];
; #pragma unroll
;     for (int i = 0; i < 4; ++i) kraw[i] = *(const u32x4*)(prow + C_GK + h * 32 + 8 * i);
; #pragma unroll
;     for (int i = 0; i < 8; ++i) vraw[i] = *(const u32x4*)(prow + C_GV + h * 64 + 8 * i);
;     float bc[32]; gla_gates(prow, wg, bg, h, lane, bc, (LAS float*)(wl + 4352));
;     { float k[32];
; #pragma unroll
;       for (int i = 0; i < 4; ++i) unpack8(kraw[i], k + 8 * i);
; #pragma unroll
;       for (int d = 0; d < 32; ++d) { const float bl = __shfl(bc[d], 63); KstT[d * 68 + lane] = (bf16)(pk2(k[d] * __expf(bl - bc[d]), 0.f) & 0xffffu); } }
;     gla_stage_vt(vraw, VT, lane);
;     WSYNC();
;     const int fr = lane & 15, quad = lane >> 4;
;     f32x4 acc[2][4];
; #pragma unroll
;     for (int db = 0; db < 2; ++db)
; #pragma unroll
;         for (int vb = 0; vb < 4; ++vb) acc[db][vb] = (f32x4){0.f, 0.f, 0.f, 0.f};
; #pragma unroll
;     for (int ks = 0; ks < 2; ++ks) { bf16x8 a[2];
; #pragma unroll
;         for (int db = 0; db < 2; ++db) { const LAS bf16* p = KstT + (db * 16 + fr) * 68 + ks * 32 + quad * 4; a[db] = mk_frag(*(const LAS u32x2*)p, *(const LAS u32x2*)(p + 16)); }
; #pragma unroll
;         for (int vb = 0; vb < 4; ++vb) { const LAS bf16* p = VT + (vb * 16 + fr) * 68 + ks * 32 + quad * 4; const bf16x8 vf = mk_frag(*(const LAS u32x2*)p, *(const LAS u32x2*)(p + 16));
; #pragma unroll
;             for (int db = 0; db < 2; ++db) acc[db][vb] = MFMA16(a[db], vf, acc[db][vb]); } }
; #pragma unroll
;     for (int db = 0; db < 2; ++db)
; #pragma unroll
;         for (int vb = 0; vb < 4; ++vb)
; #pragma unroll
	v_sub_f32_e32 v36, v36, v78
	v_mul_f32_e32 v36, 0x3fb8aa3b, v36
	v_exp_f32_e32 v36, v36
	s_nop 0
	v_mul_f32_e32 v35, v36, v35
	v_cvt_pk_bf16_f32 v35, v35, s0
	ds_write_b16 v85, v35 offset:4080
	ds_bpermute_b32 v35, v242, v72
	s_waitcnt lgkmcnt(0)
	v_sub_f32_e32 v35, v35, v72
	v_mul_f32_e32 v35, 0x3fb8aa3b, v35
	v_exp_f32_e32 v35, v35
	s_nop 0
	v_mul_f32_e32 v34, v35, v34
	v_cvt_pk_bf16_f32 v34, v34, s0
	ds_write_b16 v85, v34 offset:4216
	ds_write_b16 v85, v30 offset:4352
	ds_write_b16_d16_hi v85, v30 offset:4488
	ds_write_b16 v85, v31 offset:4624
	ds_write_b16_d16_hi v85, v31 offset:4760
	ds_write_b16 v85, v32 offset:4896
	ds_write_b16_d16_hi v85, v32 offset:5032
	ds_write_b16 v85, v33 offset:5168
	ds_write_b16_d16_hi v85, v33 offset:5304
	ds_write_b16 v85, v26 offset:5440
	ds_write_b16_d16_hi v85, v26 offset:5576
	ds_write_b16 v85, v27 offset:5712
	ds_write_b16_d16_hi v85, v27 offset:5848
	ds_write_b16 v85, v28 offset:5984
	ds_write_b16_d16_hi v85, v28 offset:6120
	ds_write_b16 v85, v29 offset:6256
	ds_write_b16_d16_hi v85, v29 offset:6392
	ds_write_b16 v85, v22 offset:6528
	ds_write_b16_d16_hi v85, v22 offset:6664
	ds_write_b16 v85, v23 offset:6800
	ds_write_b16_d16_hi v85, v23 offset:6936
	ds_write_b16 v85, v24 offset:7072
	ds_write_b16_d16_hi v85, v24 offset:7208
	ds_write_b16 v85, v25 offset:7344
	ds_write_b16_d16_hi v85, v25 offset:7480
	ds_write_b16 v85, v18 offset:7616
	ds_write_b16_d16_hi v85, v18 offset:7752
	ds_write_b16 v85, v19 offset:7888
	ds_write_b16_d16_hi v85, v19 offset:8024
	ds_write_b16 v85, v20 offset:8160
	ds_write_b16_d16_hi v85, v20 offset:8296
	ds_write_b16 v85, v21 offset:8432
	ds_write_b16_d16_hi v85, v21 offset:8568
	ds_write_b16 v85, v14 offset:8704
	ds_write_b16_d16_hi v85, v14 offset:8840
	ds_write_b16 v85, v15 offset:8976
	ds_write_b16_d16_hi v85, v15 offset:9112
	ds_write_b16 v85, v16 offset:9248
	ds_write_b16_d16_hi v85, v16 offset:9384
	ds_write_b16 v85, v17 offset:9520
	ds_write_b16_d16_hi v85, v17 offset:9656
	ds_write_b16 v85, v10 offset:9792
	ds_write_b16_d16_hi v85, v10 offset:9928
	ds_write_b16 v85, v11 offset:10064
	ds_write_b16_d16_hi v85, v11 offset:10200
	ds_write_b16 v85, v12 offset:10336
	ds_write_b16_d16_hi v85, v12 offset:10472
	ds_write_b16 v85, v13 offset:10608
	ds_write_b16_d16_hi v85, v13 offset:10744
	ds_write_b16 v85, v6 offset:10880
	ds_write_b16_d16_hi v85, v6 offset:11016
	ds_write_b16 v85, v7 offset:11152
	ds_write_b16_d16_hi v85, v7 offset:11288
	ds_write_b16 v85, v8 offset:11424
	ds_write_b16_d16_hi v85, v8 offset:11560
	ds_write_b16 v85, v9 offset:11696
	ds_write_b16_d16_hi v85, v9 offset:11832
	ds_write_b16 v85, v2 offset:11968
	ds_write_b16_d16_hi v85, v2 offset:12104
	ds_write_b16 v85, v3 offset:12240
	ds_write_b16_d16_hi v85, v3 offset:12376
	ds_write_b16 v85, v4 offset:12512
	ds_write_b16_d16_hi v85, v4 offset:12648
	ds_write_b16 v85, v5 offset:12784
	ds_write_b16_d16_hi v85, v5 offset:12920
	s_waitcnt lgkmcnt(0)
	ds_read2_b64 v[2:5], v87 offset1:4
	ds_read2_b64 v[6:9], v38 offset0:16 offset1:20
	ds_read2_b64 v[10:13], v42 offset0:32 offset1:36
	ds_read2_b64 v[18:21], v46 offset0:48 offset1:52
	ds_read2_b64 v[26:29], v47 offset0:64 offset1:68
	ds_read2_b64 v[34:37], v48 offset0:32 offset1:36
	s_waitcnt lgkmcnt(3)
	v_mfma_f32_16x16x32_bf16 v[14:17], v[2:5], v[10:13], 0
	v_mfma_f32_16x16x32_bf16 v[10:13], v[6:9], v[10:13], 0
	s_waitcnt lgkmcnt(2)
	v_mfma_f32_16x16x32_bf16 v[22:25], v[2:5], v[18:21], 0
	v_mfma_f32_16x16x32_bf16 v[18:21], v[6:9], v[18:21], 0
	s_waitcnt lgkmcnt(1)
	v_mfma_f32_16x16x32_bf16 v[30:33], v[2:5], v[26:29], 0
	v_mfma_f32_16x16x32_bf16 v[26:29], v[6:9], v[26:29], 0
	s_waitcnt lgkmcnt(0)
	v_mfma_f32_16x16x32_bf16 v[2:5], v[2:5], v[34:37], 0
	v_mfma_f32_16x16x32_bf16 v[6:9], v[6:9], v[34:37], 0
	ds_read2_b64 v[34:37], v87 offset0:8 offset1:12
	ds_read2_b64 v[38:41], v38 offset0:24 offset1:28
	ds_read2_b64 v[42:45], v42 offset0:40 offset1:44
	s_waitcnt lgkmcnt(0)
	v_mfma_f32_16x16x32_bf16 v[14:17], v[34:37], v[42:45], v[14:17]
	v_mfma_f32_16x16x32_bf16 v[10:13], v[38:41], v[42:45], v[10:13]
	ds_read2_b64 v[42:45], v46 offset0:56 offset1:60
	s_waitcnt lgkmcnt(0)
	v_mfma_f32_16x16x32_bf16 v[22:25], v[34:37], v[42:45], v[22:25]
	v_mfma_f32_16x16x32_bf16 v[18:21], v[38:41], v[42:45], v[18:21]
	ds_read2_b64 v[42:45], v47 offset0:72 offset1:76
	s_waitcnt lgkmcnt(0)
	v_mfma_f32_16x16x32_bf16 v[30:33], v[34:37], v[42:45], v[30:33]
	v_mfma_f32_16x16x32_bf16 v[26:29], v[38:41], v[42:45], v[26:29]
	ds_read2_b64 v[42:45], v48 offset0:40 offset1:44
	s_waitcnt lgkmcnt(0)
	v_mfma_f32_16x16x32_bf16 v[2:5], v[34:37], v[42:45], v[2:5]
	global_store_dword v[62:63], v14, off
	global_store_dword v[62:63], v15, off offset:256
	global_store_dword v[62:63], v16, off offset:512
	global_store_dword v[62:63], v17, off offset:768
	global_store_dword v[62:63], v22, off offset:64
	global_store_dword v[62:63], v23, off offset:320
	global_store_dword v[62:63], v24, off offset:576
	global_store_dword v[62:63], v25, off offset:832
	global_store_dword v[62:63], v30, off offset:128
	global_store_dword v[62:63], v31, off offset:384
	global_store_dword v[62:63], v32, off offset:640
	global_store_dword v[62:63], v33, off offset:896
	global_store_dword v[62:63], v2, off offset:192
	global_store_dword v[62:63], v3, off offset:448
	global_store_dword v[62:63], v4, off offset:704
	global_store_dword v[62:63], v5, off offset:960
	v_add_co_u32_e32 v2, vcc, s39, v62
	v_mfma_f32_16x16x32_bf16 v[6:9], v[38:41], v[42:45], v[6:9]
	s_nop 0
	v_addc_co_u32_e32 v3, vcc, 0, v63, vcc
	global_store_dword v[2:3], v10, off
	global_store_dword v[2:3], v11, off offset:256
	global_store_dword v[2:3], v12, off offset:512
	global_store_dword v[2:3], v13, off offset:768
	global_store_dword v[2:3], v18, off offset:64
	global_store_dword v[2:3], v19, off offset:320
	global_store_dword v[2:3], v20, off offset:576
	global_store_dword v[2:3], v21, off offset:832
	global_store_dword v[2:3], v26, off offset:128
	global_store_dword v[2:3], v27, off offset:384
	global_store_dword v[2:3], v28, off offset:640
	global_store_dword v[2:3], v29, off offset:896
	global_store_dword v[2:3], v6, off offset:192
	global_store_dword v[2:3], v7, off offset:448
	global_store_dword v[2:3], v8, off offset:704
	global_store_dword v[2:3], v9, off offset:960
	s_and_saveexec_b64 s[18:19], s[16:17]
	s_cbranch_execz .LBB0_436
; __device__ __forceinline__ void gla_local_unit(int u, const bf16* proj, const float* wg, const float* bg, float* KV, float* DEC, LAS unsigned char* wl, int lane) {
;     ...
;     if (lane == 63) {
; #pragma unroll
;         for (int d = 0; d < 32; ++d) DEC[u * 32 + d] = __expf(bc[d]); }
	v_mul_f32_e32 v2, 0x3fb8aa3b, v50
	v_mul_f32_e32 v3, 0x3fb8aa3b, v51
	v_mul_f32_e32 v4, 0x3fb8aa3b, v52
	v_mul_f32_e32 v5, 0x3fb8aa3b, v53
	v_exp_f32_e32 v2, v2
	s_ashr_i32 s71, s70, 31
	v_exp_f32_e32 v3, v3
	v_exp_f32_e32 v4, v4
	v_exp_f32_e32 v5, v5
	s_lshl_b64 s[2:3], s[70:71], 2
	s_add_u32 s74, s76, s2
	s_addc_u32 s75, s77, s3
	global_store_dwordx4 v1, v[2:5], s[74:75]
	s_nop 1
	v_mul_f32_e32 v2, 0x3fb8aa3b, v54
	v_mul_f32_e32 v3, 0x3fb8aa3b, v55
	v_mul_f32_e32 v4, 0x3fb8aa3b, v64
	v_mul_f32_e32 v5, 0x3fb8aa3b, v66
	v_exp_f32_e32 v2, v2
	v_exp_f32_e32 v3, v3
	v_exp_f32_e32 v4, v4
	v_exp_f32_e32 v5, v5
	global_store_dwordx4 v1, v[2:5], s[74:75] offset:16
	s_nop 1
	v_mul_f32_e32 v2, 0x3fb8aa3b, v68
	v_mul_f32_e32 v3, 0x3fb8aa3b, v60
	v_mul_f32_e32 v4, 0x3fb8aa3b, v58
	v_mul_f32_e32 v5, 0x3fb8aa3b, v56
	v_exp_f32_e32 v2, v2
	v_exp_f32_e32 v3, v3
	v_exp_f32_e32 v4, v4
	v_exp_f32_e32 v5, v5
	global_store_dwordx4 v1, v[2:5], s[74:75] offset:32
	s_nop 1
	v_mul_f32_e32 v2, 0x3fb8aa3b, v57
	v_mul_f32_e32 v3, 0x3fb8aa3b, v59
	v_mul_f32_e32 v4, 0x3fb8aa3b, v61
	v_mul_f32_e32 v5, 0x3fb8aa3b, v86
	v_exp_f32_e32 v2, v2
	v_exp_f32_e32 v3, v3
	v_exp_f32_e32 v4, v4
	v_exp_f32_e32 v5, v5
	global_store_dwordx4 v1, v[2:5], s[74:75] offset:48
	s_nop 1
	v_mul_f32_e32 v2, 0x3fb8aa3b, v91
	v_mul_f32_e32 v3, 0x3fb8aa3b, v96
	v_mul_f32_e32 v4, 0x3fb8aa3b, v97
	v_mul_f32_e32 v5, 0x3fb8aa3b, v104
	v_exp_f32_e32 v2, v2
	v_exp_f32_e32 v3, v3
	v_exp_f32_e32 v4, v4
	v_exp_f32_e32 v5, v5
	global_store_dwordx4 v1, v[2:5], s[74:75] offset:64
	s_nop 1
	v_mul_f32_e32 v2, 0x3fb8aa3b, v107
	v_mul_f32_e32 v3, 0x3fb8aa3b, v109
	v_mul_f32_e32 v4, 0x3fb8aa3b, v112
	v_mul_f32_e32 v5, 0x3fb8aa3b, v113
	v_exp_f32_e32 v2, v2
	v_exp_f32_e32 v3, v3
	v_exp_f32_e32 v4, v4
	v_exp_f32_e32 v5, v5
	global_store_dwordx4 v1, v[2:5], s[74:75] offset:80
	s_nop 1
	v_mul_f32_e32 v2, 0x3fb8aa3b, v114
	v_mul_f32_e32 v3, 0x3fb8aa3b, v115
	v_mul_f32_e32 v4, 0x3fb8aa3b, v117
	v_mul_f32_e32 v5, 0x3fb8aa3b, v123
	v_exp_f32_e32 v2, v2
	v_exp_f32_e32 v3, v3
	v_exp_f32_e32 v4, v4
	v_exp_f32_e32 v5, v5
	global_store_dwordx4 v1, v[2:5], s[74:75] offset:96
	s_nop 1
	v_mul_f32_e32 v2, 0x3fb8aa3b, v103
	v_mul_f32_e32 v3, 0x3fb8aa3b, v82
	v_mul_f32_e32 v4, 0x3fb8aa3b, v76
	v_mul_f32_e32 v5, 0x3fb8aa3b, v70
	v_exp_f32_e32 v2, v2
	v_exp_f32_e32 v3, v3
	v_exp_f32_e32 v4, v4
	v_exp_f32_e32 v5, v5
	global_store_dwordx4 v1, v[2:5], s[74:75] offset:112
	s_branch .LBB0_436

; #define LAS __attribute__((address_space(3)))
; __device__ __forceinline__ float bf2f(unsigned short b) { return __uint_as_float((unsigned)b << 16); }
; __device__ __forceinline__ void lru_local_unit(int u, int l, KIn in, const bf16* proj, const bf16* WAXT, float* PR, float* EN, bf16* LH, bf16* CP, LAS unsigned char* wl, int lane) {
;     const int b = u >> 8, n = (u >> 6) & 3, c = u & 63, col = n * 64 + lane; const size_t r0 = (size_t)b * SEQ + c * 64;
;     LAS bf16* XCb = (LAS bf16*)wl; LAS bf16* GP = (LAS bf16*)(wl + 9216);
;     const float* cw = in[25] + l * 1024; const float cw0 = cw[col], cw1 = cw[256 + col], cw2 = cw[512 + col], cw3 = cw[768 + col], cb = in[26][l * 256 + col];
;     const bf16* xp = proj + r0 * PP + C_RX + col;
;     const int fr = lane & 15, quad = lane >> 4;
;     bf16x8 wf[8][2];
; #pragma unroll
;     for (int nb = 0; nb < 8; ++nb)
; #pragma unroll
;         for (int ks = 0; ks < 2; ++ks) wf[nb][ks] = *(const bf16x8*)(WAXT + ((size_t)(l * 4 + n) * 128 + nb * 16 + fr) * 64 + ks * 32 + quad * 8);
;     const float ba = in[28][l * 256 + col], bx = in[30][l * 256 + col], lam_ = in[31][l * 256 + col];
;     float xm3 = 0.f, xm2 = 0.f, xm1 = 0.f;
;     if (c > 0) { xm3 = bf2f(*(xp - 3 * PP)); xm2 = bf2f(*(xp - 2 * PP)); xm1 = bf2f(*(xp - PP)); }
; #pragma unroll
;     for (int t0 = 0; t0 < 64; t0 += 32) { bf16 xv[32];
; #pragma unroll
;         for (int i = 0; i < 32; ++i) xv[i] = xp[(size_t)(t0 + i) * PP];
.LBB0_443:
	s_bfe_u32 s3, s2, 0x20006
	v_lshl_or_b32 v87, s3, 6, v78
	v_lshlrev_b32_e32 v0, 2, v87
	global_load_dword v71, v0, s[8:9]
	global_load_dword v70, v0, s[8:9] offset:1024
	global_load_dword v68, v0, s[8:9] offset:2048
	global_load_dword v69, v0, s[8:9] offset:3072
	v_or_b32_e32 v0, s25, v87
	v_lshlrev_b64 v[66:67], 2, v[0:1]
	v_lshl_or_b32 v0, s3, 13, v86
	v_lshl_add_u64 v[46:47], v[0:1], 1, v[74:75]
	v_add_co_u32_e32 v48, vcc, s39, v46
	v_lshl_add_u64 v[2:3], s[10:11], 0, v[66:67]
	s_nop 0
	v_addc_co_u32_e32 v49, vcc, 0, v47, vcc
	v_add_co_u32_e32 v42, vcc, s33, v46
	global_load_dword v72, v[2:3], off
	s_nop 0
	v_addc_co_u32_e32 v43, vcc, 0, v47, vcc
	global_load_dwordx4 v[2:5], v[46:47], off
	global_load_dwordx4 v[6:9], v[46:47], off offset:64
	global_load_dwordx4 v[10:13], v[46:47], off offset:2048
	global_load_dwordx4 v[14:17], v[46:47], off offset:2112
	global_load_dwordx4 v[18:21], v[48:49], off offset:64
	global_load_dwordx4 v[22:25], v[48:49], off offset:2048
	global_load_dwordx4 v[26:29], v[42:43], off offset:-4096
	global_load_dwordx4 v[30:33], v[42:43], off
	global_load_dwordx4 v[34:37], v[42:43], off offset:64
	global_load_dwordx4 v[38:41], v[42:43], off offset:2048
	s_nop 0
	global_load_dwordx4 v[42:45], v[42:43], off offset:2112
	v_add_co_u32_e32 v62, vcc, s40, v46
	s_waitcnt lgkmcnt(0)
	v_lshl_add_u64 v[76:77], s[18:19], 0, v[66:67]
	v_addc_co_u32_e32 v63, vcc, 0, v47, vcc
	global_load_dwordx4 v[46:49], v[48:49], off offset:2112
	s_nop 0
	global_load_dwordx4 v[50:53], v[62:63], off
	global_load_dwordx4 v[54:57], v[62:63], off offset:64
	global_load_dwordx4 v[58:61], v[62:63], off offset:2048
	s_nop 0
	global_load_dwordx4 v[62:65], v[62:63], off offset:2112
	s_ashr_i32 s20, s2, 8
	global_load_dword v88, v[76:77], off
	v_lshl_add_u64 v[76:77], s[4:5], 0, v[66:67]
	v_lshl_add_u64 v[66:67], s[6:7], 0, v[66:67]
	global_load_dword v89, v[76:77], off
	global_load_dword v73, v[66:67], off
	s_and_b32 s29, s2, 63
	s_ashr_i32 s21, s20, 31
	s_lshl_b64 s[22:23], s[20:21], 12
	s_lshl_b32 s3, s29, 6
	s_or_b32 s3, s22, s3
	s_mul_i32 s22, s23, 0x1400
	s_mul_hi_u32 s23, s3, 0x1400
	s_add_i32 s23, s23, s22
	s_mulk_i32 s3, 0x1400
	s_add_u32 s22, s12, s3
	s_addc_u32 s23, s13, s23
	v_lshlrev_b32_e32 v0, 1, v87
	v_lshl_add_u64 v[66:67], s[22:23], 0, v[0:1]
	s_mov_b64 s[22:23], 0xd800e00
	v_lshl_add_u64 v[66:67], v[66:67], 0, s[22:23]
	v_mov_b32_e32 v90, 0
	s_cmp_eq_u32 s29, 0
	v_mov_b32_e32 v125, 0
	v_mov_b32_e32 v127, 0
	v_mov_b32_e32 v126, 0
	s_cbranch_scc1 .LBB0_445
	v_add_co_u32_e32 v76, vcc, 0xffffd000, v66
	s_nop 1
	v_addc_co_u32_e32 v77, vcc, -1, v67, vcc
	global_load_ushort v125, v[76:77], off offset:-3072
	v_add_co_u32_e32 v128, vcc, 0xfffff000, v66
	s_nop 1
	v_addc_co_u32_e32 v129, vcc, -1, v67, vcc
	global_load_ushort v126, v[128:129], off offset:-1024
	v_add_co_u32_e32 v130, vcc, 0xffffe000, v66
	s_nop 1
	v_addc_co_u32_e32 v131, vcc, -1, v67, vcc
	global_load_ushort v127, v[130:131], off offset:-2048
.LBB0_445:
	global_load_ushort v91, v[66:67], off
	v_add_co_u32_e32 v94, vcc, s39, v66
	s_lshr_b32 s3, s2, 6
	s_nop 0
	v_addc_co_u32_e32 v95, vcc, 0, v67, vcc
	global_load_ushort v96, v[94:95], off offset:1024
	v_add_co_u32_e32 v94, vcc, s33, v66
	s_and_b32 s3, s3, 3
	s_nop 0
	v_addc_co_u32_e32 v95, vcc, 0, v67, vcc
	global_load_ushort v97, v[94:95], off offset:2048
	v_add_co_u32_e32 v94, vcc, s40, v66
	v_lshl_or_b32 v0, s3, 7, v80
	s_nop 0
	v_addc_co_u32_e32 v95, vcc, 0, v67, vcc
	global_load_ushort v94, v[94:95], off offset:3072
	s_movk_i32 s3, 0x5000
	v_add_co_u32_e32 v98, vcc, s3, v66
	s_movk_i32 s3, 0x6000
	s_nop 0
	v_addc_co_u32_e32 v99, vcc, 0, v67, vcc
	global_load_ushort v95, v[98:99], off
	v_add_co_u32_e32 v98, vcc, s3, v66
	s_movk_i32 s3, 0x7000
	s_nop 0
	v_addc_co_u32_e32 v99, vcc, 0, v67, vcc
	global_load_ushort v93, v[98:99], off offset:1024
	v_add_co_u32_e32 v98, vcc, s3, v66
	s_mov_b32 s3, 0x8000
	s_nop 0
	v_addc_co_u32_e32 v99, vcc, 0, v67, vcc
	global_load_ushort v100, v[98:99], off offset:2048
	v_add_co_u32_e32 v98, vcc, s3, v66
	s_mov_b32 s3, 0xa000
	s_nop 0
	v_addc_co_u32_e32 v99, vcc, 0, v67, vcc
	global_load_ushort v101, v[98:99], off offset:3072
	v_add_co_u32_e32 v98, vcc, s3, v66
	s_mov_b32 s3, 0xb000
	s_nop 0
	v_addc_co_u32_e32 v99, vcc, 0, v67, vcc
	global_load_ushort v102, v[98:99], off
	v_add_co_u32_e32 v98, vcc, s3, v66
	s_mov_b32 s3, 0xc000
	s_nop 0
	v_addc_co_u32_e32 v99, vcc, 0, v67, vcc
	global_load_ushort v103, v[98:99], off offset:1024
	v_add_co_u32_e32 v98, vcc, s3, v66
	s_mov_b32 s3, 0xd000
	s_nop 0
	v_addc_co_u32_e32 v99, vcc, 0, v67, vcc
	global_load_ushort v104, v[98:99], off offset:2048
	v_add_co_u32_e32 v98, vcc, s3, v66
	s_mov_b32 s3, 0xf000
	s_nop 0
	v_addc_co_u32_e32 v99, vcc, 0, v67, vcc
	global_load_ushort v105, v[98:99], off offset:3072
	v_add_co_u32_e32 v98, vcc, s3, v66
	s_mov_b32 s3, 0x10000
	s_nop 0
	v_addc_co_u32_e32 v99, vcc, 0, v67, vcc
	global_load_ushort v106, v[98:99], off
	v_add_co_u32_e32 v98, vcc, s3, v66
	s_mov_b32 s3, 0x11000
	s_nop 0
	v_addc_co_u32_e32 v99, vcc, 0, v67, vcc
	global_load_ushort v107, v[98:99], off offset:1024
	v_add_co_u32_e32 v98, vcc, s3, v66
	s_mov_b32 s3, 0x12000
	s_nop 0
	v_addc_co_u32_e32 v99, vcc, 0, v67, vcc
	global_load_ushort v108, v[98:99], off offset:2048
	v_add_co_u32_e32 v98, vcc, s3, v66
	s_mov_b32 s3, 0x14000
	s_nop 0
	v_addc_co_u32_e32 v99, vcc, 0, v67, vcc
	global_load_ushort v109, v[98:99], off offset:3072
	v_add_co_u32_e32 v98, vcc, s3, v66
	s_mov_b32 s3, 0x15000
	s_nop 0
	v_addc_co_u32_e32 v99, vcc, 0, v67, vcc
	global_load_ushort v110, v[98:99], off
	v_add_co_u32_e32 v98, vcc, s3, v66
	s_mov_b32 s3, 0x16000
	s_nop 0
	v_addc_co_u32_e32 v99, vcc, 0, v67, vcc
	global_load_ushort v111, v[98:99], off offset:1024
	v_add_co_u32_e32 v98, vcc, s3, v66
	s_mov_b32 s3, 0x17000
	s_nop 0
	v_addc_co_u32_e32 v99, vcc, 0, v67, vcc
	global_load_ushort v112, v[98:99], off offset:2048
	v_add_co_u32_e32 v98, vcc, s3, v66
	s_mov_b32 s3, 0x19000
	s_nop 0
	v_addc_co_u32_e32 v99, vcc, 0, v67, vcc
	global_load_ushort v113, v[98:99], off offset:3072
	v_add_co_u32_e32 v98, vcc, s3, v66
	s_mov_b32 s3, 0x1a000
	s_nop 0
	v_addc_co_u32_e32 v99, vcc, 0, v67, vcc
	global_load_ushort v114, v[98:99], off
	v_add_co_u32_e32 v98, vcc, s3, v66
	s_mov_b32 s3, 0x1b000
	s_nop 0
	v_addc_co_u32_e32 v99, vcc, 0, v67, vcc
	global_load_ushort v115, v[98:99], off offset:1024
	v_add_co_u32_e32 v98, vcc, s3, v66
	s_mov_b32 s3, 0x1c000
	s_nop 0
	v_addc_co_u32_e32 v99, vcc, 0, v67, vcc
	global_load_ushort v116, v[98:99], off offset:2048
	v_add_co_u32_e32 v98, vcc, s3, v66
	s_mov_b32 s3, 0x1e000
	s_nop 0
	v_addc_co_u32_e32 v99, vcc, 0, v67, vcc
	global_load_ushort v117, v[98:99], off offset:3072
	v_add_co_u32_e32 v98, vcc, s3, v66
	s_mov_b32 s3, 0x1f000
	s_nop 0
	v_addc_co_u32_e32 v99, vcc, 0, v67, vcc
	global_load_ushort v118, v[98:99], off
	v_add_co_u32_e32 v98, vcc, s3, v66
	s_mov_b32 s3, 0x20000
	s_nop 0
	v_addc_co_u32_e32 v99, vcc, 0, v67, vcc
	global_load_ushort v119, v[98:99], off offset:1024
	v_add_co_u32_e32 v98, vcc, s3, v66
	s_waitcnt vmcnt(26)
; __device__ __forceinline__ float bf2f(unsigned short b) { return __uint_as_float((unsigned)b << 16); }
; __device__ __forceinline__ unsigned pk2(float lo, float hi) { const f32x2_ v = {lo, hi}; return __builtin_bit_cast(unsigned, __builtin_convertvector(v, bf16x2_)); }
; __device__ __forceinline__ void lru_local_unit(int u, int l, KIn in, const bf16* proj, const bf16* WAXT, float* PR, float* EN, bf16* LH, bf16* CP, LAS unsigned char* wl, int lane) {
;     ...
;     float xm3 = 0.f, xm2 = 0.f, xm1 = 0.f;
;     if (c > 0) { xm3 = bf2f(*(xp - 3 * PP)); xm2 = bf2f(*(xp - 2 * PP)); xm1 = bf2f(*(xp - PP)); }
; #pragma unroll
;     for (int t0 = 0; t0 < 64; t0 += 32) { bf16 xv[32];
; #pragma unroll
;         for (int i = 0; i < 32; ++i) xv[i] = xp[(size_t)(t0 + i) * PP];
; #pragma unroll
;         for (int i = 0; i < 32; ++i) { const float xt = bf2f(xv[i]); XCb[(t0 + i) * 72 + lane] = (bf16)(pk2(cb + cw0 * xm3 + cw1 * xm2 + cw2 * xm1 + cw3 * xt, 0.f) & 0xffffu); xm3 = xm2; xm2 = xm1; xm1 = xt; } }
	v_lshlrev_b32_e32 v92, 16, v125
	v_lshlrev_b32_e32 v77, 16, v127
	v_lshlrev_b32_e32 v76, 16, v126
	v_fma_f32 v92, v71, v92, v72
	v_addc_co_u32_e32 v99, vcc, 0, v67, vcc
	global_load_ushort v120, v[98:99], off offset:2048
	s_mov_b32 s3, 0x21000
	v_fmac_f32_e32 v92, v70, v77
	v_add_co_u32_e32 v98, vcc, s3, v66
	s_waitcnt vmcnt(26)
	v_lshlrev_b32_e32 v91, 16, v91
	v_fmac_f32_e32 v92, v68, v76
	v_addc_co_u32_e32 v99, vcc, 0, v67, vcc
	s_mov_b32 s3, 0x23000
	v_fmac_f32_e32 v92, v69, v91
	global_load_ushort v121, v[98:99], off offset:3072
	v_add_co_u32_e32 v98, vcc, s3, v66
	v_fma_f32 v77, v71, v77, v72
	v_cvt_pk_bf16_f32 v92, v92, s0
	v_addc_co_u32_e32 v99, vcc, 0, v67, vcc
	s_mov_b32 s3, 0x24000
	v_fmac_f32_e32 v77, v70, v76
	global_load_ushort v122, v[98:99], off
	v_add_co_u32_e32 v98, vcc, s3, v66
	ds_write_b16 v81, v92
	s_waitcnt vmcnt(27)
	v_lshlrev_b32_e32 v92, 16, v96
	v_fmac_f32_e32 v77, v68, v91
	v_addc_co_u32_e32 v99, vcc, 0, v67, vcc
	v_fmac_f32_e32 v77, v69, v92
	v_fma_f32 v76, v71, v76, v72
	global_load_ushort v123, v[98:99], off offset:1024
	s_mov_b32 s3, 0x25000
	v_cvt_pk_bf16_f32 v77, v77, s0
	v_fmac_f32_e32 v76, v70, v91
	v_add_co_u32_e32 v98, vcc, s3, v66
	ds_write_b16 v81, v77 offset:144
	s_waitcnt vmcnt(27)
	v_lshlrev_b32_e32 v77, 16, v97
	v_fmac_f32_e32 v76, v68, v92
	v_addc_co_u32_e32 v99, vcc, 0, v67, vcc
	v_fmac_f32_e32 v76, v69, v77
	v_fma_f32 v91, v71, v91, v72
	global_load_ushort v124, v[98:99], off offset:2048
	s_mov_b32 s3, 0x26000
	v_cvt_pk_bf16_f32 v76, v76, s0
	v_fmac_f32_e32 v91, v70, v92
	v_add_co_u32_e32 v98, vcc, s3, v66
	ds_write_b16 v81, v76 offset:288
	s_waitcnt vmcnt(27)
	v_lshlrev_b32_e32 v76, 16, v94
	v_fmac_f32_e32 v91, v68, v77
	v_addc_co_u32_e32 v99, vcc, 0, v67, vcc
	v_fmac_f32_e32 v91, v69, v76
	v_fma_f32 v92, v71, v92, v72
	global_load_ushort v98, v[98:99], off offset:3072
	v_cvt_pk_bf16_f32 v91, v91, s0
	v_fmac_f32_e32 v92, v70, v77
	ds_write_b16 v81, v91 offset:432
	s_waitcnt vmcnt(27)
	v_lshlrev_b32_e32 v91, 16, v95
	v_fmac_f32_e32 v92, v68, v76
	v_fmac_f32_e32 v92, v69, v91
	v_fma_f32 v77, v71, v77, v72
	v_cvt_pk_bf16_f32 v92, v92, s0
	v_fmac_f32_e32 v77, v70, v76
	ds_write_b16 v81, v92 offset:576
	s_waitcnt vmcnt(26)
	v_lshlrev_b32_e32 v92, 16, v93
	v_fmac_f32_e32 v77, v68, v91
	v_fmac_f32_e32 v77, v69, v92
	v_fma_f32 v76, v71, v76, v72
	v_cvt_pk_bf16_f32 v77, v77, s0
	v_fmac_f32_e32 v76, v70, v91
	ds_write_b16 v81, v77 offset:720
	s_waitcnt vmcnt(25)
	v_lshlrev_b32_e32 v77, 16, v100
	v_fmac_f32_e32 v76, v68, v92
	v_fmac_f32_e32 v76, v69, v77
	v_fma_f32 v91, v71, v91, v72
	v_cvt_pk_bf16_f32 v76, v76, s0
	v_fmac_f32_e32 v91, v70, v92
	ds_write_b16 v81, v76 offset:864
	s_waitcnt vmcnt(24)
	v_lshlrev_b32_e32 v76, 16, v101
	v_fmac_f32_e32 v91, v68, v77
	v_fmac_f32_e32 v91, v69, v76
	v_fma_f32 v92, v71, v92, v72
	v_cvt_pk_bf16_f32 v91, v91, s0
	v_fmac_f32_e32 v92, v70, v77
	ds_write_b16 v81, v91 offset:1008
	s_waitcnt vmcnt(23)
	v_lshlrev_b32_e32 v91, 16, v102
	v_fmac_f32_e32 v92, v68, v76
	v_fmac_f32_e32 v92, v69, v91
	v_fma_f32 v77, v71, v77, v72
	v_cvt_pk_bf16_f32 v92, v92, s0
	v_fmac_f32_e32 v77, v70, v76
	ds_write_b16 v81, v92 offset:1152
	s_waitcnt vmcnt(22)
	v_lshlrev_b32_e32 v92, 16, v103
	v_fmac_f32_e32 v77, v68, v91
	v_fmac_f32_e32 v77, v69, v92
	v_fma_f32 v76, v71, v76, v72
	v_cvt_pk_bf16_f32 v77, v77, s0
	v_fmac_f32_e32 v76, v70, v91
	ds_write_b16 v81, v77 offset:1296
	s_waitcnt vmcnt(21)
	v_lshlrev_b32_e32 v77, 16, v104
	v_fmac_f32_e32 v76, v68, v92
	v_fmac_f32_e32 v76, v69, v77
	v_fma_f32 v91, v71, v91, v72
	v_cvt_pk_bf16_f32 v76, v76, s0
	v_fmac_f32_e32 v91, v70, v92
	ds_write_b16 v81, v76 offset:1440
	s_waitcnt vmcnt(20)
	v_lshlrev_b32_e32 v76, 16, v105
	v_fmac_f32_e32 v91, v68, v77
	v_fmac_f32_e32 v91, v69, v76
	v_fma_f32 v92, v71, v92, v72
	v_cvt_pk_bf16_f32 v91, v91, s0
	v_fmac_f32_e32 v92, v70, v77
	ds_write_b16 v81, v91 offset:1584
	s_waitcnt vmcnt(19)
	v_lshlrev_b32_e32 v91, 16, v106
	v_fmac_f32_e32 v92, v68, v76
	v_fmac_f32_e32 v92, v69, v91
	v_fma_f32 v77, v71, v77, v72
	v_cvt_pk_bf16_f32 v92, v92, s0
	v_fmac_f32_e32 v77, v70, v76
	ds_write_b16 v81, v92 offset:1728
	s_waitcnt vmcnt(18)
	v_lshlrev_b32_e32 v92, 16, v107
	v_fmac_f32_e32 v77, v68, v91
	v_fmac_f32_e32 v77, v69, v92
	v_fma_f32 v76, v71, v76, v72
	v_cvt_pk_bf16_f32 v77, v77, s0
	v_fmac_f32_e32 v76, v70, v91
	ds_write_b16 v81, v77 offset:1872
	s_waitcnt vmcnt(17)
	v_lshlrev_b32_e32 v77, 16, v108
	v_fmac_f32_e32 v76, v68, v92
	v_fmac_f32_e32 v76, v69, v77
	v_fma_f32 v91, v71, v91, v72
	v_cvt_pk_bf16_f32 v76, v76, s0
	v_fmac_f32_e32 v91, v70, v92
	ds_write_b16 v81, v76 offset:2016
	s_waitcnt vmcnt(16)
	v_lshlrev_b32_e32 v76, 16, v109
	v_fmac_f32_e32 v91, v68, v77
	v_fmac_f32_e32 v91, v69, v76
	v_fma_f32 v92, v71, v92, v72
	v_cvt_pk_bf16_f32 v91, v91, s0
	v_fmac_f32_e32 v92, v70, v77
	ds_write_b16 v81, v91 offset:2160
	s_waitcnt vmcnt(15)
	v_lshlrev_b32_e32 v91, 16, v110
	v_fmac_f32_e32 v92, v68, v76
	v_fmac_f32_e32 v92, v69, v91
	v_fma_f32 v77, v71, v77, v72
	v_cvt_pk_bf16_f32 v92, v92, s0
	v_fmac_f32_e32 v77, v70, v76
	ds_write_b16 v81, v92 offset:2304
	s_waitcnt vmcnt(14)
	v_lshlrev_b32_e32 v92, 16, v111
	v_fmac_f32_e32 v77, v68, v91
	v_fmac_f32_e32 v77, v69, v92
	v_fma_f32 v76, v71, v76, v72
	v_cvt_pk_bf16_f32 v77, v77, s0
	v_fmac_f32_e32 v76, v70, v91
	ds_write_b16 v81, v77 offset:2448
	s_waitcnt vmcnt(13)
	v_lshlrev_b32_e32 v77, 16, v112
	v_fmac_f32_e32 v76, v68, v92
	v_fmac_f32_e32 v76, v69, v77
	v_fma_f32 v91, v71, v91, v72
	v_cvt_pk_bf16_f32 v76, v76, s0
	v_fmac_f32_e32 v91, v70, v92
	ds_write_b16 v81, v76 offset:2592
	s_waitcnt vmcnt(12)
; __device__ __forceinline__ float bf2f(unsigned short b) { return __uint_as_float((unsigned)b << 16); }
; __device__ __forceinline__ unsigned pk2(float lo, float hi) { const f32x2_ v = {lo, hi}; return __builtin_bit_cast(unsigned, __builtin_convertvector(v, bf16x2_)); }
; __device__ __forceinline__ void lru_local_unit(int u, int l, KIn in, const bf16* proj, const bf16* WAXT, float* PR, float* EN, bf16* LH, bf16* CP, LAS unsigned char* wl, int lane) {
;     ...
;     for (int t0 = 0; t0 < 64; t0 += 32) { bf16 xv[32];
; #pragma unroll
;         for (int i = 0; i < 32; ++i) xv[i] = xp[(size_t)(t0 + i) * PP];
; #pragma unroll
;         for (int i = 0; i < 32; ++i) { const float xt = bf2f(xv[i]); XCb[(t0 + i) * 72 + lane] = (bf16)(pk2(cb + cw0 * xm3 + cw1 * xm2 + cw2 * xm1 + cw3 * xt, 0.f) & 0xffffu); xm3 = xm2; xm2 = xm1; xm1 = xt; } }
	v_lshlrev_b32_e32 v76, 16, v113
	v_fmac_f32_e32 v91, v68, v77
	v_fmac_f32_e32 v91, v69, v76
	v_fma_f32 v92, v71, v92, v72
	v_cvt_pk_bf16_f32 v91, v91, s0
	v_fmac_f32_e32 v92, v70, v77
	ds_write_b16 v81, v91 offset:2736
	s_waitcnt vmcnt(11)
	v_lshlrev_b32_e32 v91, 16, v114
	v_fmac_f32_e32 v92, v68, v76
	v_fmac_f32_e32 v92, v69, v91
	v_fma_f32 v77, v71, v77, v72
	v_cvt_pk_bf16_f32 v92, v92, s0
	v_fmac_f32_e32 v77, v70, v76
	ds_write_b16 v81, v92 offset:2880
	s_waitcnt vmcnt(10)
	v_lshlrev_b32_e32 v92, 16, v115
	v_fmac_f32_e32 v77, v68, v91
	v_fmac_f32_e32 v77, v69, v92
	v_fma_f32 v76, v71, v76, v72
	v_cvt_pk_bf16_f32 v77, v77, s0
	v_fmac_f32_e32 v76, v70, v91
	ds_write_b16 v81, v77 offset:3024
	s_waitcnt vmcnt(9)
	v_lshlrev_b32_e32 v77, 16, v116
	v_fmac_f32_e32 v76, v68, v92
	v_fmac_f32_e32 v76, v69, v77
	v_fma_f32 v91, v71, v91, v72
	v_cvt_pk_bf16_f32 v76, v76, s0
	v_fmac_f32_e32 v91, v70, v92
	ds_write_b16 v81, v76 offset:3168
	s_waitcnt vmcnt(8)
	v_lshlrev_b32_e32 v76, 16, v117
	v_fmac_f32_e32 v91, v68, v77
	v_fmac_f32_e32 v91, v69, v76
	v_fma_f32 v92, v71, v92, v72
	v_cvt_pk_bf16_f32 v91, v91, s0
	v_fmac_f32_e32 v92, v70, v77
	ds_write_b16 v81, v91 offset:3312
	s_waitcnt vmcnt(7)
	v_lshlrev_b32_e32 v91, 16, v118
	v_fmac_f32_e32 v92, v68, v76
	v_fmac_f32_e32 v92, v69, v91
	v_fma_f32 v77, v71, v77, v72
	v_cvt_pk_bf16_f32 v92, v92, s0
	v_fmac_f32_e32 v77, v70, v76
	ds_write_b16 v81, v92 offset:3456
	s_waitcnt vmcnt(6)
	v_lshlrev_b32_e32 v92, 16, v119
	v_fmac_f32_e32 v77, v68, v91
	v_fmac_f32_e32 v77, v69, v92
	v_fma_f32 v76, v71, v76, v72
	v_cvt_pk_bf16_f32 v77, v77, s0
	v_fmac_f32_e32 v76, v70, v91
	ds_write_b16 v81, v77 offset:3600
	s_waitcnt vmcnt(5)
	v_lshlrev_b32_e32 v77, 16, v120
	v_fmac_f32_e32 v76, v68, v92
	v_fmac_f32_e32 v76, v69, v77
	v_fma_f32 v91, v71, v91, v72
	v_cvt_pk_bf16_f32 v76, v76, s0
	v_fmac_f32_e32 v91, v70, v92
	ds_write_b16 v81, v76 offset:3744
	s_waitcnt vmcnt(4)
	v_lshlrev_b32_e32 v76, 16, v121
	v_fmac_f32_e32 v91, v68, v77
	v_fmac_f32_e32 v91, v69, v76
	v_fma_f32 v92, v71, v92, v72
	v_cvt_pk_bf16_f32 v91, v91, s0
	v_fmac_f32_e32 v92, v70, v77
	v_fma_f32 v77, v71, v77, v72
	ds_write_b16 v81, v91 offset:3888
	s_waitcnt vmcnt(3)
	v_lshlrev_b32_e32 v91, 16, v122
	v_fmac_f32_e32 v77, v70, v76
	s_waitcnt vmcnt(2)
	v_lshlrev_b32_e32 v94, 16, v123
	v_fmac_f32_e32 v77, v68, v91
	v_fmac_f32_e32 v92, v68, v76
	v_fmac_f32_e32 v77, v69, v94
	v_fma_f32 v76, v71, v76, v72
	v_cvt_pk_bf16_f32 v77, v77, s0
	v_fmac_f32_e32 v76, v70, v91
	ds_write_b16 v81, v77 offset:4176
	s_waitcnt vmcnt(1)
	v_lshlrev_b32_e32 v77, 16, v124
	v_fmac_f32_e32 v76, v68, v94
	v_fmac_f32_e32 v92, v69, v91
	v_fmac_f32_e32 v76, v69, v77
	v_fma_f32 v91, v71, v91, v72
	v_cvt_pk_bf16_f32 v76, v76, s0
	v_fmac_f32_e32 v91, v70, v94
	v_cvt_pk_bf16_f32 v92, v92, s0
	ds_write_b16 v81, v76 offset:4320
	s_waitcnt vmcnt(0)
	v_lshlrev_b32_e32 v76, 16, v98
	v_fmac_f32_e32 v91, v68, v77
	s_mov_b32 s3, 0x28000
	ds_write_b16 v81, v92 offset:4032
	v_fmac_f32_e32 v91, v69, v76
	v_add_co_u32_e32 v92, vcc, s3, v66
	v_cvt_pk_bf16_f32 v91, v91, s0
	s_nop 0
	v_addc_co_u32_e32 v93, vcc, 0, v67, vcc
	s_mov_b32 s3, 0x29000
	ds_write_b16 v81, v91 offset:4464
	global_load_ushort v91, v[92:93], off
	v_fma_f32 v92, v71, v94, v72
	v_add_co_u32_e32 v94, vcc, s3, v66
	s_mov_b32 s3, 0x2a000
	s_nop 0
	v_addc_co_u32_e32 v95, vcc, 0, v67, vcc
	global_load_ushort v93, v[94:95], off offset:1024
	v_add_co_u32_e32 v94, vcc, s3, v66
	s_mov_b32 s3, 0x2b000
	s_nop 0
	v_addc_co_u32_e32 v95, vcc, 0, v67, vcc
	global_load_ushort v96, v[94:95], off offset:2048
	v_add_co_u32_e32 v94, vcc, s3, v66
	s_mov_b32 s3, 0x2d000
	s_nop 0
	v_addc_co_u32_e32 v95, vcc, 0, v67, vcc
	global_load_ushort v97, v[94:95], off offset:3072
	v_add_co_u32_e32 v94, vcc, s3, v66
	s_mov_b32 s3, 0x2e000
	s_nop 0
	v_addc_co_u32_e32 v95, vcc, 0, v67, vcc
	global_load_ushort v98, v[94:95], off
	v_add_co_u32_e32 v94, vcc, s3, v66
	s_mov_b32 s3, 0x2f000
	s_nop 0
	v_addc_co_u32_e32 v95, vcc, 0, v67, vcc
	global_load_ushort v99, v[94:95], off offset:1024
	v_add_co_u32_e32 v94, vcc, s3, v66
	s_mov_b32 s3, 0x30000
	s_nop 0
	v_addc_co_u32_e32 v95, vcc, 0, v67, vcc
	global_load_ushort v100, v[94:95], off offset:2048
	v_add_co_u32_e32 v94, vcc, s3, v66
	s_mov_b32 s3, 0x32000
	s_nop 0
	v_addc_co_u32_e32 v95, vcc, 0, v67, vcc
	global_load_ushort v101, v[94:95], off offset:3072
	v_add_co_u32_e32 v94, vcc, s3, v66
	s_mov_b32 s3, 0x33000
	s_nop 0
	v_addc_co_u32_e32 v95, vcc, 0, v67, vcc
	global_load_ushort v102, v[94:95], off
	v_add_co_u32_e32 v94, vcc, s3, v66
	s_mov_b32 s3, 0x34000
	s_nop 0
	v_addc_co_u32_e32 v95, vcc, 0, v67, vcc
	global_load_ushort v103, v[94:95], off offset:1024
	v_add_co_u32_e32 v94, vcc, s3, v66
	s_mov_b32 s3, 0x35000
	s_nop 0
	v_addc_co_u32_e32 v95, vcc, 0, v67, vcc
	global_load_ushort v104, v[94:95], off offset:2048
	v_add_co_u32_e32 v94, vcc, s3, v66
	s_mov_b32 s3, 0x37000
	s_nop 0
	v_addc_co_u32_e32 v95, vcc, 0, v67, vcc
	global_load_ushort v105, v[94:95], off offset:3072
	v_add_co_u32_e32 v94, vcc, s3, v66
	s_mov_b32 s3, 0x38000
	s_nop 0
	v_addc_co_u32_e32 v95, vcc, 0, v67, vcc
	global_load_ushort v106, v[94:95], off
	v_add_co_u32_e32 v94, vcc, s3, v66
	s_mov_b32 s3, 0x39000
	s_nop 0
	v_addc_co_u32_e32 v95, vcc, 0, v67, vcc
	global_load_ushort v107, v[94:95], off offset:1024
	v_add_co_u32_e32 v94, vcc, s3, v66
	s_mov_b32 s3, 0x3a000
	s_nop 0
	v_addc_co_u32_e32 v95, vcc, 0, v67, vcc
	global_load_ushort v108, v[94:95], off offset:2048
	v_add_co_u32_e32 v94, vcc, s3, v66
	s_mov_b32 s3, 0x3c000
	s_nop 0
	v_addc_co_u32_e32 v95, vcc, 0, v67, vcc
	global_load_ushort v109, v[94:95], off offset:3072
	v_add_co_u32_e32 v94, vcc, s3, v66
; __device__ __forceinline__ float bf2f(unsigned short b) { return __uint_as_float((unsigned)b << 16); }
; __device__ __forceinline__ unsigned pk2(float lo, float hi) { const f32x2_ v = {lo, hi}; return __builtin_bit_cast(unsigned, __builtin_convertvector(v, bf16x2_)); }
; __device__ __forceinline__ void lru_local_unit(int u, int l, KIn in, const bf16* proj, const bf16* WAXT, float* PR, float* EN, bf16* LH, bf16* CP, LAS unsigned char* wl, int lane) {
;     ...
;     for (int t0 = 0; t0 < 64; t0 += 32) { bf16 xv[32];
; #pragma unroll
;         for (int i = 0; i < 32; ++i) xv[i] = xp[(size_t)(t0 + i) * PP];
; #pragma unroll
;         for (int i = 0; i < 32; ++i) { const float xt = bf2f(xv[i]); XCb[(t0 + i) * 72 + lane] = (bf16)(pk2(cb + cw0 * xm3 + cw1 * xm2 + cw2 * xm1 + cw3 * xt, 0.f) & 0xffffu); xm3 = xm2; xm2 = xm1; xm1 = xt; } }
	s_mov_b32 s3, 0x3d000
	s_nop 0
	v_addc_co_u32_e32 v95, vcc, 0, v67, vcc
	global_load_ushort v110, v[94:95], off
	v_add_co_u32_e32 v94, vcc, s3, v66
	s_mov_b32 s3, 0x3e000
	s_nop 0
	v_addc_co_u32_e32 v95, vcc, 0, v67, vcc
	global_load_ushort v111, v[94:95], off offset:1024
	v_add_co_u32_e32 v94, vcc, s3, v66
	s_mov_b32 s3, 0x3f000
	s_nop 0
	v_addc_co_u32_e32 v95, vcc, 0, v67, vcc
	global_load_ushort v112, v[94:95], off offset:2048
	v_add_co_u32_e32 v94, vcc, s3, v66
	s_mov_b32 s3, 0x41000
	s_nop 0
	v_addc_co_u32_e32 v95, vcc, 0, v67, vcc
	global_load_ushort v113, v[94:95], off offset:3072
	v_add_co_u32_e32 v94, vcc, s3, v66
	s_mov_b32 s3, 0x42000
	s_nop 0
	v_addc_co_u32_e32 v95, vcc, 0, v67, vcc
	global_load_ushort v114, v[94:95], off
	v_add_co_u32_e32 v94, vcc, s3, v66
	s_mov_b32 s3, 0x43000
	s_nop 0
	v_addc_co_u32_e32 v95, vcc, 0, v67, vcc
	global_load_ushort v115, v[94:95], off offset:1024
	v_add_co_u32_e32 v94, vcc, s3, v66
	s_mov_b32 s3, 0x44000
	s_nop 0
	v_addc_co_u32_e32 v95, vcc, 0, v67, vcc
	global_load_ushort v116, v[94:95], off offset:2048
	v_add_co_u32_e32 v94, vcc, s3, v66
	s_mov_b32 s3, 0x46000
	s_nop 0
	v_addc_co_u32_e32 v95, vcc, 0, v67, vcc
	global_load_ushort v117, v[94:95], off offset:3072
	v_add_co_u32_e32 v94, vcc, s3, v66
	s_mov_b32 s3, 0x47000
	s_nop 0
	v_addc_co_u32_e32 v95, vcc, 0, v67, vcc
	global_load_ushort v118, v[94:95], off
	v_add_co_u32_e32 v94, vcc, s3, v66
	s_mov_b32 s3, 0x48000
	s_nop 0
	v_addc_co_u32_e32 v95, vcc, 0, v67, vcc
	global_load_ushort v119, v[94:95], off offset:1024
	v_add_co_u32_e32 v94, vcc, s3, v66
	s_mov_b32 s3, 0x49000
	s_nop 0
	v_addc_co_u32_e32 v95, vcc, 0, v67, vcc
	global_load_ushort v120, v[94:95], off offset:2048
	v_add_co_u32_e32 v94, vcc, s3, v66
	s_mov_b32 s3, 0x4b000
	s_nop 0
	v_addc_co_u32_e32 v95, vcc, 0, v67, vcc
	global_load_ushort v121, v[94:95], off offset:3072
	v_add_co_u32_e32 v94, vcc, s3, v66
	s_mov_b32 s3, 0x4c000
	s_nop 0
	v_addc_co_u32_e32 v95, vcc, 0, v67, vcc
	global_load_ushort v122, v[94:95], off
	v_add_co_u32_e32 v94, vcc, s3, v66
	s_mov_b32 s3, 0x4d000
	s_nop 0
	v_addc_co_u32_e32 v95, vcc, 0, v67, vcc
	global_load_ushort v123, v[94:95], off offset:1024
	v_add_co_u32_e32 v94, vcc, s3, v66
	s_mov_b32 s3, 0x4e000
	s_nop 0
	v_addc_co_u32_e32 v95, vcc, 0, v67, vcc
	v_fmac_f32_e32 v92, v70, v77
	v_add_co_u32_e32 v66, vcc, s3, v66
	v_fma_f32 v77, v71, v77, v72
	s_waitcnt vmcnt(29)
	v_lshlrev_b32_e32 v91, 16, v91
	v_addc_co_u32_e32 v67, vcc, 0, v67, vcc
	v_fmac_f32_e32 v77, v70, v76
	global_load_ushort v94, v[94:95], off offset:2048
	v_fmac_f32_e32 v77, v68, v91
	global_load_ushort v66, v[66:67], off offset:3072
	s_waitcnt vmcnt(30)
	v_lshlrev_b32_e32 v67, 16, v93
	v_fmac_f32_e32 v92, v68, v76
	v_fmac_f32_e32 v77, v69, v67
	v_fma_f32 v76, v71, v76, v72
	v_cvt_pk_bf16_f32 v77, v77, s0
	v_fmac_f32_e32 v76, v70, v91
	ds_write_b16 v81, v77 offset:4752
	s_waitcnt vmcnt(29)
	v_lshlrev_b32_e32 v77, 16, v96
	v_fmac_f32_e32 v76, v68, v67
	v_fmac_f32_e32 v92, v69, v91
	v_fmac_f32_e32 v76, v69, v77
	v_fma_f32 v91, v71, v91, v72
	v_cvt_pk_bf16_f32 v76, v76, s0
	v_fmac_f32_e32 v91, v70, v67
	ds_write_b16 v81, v76 offset:4896
	s_waitcnt vmcnt(28)
	v_lshlrev_b32_e32 v76, 16, v97
	v_fmac_f32_e32 v91, v68, v77
	v_fmac_f32_e32 v91, v69, v76
	v_fma_f32 v67, v71, v67, v72
	v_cvt_pk_bf16_f32 v91, v91, s0
	v_fmac_f32_e32 v67, v70, v77
	ds_write_b16 v81, v91 offset:5040
	s_waitcnt vmcnt(27)
	v_lshlrev_b32_e32 v91, 16, v98
	v_fmac_f32_e32 v67, v68, v76
	v_fmac_f32_e32 v67, v69, v91
	v_fma_f32 v77, v71, v77, v72
	v_cvt_pk_bf16_f32 v67, v67, s0
	v_fmac_f32_e32 v77, v70, v76
	ds_write_b16 v81, v67 offset:5184
	s_waitcnt vmcnt(26)
	v_lshlrev_b32_e32 v67, 16, v99
	v_fmac_f32_e32 v77, v68, v91
	v_fmac_f32_e32 v77, v69, v67
	v_fma_f32 v76, v71, v76, v72
	v_cvt_pk_bf16_f32 v77, v77, s0
	v_fmac_f32_e32 v76, v70, v91
	ds_write_b16 v81, v77 offset:5328
	s_waitcnt vmcnt(25)
	v_lshlrev_b32_e32 v77, 16, v100
	v_fmac_f32_e32 v76, v68, v67
	v_fmac_f32_e32 v76, v69, v77
	v_fma_f32 v91, v71, v91, v72
	v_cvt_pk_bf16_f32 v76, v76, s0
	v_fmac_f32_e32 v91, v70, v67
	ds_write_b16 v81, v76 offset:5472
	s_waitcnt vmcnt(24)
	v_lshlrev_b32_e32 v76, 16, v101
	v_fmac_f32_e32 v91, v68, v77
	v_fmac_f32_e32 v91, v69, v76
	v_fma_f32 v67, v71, v67, v72
	v_cvt_pk_bf16_f32 v91, v91, s0
	v_fmac_f32_e32 v67, v70, v77
	ds_write_b16 v81, v91 offset:5616
	s_waitcnt vmcnt(23)
	v_lshlrev_b32_e32 v91, 16, v102
	v_fmac_f32_e32 v67, v68, v76
	v_fmac_f32_e32 v67, v69, v91
	v_fma_f32 v77, v71, v77, v72
	v_cvt_pk_bf16_f32 v67, v67, s0
	v_fmac_f32_e32 v77, v70, v76
	ds_write_b16 v81, v67 offset:5760
	s_waitcnt vmcnt(22)
	v_lshlrev_b32_e32 v67, 16, v103
	v_fmac_f32_e32 v77, v68, v91
	v_fmac_f32_e32 v77, v69, v67
	v_fma_f32 v76, v71, v76, v72
	v_cvt_pk_bf16_f32 v77, v77, s0
	v_fmac_f32_e32 v76, v70, v91
	ds_write_b16 v81, v77 offset:5904
	s_waitcnt vmcnt(21)
	v_lshlrev_b32_e32 v77, 16, v104
	v_fmac_f32_e32 v76, v68, v67
	v_fmac_f32_e32 v76, v69, v77
	v_fma_f32 v91, v71, v91, v72
	v_cvt_pk_bf16_f32 v76, v76, s0
	v_fmac_f32_e32 v91, v70, v67
	ds_write_b16 v81, v76 offset:6048
	s_waitcnt vmcnt(20)
	v_lshlrev_b32_e32 v76, 16, v105
	v_fmac_f32_e32 v91, v68, v77
	v_fmac_f32_e32 v91, v69, v76
	v_fma_f32 v67, v71, v67, v72
	v_cvt_pk_bf16_f32 v91, v91, s0
	v_fmac_f32_e32 v67, v70, v77
	ds_write_b16 v81, v91 offset:6192
	s_waitcnt vmcnt(19)
	v_lshlrev_b32_e32 v91, 16, v106
	v_fmac_f32_e32 v67, v68, v76
	v_fmac_f32_e32 v67, v69, v91
	v_fma_f32 v77, v71, v77, v72
	v_cvt_pk_bf16_f32 v67, v67, s0
	v_fmac_f32_e32 v77, v70, v76
	ds_write_b16 v81, v67 offset:6336
	s_waitcnt vmcnt(18)
; __device__ __forceinline__ float bf2f(unsigned short b) { return __uint_as_float((unsigned)b << 16); }
; __device__ __forceinline__ unsigned pk2(float lo, float hi) { const f32x2_ v = {lo, hi}; return __builtin_bit_cast(unsigned, __builtin_convertvector(v, bf16x2_)); }
; __device__ __forceinline__ void lru_local_unit(int u, int l, KIn in, const bf16* proj, const bf16* WAXT, float* PR, float* EN, bf16* LH, bf16* CP, LAS unsigned char* wl, int lane) {
;     ...
;     for (int t0 = 0; t0 < 64; t0 += 32) { bf16 xv[32];
; #pragma unroll
;         for (int i = 0; i < 32; ++i) xv[i] = xp[(size_t)(t0 + i) * PP];
; #pragma unroll
;         for (int i = 0; i < 32; ++i) { const float xt = bf2f(xv[i]); XCb[(t0 + i) * 72 + lane] = (bf16)(pk2(cb + cw0 * xm3 + cw1 * xm2 + cw2 * xm1 + cw3 * xt, 0.f) & 0xffffu); xm3 = xm2; xm2 = xm1; xm1 = xt; } }
	v_lshlrev_b32_e32 v67, 16, v107
	v_fmac_f32_e32 v77, v68, v91
	v_fmac_f32_e32 v77, v69, v67
	v_fma_f32 v76, v71, v76, v72
	v_cvt_pk_bf16_f32 v77, v77, s0
	v_fmac_f32_e32 v76, v70, v91
	ds_write_b16 v81, v77 offset:6480
	s_waitcnt vmcnt(17)
	v_lshlrev_b32_e32 v77, 16, v108
	v_fmac_f32_e32 v76, v68, v67
	v_fmac_f32_e32 v76, v69, v77
	v_fma_f32 v91, v71, v91, v72
	v_cvt_pk_bf16_f32 v76, v76, s0
	v_fmac_f32_e32 v91, v70, v67
	ds_write_b16 v81, v76 offset:6624
	s_waitcnt vmcnt(16)
	v_lshlrev_b32_e32 v76, 16, v109
	v_fmac_f32_e32 v91, v68, v77
	v_fmac_f32_e32 v91, v69, v76
	v_fma_f32 v67, v71, v67, v72
	v_cvt_pk_bf16_f32 v91, v91, s0
	v_fmac_f32_e32 v67, v70, v77
	ds_write_b16 v81, v91 offset:6768
	s_waitcnt vmcnt(15)
	v_lshlrev_b32_e32 v91, 16, v110
	v_fmac_f32_e32 v67, v68, v76
	v_fmac_f32_e32 v67, v69, v91
	v_fma_f32 v77, v71, v77, v72
	v_cvt_pk_bf16_f32 v67, v67, s0
	v_fmac_f32_e32 v77, v70, v76
	ds_write_b16 v81, v67 offset:6912
	s_waitcnt vmcnt(14)
	v_lshlrev_b32_e32 v67, 16, v111
	v_fmac_f32_e32 v77, v68, v91
	v_fmac_f32_e32 v77, v69, v67
	v_fma_f32 v76, v71, v76, v72
	v_cvt_pk_bf16_f32 v77, v77, s0
	v_fmac_f32_e32 v76, v70, v91
	ds_write_b16 v81, v77 offset:7056
	s_waitcnt vmcnt(13)
	v_lshlrev_b32_e32 v77, 16, v112
	v_fmac_f32_e32 v76, v68, v67
	v_fmac_f32_e32 v76, v69, v77
	v_fma_f32 v91, v71, v91, v72
	v_cvt_pk_bf16_f32 v76, v76, s0
	v_fmac_f32_e32 v91, v70, v67
	ds_write_b16 v81, v76 offset:7200
	s_waitcnt vmcnt(12)
	v_lshlrev_b32_e32 v76, 16, v113
	v_fmac_f32_e32 v91, v68, v77
	v_fmac_f32_e32 v91, v69, v76
	v_fma_f32 v67, v71, v67, v72
	v_cvt_pk_bf16_f32 v91, v91, s0
	v_fmac_f32_e32 v67, v70, v77
	ds_write_b16 v81, v91 offset:7344
	s_waitcnt vmcnt(11)
	v_lshlrev_b32_e32 v91, 16, v114
	v_fmac_f32_e32 v67, v68, v76
	v_fmac_f32_e32 v67, v69, v91
	v_fma_f32 v77, v71, v77, v72
	v_cvt_pk_bf16_f32 v67, v67, s0
	v_fmac_f32_e32 v77, v70, v76
	ds_write_b16 v81, v67 offset:7488
	s_waitcnt vmcnt(10)
	v_lshlrev_b32_e32 v67, 16, v115
	v_fmac_f32_e32 v77, v68, v91
	v_fmac_f32_e32 v77, v69, v67
	v_fma_f32 v76, v71, v76, v72
	v_cvt_pk_bf16_f32 v77, v77, s0
	v_fmac_f32_e32 v76, v70, v91
	ds_write_b16 v81, v77 offset:7632
	s_waitcnt vmcnt(9)
	v_lshlrev_b32_e32 v77, 16, v116
	v_fmac_f32_e32 v76, v68, v67
	v_fmac_f32_e32 v76, v69, v77
	v_fma_f32 v91, v71, v91, v72
	v_cvt_pk_bf16_f32 v76, v76, s0
	v_fmac_f32_e32 v91, v70, v67
	ds_write_b16 v81, v76 offset:7776
	s_waitcnt vmcnt(8)
	v_lshlrev_b32_e32 v76, 16, v117
	v_fmac_f32_e32 v91, v68, v77
	v_fmac_f32_e32 v91, v69, v76
	v_fma_f32 v67, v71, v67, v72
	v_cvt_pk_bf16_f32 v91, v91, s0
	v_fmac_f32_e32 v67, v70, v77
	ds_write_b16 v81, v91 offset:7920
	s_waitcnt vmcnt(7)
	v_lshlrev_b32_e32 v91, 16, v118
	v_fmac_f32_e32 v67, v68, v76
	v_fmac_f32_e32 v67, v69, v91
	v_fma_f32 v77, v71, v77, v72
	v_cvt_pk_bf16_f32 v67, v67, s0
	v_fmac_f32_e32 v77, v70, v76
	ds_write_b16 v81, v67 offset:8064
	s_waitcnt vmcnt(6)
	v_lshlrev_b32_e32 v67, 16, v119
	v_fmac_f32_e32 v77, v68, v91
	v_fmac_f32_e32 v77, v69, v67
	v_fma_f32 v76, v71, v76, v72
	v_cvt_pk_bf16_f32 v77, v77, s0
	v_fmac_f32_e32 v76, v70, v91
	ds_write_b16 v81, v77 offset:8208
	s_waitcnt vmcnt(5)
	v_lshlrev_b32_e32 v77, 16, v120
	v_fmac_f32_e32 v76, v68, v67
	v_fmac_f32_e32 v76, v69, v77
	v_fma_f32 v91, v71, v91, v72
	v_cvt_pk_bf16_f32 v76, v76, s0
	v_fmac_f32_e32 v91, v70, v67
	ds_write_b16 v81, v76 offset:8352
	s_waitcnt vmcnt(4)
	v_lshlrev_b32_e32 v76, 16, v121
	v_fmac_f32_e32 v91, v68, v77
	v_fmac_f32_e32 v91, v69, v76
	v_fma_f32 v67, v71, v67, v72
	v_cvt_pk_bf16_f32 v91, v91, s0
	v_fmac_f32_e32 v67, v70, v77
	ds_write_b16 v81, v91 offset:8496
	s_waitcnt vmcnt(3)
	v_lshlrev_b32_e32 v91, 16, v122
	v_fmac_f32_e32 v67, v68, v76
	v_fmac_f32_e32 v67, v69, v91
	v_fma_f32 v77, v71, v77, v72
	v_cvt_pk_bf16_f32 v67, v67, s0
	v_fmac_f32_e32 v77, v70, v76
	ds_write_b16 v81, v67 offset:8640
	s_waitcnt vmcnt(2)
	v_lshlrev_b32_e32 v67, 16, v123
	v_fmac_f32_e32 v77, v68, v91
	v_fmac_f32_e32 v77, v69, v67
	v_cvt_pk_bf16_f32 v77, v77, s0
	v_fma_f32 v76, v71, v76, v72
	v_fmac_f32_e32 v72, v71, v91
	ds_write_b16 v81, v77 offset:8784
	s_waitcnt vmcnt(1)
	v_lshlrev_b32_e32 v77, 16, v94
	v_fmac_f32_e32 v72, v70, v67
	s_waitcnt vmcnt(0)
; __device__ __forceinline__ float bf2f(unsigned short b) { return __uint_as_float((unsigned)b << 16); }
; __device__ __forceinline__ unsigned pk2(float lo, float hi) { const f32x2_ v = {lo, hi}; return __builtin_bit_cast(unsigned, __builtin_convertvector(v, bf16x2_)); }
; #define WSYNC() asm volatile("s_waitcnt lgkmcnt(0)" ::: "memory")
; __device__ __forceinline__ void lru_local_unit(int u, int l, KIn in, const bf16* proj, const bf16* WAXT, float* PR, float* EN, bf16* LH, bf16* CP, LAS unsigned char* wl, int lane) {
;     ...
;         for (int i = 0; i < 32; ++i) { const float xt = bf2f(xv[i]); XCb[(t0 + i) * 72 + lane] = (bf16)(pk2(cb + cw0 * xm3 + cw1 * xm2 + cw2 * xm1 + cw3 * xt, 0.f) & 0xffffu); xm3 = xm2; xm2 = xm1; xm1 = xt; } }
;     const float sp8 = -8.f * log1pf(expf(-lam_));
;     WSYNC();
;     float h = 0.f, cp = 1.f;
	v_lshlrev_b32_e32 v66, 16, v66
	v_fmac_f32_e32 v72, v68, v77
	v_fmac_f32_e32 v72, v69, v66
	v_cvt_pk_bf16_f32 v66, v72, s0
	v_fmac_f32_e32 v76, v70, v91
	ds_write_b16 v81, v66 offset:9072
	v_mul_f32_e32 v66, 0xbfb8aa3b, v73
	v_fmac_f32_e32 v76, v68, v67
	v_rndne_f32_e32 v67, v66
	v_sub_f32_e32 v68, v66, v67
	v_fma_f32 v66, v73, s97, -v66
	v_fmac_f32_e32 v66, 0xb2a5705f, v73
	v_add_f32_e32 v66, v68, v66
	v_exp_f32_e32 v66, v66
	v_cvt_i32_f32_e32 v67, v67
	s_mov_b32 s3, 0x42ce8ed0
	v_cmp_nlt_f32_e32 vcc, s3, v73
	s_mov_b32 s3, 0xc2b17218
	v_ldexp_f32 v66, v66, v67
	v_cndmask_b32_e32 v66, 0, v66, vcc
	v_cmp_ngt_f32_e32 vcc, s3, v73
	v_mov_b32_e32 v94, 0x7f800000
	v_fmac_f32_e32 v76, v69, v77
	v_cndmask_b32_e32 v68, v94, v66, vcc
	v_add_f32_e32 v69, 1.0, v68
	v_add_f32_e32 v66, -1.0, v69
	v_sub_f32_e32 v67, v66, v69
	v_add_f32_e32 v67, 1.0, v67
	v_sub_f32_e32 v66, v68, v66
	v_add_f32_e32 v70, v66, v67
	v_frexp_mant_f32_e32 v66, v69
	s_mov_b32 s3, 0x3f2aaaab
	v_cmp_gt_f32_e32 vcc, s3, v66
	v_cvt_f64_f32_e32 v[66:67], v69
	v_frexp_exp_i32_f64_e32 v66, v[66:67]
	v_subbrev_co_u32_e32 v66, vcc, 0, v66, vcc
	v_sub_u32_e32 v67, 0, v66
	v_ldexp_f32 v69, v69, v67
	v_ldexp_f32 v67, v70, v67
	v_add_f32_e32 v70, -1.0, v69
	v_add_f32_e32 v71, 1.0, v70
	v_sub_f32_e32 v71, v69, v71
	v_add_f32_e32 v71, v67, v71
	v_add_f32_e32 v72, v70, v71
	v_sub_f32_e32 v70, v70, v72
	v_add_f32_e32 v70, v71, v70
	v_add_f32_e32 v71, 1.0, v69
	v_add_f32_e32 v73, -1.0, v71
	v_sub_f32_e32 v69, v69, v73
	v_add_f32_e32 v67, v67, v69
	v_add_f32_e32 v69, v71, v67
	v_sub_f32_e32 v71, v71, v69
	v_add_f32_e32 v67, v67, v71
	v_rcp_f32_e32 v71, v69
	v_cvt_pk_bf16_f32 v76, v76, s0
	ds_write_b16 v81, v76 offset:8928
	v_cvt_f32_i32_e32 v66, v66
	v_mul_f32_e32 v73, v72, v71
	v_mul_f32_e32 v76, v69, v73
	v_fma_f32 v77, v73, v69, -v76
	v_fmac_f32_e32 v77, v73, v67
	v_add_f32_e32 v91, v76, v77
	v_sub_f32_e32 v93, v72, v91
	v_sub_f32_e32 v72, v72, v93
	v_sub_f32_e32 v76, v91, v76
	v_sub_f32_e32 v72, v72, v91
	v_add_f32_e32 v70, v70, v72
	v_sub_f32_e32 v72, v76, v77
	v_add_f32_e32 v70, v72, v70
	v_add_f32_e32 v72, v93, v70
	v_mul_f32_e32 v76, v71, v72
	v_mul_f32_e32 v77, v69, v76
	v_fma_f32 v69, v76, v69, -v77
	v_fmac_f32_e32 v69, v76, v67
	v_sub_f32_e32 v67, v93, v72
	v_add_f32_e32 v67, v70, v67
	v_add_f32_e32 v70, v77, v69
	v_sub_f32_e32 v91, v72, v70
	v_sub_f32_e32 v72, v72, v91
	v_sub_f32_e32 v77, v70, v77
	v_sub_f32_e32 v70, v72, v70
	v_add_f32_e32 v67, v67, v70
	v_sub_f32_e32 v69, v77, v69
	v_add_f32_e32 v67, v69, v67
	v_add_f32_e32 v69, v73, v76
	v_add_f32_e32 v67, v91, v67
	v_sub_f32_e32 v70, v69, v73
	v_mul_f32_e32 v67, v71, v67
	v_sub_f32_e32 v70, v76, v70
	v_add_f32_e32 v67, v70, v67
	v_mul_f32_e32 v73, 0x3f317218, v66
	s_mov_b32 s3, 0x3f317218
	v_add_f32_e32 v70, v69, v67
	v_fma_f32 v76, v66, s3, -v73
	v_mul_f32_e32 v71, v70, v70
	v_mov_b32_e32 v72, 0x3ecc95a3
	v_fmac_f32_e32 v76, 0xb102e308, v66
	v_sub_f32_e32 v66, v70, v69
	v_fmamk_f32 v72, v71, 0x3e9b6dac, v72
	v_sub_f32_e32 v66, v67, v66
	v_add_f32_e32 v67, v73, v76
	v_fmaak_f32 v72, v71, v72, 0x3f2aaada
	v_sub_f32_e32 v69, v67, v73
	v_ldexp_f32 v73, v70, 1
	v_mul_f32_e32 v70, v70, v71
	v_mul_f32_e32 v70, v70, v72
	v_add_f32_e32 v71, v73, v70
	v_sub_f32_e32 v72, v71, v73
	v_ldexp_f32 v66, v66, 1
	v_sub_f32_e32 v70, v70, v72
	v_add_f32_e32 v66, v66, v70
	v_add_f32_e32 v70, v71, v66
	v_sub_f32_e32 v71, v70, v71
	v_sub_f32_e32 v66, v66, v71
	v_add_f32_e32 v71, v67, v70
	v_sub_f32_e32 v72, v71, v67
	v_sub_f32_e32 v73, v71, v72
	v_sub_f32_e32 v69, v76, v69
	v_sub_f32_e32 v67, v67, v73
	v_sub_f32_e32 v70, v70, v72
	v_add_f32_e32 v67, v70, v67
	v_add_f32_e32 v70, v69, v66
	v_sub_f32_e32 v72, v70, v69
	v_sub_f32_e32 v73, v70, v72
	v_sub_f32_e32 v69, v69, v73
	v_sub_f32_e32 v66, v66, v72
	v_add_f32_e32 v67, v70, v67
	v_add_f32_e32 v66, v66, v69
	v_add_f32_e32 v69, v71, v67
	v_sub_f32_e32 v70, v69, v71
	v_sub_f32_e32 v67, v67, v70
	s_and_b32 s22, s28, 63
	v_add_f32_e32 v66, v66, v67
	s_lshl_b32 s22, s22, 15
	v_cvt_pk_bf16_f32 v92, v92, s0
	v_add_f32_e32 v66, v69, v66
	v_cmp_neq_f32_e32 vcc, s44, v68
	s_mov_b32 s3, 0x33800000
	s_lshl_b64 s[26:27], s[20:21], 21
	ds_write_b16 v81, v92 offset:4608
	v_cndmask_b32_e32 v66, v94, v66, vcc
	v_cmp_lt_f32_e64 vcc, |v68|, s3
	s_or_b32 s3, s26, s22
	s_waitcnt lgkmcnt(0)
	s_add_u32 s22, s12, s3
	v_cndmask_b32_e32 v66, v66, v68, vcc
	s_addc_u32 s23, s13, s27
	s_mov_b32 s34, 0
	v_mov_b32_e32 v92, 1.0
	v_mul_f32_e32 v91, 0xc1000000, v66
	v_lshl_add_u64 v[76:77], s[22:23], 0, v[0:1]
	s_mov_b64 s[26:27], -1

; #define LAS __attribute__((address_space(3)))
; #define WSYNC() asm volatile("s_waitcnt lgkmcnt(0)" ::: "memory")
; __device__ __forceinline__ void gla_gates(const bf16* prow, const float* wg, const float* bg, int h, int lane, float (&bc)[32], LAS float* Wst) {
;     ...
;     float glr[16]; unpack8(*(const u32x4*)(prow + C_GLR), glr); unpack8(*(const u32x4*)(prow + C_GLR + 8), glr + 8);
;     WSYNC();
; #pragma unroll
;     for (int d4 = 0; d4 < 8; ++d4) { f32x4 z = *(const LAS f32x4*)(Wst + 512 + 4 * d4);
; #pragma unroll
;         for (int r = 0; r < 16; ++r) { const f32x4 w = *(const LAS f32x4*)(Wst + r * 32 + 4 * d4); z += w * glr[r]; }
; #pragma unroll
;         for (int e = 0; e < 4; ++e) bc[4 * d4 + e] = (fminf(z[e], 0.f) - __logf(1.f + __expf(-fabsf(z[e])))) * (1.f / 16.f); }
.LBB0_718:
	s_or_b64 exec, exec, s[26:27]
	v_mov_b32_e32 v251, s61
	s_waitcnt lgkmcnt(0)
	ds_read_b128 v[158:161], v251 offset:12288
	ds_read_b128 v[196:199], v251 offset:10240
	ds_read_b128 v[106:109], v251 offset:10256
	ds_read_b128 v[102:105], v251 offset:10272
	ds_read_b128 v[98:101], v251 offset:10288
	ds_read_b128 v[222:225], v251 offset:10368
	ds_read_b128 v[226:229], v251 offset:10496
	ds_read_b128 v[234:237], v251 offset:10624
	ds_read_b128 v[246:249], v251 offset:10752
	ds_read_b128 v[200:203], v251 offset:10880
	ds_read_b128 v[218:221], v251 offset:11008
	s_mov_b32 s2, 0x358637bd
	s_lshl_b32 s34, s34, 1
	s_add_i32 s59, s59, s72
	s_add_i32 s84, s84, s85
	s_cmpk_gt_i32 s59, 0x7ff
	v_lshl_add_u64 v[120:121], v[120:121], 0, s[82:83]
	s_waitcnt vmcnt(1)
	v_lshlrev_b32_e32 v136, 16, v110
	v_and_b32_e32 v134, 0xffff0000, v110
	v_lshlrev_b32_e32 v132, 16, v111
	s_waitcnt vmcnt(0)
	v_lshlrev_b32_e32 v152, 16, v154
	v_and_b32_e32 v150, 0xffff0000, v154
	v_lshlrev_b32_e32 v148, 16, v155
	v_and_b32_e32 v146, 0xffff0000, v155
	s_waitcnt lgkmcnt(9)
	v_pk_fma_f32 v[154:155], v[196:197], v[152:153], v[158:159] op_sel_hi:[1,0,1]
	v_pk_fma_f32 v[158:159], v[198:199], v[152:153], v[160:161] op_sel_hi:[1,0,1]
	s_waitcnt lgkmcnt(5)
	v_pk_fma_f32 v[160:161], v[150:151], v[222:223], v[154:155] op_sel_hi:[0,1,1]
	v_and_b32_e32 v130, 0xffff0000, v111
	v_lshlrev_b32_e32 v128, 16, v112
	v_and_b32_e32 v126, 0xffff0000, v112
	v_lshlrev_b32_e32 v0, 16, v113
	v_and_b32_e32 v124, 0xffff0000, v113
	ds_read_b128 v[110:113], v251 offset:11136
	s_waitcnt lgkmcnt(5)
	v_pk_fma_f32 v[196:197], v[148:149], v[226:227], v[160:161] op_sel_hi:[0,1,1]
	v_lshlrev_b32_e32 v144, 16, v156
	v_and_b32_e32 v142, 0xffff0000, v156
	v_lshlrev_b32_e32 v140, 16, v157
	v_and_b32_e32 v138, 0xffff0000, v157
	v_pk_fma_f32 v[158:159], v[150:151], v[224:225], v[158:159] op_sel_hi:[0,1,1]
	ds_read_b128 v[154:157], v251 offset:11264
	s_waitcnt lgkmcnt(5)
	v_pk_fma_f32 v[224:225], v[146:147], v[234:235], v[196:197] op_sel_hi:[0,1,1]
	v_pk_fma_f32 v[198:199], v[148:149], v[228:229], v[158:159] op_sel_hi:[0,1,1]
	ds_read_b128 v[158:161], v251 offset:11392
	s_waitcnt lgkmcnt(5)
	v_pk_fma_f32 v[226:227], v[144:145], v[246:247], v[224:225] op_sel_hi:[0,1,1]
	v_pk_fma_f32 v[222:223], v[146:147], v[236:237], v[198:199] op_sel_hi:[0,1,1]
	ds_read_b128 v[196:199], v251 offset:11520
	s_waitcnt lgkmcnt(5)
	v_pk_fma_f32 v[226:227], v[142:143], v[200:201], v[226:227] op_sel_hi:[0,1,1]
	v_pk_fma_f32 v[228:229], v[144:145], v[248:249], v[222:223] op_sel_hi:[0,1,1]
	ds_read_b128 v[222:225], v251 offset:11648
	s_waitcnt lgkmcnt(5)
	v_pk_fma_f32 v[226:227], v[140:141], v[218:219], v[226:227] op_sel_hi:[0,1,1]
	v_pk_fma_f32 v[228:229], v[142:143], v[202:203], v[228:229] op_sel_hi:[0,1,1]
	ds_read_b128 v[200:203], v251 offset:11776
	s_waitcnt lgkmcnt(5)
	v_pk_fma_f32 v[226:227], v[138:139], v[110:111], v[226:227] op_sel_hi:[0,1,1]
	v_pk_fma_f32 v[228:229], v[140:141], v[220:221], v[228:229] op_sel_hi:[0,1,1]
	ds_read_b128 v[218:221], v251 offset:11904
	s_waitcnt lgkmcnt(5)
	v_pk_fma_f32 v[226:227], v[136:137], v[154:155], v[226:227] op_sel_hi:[0,1,1]
	v_pk_fma_f32 v[228:229], v[138:139], v[112:113], v[228:229] op_sel_hi:[0,1,1]
	ds_read_b128 v[110:113], v251 offset:12032
	s_waitcnt lgkmcnt(5)
	v_pk_fma_f32 v[158:159], v[134:135], v[158:159], v[226:227] op_sel_hi:[0,1,1]
	v_pk_fma_f32 v[228:229], v[136:137], v[156:157], v[228:229] op_sel_hi:[0,1,1]
	ds_read_b128 v[154:157], v251 offset:12160
	s_waitcnt lgkmcnt(5)
	v_pk_fma_f32 v[158:159], v[132:133], v[196:197], v[158:159] op_sel_hi:[0,1,1]
	s_waitcnt lgkmcnt(4)
	v_pk_fma_f32 v[158:159], v[130:131], v[222:223], v[158:159] op_sel_hi:[0,1,1]
	s_waitcnt lgkmcnt(3)
	v_pk_fma_f32 v[158:159], v[128:129], v[200:201], v[158:159] op_sel_hi:[0,1,1]
	s_waitcnt lgkmcnt(2)
	v_pk_fma_f32 v[158:159], v[126:127], v[218:219], v[158:159] op_sel_hi:[0,1,1]
	s_waitcnt lgkmcnt(1)
	v_pk_fma_f32 v[110:111], v[0:1], v[110:111], v[158:159] op_sel_hi:[0,1,1]
	s_waitcnt lgkmcnt(0)
	v_pk_fma_f32 v[110:111], v[124:125], v[154:155], v[110:111] op_sel_hi:[0,1,1]
	v_min_f32_e32 v153, 0, v110
	v_mul_f32_e64 v110, |v110|, s97
	v_pk_fma_f32 v[160:161], v[134:135], v[160:161], v[228:229] op_sel_hi:[0,1,1]
	v_exp_f32_e32 v110, v110
	v_pk_fma_f32 v[160:161], v[132:133], v[198:199], v[160:161] op_sel_hi:[0,1,1]
	v_mul_f32_e64 v154, |v111|, s97
	v_pk_fma_f32 v[160:161], v[130:131], v[224:225], v[160:161] op_sel_hi:[0,1,1]
	v_exp_f32_e32 v154, v154
	v_pk_fma_f32 v[160:161], v[128:129], v[202:203], v[160:161] op_sel_hi:[0,1,1]
	v_pk_fma_f32 v[160:161], v[126:127], v[220:221], v[160:161] op_sel_hi:[0,1,1]
	v_add_f32_e32 v110, 1.0, v110
	v_pk_fma_f32 v[112:113], v[0:1], v[112:113], v[160:161] op_sel_hi:[0,1,1]
	v_cmp_gt_f32_e32 vcc, s45, v110
	v_pk_fma_f32 v[112:113], v[124:125], v[156:157], v[112:113] op_sel_hi:[0,1,1]
	v_add_f32_e32 v154, 1.0, v154
	v_cndmask_b32_e64 v156, 0, 32, vcc
	v_mul_f32_e64 v155, |v112|, s97
	v_cmp_gt_f32_e64 s[26:27], s45, v154
	v_ldexp_f32 v110, v110, v156
	v_exp_f32_e32 v155, v155
	v_cndmask_b32_e64 v158, 0, 32, s[26:27]
	v_log_f32_e32 v110, v110
	v_ldexp_f32 v154, v154, v158
	v_log_f32_e32 v154, v154
	v_add_f32_e32 v155, 1.0, v155
	v_mul_f32_e32 v156, 0x3f317217, v110
	v_cmp_gt_f32_e64 s[28:29], s45, v155
	v_fma_f32 v156, v110, s31, -v156
	v_mul_f32_e32 v158, 0x3f317217, v154
	v_cndmask_b32_e64 v160, 0, 32, s[28:29]
	v_fmac_f32_e32 v156, 0x3377d1cf, v110
	v_cndmask_b32_e32 v157, 0, v240, vcc
	v_ldexp_f32 v155, v155, v160
	v_cmp_lt_f32_e64 vcc, |v110|, s44
	v_fma_f32 v158, v154, s31, -v158
	v_fmac_f32_e32 v156, 0x3f317217, v110
	v_log_f32_e32 v155, v155
	v_fmac_f32_e32 v158, 0x3377d1cf, v154
	v_cndmask_b32_e32 v110, v110, v156, vcc
	v_cndmask_b32_e64 v159, 0, v240, s[26:27]
	v_cmp_lt_f32_e64 s[26:27], |v154|, s44
	v_fmac_f32_e32 v158, 0x3f317217, v154
	v_sub_f32_e32 v110, v110, v157
	v_cndmask_b32_e64 v154, v154, v158, s[26:27]
	v_sub_f32_e32 v249, v153, v110
	v_min_f32_e32 v110, 0, v112
	v_mul_f32_e64 v112, |v113|, s97
	v_min_f32_e32 v111, 0, v111
	v_sub_f32_e32 v154, v154, v159
	v_exp_f32_e32 v112, v112
	v_sub_f32_e32 v247, v111, v154
	v_mul_f32_e32 v111, 0x3f317217, v155
	v_fma_f32 v111, v155, s31, -v111
	v_fmac_f32_e32 v111, 0x3377d1cf, v155
	v_fmac_f32_e32 v111, 0x3f317217, v155
	v_cmp_lt_f32_e64 vcc, |v155|, s44
	v_add_f32_e32 v112, 1.0, v112
	v_cndmask_b32_e64 v153, 0, v240, s[28:29]
	v_cndmask_b32_e32 v111, v155, v111, vcc
	v_cmp_gt_f32_e32 vcc, s45, v112
	v_sub_f32_e32 v111, v111, v153
	v_sub_f32_e32 v245, v110, v111
	v_cndmask_b32_e64 v153, 0, 32, vcc
	v_ldexp_f32 v112, v112, v153
	v_log_f32_e32 v112, v112
	v_min_f32_e32 v110, 0, v113
	ds_read_b128 v[154:157], v251 offset:12304
	ds_read_b128 v[158:161], v251 offset:10512
	v_mul_f32_e32 v111, 0x3f317217, v112
	v_fma_f32 v111, v112, s31, -v111
	v_fmac_f32_e32 v111, 0x3377d1cf, v112
	v_fmac_f32_e32 v111, 0x3f317217, v112
	v_cmp_lt_f32_e64 s[26:27], |v112|, s44
	s_waitcnt lgkmcnt(1)
; #define LAS __attribute__((address_space(3)))
; __device__ __forceinline__ void gla_gates(const bf16* prow, const float* wg, const float* bg, int h, int lane, float (&bc)[32], LAS float* Wst) {
;     ...
; #pragma unroll
;     for (int d4 = 0; d4 < 8; ++d4) { f32x4 z = *(const LAS f32x4*)(Wst + 512 + 4 * d4);
; #pragma unroll
;         for (int r = 0; r < 16; ++r) { const f32x4 w = *(const LAS f32x4*)(Wst + r * 32 + 4 * d4); z += w * glr[r]; }
; #pragma unroll
;         for (int e = 0; e < 4; ++e) bc[4 * d4 + e] = (fminf(z[e], 0.f) - __logf(1.f + __expf(-fabsf(z[e])))) * (1.f / 16.f); }
	v_pk_fma_f32 v[154:155], v[152:153], v[106:107], v[154:155] op_sel_hi:[0,1,1]
	v_pk_fma_f32 v[106:107], v[152:153], v[108:109], v[156:157] op_sel_hi:[0,1,1]
	v_cndmask_b32_e64 v111, v112, v111, s[26:27]
	v_cndmask_b32_e32 v112, 0, v240, vcc
	v_sub_f32_e32 v111, v111, v112
	v_sub_f32_e32 v252, v110, v111
	ds_read_b128 v[110:113], v251 offset:10384
	v_mul_f32_e32 v250, 0x3d800000, v249
	v_mul_f32_e32 v248, 0x3d800000, v247
	v_mul_f32_e32 v246, 0x3d800000, v245
	v_mul_f32_e32 v253, 0x3d800000, v252
	s_waitcnt lgkmcnt(0)
	v_pk_fma_f32 v[156:157], v[150:151], v[112:113], v[106:107] op_sel_hi:[0,1,1]
	ds_read_b128 v[106:109], v251 offset:10640
	v_pk_fma_f32 v[110:111], v[150:151], v[110:111], v[154:155] op_sel_hi:[0,1,1]
	v_pk_fma_f32 v[158:159], v[148:149], v[158:159], v[110:111] op_sel_hi:[0,1,1]
	ds_read_b128 v[110:113], v251 offset:10768
	v_pk_fma_f32 v[154:155], v[148:149], v[160:161], v[156:157] op_sel_hi:[0,1,1]
	s_waitcnt lgkmcnt(1)
	v_pk_fma_f32 v[160:161], v[146:147], v[108:109], v[154:155] op_sel_hi:[0,1,1]
	ds_read_b128 v[154:157], v251 offset:10896
	v_pk_fma_f32 v[106:107], v[146:147], v[106:107], v[158:159] op_sel_hi:[0,1,1]
	s_waitcnt lgkmcnt(1)
	v_pk_fma_f32 v[158:159], v[144:145], v[110:111], v[106:107] op_sel_hi:[0,1,1]
	ds_read_b128 v[106:109], v251 offset:11024
	v_pk_fma_f32 v[110:111], v[144:145], v[112:113], v[160:161] op_sel_hi:[0,1,1]
	s_waitcnt lgkmcnt(1)
	v_pk_fma_f32 v[156:157], v[142:143], v[156:157], v[110:111] op_sel_hi:[0,1,1]
	ds_read_b128 v[110:113], v251 offset:11152
	v_pk_fma_f32 v[154:155], v[142:143], v[154:155], v[158:159] op_sel_hi:[0,1,1]
	s_waitcnt lgkmcnt(1)
	v_pk_fma_f32 v[158:159], v[140:141], v[106:107], v[154:155] op_sel_hi:[0,1,1]
	v_pk_fma_f32 v[154:155], v[140:141], v[108:109], v[156:157] op_sel_hi:[0,1,1]
	ds_read_b128 v[106:109], v251 offset:11280
	s_waitcnt lgkmcnt(1)
	v_pk_fma_f32 v[160:161], v[138:139], v[112:113], v[154:155] op_sel_hi:[0,1,1]
	ds_read_b128 v[154:157], v251 offset:11408
	v_pk_fma_f32 v[158:159], v[138:139], v[110:111], v[158:159] op_sel_hi:[0,1,1]
	ds_read_b128 v[110:113], v251 offset:11536
	s_waitcnt lgkmcnt(2)
	v_pk_fma_f32 v[106:107], v[136:137], v[106:107], v[158:159] op_sel_hi:[0,1,1]
	v_pk_fma_f32 v[108:109], v[136:137], v[108:109], v[160:161] op_sel_hi:[0,1,1]
	s_waitcnt lgkmcnt(1)
	v_pk_fma_f32 v[108:109], v[134:135], v[156:157], v[108:109] op_sel_hi:[0,1,1]
	v_pk_fma_f32 v[106:107], v[134:135], v[154:155], v[106:107] op_sel_hi:[0,1,1]
	s_waitcnt lgkmcnt(0)
	v_pk_fma_f32 v[200:201], v[132:133], v[110:111], v[106:107] op_sel_hi:[0,1,1]
	v_pk_fma_f32 v[202:203], v[132:133], v[112:113], v[108:109] op_sel_hi:[0,1,1]
	ds_read_b128 v[106:109], v251 offset:11664
	ds_read_b128 v[110:113], v251 offset:11792
	ds_read_b128 v[154:157], v251 offset:11920
	ds_read_b128 v[158:161], v251 offset:12048
	ds_read_b128 v[196:199], v251 offset:12176
	s_waitcnt lgkmcnt(4)
	v_pk_fma_f32 v[106:107], v[130:131], v[106:107], v[200:201] op_sel_hi:[0,1,1]
	s_waitcnt lgkmcnt(3)
	v_pk_fma_f32 v[106:107], v[128:129], v[110:111], v[106:107] op_sel_hi:[0,1,1]
	s_waitcnt lgkmcnt(2)
	v_pk_fma_f32 v[106:107], v[126:127], v[154:155], v[106:107] op_sel_hi:[0,1,1]
	s_waitcnt lgkmcnt(1)
	v_pk_fma_f32 v[106:107], v[0:1], v[158:159], v[106:107] op_sel_hi:[0,1,1]
	s_waitcnt lgkmcnt(0)
	v_pk_fma_f32 v[106:107], v[124:125], v[196:197], v[106:107] op_sel_hi:[0,1,1]
	v_mul_f32_e64 v110, |v106|, s97
	v_exp_f32_e32 v110, v110
	v_pk_fma_f32 v[108:109], v[130:131], v[108:109], v[202:203] op_sel_hi:[0,1,1]
	v_pk_fma_f32 v[108:109], v[128:129], v[112:113], v[108:109] op_sel_hi:[0,1,1]
	v_pk_fma_f32 v[108:109], v[126:127], v[156:157], v[108:109] op_sel_hi:[0,1,1]
	v_add_f32_e32 v110, 1.0, v110
	v_cmp_gt_f32_e32 vcc, s45, v110
	v_pk_fma_f32 v[108:109], v[0:1], v[160:161], v[108:109] op_sel_hi:[0,1,1]
	v_pk_fma_f32 v[154:155], v[124:125], v[198:199], v[108:109] op_sel_hi:[0,1,1]
	v_cndmask_b32_e64 v111, 0, 32, vcc
	v_ldexp_f32 v110, v110, v111
	v_log_f32_e32 v110, v110
	v_mul_f32_e64 v109, |v107|, s97
	v_exp_f32_e32 v109, v109
	v_min_f32_e32 v106, 0, v106
	v_mul_f32_e32 v108, 0x3f317217, v110
	v_fma_f32 v108, v110, s31, -v108
	v_fmac_f32_e32 v108, 0x3377d1cf, v110
	v_fmac_f32_e32 v108, 0x3f317217, v110
	v_cmp_lt_f32_e64 s[26:27], |v110|, s44
	v_add_f32_e32 v109, 1.0, v109
	v_min_f32_e32 v196, 0, v107
	v_cndmask_b32_e64 v108, v110, v108, s[26:27]
	v_cndmask_b32_e32 v110, 0, v240, vcc
	v_cmp_gt_f32_e32 vcc, s45, v109
	v_sub_f32_e32 v108, v108, v110
	v_sub_f32_e32 v254, v106, v108
	v_cndmask_b32_e64 v110, 0, 32, vcc
	v_ldexp_f32 v109, v109, v110
	v_log_f32_e32 v153, v109
	v_mul_f32_e32 v231, 0x3d800000, v254
	v_mul_f32_e32 v106, 0x3f317217, v153
	v_fma_f32 v160, v153, s31, -v106
	ds_read_b128 v[106:109], v251 offset:12320
	ds_read_b128 v[110:113], v251 offset:12336
	ds_read_b128 v[198:201], v251 offset:12352
	ds_read_b128 v[218:221], v251 offset:10304
	v_fmac_f32_e32 v160, 0x3377d1cf, v153
	v_fmac_f32_e32 v160, 0x3f317217, v153
	s_waitcnt lgkmcnt(2)
	v_pk_fma_f32 v[110:111], v[152:153], v[98:99], v[110:111] op_sel_hi:[0,1,1]
	v_pk_fma_f32 v[156:157], v[152:153], v[102:103], v[106:107] op_sel_hi:[0,1,1]
	v_pk_fma_f32 v[158:159], v[152:153], v[104:105], v[108:109] op_sel_hi:[0,1,1]
	v_pk_fma_f32 v[112:113], v[152:153], v[100:101], v[112:113] op_sel_hi:[0,1,1]
	s_waitcnt lgkmcnt(0)
	v_pk_fma_f32 v[106:107], v[152:153], v[218:219], v[198:199] op_sel_hi:[0,1,1]
	v_pk_fma_f32 v[108:109], v[152:153], v[220:221], v[200:201] op_sel_hi:[0,1,1]
	ds_read_b128 v[98:101], v251 offset:12368
	ds_read_b128 v[102:105], v251 offset:10320
	ds_read_b128 v[198:201], v251 offset:12384
	ds_read_b128 v[218:221], v251 offset:10336
	v_cmp_lt_f32_e64 s[26:27], |v153|, s44
	s_nop 1
	v_cndmask_b32_e64 v153, v153, v160, s[26:27]
	s_waitcnt lgkmcnt(2)
; #define LAS __attribute__((address_space(3)))
; __device__ __forceinline__ void gla_gates(const bf16* prow, const float* wg, const float* bg, int h, int lane, float (&bc)[32], LAS float* Wst) {
;     ...
; #pragma unroll
;     for (int d4 = 0; d4 < 8; ++d4) { f32x4 z = *(const LAS f32x4*)(Wst + 512 + 4 * d4);
; #pragma unroll
;         for (int r = 0; r < 16; ++r) { const f32x4 w = *(const LAS f32x4*)(Wst + r * 32 + 4 * d4); z += w * glr[r]; }
; #pragma unroll
;         for (int e = 0; e < 4; ++e) bc[4 * d4 + e] = (fminf(z[e], 0.f) - __logf(1.f + __expf(-fabsf(z[e])))) * (1.f / 16.f); }
	v_pk_fma_f32 v[102:103], v[152:153], v[102:103], v[98:99] op_sel_hi:[0,1,1]
	v_pk_fma_f32 v[104:105], v[152:153], v[104:105], v[100:101] op_sel_hi:[0,1,1]
	s_waitcnt lgkmcnt(0)
	v_pk_fma_f32 v[98:99], v[152:153], v[218:219], v[198:199] op_sel_hi:[0,1,1]
	v_pk_fma_f32 v[100:101], v[152:153], v[220:221], v[200:201] op_sel_hi:[0,1,1]
	ds_read_b128 v[198:201], v251 offset:12400
	ds_read_b128 v[218:221], v251 offset:10352
	v_cndmask_b32_e32 v160, 0, v240, vcc
	v_sub_f32_e32 v197, v153, v160
	v_mul_f32_e64 v153, |v154|, s97
	v_exp_f32_e32 v202, v153
	s_waitcnt lgkmcnt(0)
	v_pk_fma_f32 v[160:161], v[152:153], v[218:219], v[198:199] op_sel_hi:[0,1,1]
	v_pk_fma_f32 v[152:153], v[152:153], v[220:221], v[200:201] op_sel_hi:[0,1,1]
	ds_read_b128 v[198:201], v251 offset:10400
	ds_read_b128 v[222:225], v251 offset:10528
	v_sub_f32_e32 v220, v196, v197
	v_add_f32_e32 v218, 1.0, v202
	v_cmp_gt_f32_e32 vcc, s45, v218
	s_waitcnt lgkmcnt(1)
	v_pk_fma_f32 v[196:197], v[150:151], v[200:201], v[158:159] op_sel_hi:[0,1,1]
	v_pk_fma_f32 v[198:199], v[150:151], v[198:199], v[156:157] op_sel_hi:[0,1,1]
	ds_read_b128 v[156:159], v251 offset:10656
	s_waitcnt lgkmcnt(1)
	v_pk_fma_f32 v[200:201], v[148:149], v[222:223], v[198:199] op_sel_hi:[0,1,1]
	v_pk_fma_f32 v[202:203], v[148:149], v[224:225], v[196:197] op_sel_hi:[0,1,1]
	ds_read_b128 v[196:199], v251 offset:10784
	v_cndmask_b32_e64 v219, 0, 32, vcc
	s_waitcnt lgkmcnt(1)
	v_pk_fma_f32 v[202:203], v[146:147], v[158:159], v[202:203] op_sel_hi:[0,1,1]
	v_pk_fma_f32 v[200:201], v[146:147], v[156:157], v[200:201] op_sel_hi:[0,1,1]
	ds_read_b128 v[156:159], v251 offset:10912
	s_waitcnt lgkmcnt(1)
	v_pk_fma_f32 v[200:201], v[144:145], v[196:197], v[200:201] op_sel_hi:[0,1,1]
	v_pk_fma_f32 v[202:203], v[144:145], v[198:199], v[202:203] op_sel_hi:[0,1,1]
	ds_read_b128 v[196:199], v251 offset:11040
	v_ldexp_f32 v218, v218, v219
	s_waitcnt lgkmcnt(1)
	v_pk_fma_f32 v[202:203], v[142:143], v[158:159], v[202:203] op_sel_hi:[0,1,1]
	v_pk_fma_f32 v[200:201], v[142:143], v[156:157], v[200:201] op_sel_hi:[0,1,1]
	ds_read_b128 v[156:159], v251 offset:11168
	s_waitcnt lgkmcnt(1)
	v_pk_fma_f32 v[200:201], v[140:141], v[196:197], v[200:201] op_sel_hi:[0,1,1]
	v_pk_fma_f32 v[202:203], v[140:141], v[198:199], v[202:203] op_sel_hi:[0,1,1]
	ds_read_b128 v[196:199], v251 offset:11296
	v_log_f32_e32 v218, v218
	s_waitcnt lgkmcnt(1)
	v_pk_fma_f32 v[202:203], v[138:139], v[158:159], v[202:203] op_sel_hi:[0,1,1]
	v_pk_fma_f32 v[200:201], v[138:139], v[156:157], v[200:201] op_sel_hi:[0,1,1]
	ds_read_b128 v[156:159], v251 offset:11424
	s_waitcnt lgkmcnt(1)
	v_pk_fma_f32 v[200:201], v[136:137], v[196:197], v[200:201] op_sel_hi:[0,1,1]
	v_pk_fma_f32 v[202:203], v[136:137], v[198:199], v[202:203] op_sel_hi:[0,1,1]
	ds_read_b128 v[196:199], v251 offset:11552
	v_cmp_lt_f32_e64 s[26:27], |v218|, s44
	s_waitcnt lgkmcnt(1)
	v_pk_fma_f32 v[158:159], v[134:135], v[158:159], v[202:203] op_sel_hi:[0,1,1]
	v_pk_fma_f32 v[156:157], v[134:135], v[156:157], v[200:201] op_sel_hi:[0,1,1]
	v_mul_f32_e32 v200, 0x3f317217, v218
	s_waitcnt lgkmcnt(0)
	v_pk_fma_f32 v[196:197], v[132:133], v[196:197], v[156:157] op_sel_hi:[0,1,1]
	v_pk_fma_f32 v[198:199], v[132:133], v[198:199], v[158:159] op_sel_hi:[0,1,1]
	ds_read_b128 v[156:159], v251 offset:11680
	v_fma_f32 v200, v218, s31, -v200
	v_fmac_f32_e32 v200, 0x3377d1cf, v218
	v_fmac_f32_e32 v200, 0x3f317217, v218
	v_cndmask_b32_e64 v202, v218, v200, s[26:27]
	s_waitcnt lgkmcnt(0)
	v_pk_fma_f32 v[198:199], v[130:131], v[158:159], v[198:199] op_sel_hi:[0,1,1]
	v_pk_fma_f32 v[196:197], v[130:131], v[156:157], v[196:197] op_sel_hi:[0,1,1]
	ds_read_b128 v[156:159], v251 offset:11808
	v_mul_f32_e64 v200, |v155|, s97
	v_exp_f32_e32 v218, v200
	v_cndmask_b32_e32 v203, 0, v240, vcc
	v_min_f32_e32 v154, 0, v154
	s_waitcnt lgkmcnt(0)
	v_pk_fma_f32 v[156:157], v[128:129], v[156:157], v[196:197] op_sel_hi:[0,1,1]
	v_pk_fma_f32 v[200:201], v[128:129], v[158:159], v[198:199] op_sel_hi:[0,1,1]
	ds_read_b128 v[196:199], v251 offset:11936
	v_sub_f32_e32 v158, v202, v203
	v_sub_f32_e32 v158, v154, v158
	v_add_f32_e32 v154, 1.0, v218
	v_cmp_gt_f32_e32 vcc, s45, v154
	s_waitcnt lgkmcnt(0)
	v_pk_fma_f32 v[200:201], v[126:127], v[198:199], v[200:201] op_sel_hi:[0,1,1]
	v_pk_fma_f32 v[156:157], v[126:127], v[196:197], v[156:157] op_sel_hi:[0,1,1]
	ds_read_b128 v[196:199], v251 offset:12064
	v_cndmask_b32_e64 v202, 0, 32, vcc
	v_ldexp_f32 v154, v154, v202
	v_log_f32_e32 v202, v154
	v_min_f32_e32 v203, 0, v155
	s_waitcnt lgkmcnt(0)
	v_pk_fma_f32 v[156:157], v[0:1], v[196:197], v[156:157] op_sel_hi:[0,1,1]
	v_pk_fma_f32 v[200:201], v[0:1], v[198:199], v[200:201] op_sel_hi:[0,1,1]
	ds_read_b128 v[196:199], v251 offset:12192
	v_mul_f32_e32 v154, 0x3f317217, v202
	v_fma_f32 v218, v202, s31, -v154
	v_fmac_f32_e32 v218, 0x3377d1cf, v202
	v_fmac_f32_e32 v218, 0x3f317217, v202
	s_waitcnt lgkmcnt(0)
	v_pk_fma_f32 v[154:155], v[124:125], v[198:199], v[200:201] op_sel_hi:[0,1,1]
	v_pk_fma_f32 v[156:157], v[124:125], v[196:197], v[156:157] op_sel_hi:[0,1,1]
	ds_read_b128 v[196:199], v251 offset:10416
	v_mul_f32_e64 v200, |v156|, s97
	v_exp_f32_e32 v200, v200
	v_cmp_lt_f32_e64 s[26:27], |v202|, s44
	v_min_f32_e32 v156, 0, v156
	s_waitcnt lgkmcnt(0)
	v_pk_fma_f32 v[198:199], v[150:151], v[198:199], v[112:113] op_sel_hi:[0,1,1]
	v_pk_fma_f32 v[196:197], v[150:151], v[196:197], v[110:111] op_sel_hi:[0,1,1]
	ds_read_b128 v[110:113], v251 offset:10544
	v_add_f32_e32 v200, 1.0, v200
	v_cndmask_b32_e64 v201, v202, v218, s[26:27]
	v_cndmask_b32_e32 v202, 0, v240, vcc
	v_cmp_gt_f32_e32 vcc, s45, v200
	s_waitcnt lgkmcnt(0)
; #define LAS __attribute__((address_space(3)))
; __device__ __forceinline__ void gla_gates(const bf16* prow, const float* wg, const float* bg, int h, int lane, float (&bc)[32], LAS float* Wst) {
;     ...
; #pragma unroll
;     for (int d4 = 0; d4 < 8; ++d4) { f32x4 z = *(const LAS f32x4*)(Wst + 512 + 4 * d4);
; #pragma unroll
;         for (int r = 0; r < 16; ++r) { const f32x4 w = *(const LAS f32x4*)(Wst + r * 32 + 4 * d4); z += w * glr[r]; }
; #pragma unroll
;         for (int e = 0; e < 4; ++e) bc[4 * d4 + e] = (fminf(z[e], 0.f) - __logf(1.f + __expf(-fabsf(z[e])))) * (1.f / 16.f); }
	v_pk_fma_f32 v[196:197], v[148:149], v[110:111], v[196:197] op_sel_hi:[0,1,1]
	v_pk_fma_f32 v[198:199], v[148:149], v[112:113], v[198:199] op_sel_hi:[0,1,1]
	ds_read_b128 v[110:113], v251 offset:10672
	v_sub_f32_e32 v201, v201, v202
	v_cndmask_b32_e64 v202, 0, 32, vcc
	v_ldexp_f32 v200, v200, v202
	v_log_f32_e32 v200, v200
	s_waitcnt lgkmcnt(0)
	v_pk_fma_f32 v[198:199], v[146:147], v[112:113], v[198:199] op_sel_hi:[0,1,1]
	v_pk_fma_f32 v[196:197], v[146:147], v[110:111], v[196:197] op_sel_hi:[0,1,1]
	ds_read_b128 v[110:113], v251 offset:10800
	v_sub_f32_e32 v223, v203, v201
	v_mul_f32_e32 v201, 0x3f317217, v200
	v_fma_f32 v201, v200, s31, -v201
	v_fmac_f32_e32 v201, 0x3377d1cf, v200
	s_waitcnt lgkmcnt(0)
	v_pk_fma_f32 v[196:197], v[144:145], v[110:111], v[196:197] op_sel_hi:[0,1,1]
	v_pk_fma_f32 v[198:199], v[144:145], v[112:113], v[198:199] op_sel_hi:[0,1,1]
	ds_read_b128 v[110:113], v251 offset:10928
	v_fmac_f32_e32 v201, 0x3f317217, v200
	v_cmp_lt_f32_e64 s[26:27], |v200|, s44
	v_mul_f32_e32 v222, 0x3d800000, v220
	v_mul_f32_e32 v159, 0x3d800000, v158
	s_waitcnt lgkmcnt(0)
	v_pk_fma_f32 v[198:199], v[142:143], v[112:113], v[198:199] op_sel_hi:[0,1,1]
	v_pk_fma_f32 v[196:197], v[142:143], v[110:111], v[196:197] op_sel_hi:[0,1,1]
	ds_read_b128 v[110:113], v251 offset:11056
	v_cndmask_b32_e64 v200, v200, v201, s[26:27]
	v_cndmask_b32_e32 v201, 0, v240, vcc
	v_sub_f32_e32 v200, v200, v201
	v_mul_f32_e64 v201, |v157|, s97
	s_waitcnt lgkmcnt(0)
	v_pk_fma_f32 v[196:197], v[140:141], v[110:111], v[196:197] op_sel_hi:[0,1,1]
	v_pk_fma_f32 v[198:199], v[140:141], v[112:113], v[198:199] op_sel_hi:[0,1,1]
	ds_read_b128 v[110:113], v251 offset:11184
	v_exp_f32_e32 v201, v201
	v_sub_f32_e32 v156, v156, v200
	v_min_f32_e32 v157, 0, v157
	v_mul_f32_e32 v232, 0x3d800000, v223
	s_waitcnt lgkmcnt(0)
	v_pk_fma_f32 v[198:199], v[138:139], v[112:113], v[198:199] op_sel_hi:[0,1,1]
	v_pk_fma_f32 v[196:197], v[138:139], v[110:111], v[196:197] op_sel_hi:[0,1,1]
	ds_read_b128 v[110:113], v251 offset:11312
	v_add_f32_e32 v200, 1.0, v201
	v_cmp_gt_f32_e32 vcc, s45, v200
	v_mul_f32_e32 v236, 0x3d800000, v156
	s_waitcnt lgkmcnt(0)
	v_pk_fma_f32 v[196:197], v[136:137], v[110:111], v[196:197] op_sel_hi:[0,1,1]
	v_pk_fma_f32 v[198:199], v[136:137], v[112:113], v[198:199] op_sel_hi:[0,1,1]
	ds_read_b128 v[110:113], v251 offset:11440
	v_cndmask_b32_e64 v201, 0, 32, vcc
	v_ldexp_f32 v200, v200, v201
	v_log_f32_e32 v200, v200
	v_cndmask_b32_e32 v202, 0, v240, vcc
	s_waitcnt lgkmcnt(0)
	v_pk_fma_f32 v[198:199], v[134:135], v[112:113], v[198:199] op_sel_hi:[0,1,1]
	v_pk_fma_f32 v[196:197], v[134:135], v[110:111], v[196:197] op_sel_hi:[0,1,1]
	ds_read_b128 v[110:113], v251 offset:11568
	v_mul_f32_e32 v201, 0x3f317217, v200
	v_fma_f32 v201, v200, s31, -v201
	v_fmac_f32_e32 v201, 0x3377d1cf, v200
	v_fmac_f32_e32 v201, 0x3f317217, v200
	s_waitcnt lgkmcnt(0)
	v_pk_fma_f32 v[196:197], v[132:133], v[110:111], v[196:197] op_sel_hi:[0,1,1]
	v_pk_fma_f32 v[198:199], v[132:133], v[112:113], v[198:199] op_sel_hi:[0,1,1]
	ds_read_b128 v[110:113], v251 offset:11696
	v_cmp_lt_f32_e64 s[26:27], |v200|, s44
	s_waitcnt lgkmcnt(0)
	v_pk_fma_f32 v[198:199], v[130:131], v[112:113], v[198:199] op_sel_hi:[0,1,1]
	v_cndmask_b32_e64 v200, v200, v201, s[26:27]
	v_mul_f32_e64 v201, |v154|, s97
	v_exp_f32_e32 v201, v201
	v_pk_fma_f32 v[196:197], v[130:131], v[110:111], v[196:197] op_sel_hi:[0,1,1]
	ds_read_b128 v[110:113], v251 offset:11824
	v_sub_f32_e32 v200, v200, v202
	v_sub_f32_e32 v157, v157, v200
	v_add_f32_e32 v200, 1.0, v201
	v_cmp_gt_f32_e32 vcc, s45, v200
	s_waitcnt lgkmcnt(0)
	v_pk_fma_f32 v[196:197], v[128:129], v[110:111], v[196:197] op_sel_hi:[0,1,1]
	v_pk_fma_f32 v[198:199], v[128:129], v[112:113], v[198:199] op_sel_hi:[0,1,1]
	v_cndmask_b32_e64 v201, 0, 32, vcc
	v_ldexp_f32 v200, v200, v201
	ds_read_b128 v[110:113], v251 offset:11952
	v_log_f32_e32 v200, v200
	v_min_f32_e32 v154, 0, v154
	v_mul_f32_e32 v235, 0x3d800000, v157
	v_mul_f32_e32 v201, 0x3f317217, v200
	s_waitcnt lgkmcnt(0)
	v_pk_fma_f32 v[198:199], v[126:127], v[112:113], v[198:199] op_sel_hi:[0,1,1]
	v_pk_fma_f32 v[196:197], v[126:127], v[110:111], v[196:197] op_sel_hi:[0,1,1]
	ds_read_b128 v[110:113], v251 offset:12080
	v_fma_f32 v201, v200, s31, -v201
	v_fmac_f32_e32 v201, 0x3377d1cf, v200
	v_fmac_f32_e32 v201, 0x3f317217, v200
	v_cmp_lt_f32_e64 s[26:27], |v200|, s44
	s_nop 1
	v_cndmask_b32_e64 v202, v200, v201, s[26:27]
	v_mul_f32_e64 v200, |v155|, s97
	v_exp_f32_e32 v203, v200
	s_waitcnt lgkmcnt(0)
	v_pk_fma_f32 v[200:201], v[0:1], v[110:111], v[196:197] op_sel_hi:[0,1,1]
	v_pk_fma_f32 v[110:111], v[0:1], v[112:113], v[198:199] op_sel_hi:[0,1,1]
	ds_read_b128 v[196:199], v251 offset:12208
	v_cndmask_b32_e32 v112, 0, v240, vcc
	v_sub_f32_e32 v202, v202, v112
	v_add_f32_e32 v203, 1.0, v203
	v_cmp_gt_f32_e32 vcc, s45, v203
	s_waitcnt lgkmcnt(0)
	v_pk_fma_f32 v[110:111], v[124:125], v[198:199], v[110:111] op_sel_hi:[0,1,1]
	v_pk_fma_f32 v[112:113], v[124:125], v[196:197], v[200:201] op_sel_hi:[0,1,1]
	ds_read_b128 v[196:199], v251 offset:10432
	v_cndmask_b32_e64 v200, 0, 32, vcc
	v_ldexp_f32 v200, v203, v200
	v_log_f32_e32 v200, v200
	v_sub_f32_e32 v234, v154, v202
	s_waitcnt lgkmcnt(0)
	v_pk_fma_f32 v[198:199], v[150:151], v[198:199], v[108:109] op_sel_hi:[0,1,1]
	v_pk_fma_f32 v[196:197], v[150:151], v[196:197], v[106:107] op_sel_hi:[0,1,1]
	ds_read_b128 v[106:109], v251 offset:10560
	v_mul_f32_e32 v154, 0x3f317217, v200
	v_min_f32_e32 v201, 0, v155
	v_fma_f32 v202, v200, s31, -v154
	v_fmac_f32_e32 v202, 0x3377d1cf, v200
	s_waitcnt lgkmcnt(0)
; #define LAS __attribute__((address_space(3)))
; __device__ __forceinline__ void gla_gates(const bf16* prow, const float* wg, const float* bg, int h, int lane, float (&bc)[32], LAS float* Wst) {
;     ...
; #pragma unroll
;     for (int d4 = 0; d4 < 8; ++d4) { f32x4 z = *(const LAS f32x4*)(Wst + 512 + 4 * d4);
; #pragma unroll
;         for (int r = 0; r < 16; ++r) { const f32x4 w = *(const LAS f32x4*)(Wst + r * 32 + 4 * d4); z += w * glr[r]; }
; #pragma unroll
;         for (int e = 0; e < 4; ++e) bc[4 * d4 + e] = (fminf(z[e], 0.f) - __logf(1.f + __expf(-fabsf(z[e])))) * (1.f / 16.f); }
	v_pk_fma_f32 v[154:155], v[148:149], v[106:107], v[196:197] op_sel_hi:[0,1,1]
	v_pk_fma_f32 v[196:197], v[148:149], v[108:109], v[198:199] op_sel_hi:[0,1,1]
	ds_read_b128 v[106:109], v251 offset:10688
	v_mul_f32_e64 v198, |v112|, s97
	v_exp_f32_e32 v198, v198
	v_fmac_f32_e32 v202, 0x3f317217, v200
	v_cmp_lt_f32_e64 s[26:27], |v200|, s44
	s_waitcnt lgkmcnt(0)
	v_pk_fma_f32 v[196:197], v[146:147], v[108:109], v[196:197] op_sel_hi:[0,1,1]
	v_pk_fma_f32 v[154:155], v[146:147], v[106:107], v[154:155] op_sel_hi:[0,1,1]
	ds_read_b128 v[106:109], v251 offset:10816
	v_add_f32_e32 v198, 1.0, v198
	v_cndmask_b32_e64 v200, v200, v202, s[26:27]
	v_cmp_gt_f32_e64 s[26:27], s45, v198
	v_cndmask_b32_e32 v202, 0, v240, vcc
	s_waitcnt lgkmcnt(0)
	v_pk_fma_f32 v[154:155], v[144:145], v[106:107], v[154:155] op_sel_hi:[0,1,1]
	v_pk_fma_f32 v[196:197], v[144:145], v[108:109], v[196:197] op_sel_hi:[0,1,1]
	ds_read_b128 v[106:109], v251 offset:10944
	v_cndmask_b32_e64 v199, 0, 32, s[26:27]
	v_ldexp_f32 v198, v198, v199
	v_log_f32_e32 v203, v198
	v_min_f32_e32 v112, 0, v112
	s_waitcnt lgkmcnt(0)
	v_pk_fma_f32 v[196:197], v[142:143], v[108:109], v[196:197] op_sel_hi:[0,1,1]
	v_pk_fma_f32 v[198:199], v[142:143], v[106:107], v[154:155] op_sel_hi:[0,1,1]
	ds_read_b128 v[106:109], v251 offset:11072
	v_sub_f32_e32 v154, v200, v202
	v_sub_f32_e32 v155, v201, v154
	v_mul_f32_e32 v154, 0x3f317217, v203
	v_fma_f32 v154, v203, s31, -v154
	s_waitcnt lgkmcnt(0)
	v_pk_fma_f32 v[198:199], v[140:141], v[106:107], v[198:199] op_sel_hi:[0,1,1]
	v_pk_fma_f32 v[196:197], v[140:141], v[108:109], v[196:197] op_sel_hi:[0,1,1]
	ds_read_b128 v[106:109], v251 offset:11200
	v_fmac_f32_e32 v154, 0x3377d1cf, v203
	v_fmac_f32_e32 v154, 0x3f317217, v203
	v_cmp_lt_f32_e64 vcc, |v203|, s44
	v_cndmask_b32_e64 v200, 0, v240, s[26:27]
	s_waitcnt lgkmcnt(0)
	v_pk_fma_f32 v[196:197], v[138:139], v[108:109], v[196:197] op_sel_hi:[0,1,1]
	v_pk_fma_f32 v[198:199], v[138:139], v[106:107], v[198:199] op_sel_hi:[0,1,1]
	ds_read_b128 v[106:109], v251 offset:11328
	v_cndmask_b32_e32 v154, v203, v154, vcc
	v_sub_f32_e32 v154, v154, v200
	v_mul_f32_e64 v200, |v113|, s97
	v_exp_f32_e32 v200, v200
	s_waitcnt lgkmcnt(0)
	v_pk_fma_f32 v[198:199], v[136:137], v[106:107], v[198:199] op_sel_hi:[0,1,1]
	v_pk_fma_f32 v[196:197], v[136:137], v[108:109], v[196:197] op_sel_hi:[0,1,1]
	ds_read_b128 v[106:109], v251 offset:11456
	v_sub_f32_e32 v154, v112, v154
	v_add_f32_e32 v112, 1.0, v200
	v_cmp_gt_f32_e32 vcc, s45, v112
	v_min_f32_e32 v221, 0, v113
	s_waitcnt lgkmcnt(0)
	v_pk_fma_f32 v[196:197], v[134:135], v[108:109], v[196:197] op_sel_hi:[0,1,1]
	v_pk_fma_f32 v[198:199], v[134:135], v[106:107], v[198:199] op_sel_hi:[0,1,1]
	ds_read_b128 v[106:109], v251 offset:10448
	v_cndmask_b32_e64 v200, 0, 32, vcc
	v_ldexp_f32 v112, v112, v200
	v_log_f32_e32 v112, v112
	v_mul_f32_e32 v237, 0x3d800000, v154
	s_waitcnt lgkmcnt(0)
	v_pk_fma_f32 v[108:109], v[150:151], v[108:109], v[104:105] op_sel_hi:[0,1,1]
	v_pk_fma_f32 v[106:107], v[150:151], v[106:107], v[102:103] op_sel_hi:[0,1,1]
	ds_read_b128 v[102:105], v251 offset:10464
	v_mul_f32_e32 v113, 0x3f317217, v112
	v_fma_f32 v113, v112, s31, -v113
	v_fmac_f32_e32 v113, 0x3377d1cf, v112
	v_fmac_f32_e32 v113, 0x3f317217, v112
	s_waitcnt lgkmcnt(0)
	v_pk_fma_f32 v[104:105], v[150:151], v[104:105], v[100:101] op_sel_hi:[0,1,1]
	v_pk_fma_f32 v[102:103], v[150:151], v[102:103], v[98:99] op_sel_hi:[0,1,1]
	ds_read_b128 v[98:101], v251 offset:10480
	v_cmp_lt_f32_e64 s[26:27], |v112|, s44
	s_waitcnt lgkmcnt(0)
	v_pk_fma_f32 v[200:201], v[150:151], v[98:99], v[160:161] op_sel_hi:[0,1,1]
	v_cndmask_b32_e64 v202, v112, v113, s[26:27]
	v_pk_fma_f32 v[112:113], v[150:151], v[100:101], v[152:153] op_sel_hi:[0,1,1]
	ds_read_b128 v[98:101], v251 offset:10576
	v_cndmask_b32_e32 v150, 0, v240, vcc
	v_sub_f32_e32 v150, v202, v150
	v_mul_f32_e64 v152, |v110|, s97
	v_exp_f32_e32 v152, v152
	s_waitcnt lgkmcnt(0)
	v_pk_fma_f32 v[202:203], v[148:149], v[98:99], v[106:107] op_sel_hi:[0,1,1]
	v_pk_fma_f32 v[218:219], v[148:149], v[100:101], v[108:109] op_sel_hi:[0,1,1]
	ds_read_b128 v[98:101], v251 offset:10592
	v_add_f32_e32 v106, 1.0, v152
	v_cmp_gt_f32_e32 vcc, s45, v106
	v_min_f32_e32 v110, 0, v110
	v_sub_f32_e32 v150, v221, v150
	s_waitcnt lgkmcnt(0)
	v_pk_fma_f32 v[224:225], v[148:149], v[98:99], v[102:103] op_sel_hi:[0,1,1]
	v_pk_fma_f32 v[102:103], v[148:149], v[100:101], v[104:105] op_sel_hi:[0,1,1]
	ds_read_b128 v[98:101], v251 offset:10608
	v_cndmask_b32_e64 v104, 0, 32, vcc
	v_ldexp_f32 v104, v106, v104
	v_log_f32_e32 v108, v104
	v_mul_f32_e32 v160, 0x3d800000, v234
	s_waitcnt lgkmcnt(0)
	v_pk_fma_f32 v[200:201], v[148:149], v[98:99], v[200:201] op_sel_hi:[0,1,1]
	v_pk_fma_f32 v[226:227], v[148:149], v[100:101], v[112:113] op_sel_hi:[0,1,1]
	ds_read_b128 v[98:101], v251 offset:11584
	v_mul_f32_e32 v104, 0x3f317217, v108
	v_fma_f32 v109, v108, s31, -v104
	v_fmac_f32_e32 v109, 0x3377d1cf, v108
	v_fmac_f32_e32 v109, 0x3f317217, v108
	s_waitcnt lgkmcnt(0)
	v_pk_fma_f32 v[104:105], v[132:133], v[98:99], v[198:199] op_sel_hi:[0,1,1]
	v_pk_fma_f32 v[106:107], v[132:133], v[100:101], v[196:197] op_sel_hi:[0,1,1]
	ds_read_b128 v[98:101], v251 offset:11712
	v_cmp_lt_f32_e64 s[26:27], |v108|, s44
	v_cndmask_b32_e32 v112, 0, v240, vcc
	v_mul_f32_e32 v152, 0x3d800000, v155
	v_cndmask_b32_e64 v108, v108, v109, s[26:27]
	s_waitcnt lgkmcnt(0)
	v_pk_fma_f32 v[106:107], v[130:131], v[100:101], v[106:107] op_sel_hi:[0,1,1]
	v_pk_fma_f32 v[104:105], v[130:131], v[98:99], v[104:105] op_sel_hi:[0,1,1]
	ds_read_b128 v[98:101], v251 offset:11840
	v_mul_f32_e64 v109, |v111|, s97
	v_exp_f32_e32 v109, v109
	v_sub_f32_e32 v108, v108, v112
	v_sub_f32_e32 v148, v110, v108
	s_waitcnt lgkmcnt(0)
; #define LAS __attribute__((address_space(3)))
; __device__ __forceinline__ void gla_gates(const bf16* prow, const float* wg, const float* bg, int h, int lane, float (&bc)[32], LAS float* Wst) {
;     ...
; #pragma unroll
;     for (int d4 = 0; d4 < 8; ++d4) { f32x4 z = *(const LAS f32x4*)(Wst + 512 + 4 * d4);
; #pragma unroll
;         for (int r = 0; r < 16; ++r) { const f32x4 w = *(const LAS f32x4*)(Wst + r * 32 + 4 * d4); z += w * glr[r]; }
; #pragma unroll
;         for (int e = 0; e < 4; ++e) bc[4 * d4 + e] = (fminf(z[e], 0.f) - __logf(1.f + __expf(-fabsf(z[e])))) * (1.f / 16.f); }
	v_pk_fma_f32 v[104:105], v[128:129], v[98:99], v[104:105] op_sel_hi:[0,1,1]
	v_pk_fma_f32 v[106:107], v[128:129], v[100:101], v[106:107] op_sel_hi:[0,1,1]
	ds_read_b128 v[98:101], v251 offset:11968
	v_add_f32_e32 v109, 1.0, v109
	v_cmp_gt_f32_e32 vcc, s45, v109
	v_min_f32_e32 v110, 0, v111
	s_waitcnt lgkmcnt(0)
	v_pk_fma_f32 v[106:107], v[126:127], v[100:101], v[106:107] op_sel_hi:[0,1,1]
	v_cndmask_b32_e64 v112, 0, 32, vcc
	v_pk_fma_f32 v[104:105], v[126:127], v[98:99], v[104:105] op_sel_hi:[0,1,1]
	ds_read_b128 v[98:101], v251 offset:12096
	v_ldexp_f32 v109, v109, v112
	v_log_f32_e32 v109, v109
	s_waitcnt lgkmcnt(0)
	v_pk_fma_f32 v[104:105], v[0:1], v[98:99], v[104:105] op_sel_hi:[0,1,1]
	v_pk_fma_f32 v[106:107], v[0:1], v[100:101], v[106:107] op_sel_hi:[0,1,1]
	ds_read_b128 v[98:101], v251 offset:12224
	v_mul_f32_e32 v108, 0x3f317217, v109
	v_fma_f32 v108, v109, s31, -v108
	v_fmac_f32_e32 v108, 0x3377d1cf, v109
	v_fmac_f32_e32 v108, 0x3f317217, v109
	v_cmp_lt_f32_e64 s[26:27], |v109|, s44
	s_waitcnt lgkmcnt(0)
	v_pk_fma_f32 v[106:107], v[124:125], v[100:101], v[106:107] op_sel_hi:[0,1,1]
	v_cndmask_b32_e64 v111, v109, v108, s[26:27]
	v_pk_fma_f32 v[108:109], v[124:125], v[98:99], v[104:105] op_sel_hi:[0,1,1]
	v_mul_f32_e64 v98, |v108|, s97
	v_exp_f32_e32 v98, v98
	v_cndmask_b32_e32 v99, 0, v240, vcc
	v_sub_f32_e32 v104, v111, v99
	v_sub_f32_e32 v153, v110, v104
	v_add_f32_e32 v105, 1.0, v98
	ds_read_b128 v[98:101], v251 offset:10704
	v_cmp_gt_f32_e32 vcc, s45, v105
	v_min_f32_e32 v108, 0, v108
	v_mul_f32_e32 v229, 0x3d800000, v153
	v_cndmask_b32_e64 v111, 0, 32, vcc
	v_ldexp_f32 v105, v105, v111
	ds_read_b128 v[110:113], v251 offset:10736
	s_waitcnt lgkmcnt(1)
	v_pk_fma_f32 v[196:197], v[146:147], v[100:101], v[218:219] op_sel_hi:[0,1,1]
	v_pk_fma_f32 v[198:199], v[146:147], v[98:99], v[202:203] op_sel_hi:[0,1,1]
	ds_read_b128 v[98:101], v251 offset:10720
	v_log_f32_e32 v161, v105
	s_waitcnt lgkmcnt(0)
	v_pk_fma_f32 v[102:103], v[146:147], v[100:101], v[102:103] op_sel_hi:[0,1,1]
	v_mul_f32_e32 v104, 0x3f317217, v161
	v_pk_fma_f32 v[100:101], v[146:147], v[110:111], v[200:201] op_sel_hi:[0,1,1]
	v_mul_f32_e64 v110, |v109|, s97
	v_fma_f32 v202, v161, s31, -v104
	v_pk_fma_f32 v[104:105], v[146:147], v[98:99], v[224:225] op_sel_hi:[0,1,1]
	v_pk_fma_f32 v[98:99], v[146:147], v[112:113], v[226:227] op_sel_hi:[0,1,1]
	v_exp_f32_e32 v200, v110
	ds_read_b128 v[110:113], v251 offset:10832
	v_fmac_f32_e32 v202, 0x3377d1cf, v161
	v_fmac_f32_e32 v202, 0x3f317217, v161
	v_cmp_lt_f32_e64 s[26:27], |v161|, s44
	v_cndmask_b32_e32 v146, 0, v240, vcc
	s_waitcnt lgkmcnt(0)
	v_pk_fma_f32 v[198:199], v[144:145], v[110:111], v[198:199] op_sel_hi:[0,1,1]
	v_cndmask_b32_e64 v202, v161, v202, s[26:27]
	v_sub_f32_e32 v146, v202, v146
	v_pk_fma_f32 v[196:197], v[144:145], v[112:113], v[196:197] op_sel_hi:[0,1,1]
	ds_read_b128 v[110:113], v251 offset:10960
	v_sub_f32_e32 v146, v108, v146
	v_add_f32_e32 v108, 1.0, v200
	v_cmp_gt_f32_e32 vcc, s45, v108
	v_min_f32_e32 v201, 0, v109
	s_waitcnt lgkmcnt(0)
	v_pk_fma_f32 v[196:197], v[142:143], v[112:113], v[196:197] op_sel_hi:[0,1,1]
	v_cndmask_b32_e64 v200, 0, 32, vcc
	v_ldexp_f32 v108, v108, v200
	v_log_f32_e32 v200, v108
	v_pk_fma_f32 v[198:199], v[142:143], v[110:111], v[198:199] op_sel_hi:[0,1,1]
	ds_read_b128 v[110:113], v251 offset:11088
	v_mul_f32_e32 v161, 0x3d800000, v150
	v_mul_f32_e32 v108, 0x3f317217, v200
	v_fma_f32 v202, v200, s31, -v108
	v_fmac_f32_e32 v202, 0x3377d1cf, v200
	s_waitcnt lgkmcnt(0)
	v_pk_fma_f32 v[198:199], v[140:141], v[110:111], v[198:199] op_sel_hi:[0,1,1]
	ds_read_b128 v[108:111], v251 offset:11216
	v_pk_fma_f32 v[112:113], v[140:141], v[112:113], v[196:197] op_sel_hi:[0,1,1]
	v_mul_f32_e64 v196, |v106|, s97
	v_exp_f32_e32 v203, v196
	v_fmac_f32_e32 v202, 0x3f317217, v200
	s_waitcnt lgkmcnt(0)
	v_pk_fma_f32 v[112:113], v[138:139], v[110:111], v[112:113] op_sel_hi:[0,1,1]
	v_pk_fma_f32 v[196:197], v[138:139], v[108:109], v[198:199] op_sel_hi:[0,1,1]
	ds_read_b128 v[108:111], v251 offset:11344
	v_cmp_lt_f32_e64 s[26:27], |v200|, s44
	v_cndmask_b32_e32 v199, 0, v240, vcc
	v_min_f32_e32 v106, 0, v106
	v_cndmask_b32_e64 v198, v200, v202, s[26:27]
	s_waitcnt lgkmcnt(0)
	v_pk_fma_f32 v[196:197], v[136:137], v[108:109], v[196:197] op_sel_hi:[0,1,1]
	v_pk_fma_f32 v[112:113], v[136:137], v[110:111], v[112:113] op_sel_hi:[0,1,1]
	ds_read_b128 v[108:111], v251 offset:11472
	v_sub_f32_e32 v198, v198, v199
	v_add_f32_e32 v199, 1.0, v203
	v_cmp_gt_f32_e32 vcc, s45, v199
	v_sub_f32_e32 v238, v201, v198
	s_waitcnt lgkmcnt(0)
	v_pk_fma_f32 v[112:113], v[134:135], v[110:111], v[112:113] op_sel_hi:[0,1,1]
	v_pk_fma_f32 v[196:197], v[134:135], v[108:109], v[196:197] op_sel_hi:[0,1,1]
	ds_read_b128 v[108:111], v251 offset:11600
	v_cndmask_b32_e64 v200, 0, 32, vcc
	v_ldexp_f32 v199, v199, v200
	v_log_f32_e32 v199, v199
	v_mul_f32_e64 v200, |v107|, s97
	s_waitcnt lgkmcnt(0)
	v_pk_fma_f32 v[196:197], v[132:133], v[108:109], v[196:197] op_sel_hi:[0,1,1]
	v_pk_fma_f32 v[112:113], v[132:133], v[110:111], v[112:113] op_sel_hi:[0,1,1]
	ds_read_b128 v[108:111], v251 offset:11728
	v_mul_f32_e32 v198, 0x3f317217, v199
	v_fma_f32 v198, v199, s31, -v198
	v_fmac_f32_e32 v198, 0x3377d1cf, v199
	v_exp_f32_e32 v200, v200
	s_waitcnt lgkmcnt(0)
	v_pk_fma_f32 v[112:113], v[130:131], v[110:111], v[112:113] op_sel_hi:[0,1,1]
	v_pk_fma_f32 v[196:197], v[130:131], v[108:109], v[196:197] op_sel_hi:[0,1,1]
	ds_read_b128 v[108:111], v251 offset:11856
	v_fmac_f32_e32 v198, 0x3f317217, v199
	v_cmp_lt_f32_e64 s[26:27], |v199|, s44
	v_mul_f32_e32 v224, 0x3d800000, v148
	v_mul_f32_e32 v225, 0x3d800000, v146
	s_waitcnt lgkmcnt(0)
; #define LAS __attribute__((address_space(3)))
; __device__ __forceinline__ void gla_gates(const bf16* prow, const float* wg, const float* bg, int h, int lane, float (&bc)[32], LAS float* Wst) {
;     ...
; #pragma unroll
;     for (int d4 = 0; d4 < 8; ++d4) { f32x4 z = *(const LAS f32x4*)(Wst + 512 + 4 * d4);
; #pragma unroll
;         for (int r = 0; r < 16; ++r) { const f32x4 w = *(const LAS f32x4*)(Wst + r * 32 + 4 * d4); z += w * glr[r]; }
; #pragma unroll
;         for (int e = 0; e < 4; ++e) bc[4 * d4 + e] = (fminf(z[e], 0.f) - __logf(1.f + __expf(-fabsf(z[e])))) * (1.f / 16.f); }
	v_pk_fma_f32 v[196:197], v[128:129], v[108:109], v[196:197] op_sel_hi:[0,1,1]
	v_pk_fma_f32 v[112:113], v[128:129], v[110:111], v[112:113] op_sel_hi:[0,1,1]
	ds_read_b128 v[108:111], v251 offset:11984
	v_cndmask_b32_e64 v198, v199, v198, s[26:27]
	v_cndmask_b32_e32 v199, 0, v240, vcc
	v_sub_f32_e32 v198, v198, v199
	v_add_f32_e32 v199, 1.0, v200
	s_waitcnt lgkmcnt(0)
	v_pk_fma_f32 v[112:113], v[126:127], v[110:111], v[112:113] op_sel_hi:[0,1,1]
	v_pk_fma_f32 v[196:197], v[126:127], v[108:109], v[196:197] op_sel_hi:[0,1,1]
	ds_read_b128 v[108:111], v251 offset:12112
	v_sub_f32_e32 v219, v106, v198
	v_min_f32_e32 v198, 0, v107
	v_cmp_gt_f32_e32 vcc, s45, v199
	v_mul_f32_e32 v228, 0x3d800000, v238
	s_waitcnt lgkmcnt(0)
	v_pk_fma_f32 v[106:107], v[0:1], v[108:109], v[196:197] op_sel_hi:[0,1,1]
	v_pk_fma_f32 v[196:197], v[0:1], v[110:111], v[112:113] op_sel_hi:[0,1,1]
	ds_read_b128 v[110:113], v251 offset:12240
	v_cndmask_b32_e64 v200, 0, 32, vcc
	v_ldexp_f32 v199, v199, v200
	v_log_f32_e32 v199, v199
	v_mul_f32_e32 v227, 0x3d800000, v219
	s_waitcnt lgkmcnt(0)
	v_pk_fma_f32 v[108:109], v[124:125], v[110:111], v[106:107] op_sel_hi:[0,1,1]
	v_mul_f32_e64 v106, |v108|, s97
	v_exp_f32_e32 v106, v106
	v_mul_f32_e32 v200, 0x3f317217, v199
	v_fma_f32 v200, v199, s31, -v200
	v_fmac_f32_e32 v200, 0x3377d1cf, v199
	v_fmac_f32_e32 v200, 0x3f317217, v199
	v_cmp_lt_f32_e64 s[26:27], |v199|, s44
	v_add_f32_e32 v106, 1.0, v106
	v_cndmask_b32_e32 v110, 0, v240, vcc
	v_cndmask_b32_e64 v107, v199, v200, s[26:27]
	v_cmp_gt_f32_e32 vcc, s45, v106
	v_sub_f32_e32 v107, v107, v110
	v_sub_f32_e32 v218, v198, v107
	v_cndmask_b32_e64 v110, 0, 32, vcc
	v_ldexp_f32 v106, v106, v110
	v_log_f32_e32 v110, v106
	v_pk_fma_f32 v[106:107], v[124:125], v[112:113], v[196:197] op_sel_hi:[0,1,1]
	ds_read_b128 v[196:199], v251 offset:10848
	v_min_f32_e32 v108, 0, v108
	v_mul_f32_e32 v111, 0x3f317217, v110
	v_fma_f32 v111, v110, s31, -v111
	v_fmac_f32_e32 v111, 0x3377d1cf, v110
	s_waitcnt lgkmcnt(0)
	v_pk_fma_f32 v[112:113], v[144:145], v[196:197], v[104:105] op_sel_hi:[0,1,1]
	v_pk_fma_f32 v[196:197], v[144:145], v[198:199], v[102:103] op_sel_hi:[0,1,1]
	ds_read_b128 v[102:105], v251 offset:10864
	v_fmac_f32_e32 v111, 0x3f317217, v110
	v_cmp_lt_f32_e64 s[26:27], |v110|, s44
	s_waitcnt lgkmcnt(0)
	v_pk_fma_f32 v[104:105], v[144:145], v[104:105], v[98:99] op_sel_hi:[0,1,1]
	v_cndmask_b32_e64 v110, v110, v111, s[26:27]
	v_cndmask_b32_e32 v111, 0, v240, vcc
	v_mul_f32_e64 v98, |v109|, s97
	v_sub_f32_e32 v110, v110, v111
	v_pk_fma_f32 v[102:103], v[144:145], v[102:103], v[100:101] op_sel_hi:[0,1,1]
	v_exp_f32_e32 v111, v98
	ds_read_b128 v[98:101], v251 offset:10976
	v_sub_f32_e32 v144, v108, v110
	v_mul_f32_e32 v226, 0x3d800000, v144
	v_add_f32_e32 v108, 1.0, v111
	v_cmp_gt_f32_e32 vcc, s45, v108
	s_waitcnt lgkmcnt(0)
	v_pk_fma_f32 v[110:111], v[142:143], v[100:101], v[196:197] op_sel_hi:[0,1,1]
	v_pk_fma_f32 v[112:113], v[142:143], v[98:99], v[112:113] op_sel_hi:[0,1,1]
	ds_read_b128 v[98:101], v251 offset:11104
	v_cndmask_b32_e64 v196, 0, 32, vcc
	v_ldexp_f32 v108, v108, v196
	v_log_f32_e32 v196, v108
	v_min_f32_e32 v197, 0, v109
	s_waitcnt lgkmcnt(0)
	v_pk_fma_f32 v[112:113], v[140:141], v[98:99], v[112:113] op_sel_hi:[0,1,1]
	v_pk_fma_f32 v[110:111], v[140:141], v[100:101], v[110:111] op_sel_hi:[0,1,1]
	ds_read_b128 v[98:101], v251 offset:11232
	v_mul_f32_e32 v108, 0x3f317217, v196
	v_fma_f32 v198, v196, s31, -v108
	v_fmac_f32_e32 v198, 0x3377d1cf, v196
	v_fmac_f32_e32 v198, 0x3f317217, v196
	s_waitcnt lgkmcnt(0)
	v_pk_fma_f32 v[108:109], v[138:139], v[100:101], v[110:111] op_sel_hi:[0,1,1]
	v_pk_fma_f32 v[110:111], v[138:139], v[98:99], v[112:113] op_sel_hi:[0,1,1]
	ds_read_b128 v[98:101], v251 offset:10992
	v_cmp_lt_f32_e64 s[26:27], |v196|, s44
	v_cndmask_b32_e32 v113, 0, v240, vcc
	s_waitcnt lgkmcnt(0)
	v_pk_fma_f32 v[104:105], v[142:143], v[100:101], v[104:105] op_sel_hi:[0,1,1]
	v_pk_fma_f32 v[102:103], v[142:143], v[98:99], v[102:103] op_sel_hi:[0,1,1]
	ds_read_b128 v[98:101], v251 offset:11360
	v_cndmask_b32_e64 v112, v196, v198, s[26:27]
	v_sub_f32_e32 v112, v112, v113
	v_mul_f32_e64 v113, |v106|, s97
	v_exp_f32_e32 v113, v113
	s_waitcnt lgkmcnt(0)
	v_pk_fma_f32 v[110:111], v[136:137], v[98:99], v[110:111] op_sel_hi:[0,1,1]
	v_pk_fma_f32 v[108:109], v[136:137], v[100:101], v[108:109] op_sel_hi:[0,1,1]
	ds_read_b128 v[98:101], v251 offset:11488
	v_sub_f32_e32 v142, v197, v112
	v_add_f32_e32 v112, 1.0, v113
	v_cmp_gt_f32_e32 vcc, s45, v112
	v_min_f32_e32 v106, 0, v106
	s_waitcnt lgkmcnt(0)
	v_pk_fma_f32 v[108:109], v[134:135], v[100:101], v[108:109] op_sel_hi:[0,1,1]
	v_pk_fma_f32 v[110:111], v[134:135], v[98:99], v[110:111] op_sel_hi:[0,1,1]
	ds_read_b128 v[98:101], v251 offset:11120
	v_cndmask_b32_e64 v113, 0, 32, vcc
	v_ldexp_f32 v112, v112, v113
	v_log_f32_e32 v112, v112
	v_mul_f32_e32 v197, 0x3d800000, v218
	s_waitcnt lgkmcnt(0)
	v_pk_fma_f32 v[102:103], v[140:141], v[98:99], v[102:103] op_sel_hi:[0,1,1]
	v_pk_fma_f32 v[104:105], v[140:141], v[100:101], v[104:105] op_sel_hi:[0,1,1]
	ds_read_b128 v[98:101], v251 offset:11616
	v_mul_f32_e32 v113, 0x3f317217, v112
	v_fma_f32 v113, v112, s31, -v113
	v_fmac_f32_e32 v113, 0x3377d1cf, v112
	v_fmac_f32_e32 v113, 0x3f317217, v112
	s_waitcnt lgkmcnt(0)
	v_pk_fma_f32 v[110:111], v[132:133], v[98:99], v[110:111] op_sel_hi:[0,1,1]
	v_pk_fma_f32 v[108:109], v[132:133], v[100:101], v[108:109] op_sel_hi:[0,1,1]
	ds_read_b128 v[98:101], v251 offset:11744
	v_cmp_lt_f32_e64 s[26:27], |v112|, s44
	v_mul_f32_e32 v198, 0x3d800000, v142
	s_waitcnt lgkmcnt(0)
; #define LAS __attribute__((address_space(3)))
; __device__ __forceinline__ void gla_gates(const bf16* prow, const float* wg, const float* bg, int h, int lane, float (&bc)[32], LAS float* Wst) {
;     ...
; #pragma unroll
;     for (int d4 = 0; d4 < 8; ++d4) { f32x4 z = *(const LAS f32x4*)(Wst + 512 + 4 * d4);
; #pragma unroll
;         for (int r = 0; r < 16; ++r) { const f32x4 w = *(const LAS f32x4*)(Wst + r * 32 + 4 * d4); z += w * glr[r]; }
; #pragma unroll
;         for (int e = 0; e < 4; ++e) bc[4 * d4 + e] = (fminf(z[e], 0.f) - __logf(1.f + __expf(-fabsf(z[e])))) * (1.f / 16.f); }
	v_pk_fma_f32 v[108:109], v[130:131], v[100:101], v[108:109] op_sel_hi:[0,1,1]
	v_pk_fma_f32 v[110:111], v[130:131], v[98:99], v[110:111] op_sel_hi:[0,1,1]
	ds_read_b128 v[98:101], v251 offset:11872
	v_cndmask_b32_e64 v112, v112, v113, s[26:27]
	v_cndmask_b32_e32 v113, 0, v240, vcc
	v_sub_f32_e32 v112, v112, v113
	v_sub_f32_e32 v140, v106, v112
	v_mul_f32_e64 v106, |v107|, s97
	s_waitcnt lgkmcnt(0)
	v_pk_fma_f32 v[110:111], v[128:129], v[98:99], v[110:111] op_sel_hi:[0,1,1]
	v_pk_fma_f32 v[108:109], v[128:129], v[100:101], v[108:109] op_sel_hi:[0,1,1]
	ds_read_b128 v[98:101], v251 offset:12000
	v_exp_f32_e32 v106, v106
	v_min_f32_e32 v112, 0, v107
	v_mul_f32_e32 v196, 0x3d800000, v140
	v_add_f32_e32 v113, 1.0, v106
	s_waitcnt lgkmcnt(0)
	v_pk_fma_f32 v[106:107], v[126:127], v[100:101], v[108:109] op_sel_hi:[0,1,1]
	v_pk_fma_f32 v[108:109], v[126:127], v[98:99], v[110:111] op_sel_hi:[0,1,1]
	ds_read_b128 v[98:101], v251 offset:11248
	v_cmp_gt_f32_e32 vcc, s45, v113
	s_waitcnt lgkmcnt(0)
	v_pk_fma_f32 v[104:105], v[138:139], v[100:101], v[104:105] op_sel_hi:[0,1,1]
	v_pk_fma_f32 v[102:103], v[138:139], v[98:99], v[102:103] op_sel_hi:[0,1,1]
	ds_read_b128 v[98:101], v251 offset:12128
	v_cndmask_b32_e64 v110, 0, 32, vcc
	v_ldexp_f32 v110, v113, v110
	v_log_f32_e32 v110, v110
	s_waitcnt lgkmcnt(0)
	v_pk_fma_f32 v[108:109], v[0:1], v[98:99], v[108:109] op_sel_hi:[0,1,1]
	v_pk_fma_f32 v[106:107], v[0:1], v[100:101], v[106:107] op_sel_hi:[0,1,1]
	ds_read_b128 v[98:101], v251 offset:12256
	v_mul_f32_e32 v111, 0x3f317217, v110
	v_fma_f32 v111, v110, s31, -v111
	v_fmac_f32_e32 v111, 0x3377d1cf, v110
	v_fmac_f32_e32 v111, 0x3f317217, v110
	s_waitcnt lgkmcnt(0)
	v_pk_fma_f32 v[108:109], v[124:125], v[98:99], v[108:109] op_sel_hi:[0,1,1]
	v_mul_f32_e64 v98, |v108|, s97
	v_exp_f32_e32 v98, v98
	v_cmp_lt_f32_e64 s[26:27], |v110|, s44
	v_pk_fma_f32 v[106:107], v[124:125], v[100:101], v[106:107] op_sel_hi:[0,1,1]
	v_min_f32_e32 v201, 0, v107
	v_cndmask_b32_e64 v110, v110, v111, s[26:27]
	v_cndmask_b32_e32 v111, 0, v240, vcc
	v_sub_f32_e32 v110, v110, v111
	v_sub_f32_e32 v138, v112, v110
	v_add_f32_e32 v110, 1.0, v98
	v_cmp_gt_f32_e32 vcc, s45, v110
	ds_read_b128 v[98:101], v251 offset:11376
	v_mul_f32_e32 v200, 0x3d800000, v138
	v_cndmask_b32_e64 v111, 0, 32, vcc
	v_ldexp_f32 v110, v110, v111
	v_log_f32_e32 v112, v110
	s_waitcnt lgkmcnt(0)
	v_pk_fma_f32 v[110:111], v[136:137], v[98:99], v[102:103] op_sel_hi:[0,1,1]
	v_mul_f32_e64 v102, |v109|, s97
	v_exp_f32_e32 v102, v102
	v_pk_fma_f32 v[98:99], v[136:137], v[100:101], v[104:105] op_sel_hi:[0,1,1]
	v_mul_f32_e32 v101, 0x3f317217, v112
	v_fma_f32 v101, v112, s31, -v101
	v_fmac_f32_e32 v101, 0x3377d1cf, v112
	v_fmac_f32_e32 v101, 0x3f317217, v112
	v_cmp_lt_f32_e64 s[26:27], |v112|, s44
	v_add_f32_e32 v102, 1.0, v102
	v_cndmask_b32_e32 v103, 0, v240, vcc
	v_cndmask_b32_e64 v101, v112, v101, s[26:27]
	v_cmp_gt_f32_e32 vcc, s45, v102
	v_sub_f32_e32 v101, v101, v103
	v_min_f32_e32 v100, 0, v108
	v_cndmask_b32_e64 v103, 0, 32, vcc
	v_ldexp_f32 v102, v102, v103
	v_log_f32_e32 v102, v102
	v_mul_f32_e64 v103, |v106|, s97
	v_exp_f32_e32 v103, v103
	v_sub_f32_e32 v239, v100, v101
	v_mul_f32_e32 v101, 0x3f317217, v102
	v_fma_f32 v101, v102, s31, -v101
	v_fmac_f32_e32 v101, 0x3377d1cf, v102
	v_fmac_f32_e32 v101, 0x3f317217, v102
	v_cmp_lt_f32_e64 s[26:27], |v102|, s44
	v_add_f32_e32 v103, 1.0, v103
	v_min_f32_e32 v100, 0, v109
	v_cndmask_b32_e64 v101, v102, v101, s[26:27]
	v_cndmask_b32_e32 v102, 0, v240, vcc
	v_cmp_gt_f32_e32 vcc, s45, v103
	v_sub_f32_e32 v101, v101, v102
	v_sub_f32_e32 v199, v100, v101
	v_cndmask_b32_e64 v104, 0, 32, vcc
	v_ldexp_f32 v103, v103, v104
	v_log_f32_e32 v103, v103
	v_cndmask_b32_e32 v102, 0, v240, vcc
	v_min_f32_e32 v100, 0, v106
	v_mul_f32_e32 v230, 0x3d800000, v239
	v_mul_f32_e32 v101, 0x3f317217, v103
	v_fma_f32 v101, v103, s31, -v101
	v_fmac_f32_e32 v101, 0x3377d1cf, v103
	v_fmac_f32_e32 v101, 0x3f317217, v103
	v_cmp_lt_f32_e64 s[26:27], |v103|, s44
	s_nop 1
	v_cndmask_b32_e64 v101, v103, v101, s[26:27]
	v_mul_f32_e64 v103, |v107|, s97
	v_exp_f32_e32 v103, v103
	v_sub_f32_e32 v101, v101, v102
	v_sub_f32_e32 v136, v100, v101
	v_add_f32_e32 v104, 1.0, v103
	ds_read_b128 v[100:103], v251 offset:11504
	v_cmp_gt_f32_e32 vcc, s45, v104
	s_waitcnt lgkmcnt(0)
	v_pk_fma_f32 v[98:99], v[134:135], v[102:103], v[98:99] op_sel_hi:[0,1,1]
	v_cndmask_b32_e64 v105, 0, 32, vcc
	v_ldexp_f32 v104, v104, v105
	v_log_f32_e32 v112, v104
	ds_read_b128 v[102:105], v251 offset:11632
	v_pk_fma_f32 v[100:101], v[134:135], v[100:101], v[110:111] op_sel_hi:[0,1,1]
	v_mul_f32_e32 v106, 0x3f317217, v112
	v_fma_f32 v110, v112, s31, -v106
	s_waitcnt lgkmcnt(0)
	v_pk_fma_f32 v[106:107], v[132:133], v[102:103], v[100:101] op_sel_hi:[0,1,1]
	v_pk_fma_f32 v[108:109], v[132:133], v[104:105], v[98:99] op_sel_hi:[0,1,1]
	ds_read_b128 v[98:101], v251 offset:11760
	ds_read_b128 v[102:105], v251 offset:11888
	v_fmac_f32_e32 v110, 0x3377d1cf, v112
	v_fmac_f32_e32 v110, 0x3f317217, v112
	v_cmp_lt_f32_e64 s[26:27], |v112|, s44
	s_waitcnt lgkmcnt(1)
	v_pk_fma_f32 v[100:101], v[130:131], v[100:101], v[108:109] op_sel_hi:[0,1,1]
	v_pk_fma_f32 v[98:99], v[130:131], v[98:99], v[106:107] op_sel_hi:[0,1,1]
	v_cndmask_b32_e64 v134, v112, v110, s[26:27]
	s_waitcnt lgkmcnt(0)
	v_pk_fma_f32 v[112:113], v[128:129], v[102:103], v[98:99] op_sel_hi:[0,1,1]
	v_pk_fma_f32 v[110:111], v[128:129], v[104:105], v[100:101] op_sel_hi:[0,1,1]
	ds_read_b128 v[98:101], v251 offset:12016
	ds_read_b128 v[102:105], v251 offset:12144
	ds_read_b128 v[106:109], v251 offset:12272
	v_cndmask_b32_e32 v130, 0, v240, vcc
	v_sub_f32_e32 v128, v134, v130
	s_waitcnt lgkmcnt(2)
; #define LAS __attribute__((address_space(3)))
; #define WSYNC() asm volatile("s_waitcnt lgkmcnt(0)" ::: "memory")
; __device__ __forceinline__ void gla_gates(const bf16* prow, const float* wg, const float* bg, int h, int lane, float (&bc)[32], LAS float* Wst) {
;     ...
;     for (int d4 = 0; d4 < 8; ++d4) { f32x4 z = *(const LAS f32x4*)(Wst + 512 + 4 * d4);
; #pragma unroll
;         for (int r = 0; r < 16; ++r) { const f32x4 w = *(const LAS f32x4*)(Wst + r * 32 + 4 * d4); z += w * glr[r]; }
; #pragma unroll
;         for (int e = 0; e < 4; ++e) bc[4 * d4 + e] = (fminf(z[e], 0.f) - __logf(1.f + __expf(-fabsf(z[e])))) * (1.f / 16.f); }
;     WSYNC();
; #pragma unroll
;     for (int d = 0; d < 32; ++d) { float v = bc[d];
; #pragma unroll
;         for (int off = 1; off < 64; off <<= 1) { const float t = __shfl_up(v, off); if (lane >= off) v += t; }
;         bc[d] = v; }
	v_pk_fma_f32 v[98:99], v[126:127], v[98:99], v[112:113] op_sel_hi:[0,1,1]
	s_waitcnt lgkmcnt(1)
	v_pk_fma_f32 v[98:99], v[0:1], v[102:103], v[98:99] op_sel_hi:[0,1,1]
	s_waitcnt lgkmcnt(0)
	v_pk_fma_f32 v[98:99], v[124:125], v[106:107], v[98:99] op_sel_hi:[0,1,1]
	v_mul_f32_e64 v102, |v98|, s97
	v_exp_f32_e32 v102, v102
	v_pk_fma_f32 v[100:101], v[126:127], v[100:101], v[110:111] op_sel_hi:[0,1,1]
	v_pk_fma_f32 v[100:101], v[0:1], v[104:105], v[100:101] op_sel_hi:[0,1,1]
	v_min_f32_e32 v0, 0, v98
	v_add_f32_e32 v102, 1.0, v102
	v_cmp_gt_f32_e32 vcc, s45, v102
	v_pk_fma_f32 v[100:101], v[124:125], v[108:109], v[100:101] op_sel_hi:[0,1,1]
	v_min_f32_e32 v111, 0, v101
	v_cndmask_b32_e64 v103, 0, 32, vcc
	v_ldexp_f32 v102, v102, v103
	v_log_f32_e32 v102, v102
	v_mul_f32_e64 v103, |v99|, s97
	v_exp_f32_e32 v103, v103
	v_sub_f32_e32 v128, v201, v128
	v_mul_f32_e32 v98, 0x3f317217, v102
	v_fma_f32 v98, v102, s31, -v98
	v_fmac_f32_e32 v98, 0x3377d1cf, v102
	v_fmac_f32_e32 v98, 0x3f317217, v102
	v_cmp_lt_f32_e64 s[26:27], |v102|, s44
	v_mul_f32_e32 v132, 0x3d800000, v199
	v_mul_f32_e32 v113, 0x3d800000, v136
	v_cndmask_b32_e64 v98, v102, v98, s[26:27]
	v_cndmask_b32_e32 v102, 0, v240, vcc
	v_sub_f32_e32 v98, v98, v102
	v_add_f32_e32 v102, 1.0, v103
	v_cmp_gt_f32_e32 vcc, s45, v102
	v_sub_f32_e32 v107, v0, v98
	v_min_f32_e32 v0, 0, v99
	v_cndmask_b32_e64 v103, 0, 32, vcc
	v_ldexp_f32 v102, v102, v103
	v_log_f32_e32 v102, v102
	v_mul_f32_e64 v99, |v100|, s97
	v_exp_f32_e32 v99, v99
	v_mul_f32_e32 v106, 0x3d800000, v128
	v_mul_f32_e32 v98, 0x3f317217, v102
	v_fma_f32 v98, v102, s31, -v98
	v_fmac_f32_e32 v98, 0x3377d1cf, v102
	v_fmac_f32_e32 v98, 0x3f317217, v102
	v_cmp_lt_f32_e64 s[26:27], |v102|, s44
	v_add_f32_e32 v99, 1.0, v99
	v_mul_f32_e32 v108, 0x3d800000, v107
	v_cndmask_b32_e64 v98, v102, v98, s[26:27]
	v_cndmask_b32_e32 v102, 0, v240, vcc
	v_cmp_gt_f32_e32 vcc, s45, v99
	v_sub_f32_e32 v98, v98, v102
	v_sub_f32_e32 v104, v0, v98
	v_cndmask_b32_e64 v102, 0, 32, vcc
	v_ldexp_f32 v99, v99, v102
	v_log_f32_e32 v99, v99
	v_min_f32_e32 v0, 0, v100
	v_cndmask_b32_e32 v100, 0, v240, vcc
	v_mul_f32_e32 v105, 0x3d800000, v104
	v_mul_f32_e32 v98, 0x3f317217, v99
	v_fma_f32 v98, v99, s31, -v98
	v_fmac_f32_e32 v98, 0x3377d1cf, v99
	v_fmac_f32_e32 v98, 0x3f317217, v99
	v_cmp_lt_f32_e64 s[26:27], |v99|, s44
	s_waitcnt lgkmcnt(0)
	s_nop 1
	v_cndmask_b32_e64 v98, v99, v98, s[26:27]
	v_mul_f32_e64 v99, |v101|, s97
	v_exp_f32_e32 v99, v99
	v_sub_f32_e32 v98, v98, v100
	v_sub_f32_e32 v98, v0, v98
	v_and_b32_e32 v0, 64, v241
	v_add_f32_e32 v100, 1.0, v99
	v_add_u32_e32 v99, -1, v241
	v_cmp_lt_i32_e32 vcc, v99, v0
	s_nop 1
	v_cndmask_b32_e32 v99, v99, v241, vcc
	v_lshlrev_b32_e32 v99, 2, v99
	ds_bpermute_b32 v102, v99, v250
	v_cmp_gt_f32_e32 vcc, s45, v100
	ds_bpermute_b32 v201, v99, v246
	s_waitcnt lgkmcnt(1)
	v_fmac_f32_e32 v102, 0x3d800000, v249
	v_cndmask_b32_e64 v103, 0, 32, vcc
	v_ldexp_f32 v100, v100, v103
	v_log_f32_e32 v109, v100
	v_add_u32_e32 v100, -2, v241
	v_cmp_lt_i32_e64 s[26:27], v100, v0
	v_cndmask_b32_e64 v102, v102, v250, s[6:7]
	v_mul_f32_e32 v101, 0x3f317217, v109
	v_cndmask_b32_e64 v100, v100, v241, s[26:27]
	v_lshlrev_b32_e32 v100, 2, v100
	ds_bpermute_b32 v110, v100, v102
	v_fma_f32 v112, v109, s31, -v101
	v_fmac_f32_e32 v112, 0x3377d1cf, v109
	v_fmac_f32_e32 v112, 0x3f317217, v109
	s_waitcnt lgkmcnt(1)
	v_fmac_f32_e32 v201, 0x3d800000, v245
	s_waitcnt lgkmcnt(0)
	v_add_f32_e32 v101, v102, v110
	v_cndmask_b32_e64 v102, v101, v102, s[8:9]
	v_add_u32_e32 v101, -4, v241
	v_cmp_lt_i32_e64 s[26:27], v101, v0
	v_cndmask_b32_e64 v201, v201, v246, s[6:7]
	ds_bpermute_b32 v202, v100, v201
	v_cndmask_b32_e64 v101, v101, v241, s[26:27]
	v_lshlrev_b32_e32 v101, 2, v101
	ds_bpermute_b32 v110, v101, v102
	v_cmp_lt_f32_e64 s[26:27], |v109|, s44
	v_mul_f32_e32 v103, 0x3d800000, v98
	s_waitcnt lgkmcnt(0)
	v_add_f32_e32 v110, v102, v110
	v_cndmask_b32_e64 v109, v109, v112, s[26:27]
	v_cndmask_b32_e64 v112, v110, v102, s[10:11]
	v_add_u32_e32 v102, -8, v241
	v_cmp_lt_i32_e64 s[26:27], v102, v0
	v_cndmask_b32_e32 v110, 0, v240, vcc
	v_sub_f32_e32 v109, v109, v110
	v_cndmask_b32_e64 v102, v102, v241, s[26:27]
	v_lshlrev_b32_e32 v102, 2, v102
	ds_bpermute_b32 v124, v102, v112
	v_sub_f32_e32 v109, v111, v109
	v_mul_f32_e32 v110, 0x3d800000, v109
	s_waitcnt lgkmcnt(0)
	v_add_f32_e32 v111, v112, v124
	ds_bpermute_b32 v124, v99, v248
	v_cndmask_b32_e64 v112, v111, v112, s[12:13]
	v_add_u32_e32 v111, -16, v241
	v_cmp_lt_i32_e32 vcc, v111, v0
	s_waitcnt lgkmcnt(0)
	v_fmac_f32_e32 v124, 0x3d800000, v247
	v_cndmask_b32_e64 v124, v124, v248, s[6:7]
	ds_bpermute_b32 v130, v100, v124
	v_cndmask_b32_e32 v111, v111, v241, vcc
	v_lshlrev_b32_e32 v111, 2, v111
	ds_bpermute_b32 v126, v111, v112
	s_waitcnt lgkmcnt(1)
	v_add_f32_e32 v130, v124, v130
	v_cndmask_b32_e64 v124, v130, v124, s[8:9]
	ds_bpermute_b32 v130, v101, v124
	s_waitcnt lgkmcnt(1)
	v_add_f32_e32 v126, v112, v126
	v_cndmask_b32_e64 v126, v126, v112, s[14:15]
	v_subrev_u32_e32 v112, 32, v241
	v_cmp_lt_i32_e32 vcc, v112, v0
	s_waitcnt lgkmcnt(0)
	v_add_f32_e32 v130, v124, v130
	v_cndmask_b32_e64 v124, v130, v124, s[10:11]
	v_cndmask_b32_e32 v112, v112, v241, vcc
	v_lshlrev_b32_e32 v112, 2, v112
	ds_bpermute_b32 v134, v112, v126
	ds_bpermute_b32 v130, v102, v124
	s_waitcnt lgkmcnt(1)
	v_add_f32_e32 v134, v126, v134
	s_waitcnt lgkmcnt(0)
	v_add_f32_e32 v130, v124, v130
	v_cndmask_b32_e64 v130, v130, v124, s[12:13]
	v_cndmask_b32_e64 v124, v134, v126, s[4:5]
	v_add_f32_e32 v126, v201, v202
	v_cndmask_b32_e64 v126, v126, v201, s[8:9]
	ds_bpermute_b32 v203, v111, v130
	ds_bpermute_b32 v134, v101, v126
	ds_bpermute_b32 v202, v99, v253
	s_waitcnt lgkmcnt(2)
; __device__ __forceinline__ void gla_gates(const bf16* prow, const float* wg, const float* bg, int h, int lane, float (&bc)[32], LAS float* Wst) {
;     ...
; #pragma unroll
;     for (int d = 0; d < 32; ++d) { float v = bc[d];
; #pragma unroll
;         for (int off = 1; off < 64; off <<= 1) { const float t = __shfl_up(v, off); if (lane >= off) v += t; }
;         bc[d] = v; }
	v_add_f32_e32 v201, v130, v203
	s_waitcnt lgkmcnt(1)
	v_add_f32_e32 v134, v126, v134
	v_cndmask_b32_e64 v130, v201, v130, s[14:15]
	v_cndmask_b32_e64 v126, v134, v126, s[10:11]
	s_waitcnt lgkmcnt(0)
	v_fmac_f32_e32 v202, 0x3d800000, v252
	ds_bpermute_b32 v201, v112, v130
	ds_bpermute_b32 v134, v102, v126
	v_cndmask_b32_e64 v202, v202, v253, s[6:7]
	ds_bpermute_b32 v203, v100, v202
	s_waitcnt lgkmcnt(2)
	v_add_f32_e32 v201, v130, v201
	s_waitcnt lgkmcnt(1)
	v_add_f32_e32 v134, v126, v134
	v_cndmask_b32_e64 v134, v134, v126, s[12:13]
	v_cndmask_b32_e64 v126, v201, v130, s[4:5]
	s_waitcnt lgkmcnt(0)
	v_add_f32_e32 v130, v202, v203
	v_cndmask_b32_e64 v130, v130, v202, s[8:9]
	ds_bpermute_b32 v221, v111, v134
	ds_bpermute_b32 v201, v101, v130
	ds_bpermute_b32 v203, v99, v231
	s_waitcnt lgkmcnt(2)
	v_add_f32_e32 v202, v134, v221
	s_waitcnt lgkmcnt(1)
	v_add_f32_e32 v201, v130, v201
	v_cndmask_b32_e64 v134, v202, v134, s[14:15]
	v_cndmask_b32_e64 v130, v201, v130, s[10:11]
	s_waitcnt lgkmcnt(0)
	v_fmac_f32_e32 v203, 0x3d800000, v254
	ds_bpermute_b32 v202, v112, v134
	ds_bpermute_b32 v201, v102, v130
	v_cndmask_b32_e64 v203, v203, v231, s[6:7]
	ds_bpermute_b32 v221, v100, v203
	s_waitcnt lgkmcnt(2)
	v_add_f32_e32 v202, v134, v202
	s_waitcnt lgkmcnt(1)
	v_add_f32_e32 v201, v130, v201
	v_cndmask_b32_e64 v201, v201, v130, s[12:13]
	v_cndmask_b32_e64 v130, v202, v134, s[4:5]
	s_waitcnt lgkmcnt(0)
	v_add_f32_e32 v134, v203, v221
	v_cndmask_b32_e64 v134, v134, v203, s[8:9]
	ds_bpermute_b32 v231, v111, v201
	ds_bpermute_b32 v202, v101, v134
	ds_bpermute_b32 v221, v99, v222
	s_waitcnt lgkmcnt(2)
	v_add_f32_e32 v203, v201, v231
	s_waitcnt lgkmcnt(1)
	v_add_f32_e32 v202, v134, v202
	v_cndmask_b32_e64 v201, v203, v201, s[14:15]
	v_cndmask_b32_e64 v134, v202, v134, s[10:11]
	s_waitcnt lgkmcnt(0)
	v_fmac_f32_e32 v221, 0x3d800000, v220
	ds_bpermute_b32 v203, v112, v201
	ds_bpermute_b32 v202, v102, v134
	v_cndmask_b32_e64 v220, v221, v222, s[6:7]
	ds_bpermute_b32 v221, v100, v220
	s_waitcnt lgkmcnt(2)
	v_add_f32_e32 v203, v201, v203
	s_waitcnt lgkmcnt(1)
	v_add_f32_e32 v202, v134, v202
	v_cndmask_b32_e64 v202, v202, v134, s[12:13]
	v_cndmask_b32_e64 v134, v203, v201, s[4:5]
	s_waitcnt lgkmcnt(0)
	v_add_f32_e32 v201, v220, v221
	v_cndmask_b32_e64 v201, v201, v220, s[8:9]
	ds_bpermute_b32 v222, v111, v202
	ds_bpermute_b32 v203, v101, v201
	ds_bpermute_b32 v221, v99, v159
	s_waitcnt lgkmcnt(2)
	v_add_f32_e32 v220, v202, v222
	s_waitcnt lgkmcnt(1)
	v_add_f32_e32 v203, v201, v203
	v_cndmask_b32_e64 v202, v220, v202, s[14:15]
	v_cndmask_b32_e64 v201, v203, v201, s[10:11]
	s_waitcnt lgkmcnt(0)
	v_fmac_f32_e32 v221, 0x3d800000, v158
	ds_bpermute_b32 v220, v112, v202
	ds_bpermute_b32 v203, v102, v201
	v_cndmask_b32_e64 v159, v221, v159, s[6:7]
	ds_bpermute_b32 v221, v100, v159
	s_waitcnt lgkmcnt(2)
	v_add_f32_e32 v220, v202, v220
	s_waitcnt lgkmcnt(1)
	v_add_f32_e32 v158, v201, v203
	v_cndmask_b32_e64 v201, v158, v201, s[12:13]
	v_cndmask_b32_e64 v158, v220, v202, s[4:5]
	s_waitcnt lgkmcnt(0)
	v_add_f32_e32 v202, v159, v221
	v_cndmask_b32_e64 v159, v202, v159, s[8:9]
	ds_bpermute_b32 v203, v111, v201
	ds_bpermute_b32 v202, v101, v159
	ds_bpermute_b32 v220, v99, v232
	s_waitcnt lgkmcnt(2)
	v_add_f32_e32 v203, v201, v203
	s_waitcnt lgkmcnt(1)
	v_add_f32_e32 v202, v159, v202
	v_cndmask_b32_e64 v201, v203, v201, s[14:15]
	v_cndmask_b32_e64 v159, v202, v159, s[10:11]
	s_waitcnt lgkmcnt(0)
	v_fmac_f32_e32 v220, 0x3d800000, v223
	ds_bpermute_b32 v203, v112, v201
	ds_bpermute_b32 v202, v102, v159
	v_cndmask_b32_e64 v220, v220, v232, s[6:7]
	ds_bpermute_b32 v221, v100, v220
	s_waitcnt lgkmcnt(2)
	v_add_f32_e32 v203, v201, v203
	s_waitcnt lgkmcnt(1)
	v_add_f32_e32 v202, v159, v202
	v_cndmask_b32_e64 v202, v202, v159, s[12:13]
	v_cndmask_b32_e64 v159, v203, v201, s[4:5]
	s_waitcnt lgkmcnt(0)
	v_add_f32_e32 v201, v220, v221
	v_cndmask_b32_e64 v201, v201, v220, s[8:9]
	ds_bpermute_b32 v222, v111, v202
	ds_bpermute_b32 v203, v101, v201
	ds_bpermute_b32 v221, v99, v236
	s_waitcnt lgkmcnt(2)
	v_add_f32_e32 v220, v202, v222
	s_waitcnt lgkmcnt(1)
	v_add_f32_e32 v203, v201, v203
	v_cndmask_b32_e64 v202, v220, v202, s[14:15]
	v_cndmask_b32_e64 v201, v203, v201, s[10:11]
	s_waitcnt lgkmcnt(0)
	v_fmac_f32_e32 v221, 0x3d800000, v156
	ds_bpermute_b32 v220, v112, v202
	ds_bpermute_b32 v203, v102, v201
	v_cndmask_b32_e64 v221, v221, v236, s[6:7]
	ds_bpermute_b32 v222, v100, v221
	s_waitcnt lgkmcnt(2)
	v_add_f32_e32 v220, v202, v220
	s_waitcnt lgkmcnt(1)
	v_add_f32_e32 v156, v201, v203
	v_cndmask_b32_e64 v201, v156, v201, s[12:13]
	v_cndmask_b32_e64 v156, v220, v202, s[4:5]
	s_waitcnt lgkmcnt(0)
	v_add_f32_e32 v202, v221, v222
	v_cndmask_b32_e64 v202, v202, v221, s[8:9]
	ds_bpermute_b32 v203, v111, v201
	ds_bpermute_b32 v220, v101, v202
	ds_bpermute_b32 v221, v99, v235
	s_waitcnt lgkmcnt(2)
	v_add_f32_e32 v203, v201, v203
	s_waitcnt lgkmcnt(1)
	v_add_f32_e32 v220, v202, v220
	v_cndmask_b32_e64 v201, v203, v201, s[14:15]
	v_cndmask_b32_e64 v202, v220, v202, s[10:11]
	s_waitcnt lgkmcnt(0)
	v_fmac_f32_e32 v221, 0x3d800000, v157
	ds_bpermute_b32 v203, v112, v201
	ds_bpermute_b32 v220, v102, v202
	v_cndmask_b32_e64 v221, v221, v235, s[6:7]
	ds_bpermute_b32 v222, v100, v221
	s_waitcnt lgkmcnt(2)
	v_add_f32_e32 v203, v201, v203
	s_waitcnt lgkmcnt(1)
	v_add_f32_e32 v157, v202, v220
	v_cndmask_b32_e64 v202, v157, v202, s[12:13]
	v_cndmask_b32_e64 v157, v203, v201, s[4:5]
	s_waitcnt lgkmcnt(0)
	v_add_f32_e32 v201, v221, v222
	v_cndmask_b32_e64 v201, v201, v221, s[8:9]
	ds_bpermute_b32 v220, v111, v202
	ds_bpermute_b32 v203, v101, v201
	ds_bpermute_b32 v221, v99, v160
	s_waitcnt lgkmcnt(2)
; #define WSYNC() asm volatile("s_waitcnt lgkmcnt(0)" ::: "memory")
; __device__ __forceinline__ void gla_gates(const bf16* prow, const float* wg, const float* bg, int h, int lane, float (&bc)[32], LAS float* Wst) {
;     ...
;         for (int e = 0; e < 4; ++e) bc[4 * d4 + e] = (fminf(z[e], 0.f) - __logf(1.f + __expf(-fabsf(z[e])))) * (1.f / 16.f); }
;     WSYNC();
; #pragma unroll
;     for (int d = 0; d < 32; ++d) { float v = bc[d];
; #pragma unroll
;         for (int off = 1; off < 64; off <<= 1) { const float t = __shfl_up(v, off); if (lane >= off) v += t; }
;         bc[d] = v; }
	v_add_f32_e32 v220, v202, v220
	s_waitcnt lgkmcnt(1)
	v_add_f32_e32 v203, v201, v203
	v_cndmask_b32_e64 v202, v220, v202, s[14:15]
	v_cndmask_b32_e64 v201, v203, v201, s[10:11]
	s_waitcnt lgkmcnt(0)
	v_fmac_f32_e32 v221, 0x3d800000, v234
	ds_bpermute_b32 v220, v112, v202
	ds_bpermute_b32 v203, v102, v201
	v_cndmask_b32_e64 v221, v221, v160, s[6:7]
	ds_bpermute_b32 v222, v100, v221
	s_waitcnt lgkmcnt(2)
	v_add_f32_e32 v220, v202, v220
	s_waitcnt lgkmcnt(1)
	v_add_f32_e32 v160, v201, v203
	v_cndmask_b32_e64 v201, v160, v201, s[12:13]
	v_cndmask_b32_e64 v160, v220, v202, s[4:5]
	s_waitcnt lgkmcnt(0)
	v_add_f32_e32 v202, v221, v222
	v_cndmask_b32_e64 v202, v202, v221, s[8:9]
	ds_bpermute_b32 v220, v101, v202
	ds_bpermute_b32 v203, v111, v201
	ds_bpermute_b32 v221, v99, v152
	s_waitcnt lgkmcnt(2)
	v_add_f32_e32 v220, v202, v220
	v_cndmask_b32_e64 v202, v220, v202, s[10:11]
	ds_bpermute_b32 v220, v102, v202
	s_waitcnt lgkmcnt(2)
	v_add_f32_e32 v203, v201, v203
	v_cndmask_b32_e64 v201, v203, v201, s[14:15]
	s_waitcnt lgkmcnt(1)
	v_fmac_f32_e32 v221, 0x3d800000, v155
	ds_bpermute_b32 v203, v112, v201
	v_cndmask_b32_e64 v155, v221, v152, s[6:7]
	ds_bpermute_b32 v221, v100, v155
	s_waitcnt lgkmcnt(2)
	v_add_f32_e32 v152, v202, v220
	v_cndmask_b32_e64 v202, v152, v202, s[12:13]
	ds_bpermute_b32 v220, v111, v202
	s_waitcnt lgkmcnt(2)
	v_add_f32_e32 v203, v201, v203
	v_cndmask_b32_e64 v152, v203, v201, s[4:5]
	s_waitcnt lgkmcnt(1)
	v_add_f32_e32 v201, v155, v221
	v_cndmask_b32_e64 v155, v201, v155, s[8:9]
	ds_bpermute_b32 v201, v101, v155
	s_waitcnt lgkmcnt(1)
	v_add_f32_e32 v203, v202, v220
	ds_bpermute_b32 v220, v99, v237
	v_cndmask_b32_e64 v202, v203, v202, s[14:15]
	ds_bpermute_b32 v203, v112, v202
	s_waitcnt lgkmcnt(2)
	v_add_f32_e32 v201, v155, v201
	v_cndmask_b32_e64 v155, v201, v155, s[10:11]
	s_waitcnt lgkmcnt(1)
	v_fmac_f32_e32 v220, 0x3d800000, v154
	ds_bpermute_b32 v201, v102, v155
	v_cndmask_b32_e64 v220, v220, v237, s[6:7]
	ds_bpermute_b32 v221, v100, v220
	s_waitcnt lgkmcnt(2)
	v_add_f32_e32 v203, v202, v203
	s_waitcnt lgkmcnt(1)
	v_add_f32_e32 v154, v155, v201
	v_cndmask_b32_e64 v155, v154, v155, s[12:13]
	v_cndmask_b32_e64 v154, v203, v202, s[4:5]
	s_waitcnt lgkmcnt(0)
	v_add_f32_e32 v202, v220, v221
	v_cndmask_b32_e64 v202, v202, v220, s[8:9]
	ds_bpermute_b32 v203, v101, v202
	ds_bpermute_b32 v201, v111, v155
	ds_bpermute_b32 v220, v99, v161
	s_waitcnt lgkmcnt(2)
	v_add_f32_e32 v203, v202, v203
	v_cndmask_b32_e64 v202, v203, v202, s[10:11]
	ds_bpermute_b32 v203, v102, v202
	s_waitcnt lgkmcnt(2)
	v_add_f32_e32 v201, v155, v201
	v_cndmask_b32_e64 v155, v201, v155, s[14:15]
	s_waitcnt lgkmcnt(1)
	v_fmac_f32_e32 v220, 0x3d800000, v150
	ds_bpermute_b32 v201, v112, v155
	v_cndmask_b32_e64 v161, v220, v161, s[6:7]
	ds_bpermute_b32 v220, v100, v161
	s_waitcnt lgkmcnt(2)
	v_add_f32_e32 v150, v202, v203
	v_cndmask_b32_e64 v202, v150, v202, s[12:13]
	ds_bpermute_b32 v203, v111, v202
	s_waitcnt lgkmcnt(2)
	v_add_f32_e32 v201, v155, v201
	v_cndmask_b32_e64 v150, v201, v155, s[4:5]
	s_waitcnt lgkmcnt(1)
	v_add_f32_e32 v155, v161, v220
	v_cndmask_b32_e64 v155, v155, v161, s[8:9]
	ds_bpermute_b32 v161, v101, v155
	s_waitcnt lgkmcnt(1)
	v_add_f32_e32 v201, v202, v203
	ds_bpermute_b32 v203, v99, v224
	v_cndmask_b32_e64 v201, v201, v202, s[14:15]
	ds_bpermute_b32 v202, v112, v201
	s_waitcnt lgkmcnt(2)
	v_add_f32_e32 v161, v155, v161
	v_cndmask_b32_e64 v155, v161, v155, s[10:11]
	s_waitcnt lgkmcnt(1)
	v_fmac_f32_e32 v203, 0x3d800000, v148
	ds_bpermute_b32 v161, v102, v155
	v_cndmask_b32_e64 v203, v203, v224, s[6:7]
	ds_bpermute_b32 v220, v100, v203
	s_waitcnt lgkmcnt(2)
	v_add_f32_e32 v202, v201, v202
	s_waitcnt lgkmcnt(1)
	v_add_f32_e32 v148, v155, v161
	v_cndmask_b32_e64 v155, v148, v155, s[12:13]
	v_cndmask_b32_e64 v148, v202, v201, s[4:5]
	s_waitcnt lgkmcnt(0)
	v_add_f32_e32 v201, v203, v220
	v_cndmask_b32_e64 v201, v201, v203, s[8:9]
	ds_bpermute_b32 v161, v111, v155
	ds_bpermute_b32 v202, v101, v201
	ds_bpermute_b32 v203, v99, v229
	s_waitcnt lgkmcnt(2)
	v_add_f32_e32 v161, v155, v161
	s_waitcnt lgkmcnt(1)
	v_add_f32_e32 v202, v201, v202
	v_cndmask_b32_e64 v155, v161, v155, s[14:15]
	v_cndmask_b32_e64 v201, v202, v201, s[10:11]
	s_waitcnt lgkmcnt(0)
	v_fmac_f32_e32 v203, 0x3d800000, v153
	ds_bpermute_b32 v161, v112, v155
	ds_bpermute_b32 v202, v102, v201
	v_cndmask_b32_e64 v203, v203, v229, s[6:7]
	ds_bpermute_b32 v220, v100, v203
	s_waitcnt lgkmcnt(2)
	v_add_f32_e32 v161, v155, v161
	s_waitcnt lgkmcnt(1)
	v_add_f32_e32 v153, v201, v202
	v_cndmask_b32_e64 v201, v153, v201, s[12:13]
	v_cndmask_b32_e64 v153, v161, v155, s[4:5]
	s_waitcnt lgkmcnt(0)
	v_add_f32_e32 v155, v203, v220
	v_cndmask_b32_e64 v155, v155, v203, s[8:9]
	ds_bpermute_b32 v202, v111, v201
	ds_bpermute_b32 v161, v101, v155
	ds_bpermute_b32 v203, v99, v225
	s_waitcnt lgkmcnt(2)
	v_add_f32_e32 v202, v201, v202
	s_waitcnt lgkmcnt(1)
	v_add_f32_e32 v161, v155, v161
	v_cndmask_b32_e64 v201, v202, v201, s[14:15]
	v_cndmask_b32_e64 v155, v161, v155, s[10:11]
	s_waitcnt lgkmcnt(0)
	v_fmac_f32_e32 v203, 0x3d800000, v146
	ds_bpermute_b32 v202, v112, v201
	ds_bpermute_b32 v161, v102, v155
	v_cndmask_b32_e64 v203, v203, v225, s[6:7]
	ds_bpermute_b32 v220, v100, v203
	s_waitcnt lgkmcnt(2)
	v_add_f32_e32 v202, v201, v202
	s_waitcnt lgkmcnt(1)
	v_add_f32_e32 v146, v155, v161
	v_cndmask_b32_e64 v155, v146, v155, s[12:13]
	v_cndmask_b32_e64 v146, v202, v201, s[4:5]
	s_waitcnt lgkmcnt(0)
	v_add_f32_e32 v201, v203, v220
	ds_bpermute_b32 v161, v111, v155
	v_cndmask_b32_e64 v201, v201, v203, s[8:9]
	ds_bpermute_b32 v202, v101, v201
	ds_bpermute_b32 v203, v99, v228
	s_waitcnt lgkmcnt(2)
; #define WSYNC() asm volatile("s_waitcnt lgkmcnt(0)" ::: "memory")
; __device__ __forceinline__ void gla_gates(const bf16* prow, const float* wg, const float* bg, int h, int lane, float (&bc)[32], LAS float* Wst) {
;     ...
;         for (int e = 0; e < 4; ++e) bc[4 * d4 + e] = (fminf(z[e], 0.f) - __logf(1.f + __expf(-fabsf(z[e])))) * (1.f / 16.f); }
;     WSYNC();
; #pragma unroll
;     for (int d = 0; d < 32; ++d) { float v = bc[d];
; #pragma unroll
;         for (int off = 1; off < 64; off <<= 1) { const float t = __shfl_up(v, off); if (lane >= off) v += t; }
;         bc[d] = v; }
	v_add_f32_e32 v161, v155, v161
	v_cndmask_b32_e64 v155, v161, v155, s[14:15]
	s_waitcnt lgkmcnt(1)
	v_add_f32_e32 v202, v201, v202
	s_waitcnt lgkmcnt(0)
	v_fmac_f32_e32 v203, 0x3d800000, v238
	ds_bpermute_b32 v161, v112, v155
	v_cndmask_b32_e64 v201, v202, v201, s[10:11]
	v_cndmask_b32_e64 v203, v203, v228, s[6:7]
	ds_bpermute_b32 v202, v102, v201
	ds_bpermute_b32 v220, v100, v203
	s_waitcnt lgkmcnt(2)
	v_add_f32_e32 v161, v155, v161
	v_cndmask_b32_e64 v155, v161, v155, s[4:5]
	s_waitcnt lgkmcnt(1)
	v_add_f32_e32 v202, v201, v202
	s_waitcnt lgkmcnt(0)
	v_add_f32_e32 v161, v203, v220
	v_cndmask_b32_e64 v201, v202, v201, s[12:13]
	v_cndmask_b32_e64 v161, v161, v203, s[8:9]
	ds_bpermute_b32 v202, v111, v201
	ds_bpermute_b32 v203, v101, v161
	ds_bpermute_b32 v220, v99, v227
	s_waitcnt lgkmcnt(2)
	v_add_f32_e32 v202, v201, v202
	s_waitcnt lgkmcnt(1)
	v_add_f32_e32 v203, v161, v203
	v_cndmask_b32_e64 v201, v202, v201, s[14:15]
	v_cndmask_b32_e64 v161, v203, v161, s[10:11]
	s_waitcnt lgkmcnt(0)
	v_fmac_f32_e32 v220, 0x3d800000, v219
	ds_bpermute_b32 v202, v112, v201
	ds_bpermute_b32 v203, v102, v161
	v_cndmask_b32_e64 v219, v220, v227, s[6:7]
	ds_bpermute_b32 v220, v100, v219
	s_waitcnt lgkmcnt(2)
	v_add_f32_e32 v202, v201, v202
	s_waitcnt lgkmcnt(1)
	v_add_f32_e32 v203, v161, v203
	v_cndmask_b32_e64 v203, v203, v161, s[12:13]
	v_cndmask_b32_e64 v161, v202, v201, s[4:5]
	s_waitcnt lgkmcnt(0)
	v_add_f32_e32 v201, v219, v220
	v_cndmask_b32_e64 v201, v201, v219, s[8:9]
	ds_bpermute_b32 v221, v111, v203
	ds_bpermute_b32 v202, v101, v201
	ds_bpermute_b32 v220, v99, v197
	s_waitcnt lgkmcnt(2)
	v_add_f32_e32 v219, v203, v221
	s_waitcnt lgkmcnt(1)
	v_add_f32_e32 v202, v201, v202
	v_cndmask_b32_e64 v203, v219, v203, s[14:15]
	v_cndmask_b32_e64 v201, v202, v201, s[10:11]
	s_waitcnt lgkmcnt(0)
	v_fmac_f32_e32 v220, 0x3d800000, v218
	ds_bpermute_b32 v219, v112, v203
	ds_bpermute_b32 v202, v102, v201
	v_cndmask_b32_e64 v218, v220, v197, s[6:7]
	ds_bpermute_b32 v220, v100, v218
	s_waitcnt lgkmcnt(2)
	v_add_f32_e32 v219, v203, v219
	s_waitcnt lgkmcnt(1)
	v_add_f32_e32 v197, v201, v202
	v_cndmask_b32_e64 v201, v197, v201, s[12:13]
	v_cndmask_b32_e64 v197, v219, v203, s[4:5]
	s_waitcnt lgkmcnt(0)
	v_add_f32_e32 v203, v218, v220
	v_cndmask_b32_e64 v203, v203, v218, s[8:9]
	ds_bpermute_b32 v202, v111, v201
	ds_bpermute_b32 v218, v101, v203
	ds_bpermute_b32 v219, v99, v226
	s_waitcnt lgkmcnt(2)
	v_add_f32_e32 v202, v201, v202
	s_waitcnt lgkmcnt(1)
	v_add_f32_e32 v218, v203, v218
	v_cndmask_b32_e64 v201, v202, v201, s[14:15]
	v_cndmask_b32_e64 v203, v218, v203, s[10:11]
	s_waitcnt lgkmcnt(0)
	v_fmac_f32_e32 v219, 0x3d800000, v144
	ds_bpermute_b32 v202, v112, v201
	ds_bpermute_b32 v218, v102, v203
	v_cndmask_b32_e64 v219, v219, v226, s[6:7]
	ds_bpermute_b32 v220, v100, v219
	s_waitcnt lgkmcnt(2)
	v_add_f32_e32 v202, v201, v202
	s_waitcnt lgkmcnt(1)
	v_add_f32_e32 v144, v203, v218
	v_cndmask_b32_e64 v203, v144, v203, s[12:13]
	v_cndmask_b32_e64 v144, v202, v201, s[4:5]
	s_waitcnt lgkmcnt(0)
	v_add_f32_e32 v201, v219, v220
	v_cndmask_b32_e64 v201, v201, v219, s[8:9]
	ds_bpermute_b32 v218, v111, v203
	ds_bpermute_b32 v202, v101, v201
	ds_bpermute_b32 v219, v99, v198
	s_waitcnt lgkmcnt(2)
	v_add_f32_e32 v218, v203, v218
	s_waitcnt lgkmcnt(1)
	v_add_f32_e32 v202, v201, v202
	v_cndmask_b32_e64 v203, v218, v203, s[14:15]
	v_cndmask_b32_e64 v201, v202, v201, s[10:11]
	s_waitcnt lgkmcnt(0)
	v_fmac_f32_e32 v219, 0x3d800000, v142
	ds_bpermute_b32 v218, v112, v203
	ds_bpermute_b32 v202, v102, v201
	v_cndmask_b32_e64 v198, v219, v198, s[6:7]
	ds_bpermute_b32 v219, v100, v198
	s_waitcnt lgkmcnt(2)
	v_add_f32_e32 v218, v203, v218
	s_waitcnt lgkmcnt(1)
	v_add_f32_e32 v142, v201, v202
	v_cndmask_b32_e64 v201, v142, v201, s[12:13]
	v_cndmask_b32_e64 v142, v218, v203, s[4:5]
	s_waitcnt lgkmcnt(0)
	v_add_f32_e32 v203, v198, v219
	v_cndmask_b32_e64 v198, v203, v198, s[8:9]
	ds_bpermute_b32 v202, v111, v201
	ds_bpermute_b32 v203, v101, v198
	ds_bpermute_b32 v218, v99, v196
	s_waitcnt lgkmcnt(2)
	v_add_f32_e32 v202, v201, v202
	s_waitcnt lgkmcnt(1)
	v_add_f32_e32 v203, v198, v203
	v_cndmask_b32_e64 v201, v202, v201, s[14:15]
	v_cndmask_b32_e64 v198, v203, v198, s[10:11]
	s_waitcnt lgkmcnt(0)
	v_fmac_f32_e32 v218, 0x3d800000, v140
	ds_bpermute_b32 v202, v112, v201
	ds_bpermute_b32 v203, v102, v198
	v_cndmask_b32_e64 v196, v218, v196, s[6:7]
	ds_bpermute_b32 v218, v100, v196
	s_waitcnt lgkmcnt(2)
	v_add_f32_e32 v202, v201, v202
	s_waitcnt lgkmcnt(1)
	v_add_f32_e32 v140, v198, v203
	v_cndmask_b32_e64 v198, v140, v198, s[12:13]
	v_cndmask_b32_e64 v140, v202, v201, s[4:5]
	s_waitcnt lgkmcnt(0)
	v_add_f32_e32 v201, v196, v218
	ds_bpermute_b32 v203, v111, v198
	v_cndmask_b32_e64 v196, v201, v196, s[8:9]
	ds_bpermute_b32 v201, v101, v196
	s_waitcnt lgkmcnt(1)
	v_add_f32_e32 v202, v198, v203
	ds_bpermute_b32 v203, v99, v200
	s_waitcnt lgkmcnt(1)
	v_add_f32_e32 v201, v196, v201
	v_cndmask_b32_e64 v196, v201, v196, s[10:11]
	ds_bpermute_b32 v201, v102, v196
	v_cndmask_b32_e64 v198, v202, v198, s[14:15]
	ds_bpermute_b32 v202, v112, v198
	s_waitcnt lgkmcnt(2)
	v_fmac_f32_e32 v203, 0x3d800000, v138
	v_cndmask_b32_e64 v200, v203, v200, s[6:7]
	ds_bpermute_b32 v203, v100, v200
	s_waitcnt lgkmcnt(2)
	v_add_f32_e32 v138, v196, v201
	v_cndmask_b32_e64 v196, v138, v196, s[12:13]
	s_waitcnt lgkmcnt(1)
	v_add_f32_e32 v202, v198, v202
	ds_bpermute_b32 v201, v111, v196
	v_cndmask_b32_e64 v138, v202, v198, s[4:5]
	ds_bpermute_b32 v202, v99, v230
	s_waitcnt lgkmcnt(2)
	v_add_f32_e32 v198, v200, v203
	v_cndmask_b32_e64 v198, v198, v200, s[8:9]
	ds_bpermute_b32 v200, v101, v198
	s_waitcnt lgkmcnt(2)
; #define WSYNC() asm volatile("s_waitcnt lgkmcnt(0)" ::: "memory")
; __device__ __forceinline__ void gla_gates(const bf16* prow, const float* wg, const float* bg, int h, int lane, float (&bc)[32], LAS float* Wst) {
;     ...
;         for (int e = 0; e < 4; ++e) bc[4 * d4 + e] = (fminf(z[e], 0.f) - __logf(1.f + __expf(-fabsf(z[e])))) * (1.f / 16.f); }
;     WSYNC();
; #pragma unroll
;     for (int d = 0; d < 32; ++d) { float v = bc[d];
; #pragma unroll
;         for (int off = 1; off < 64; off <<= 1) { const float t = __shfl_up(v, off); if (lane >= off) v += t; }
;         bc[d] = v; }
	v_add_f32_e32 v201, v196, v201
	v_cndmask_b32_e64 v196, v201, v196, s[14:15]
	s_waitcnt lgkmcnt(1)
	v_fmac_f32_e32 v202, 0x3d800000, v239
	ds_bpermute_b32 v201, v112, v196
	v_cndmask_b32_e64 v202, v202, v230, s[6:7]
	ds_bpermute_b32 v203, v100, v202
	s_waitcnt lgkmcnt(2)
	v_add_f32_e32 v200, v198, v200
	v_cndmask_b32_e64 v198, v200, v198, s[10:11]
	ds_bpermute_b32 v200, v102, v198
	s_waitcnt lgkmcnt(2)
	v_add_f32_e32 v201, v196, v201
	v_cndmask_b32_e64 v196, v201, v196, s[4:5]
	s_waitcnt lgkmcnt(1)
	v_add_f32_e32 v201, v202, v203
	v_cndmask_b32_e64 v201, v201, v202, s[8:9]
	ds_bpermute_b32 v202, v101, v201
	s_waitcnt lgkmcnt(1)
	v_add_f32_e32 v200, v198, v200
	v_cndmask_b32_e64 v198, v200, v198, s[12:13]
	ds_bpermute_b32 v200, v111, v198
	ds_bpermute_b32 v203, v99, v132
	s_waitcnt lgkmcnt(2)
	v_add_f32_e32 v202, v201, v202
	v_cndmask_b32_e64 v201, v202, v201, s[10:11]
	ds_bpermute_b32 v202, v102, v201
	s_waitcnt lgkmcnt(2)
	v_add_f32_e32 v200, v198, v200
	v_cndmask_b32_e64 v198, v200, v198, s[14:15]
	s_waitcnt lgkmcnt(1)
	v_fmac_f32_e32 v203, 0x3d800000, v199
	ds_bpermute_b32 v200, v112, v198
	v_cndmask_b32_e64 v199, v203, v132, s[6:7]
	ds_bpermute_b32 v203, v100, v199
	s_waitcnt lgkmcnt(2)
	v_add_f32_e32 v132, v201, v202
	v_cndmask_b32_e64 v201, v132, v201, s[12:13]
	ds_bpermute_b32 v202, v111, v201
	s_waitcnt lgkmcnt(2)
	v_add_f32_e32 v200, v198, v200
	v_cndmask_b32_e64 v132, v200, v198, s[4:5]
	s_waitcnt lgkmcnt(1)
	v_add_f32_e32 v198, v199, v203
	v_cndmask_b32_e64 v198, v198, v199, s[8:9]
	ds_bpermute_b32 v199, v101, v198
	s_waitcnt lgkmcnt(1)
	v_add_f32_e32 v200, v201, v202
	ds_bpermute_b32 v202, v99, v113
	v_cndmask_b32_e64 v200, v200, v201, s[14:15]
	ds_bpermute_b32 v201, v112, v200
	s_waitcnt lgkmcnt(2)
	v_add_f32_e32 v199, v198, v199
	v_cndmask_b32_e64 v198, v199, v198, s[10:11]
	s_waitcnt lgkmcnt(1)
	v_fmac_f32_e32 v202, 0x3d800000, v136
	ds_bpermute_b32 v199, v102, v198
	v_cndmask_b32_e64 v136, v202, v113, s[6:7]
	ds_bpermute_b32 v202, v100, v136
	s_waitcnt lgkmcnt(2)
	v_add_f32_e32 v201, v200, v201
	s_waitcnt lgkmcnt(1)
	v_add_f32_e32 v113, v198, v199
	v_cndmask_b32_e64 v198, v113, v198, s[12:13]
	v_cndmask_b32_e64 v113, v201, v200, s[4:5]
	s_waitcnt lgkmcnt(0)
	v_add_f32_e32 v200, v136, v202
	v_cndmask_b32_e64 v136, v200, v136, s[8:9]
	ds_bpermute_b32 v199, v111, v198
	ds_bpermute_b32 v200, v101, v136
	ds_bpermute_b32 v201, v99, v106
	s_waitcnt lgkmcnt(2)
	v_add_f32_e32 v199, v198, v199
	s_waitcnt lgkmcnt(1)
	v_add_f32_e32 v200, v136, v200
	v_cndmask_b32_e64 v198, v199, v198, s[14:15]
	v_cndmask_b32_e64 v136, v200, v136, s[10:11]
	s_waitcnt lgkmcnt(0)
	v_fmac_f32_e32 v201, 0x3d800000, v128
	ds_bpermute_b32 v199, v112, v198
	ds_bpermute_b32 v200, v102, v136
	v_cndmask_b32_e64 v128, v201, v106, s[6:7]
	ds_bpermute_b32 v201, v100, v128
	s_waitcnt lgkmcnt(2)
	v_add_f32_e32 v199, v198, v199
	s_waitcnt lgkmcnt(1)
	v_add_f32_e32 v106, v136, v200
	v_cndmask_b32_e64 v136, v106, v136, s[12:13]
	v_cndmask_b32_e64 v106, v199, v198, s[4:5]
	s_waitcnt lgkmcnt(0)
	v_add_f32_e32 v198, v128, v201
	v_cndmask_b32_e64 v128, v198, v128, s[8:9]
	ds_bpermute_b32 v200, v111, v136
	ds_bpermute_b32 v198, v101, v128
	s_waitcnt lgkmcnt(1)
	v_add_f32_e32 v199, v136, v200
	s_waitcnt lgkmcnt(0)
	v_add_f32_e32 v198, v128, v198
	v_cndmask_b32_e64 v136, v199, v136, s[14:15]
	ds_bpermute_b32 v199, v99, v108
	v_cndmask_b32_e64 v128, v198, v128, s[10:11]
	ds_bpermute_b32 v198, v102, v128
	ds_bpermute_b32 v200, v112, v136
	s_waitcnt lgkmcnt(2)
	v_fmac_f32_e32 v199, 0x3d800000, v107
	v_cndmask_b32_e64 v107, v199, v108, s[6:7]
	s_waitcnt lgkmcnt(1)
	v_add_f32_e32 v198, v128, v198
	ds_bpermute_b32 v108, v100, v107
	v_cndmask_b32_e64 v128, v198, v128, s[12:13]
	ds_bpermute_b32 v198, v111, v128
	s_waitcnt lgkmcnt(2)
	v_add_f32_e32 v199, v136, v200
	s_waitcnt lgkmcnt(1)
	v_add_f32_e32 v108, v107, v108
	v_cndmask_b32_e64 v108, v108, v107, s[8:9]
	v_cndmask_b32_e64 v107, v199, v136, s[4:5]
	s_waitcnt lgkmcnt(0)
	v_add_f32_e32 v136, v128, v198
	ds_bpermute_b32 v198, v99, v105
	v_cndmask_b32_e64 v128, v136, v128, s[14:15]
	ds_bpermute_b32 v200, v101, v108
	s_waitcnt lgkmcnt(1)
	v_fmac_f32_e32 v198, 0x3d800000, v104
	v_cndmask_b32_e64 v104, v198, v105, s[6:7]
	ds_bpermute_b32 v105, v100, v104
	ds_bpermute_b32 v198, v112, v128
	s_waitcnt lgkmcnt(2)
	v_add_f32_e32 v136, v108, v200
	v_cndmask_b32_e64 v108, v136, v108, s[10:11]
	ds_bpermute_b32 v136, v102, v108
	s_waitcnt lgkmcnt(2)
	v_add_f32_e32 v105, v104, v105
	v_cndmask_b32_e64 v104, v105, v104, s[8:9]
	ds_bpermute_b32 v105, v101, v104
	s_waitcnt lgkmcnt(2)
	v_add_f32_e32 v198, v128, v198
	s_waitcnt lgkmcnt(1)
	v_add_f32_e32 v136, v108, v136
	v_cndmask_b32_e64 v108, v136, v108, s[12:13]
	ds_bpermute_b32 v136, v111, v108
	s_waitcnt lgkmcnt(1)
	v_add_f32_e32 v105, v104, v105
	v_cndmask_b32_e64 v199, v105, v104, s[10:11]
	v_cndmask_b32_e64 v104, v198, v128, s[4:5]
	ds_bpermute_b32 v128, v99, v103
	ds_bpermute_b32 v99, v99, v110
	s_waitcnt lgkmcnt(2)
	v_add_f32_e32 v136, v108, v136
	v_cndmask_b32_e64 v108, v136, v108, s[14:15]
	ds_bpermute_b32 v136, v112, v108
	s_waitcnt lgkmcnt(2)
	v_fmac_f32_e32 v128, 0x3d800000, v98
	v_cndmask_b32_e64 v98, v128, v103, s[6:7]
	s_waitcnt lgkmcnt(1)
	v_fmac_f32_e32 v99, 0x3d800000, v109
	ds_bpermute_b32 v103, v100, v98
	v_cndmask_b32_e64 v99, v99, v110, s[6:7]
	ds_bpermute_b32 v100, v100, v99
	ds_bpermute_b32 v200, v102, v199
	s_waitcnt lgkmcnt(3)
	v_add_f32_e32 v105, v108, v136
	s_waitcnt lgkmcnt(2)
	v_add_f32_e32 v103, v98, v103
	v_cndmask_b32_e64 v98, v103, v98, s[8:9]
	s_waitcnt lgkmcnt(1)
; #define LAS __attribute__((address_space(3)))
; __device__ __forceinline__ unsigned pk2(float lo, float hi) { const f32x2_ v = {lo, hi}; return __builtin_bit_cast(unsigned, __builtin_convertvector(v, bf16x2_)); }
; __device__ __forceinline__ void gla_gates(const bf16* prow, const float* wg, const float* bg, int h, int lane, float (&bc)[32], LAS float* Wst) {
;     ...
; #pragma unroll
;     for (int d = 0; d < 32; ++d) { float v = bc[d];
; #pragma unroll
;         for (int off = 1; off < 64; off <<= 1) { const float t = __shfl_up(v, off); if (lane >= off) v += t; }
;         bc[d] = v; }
; __device__ __forceinline__ void gla_out_unit(int u, const bf16* proj, const float* wg, const float* bg, const float* gn, const float* SP, bf16* MIXO, LAS unsigned char* wl, int lane) {
;     ...
;     { float k[32], q[32];
; #pragma unroll
;       for (int i = 0; i < 4; ++i) { unpack8(kraw[i], k + 8 * i); unpack8(qraw[i], q + 8 * i); }
; #pragma unroll
;       for (int d4 = 0; d4 < 8; ++d4) { float qq[4], kk[4];
; #pragma unroll
;           for (int e = 0; e < 4; ++e) { const int d = 4 * d4 + e; qq[e] = q[d] * 0.17677669529663687f * __expf(bc[d]); kk[e] = k[d] * __expf(-bc[d]); }
;           u32x2 wq, wk; wq.x = pk2(qq[0], qq[1]); wq.y = pk2(qq[2], qq[3]); wk.x = pk2(kk[0], kk[1]); wk.y = pk2(kk[2], kk[3]);
;           *(LAS u32x2*)(Qd + lane * 40 + 4 * d4) = wq; *(LAS u32x2*)(Kd + lane * 40 + 4 * d4) = wk; } }
	v_add_f32_e32 v100, v99, v100
	ds_bpermute_b32 v103, v101, v98
	v_cndmask_b32_e64 v99, v100, v99, s[8:9]
	ds_bpermute_b32 v100, v101, v99
	v_cndmask_b32_e64 v105, v105, v108, s[4:5]
	s_waitcnt lgkmcnt(2)
	v_add_f32_e32 v108, v199, v200
	s_waitcnt lgkmcnt(1)
	v_add_f32_e32 v103, v98, v103
	v_cndmask_b32_e64 v98, v103, v98, s[10:11]
	s_waitcnt lgkmcnt(0)
	v_add_f32_e32 v100, v99, v100
	ds_bpermute_b32 v103, v102, v98
	v_cndmask_b32_e64 v99, v100, v99, s[10:11]
	ds_bpermute_b32 v100, v102, v99
	v_cndmask_b32_e64 v108, v108, v199, s[12:13]
	ds_bpermute_b32 v109, v111, v108
	s_waitcnt lgkmcnt(2)
	v_add_f32_e32 v102, v98, v103
	v_cndmask_b32_e64 v98, v102, v98, s[12:13]
	s_waitcnt lgkmcnt(1)
	v_add_f32_e32 v100, v99, v100
	ds_bpermute_b32 v102, v111, v98
	v_cndmask_b32_e64 v99, v100, v99, s[12:13]
	ds_bpermute_b32 v100, v111, v99
	s_waitcnt lgkmcnt(2)
	v_add_f32_e32 v101, v108, v109
	v_cndmask_b32_e64 v101, v101, v108, s[14:15]
	s_waitcnt lgkmcnt(1)
	v_add_f32_e32 v102, v98, v102
	ds_bpermute_b32 v103, v112, v101
	v_cndmask_b32_e64 v98, v102, v98, s[14:15]
	s_waitcnt lgkmcnt(1)
	v_add_f32_e32 v100, v99, v100
	ds_bpermute_b32 v102, v112, v98
	v_cndmask_b32_e64 v99, v100, v99, s[14:15]
	ds_bpermute_b32 v100, v112, v99
	s_waitcnt lgkmcnt(2)
	v_add_f32_e32 v103, v101, v103
	v_cndmask_b32_e64 v110, v103, v101, s[4:5]
	s_waitcnt lgkmcnt(1)
	v_add_f32_e32 v101, v98, v102
	v_cndmask_b32_e64 v111, v101, v98, s[4:5]
	s_waitcnt lgkmcnt(0)
	v_add_f32_e32 v98, v99, v100
	v_cndmask_b32_e64 v112, v98, v99, s[4:5]
	v_mul_f32_e32 v99, 0xbfb8aa3b, v124
	v_mul_f32_e32 v98, 0x3fb8aa3b, v124
	v_exp_f32_e32 v100, v99
	v_mul_f32_e32 v99, 0x3fb8aa3b, v126
	v_exp_f32_e32 v98, v98
	v_exp_f32_e32 v99, v99
	v_lshlrev_b32_e32 v102, 16, v94
	v_and_b32_e32 v103, 0xffff0000, v94
	v_mul_f32_e32 v94, 0xbfb8aa3b, v126
	v_exp_f32_e32 v101, v94
	v_pk_mul_f32 v[102:103], v[102:103], s[54:55] op_sel_hi:[1,0]
	v_lshlrev_b32_e32 v108, 16, v95
	v_pk_mul_f32 v[98:99], v[102:103], v[98:99]
	v_lshlrev_b32_e32 v102, 16, v90
	v_and_b32_e32 v103, 0xffff0000, v90
	v_mul_f32_e32 v90, 0x3fb8aa3b, v130
	v_pk_mul_f32 v[100:101], v[100:101], v[102:103]
	v_exp_f32_e32 v102, v90
	v_mul_f32_e32 v90, 0xbfb8aa3b, v130
	v_exp_f32_e32 v94, v90
	v_mul_f32_e32 v90, 0x3fb8aa3b, v134
	v_exp_f32_e32 v103, v90
	v_mul_f32_e32 v90, 0xbfb8aa3b, v134
	v_and_b32_e32 v109, 0xffff0000, v95
	v_exp_f32_e32 v95, v90
	v_pk_mul_f32 v[108:109], v[108:109], s[54:55] op_sel_hi:[1,0]
	v_lshlrev_b32_e32 v90, 16, v91
	v_and_b32_e32 v91, 0xffff0000, v91
	v_pk_mul_f32 v[102:103], v[108:109], v[102:103]
	v_pk_mul_f32 v[108:109], v[94:95], v[90:91]
	v_cvt_pk_bf16_f32 v90, v98, v99
	v_mul_f32_e32 v99, 0xbfb8aa3b, v158
	v_cvt_pk_bf16_f32 v94, v100, v101
	v_mul_f32_e32 v98, 0x3fb8aa3b, v158
	v_exp_f32_e32 v100, v99
	v_mul_f32_e32 v99, 0x3fb8aa3b, v159
	v_cvt_pk_bf16_f32 v91, v102, v103
	v_exp_f32_e32 v98, v98
	v_exp_f32_e32 v99, v99
	v_lshlrev_b32_e32 v102, 16, v96
	v_and_b32_e32 v103, 0xffff0000, v96
	v_mul_f32_e32 v96, 0xbfb8aa3b, v159
	v_exp_f32_e32 v101, v96
	v_pk_mul_f32 v[102:103], v[102:103], s[54:55] op_sel_hi:[1,0]
	v_cvt_pk_bf16_f32 v95, v108, v109
	v_pk_mul_f32 v[98:99], v[102:103], v[98:99]
	v_lshlrev_b32_e32 v102, 16, v92
	v_and_b32_e32 v103, 0xffff0000, v92
	v_mul_f32_e32 v92, 0x3fb8aa3b, v156
	v_pk_mul_f32 v[100:101], v[100:101], v[102:103]
	v_exp_f32_e32 v102, v92
	v_mul_f32_e32 v92, 0xbfb8aa3b, v156
	v_exp_f32_e32 v96, v92
	v_mul_f32_e32 v92, 0x3fb8aa3b, v157
	v_exp_f32_e32 v103, v92
	v_mul_f32_e32 v92, 0xbfb8aa3b, v157
	v_lshlrev_b32_e32 v108, 16, v97
	v_and_b32_e32 v109, 0xffff0000, v97
	v_exp_f32_e32 v97, v92
	v_pk_mul_f32 v[108:109], v[108:109], s[54:55] op_sel_hi:[1,0]
	v_lshlrev_b32_e32 v92, 16, v93
	v_pk_mul_f32 v[102:103], v[108:109], v[102:103]
	v_and_b32_e32 v93, 0xffff0000, v93
	v_pk_mul_f32 v[108:109], v[96:97], v[92:93]
	v_cvt_pk_bf16_f32 v92, v98, v99
	v_cvt_pk_bf16_f32 v93, v102, v103
	v_cvt_pk_bf16_f32 v96, v100, v101
	v_cvt_pk_bf16_f32 v97, v108, v109
	ds_write_b128 v143, v[90:93]
	ds_write_b128 v143, v[94:97] offset:5120
	v_mul_f32_e32 v91, 0xbfb8aa3b, v160
	v_mul_f32_e32 v90, 0x3fb8aa3b, v160
	v_exp_f32_e32 v92, v91
	v_mul_f32_e32 v91, 0x3fb8aa3b, v152
	v_exp_f32_e32 v90, v90
	v_exp_f32_e32 v91, v91
	v_lshlrev_b32_e32 v94, 16, v86
	v_and_b32_e32 v95, 0xffff0000, v86
	v_mul_f32_e32 v86, 0xbfb8aa3b, v152
	v_exp_f32_e32 v93, v86
	v_pk_mul_f32 v[94:95], v[94:95], s[54:55] op_sel_hi:[1,0]
	v_lshlrev_b32_e32 v96, 16, v87
	v_pk_mul_f32 v[90:91], v[94:95], v[90:91]
	v_lshlrev_b32_e32 v94, 16, v82
	v_and_b32_e32 v95, 0xffff0000, v82
	v_mul_f32_e32 v82, 0x3fb8aa3b, v154
	v_pk_mul_f32 v[92:93], v[92:93], v[94:95]
	v_exp_f32_e32 v94, v82
	v_mul_f32_e32 v82, 0xbfb8aa3b, v154
	v_exp_f32_e32 v86, v82
	v_mul_f32_e32 v82, 0x3fb8aa3b, v150
	v_exp_f32_e32 v95, v82
	v_mul_f32_e32 v82, 0xbfb8aa3b, v150
	v_and_b32_e32 v97, 0xffff0000, v87
	v_exp_f32_e32 v87, v82
	v_pk_mul_f32 v[96:97], v[96:97], s[54:55] op_sel_hi:[1,0]
	v_lshlrev_b32_e32 v82, 16, v83
	v_and_b32_e32 v83, 0xffff0000, v83
	v_pk_mul_f32 v[94:95], v[96:97], v[94:95]
	v_pk_mul_f32 v[96:97], v[86:87], v[82:83]
	v_cvt_pk_bf16_f32 v82, v90, v91
	v_mul_f32_e32 v91, 0xbfb8aa3b, v148
	v_cvt_pk_bf16_f32 v86, v92, v93
	v_mul_f32_e32 v90, 0x3fb8aa3b, v148
	v_exp_f32_e32 v92, v91
	v_mul_f32_e32 v91, 0x3fb8aa3b, v153
	v_cvt_pk_bf16_f32 v83, v94, v95
	v_exp_f32_e32 v90, v90
	v_exp_f32_e32 v91, v91
	v_lshlrev_b32_e32 v94, 16, v88
	v_and_b32_e32 v95, 0xffff0000, v88
	v_mul_f32_e32 v88, 0xbfb8aa3b, v153
	v_exp_f32_e32 v93, v88
	v_pk_mul_f32 v[94:95], v[94:95], s[54:55] op_sel_hi:[1,0]
	v_cvt_pk_bf16_f32 v87, v96, v97
	v_pk_mul_f32 v[90:91], v[94:95], v[90:91]
; #define LAS __attribute__((address_space(3)))
; __device__ __forceinline__ unsigned pk2(float lo, float hi) { const f32x2_ v = {lo, hi}; return __builtin_bit_cast(unsigned, __builtin_convertvector(v, bf16x2_)); }
; __device__ __forceinline__ void gla_out_unit(int u, const bf16* proj, const float* wg, const float* bg, const float* gn, const float* SP, bf16* MIXO, LAS unsigned char* wl, int lane) {
;     ...
;     { float k[32], q[32];
; #pragma unroll
;       for (int i = 0; i < 4; ++i) { unpack8(kraw[i], k + 8 * i); unpack8(qraw[i], q + 8 * i); }
; #pragma unroll
;       for (int d4 = 0; d4 < 8; ++d4) { float qq[4], kk[4];
; #pragma unroll
;           for (int e = 0; e < 4; ++e) { const int d = 4 * d4 + e; qq[e] = q[d] * 0.17677669529663687f * __expf(bc[d]); kk[e] = k[d] * __expf(-bc[d]); }
;           u32x2 wq, wk; wq.x = pk2(qq[0], qq[1]); wq.y = pk2(qq[2], qq[3]); wk.x = pk2(kk[0], kk[1]); wk.y = pk2(kk[2], kk[3]);
;           *(LAS u32x2*)(Qd + lane * 40 + 4 * d4) = wq; *(LAS u32x2*)(Kd + lane * 40 + 4 * d4) = wk; } }
	v_lshlrev_b32_e32 v94, 16, v84
	v_and_b32_e32 v95, 0xffff0000, v84
	v_mul_f32_e32 v84, 0x3fb8aa3b, v146
	v_pk_mul_f32 v[92:93], v[92:93], v[94:95]
	v_exp_f32_e32 v94, v84
	v_mul_f32_e32 v84, 0xbfb8aa3b, v146
	v_exp_f32_e32 v88, v84
	v_mul_f32_e32 v84, 0x3fb8aa3b, v155
	v_exp_f32_e32 v95, v84
	v_mul_f32_e32 v84, 0xbfb8aa3b, v155
	v_lshlrev_b32_e32 v96, 16, v89
	v_and_b32_e32 v97, 0xffff0000, v89
	v_exp_f32_e32 v89, v84
	v_pk_mul_f32 v[96:97], v[96:97], s[54:55] op_sel_hi:[1,0]
	v_lshlrev_b32_e32 v84, 16, v85
	v_pk_mul_f32 v[94:95], v[96:97], v[94:95]
	v_and_b32_e32 v85, 0xffff0000, v85
	v_pk_mul_f32 v[96:97], v[88:89], v[84:85]
	v_cvt_pk_bf16_f32 v84, v90, v91
	v_cvt_pk_bf16_f32 v85, v94, v95
	v_cvt_pk_bf16_f32 v88, v92, v93
	v_cvt_pk_bf16_f32 v89, v96, v97
	ds_write_b128 v143, v[82:85] offset:16
	ds_write_b128 v143, v[86:89] offset:5136
	v_mul_f32_e32 v83, 0xbfb8aa3b, v161
	v_mul_f32_e32 v82, 0x3fb8aa3b, v161
	v_exp_f32_e32 v84, v83
	v_mul_f32_e32 v83, 0x3fb8aa3b, v197
	v_exp_f32_e32 v82, v82
	v_exp_f32_e32 v83, v83
	v_lshlrev_b32_e32 v86, 16, v78
	v_and_b32_e32 v87, 0xffff0000, v78
	v_mul_f32_e32 v78, 0xbfb8aa3b, v197
	v_exp_f32_e32 v85, v78
	v_pk_mul_f32 v[86:87], v[86:87], s[54:55] op_sel_hi:[1,0]
	v_lshlrev_b32_e32 v88, 16, v79
	v_pk_mul_f32 v[82:83], v[86:87], v[82:83]
	v_lshlrev_b32_e32 v86, 16, v74
	v_and_b32_e32 v87, 0xffff0000, v74
	v_mul_f32_e32 v74, 0x3fb8aa3b, v144
	v_pk_mul_f32 v[84:85], v[84:85], v[86:87]
	v_exp_f32_e32 v86, v74
	v_mul_f32_e32 v74, 0xbfb8aa3b, v144
	v_exp_f32_e32 v78, v74
	v_mul_f32_e32 v74, 0x3fb8aa3b, v142
	v_exp_f32_e32 v87, v74
	v_mul_f32_e32 v74, 0xbfb8aa3b, v142
	v_and_b32_e32 v89, 0xffff0000, v79
	v_exp_f32_e32 v79, v74
	v_pk_mul_f32 v[88:89], v[88:89], s[54:55] op_sel_hi:[1,0]
	v_lshlrev_b32_e32 v74, 16, v75
	v_and_b32_e32 v75, 0xffff0000, v75
	v_pk_mul_f32 v[86:87], v[88:89], v[86:87]
	v_pk_mul_f32 v[88:89], v[78:79], v[74:75]
	v_cvt_pk_bf16_f32 v74, v82, v83
	v_mul_f32_e32 v83, 0xbfb8aa3b, v140
	v_cvt_pk_bf16_f32 v78, v84, v85
	v_mul_f32_e32 v82, 0x3fb8aa3b, v140
	v_exp_f32_e32 v84, v83
	v_mul_f32_e32 v83, 0x3fb8aa3b, v138
	v_cvt_pk_bf16_f32 v75, v86, v87
	v_exp_f32_e32 v82, v82
	v_exp_f32_e32 v83, v83
	v_lshlrev_b32_e32 v86, 16, v80
	v_and_b32_e32 v87, 0xffff0000, v80
	v_mul_f32_e32 v80, 0xbfb8aa3b, v138
	v_exp_f32_e32 v85, v80
	v_pk_mul_f32 v[86:87], v[86:87], s[54:55] op_sel_hi:[1,0]
	v_cvt_pk_bf16_f32 v79, v88, v89
	v_pk_mul_f32 v[82:83], v[86:87], v[82:83]
	v_lshlrev_b32_e32 v86, 16, v76
	v_and_b32_e32 v87, 0xffff0000, v76
	v_mul_f32_e32 v76, 0x3fb8aa3b, v196
	v_pk_mul_f32 v[84:85], v[84:85], v[86:87]
	v_exp_f32_e32 v86, v76
	v_mul_f32_e32 v76, 0xbfb8aa3b, v196
	v_exp_f32_e32 v80, v76
	v_mul_f32_e32 v76, 0x3fb8aa3b, v132
	v_exp_f32_e32 v87, v76
	v_mul_f32_e32 v76, 0xbfb8aa3b, v132
	v_lshlrev_b32_e32 v88, 16, v81
	v_and_b32_e32 v89, 0xffff0000, v81
	v_exp_f32_e32 v81, v76
	v_pk_mul_f32 v[88:89], v[88:89], s[54:55] op_sel_hi:[1,0]
	v_lshlrev_b32_e32 v76, 16, v77
	v_pk_mul_f32 v[86:87], v[88:89], v[86:87]
	v_and_b32_e32 v77, 0xffff0000, v77
	v_pk_mul_f32 v[88:89], v[80:81], v[76:77]
	v_cvt_pk_bf16_f32 v76, v82, v83
	v_cvt_pk_bf16_f32 v77, v86, v87
	v_cvt_pk_bf16_f32 v80, v84, v85
	v_cvt_pk_bf16_f32 v81, v88, v89
	ds_write_b128 v143, v[74:77] offset:32
	ds_write_b128 v143, v[78:81] offset:5152
	v_mul_f32_e32 v75, 0xbfb8aa3b, v113
	v_mul_f32_e32 v74, 0x3fb8aa3b, v113
	v_exp_f32_e32 v76, v75
	v_mul_f32_e32 v75, 0x3fb8aa3b, v106
	v_exp_f32_e32 v74, v74
	v_exp_f32_e32 v75, v75
	v_lshlrev_b32_e32 v78, 16, v70
	v_and_b32_e32 v79, 0xffff0000, v70
	v_mul_f32_e32 v70, 0xbfb8aa3b, v106
	v_exp_f32_e32 v77, v70
	v_pk_mul_f32 v[78:79], v[78:79], s[54:55] op_sel_hi:[1,0]
	v_lshlrev_b32_e32 v80, 16, v71
	v_pk_mul_f32 v[74:75], v[78:79], v[74:75]
	v_lshlrev_b32_e32 v78, 16, v66
	v_and_b32_e32 v79, 0xffff0000, v66
	v_mul_f32_e32 v66, 0x3fb8aa3b, v107
	v_pk_mul_f32 v[76:77], v[76:77], v[78:79]
	v_exp_f32_e32 v78, v66
	v_mul_f32_e32 v66, 0xbfb8aa3b, v107
	v_exp_f32_e32 v70, v66
	v_mul_f32_e32 v66, 0x3fb8aa3b, v104
	v_exp_f32_e32 v79, v66
	v_mul_f32_e32 v66, 0xbfb8aa3b, v104
	v_and_b32_e32 v81, 0xffff0000, v71
	v_exp_f32_e32 v71, v66
	v_pk_mul_f32 v[80:81], v[80:81], s[54:55] op_sel_hi:[1,0]
	v_lshlrev_b32_e32 v66, 16, v67
	v_and_b32_e32 v67, 0xffff0000, v67
	v_pk_mul_f32 v[78:79], v[80:81], v[78:79]
	v_pk_mul_f32 v[80:81], v[70:71], v[66:67]
	v_cvt_pk_bf16_f32 v66, v74, v75
	v_mul_f32_e32 v75, 0xbfb8aa3b, v105
	v_cvt_pk_bf16_f32 v70, v76, v77
	v_mul_f32_e32 v74, 0x3fb8aa3b, v105
	v_exp_f32_e32 v76, v75
	v_mul_f32_e32 v75, 0x3fb8aa3b, v110
	v_cvt_pk_bf16_f32 v67, v78, v79
	v_exp_f32_e32 v74, v74
	v_exp_f32_e32 v75, v75
	v_lshlrev_b32_e32 v78, 16, v72
	v_and_b32_e32 v79, 0xffff0000, v72
	v_mul_f32_e32 v72, 0xbfb8aa3b, v110
	v_exp_f32_e32 v77, v72
	v_pk_mul_f32 v[78:79], v[78:79], s[54:55] op_sel_hi:[1,0]
	v_cvt_pk_bf16_f32 v71, v80, v81
	v_pk_mul_f32 v[74:75], v[78:79], v[74:75]
	v_lshlrev_b32_e32 v78, 16, v68
	v_and_b32_e32 v79, 0xffff0000, v68
	v_mul_f32_e32 v68, 0x3fb8aa3b, v111
	v_pk_mul_f32 v[76:77], v[76:77], v[78:79]
	v_exp_f32_e32 v78, v68
	v_mul_f32_e32 v68, 0xbfb8aa3b, v111
	v_exp_f32_e32 v72, v68
	v_mul_f32_e32 v68, 0x3fb8aa3b, v112
	v_exp_f32_e32 v79, v68
	v_mul_f32_e32 v68, 0xbfb8aa3b, v112
	v_lshlrev_b32_e32 v80, 16, v73
	v_and_b32_e32 v81, 0xffff0000, v73
	v_exp_f32_e32 v73, v68
	v_pk_mul_f32 v[80:81], v[80:81], s[54:55] op_sel_hi:[1,0]
	v_lshlrev_b32_e32 v68, 16, v69
	v_pk_mul_f32 v[78:79], v[80:81], v[78:79]
	v_and_b32_e32 v69, 0xffff0000, v69
	v_pk_mul_f32 v[80:81], v[72:73], v[68:69]
	v_cvt_pk_bf16_f32 v68, v74, v75
	v_cvt_pk_bf16_f32 v69, v78, v79
	v_cvt_pk_bf16_f32 v72, v76, v77
; #define LAS __attribute__((address_space(3)))
; __device__ __forceinline__ unsigned pk2(float lo, float hi) { const f32x2_ v = {lo, hi}; return __builtin_bit_cast(unsigned, __builtin_convertvector(v, bf16x2_)); }
; #define MFMA16(a, b, c) __builtin_amdgcn_mfma_f32_16x16x32_bf16((a), (b), (c), 0, 0, 0)
; __device__ __forceinline__ void gla_stage_vt(const u32x4 (&vraw)[8], LAS bf16* VT, int lane) {
; #pragma unroll
;     for (int i = 0; i < 8; ++i) { const u32x4 w = vraw[i]; const unsigned ww[4] = {w.x, w.y, w.z, w.w};
; #pragma unroll
;         for (int e = 0; e < 4; ++e) { VT[(8 * i + 2 * e) * 68 + lane] = (bf16)(ww[e] & 0xffffu); VT[(8 * i + 2 * e + 1) * 68 + lane] = (bf16)(ww[e] >> 16); } }
; }
; __device__ __forceinline__ void gla_out_unit(int u, const bf16* proj, const float* wg, const float* bg, const float* gn, const float* SP, bf16* MIXO, LAS unsigned char* wl, int lane) {
;     ...
;     bf16x8 qf[4], kf[4];
; #pragma unroll
;     for (int t = 0; t < 4; ++t) { qf[t] = *(const LAS bf16x8*)(Qd + (t * 16 + fr) * 40 + quad * 8); kf[t] = *(const LAS bf16x8*)(Kd + (t * 16 + fr) * 40 + quad * 8); }
;     bf16x8 pf[4][2];
; #pragma unroll
;     for (int qb = 0; qb < 4; ++qb)
; #pragma unroll
;         for (int ks = 0; ks < 2; ++ks) { if (ks > (qb >> 1)) continue;
;             const f32x4 z = {0.f, 0.f, 0.f, 0.f}; f32x4 s0 = MFMA16(kf[2 * ks], qf[qb], z), s1 = z;
;             if (2 * ks + 1 <= qb) s1 = MFMA16(kf[2 * ks + 1], qf[qb], z);
; #pragma unroll
;             for (int j = 0; j < 4; ++j) { if (2 * ks == qb && quad * 4 + j > fr) s0[j] = 0.f; if (2 * ks + 1 == qb && quad * 4 + j > fr) s1[j] = 0.f; }
;             u32x4 w; w.x = pk2(s0[0], s0[1]); w.y = pk2(s0[2], s0[3]); w.z = pk2(s1[0], s1[1]); w.w = pk2(s1[2], s1[3]); pf[qb][ks] = __builtin_bit_cast(bf16x8, w); }
;     f32x4 o[4][4];
; #pragma unroll
;     for (int qb = 0; qb < 4; ++qb)
; #pragma unroll
;         for (int vb = 0; vb < 4; ++vb) o[qb][vb] = (f32x4){0.f, 0.f, 0.f, 0.f};
; #pragma unroll
;     for (int ks = 0; ks < 2; ++ks)
; #pragma unroll
;         for (int vb = 0; vb < 4; ++vb) { const LAS bf16* p = VT + (vb * 16 + fr) * 68 + ks * 32 + quad * 4; const bf16x8 vf = mk_frag(*(const LAS u32x2*)p, *(const LAS u32x2*)(p + 16));
; #pragma unroll
;             for (int qb = 0; qb < 4; ++qb) { if (qb >= 2 * ks) o[qb][vb] = MFMA16(pf[qb][ks], vf, o[qb][vb]); } }
	v_cvt_pk_bf16_f32 v73, v80, v81
	ds_write_b128 v143, v[66:69] offset:48
	ds_write_b128 v143, v[70:73] offset:5168
	ds_write_b16 v145, v62 offset:10240
	ds_write_b16_d16_hi v145, v62 offset:10376
	ds_write_b16 v145, v63 offset:10512
	ds_write_b16_d16_hi v145, v63 offset:10648
	ds_write_b16 v145, v64 offset:10784
	ds_write_b16_d16_hi v145, v64 offset:10920
	ds_write_b16 v145, v65 offset:11056
	ds_write_b16_d16_hi v145, v65 offset:11192
	ds_write_b16 v145, v58 offset:11328
	ds_write_b16_d16_hi v145, v58 offset:11464
	ds_write_b16 v145, v59 offset:11600
	ds_write_b16_d16_hi v145, v59 offset:11736
	ds_write_b16 v145, v60 offset:11872
	ds_write_b16_d16_hi v145, v60 offset:12008
	ds_write_b16 v145, v61 offset:12144
	ds_write_b16_d16_hi v145, v61 offset:12280
	ds_write_b16 v145, v54 offset:12416
	ds_write_b16_d16_hi v145, v54 offset:12552
	ds_write_b16 v145, v55 offset:12688
	ds_write_b16_d16_hi v145, v55 offset:12824
	ds_write_b16 v145, v56 offset:12960
	ds_write_b16_d16_hi v145, v56 offset:13096
	ds_write_b16 v145, v57 offset:13232
	ds_write_b16_d16_hi v145, v57 offset:13368
	ds_write_b16 v145, v50 offset:13504
	ds_write_b16_d16_hi v145, v50 offset:13640
	ds_write_b16 v145, v51 offset:13776
	ds_write_b16_d16_hi v145, v51 offset:13912
	ds_write_b16 v145, v52 offset:14048
	ds_write_b16_d16_hi v145, v52 offset:14184
	ds_write_b16 v145, v53 offset:14320
	ds_write_b16_d16_hi v145, v53 offset:14456
	ds_write_b16 v145, v46 offset:14592
	ds_write_b16_d16_hi v145, v46 offset:14728
	ds_write_b16 v145, v47 offset:14864
	ds_write_b16_d16_hi v145, v47 offset:15000
	ds_write_b16 v145, v48 offset:15136
	ds_write_b16_d16_hi v145, v48 offset:15272
	ds_write_b16 v145, v49 offset:15408
	ds_write_b16_d16_hi v145, v49 offset:15544
	ds_write_b16 v145, v42 offset:15680
	ds_write_b16_d16_hi v145, v42 offset:15816
	ds_write_b16 v145, v43 offset:15952
	ds_write_b16_d16_hi v145, v43 offset:16088
	ds_write_b16 v145, v44 offset:16224
	ds_write_b16_d16_hi v145, v44 offset:16360
	ds_write_b16 v145, v45 offset:16496
	ds_write_b16_d16_hi v145, v45 offset:16632
	ds_write_b16 v145, v38 offset:16768
	ds_write_b16_d16_hi v145, v38 offset:16904
	ds_write_b16 v145, v39 offset:17040
	ds_write_b16_d16_hi v145, v39 offset:17176
	ds_write_b16 v145, v40 offset:17312
	ds_write_b16_d16_hi v145, v40 offset:17448
	ds_write_b16 v145, v41 offset:17584
	ds_write_b16_d16_hi v145, v41 offset:17720
	ds_write_b16 v145, v34 offset:17856
	ds_write_b16_d16_hi v145, v34 offset:17992
	ds_write_b16 v145, v35 offset:18128
	ds_write_b16_d16_hi v145, v35 offset:18264
	ds_write_b16 v145, v36 offset:18400
	ds_write_b16_d16_hi v145, v36 offset:18536
	ds_write_b16 v145, v37 offset:18672
	ds_write_b16_d16_hi v145, v37 offset:18808
	s_waitcnt lgkmcnt(0)
	ds_read_b128 v[34:37], v147 offset:5120
	ds_read_b128 v[94:97], v147
	ds_read_b128 v[78:81], v149
	ds_read_b128 v[42:45], v149 offset:5120
	s_waitcnt lgkmcnt(2)
	v_mfma_f32_16x16x32_bf16 v[38:41], v[34:37], v[94:97], 0
	ds_read_b128 v[62:65], v151
	ds_read_b128 v[54:57], v151 offset:5120
	ds_read_b128 v[46:49], v162
	v_mov_b32_e32 v70, s35
	v_mov_b32_e32 v86, s35
	s_waitcnt lgkmcnt(3)
	v_mfma_f32_16x16x32_bf16 v[58:61], v[42:45], v[78:81], 0
	s_nop 0
	v_cndmask_b32_e64 v74, v38, v70, s[16:17]
	v_cndmask_b32_e64 v38, v74, v38, s[18:19]
	ds_read_b128 v[66:69], v162 offset:5120
	v_mfma_f32_16x16x32_bf16 v[50:53], v[34:37], v[78:81], 0
	s_nop 2
	v_cndmask_b32_e64 v86, v58, v86, s[16:17]
	v_cndmask_b32_e64 v39, 0, v39, s[18:19]
	v_cndmask_b32_e64 v40, v40, 0, s[20:21]
	s_waitcnt lgkmcnt(3)
	v_mfma_f32_16x16x32_bf16 v[70:73], v[34:37], v[62:65], 0
	v_cndmask_b32_e64 v41, v41, 0, s[22:23]
	v_cndmask_b32_e64 v86, v86, v58, s[18:19]
	v_cndmask_b32_e64 v87, 0, v59, s[18:19]
	v_mfma_f32_16x16x32_bf16 v[74:77], v[42:45], v[62:65], 0
	v_cndmask_b32_e64 v88, v60, 0, s[20:21]
	v_cndmask_b32_e64 v89, v61, 0, s[22:23]
	v_add_u32_e32 v126, 0x2800, v164
	s_waitcnt lgkmcnt(1)
	v_mfma_f32_16x16x32_bf16 v[34:37], v[34:37], v[46:49], 0
	v_cvt_pk_bf16_f32 v38, v38, v39
	v_cvt_pk_bf16_f32 v39, v40, v41
	v_mov_b32_e32 v40, v1
	v_mfma_f32_16x16x32_bf16 v[42:45], v[42:45], v[46:49], 0
	v_mov_b32_e32 v41, v1
	v_cvt_pk_bf16_f32 v50, v50, v51
	v_cvt_pk_bf16_f32 v51, v52, v53
	v_mfma_f32_16x16x32_bf16 v[82:85], v[54:57], v[62:65], 0
	ds_read2_b64 v[58:61], v126 offset1:4
	v_cvt_pk_bf16_f32 v52, v86, v87
	v_cvt_pk_bf16_f32 v53, v88, v89
	v_cvt_pk_bf16_f32 v70, v70, v71
	v_cvt_pk_bf16_f32 v71, v72, v73
	v_cvt_pk_bf16_f32 v72, v74, v75
	v_cvt_pk_bf16_f32 v73, v76, v77
	v_cvt_pk_bf16_f32 v34, v34, v35
	v_cvt_pk_bf16_f32 v35, v36, v37
	v_cvt_pk_bf16_f32 v36, v42, v43
	v_cvt_pk_bf16_f32 v37, v44, v45
	v_mov_b32_e32 v124, s35
	v_cndmask_b32_e64 v124, v82, v124, s[16:17]
	v_add_u32_e32 v128, 0x3000, v164
	v_add_u32_e32 v130, 0x3800, v164
	v_cndmask_b32_e64 v82, v124, v82, s[18:19]
	v_add_u32_e32 v124, 0x2800, v165
	s_waitcnt lgkmcnt(0)
	v_mfma_f32_16x16x32_bf16 v[86:89], v[38:41], v[58:61], 0
	ds_read2_b64 v[110:113], v130 offset0:32 offset1:36
	ds_read2_b64 v[200:203], v124 offset1:4
	v_cndmask_b32_e64 v83, 0, v83, s[18:19]
	v_mfma_f32_16x16x32_bf16 v[74:77], v[50:53], v[58:61], 0
	v_cndmask_b32_e64 v84, v84, 0, s[20:21]
	v_cndmask_b32_e64 v85, v85, 0, s[22:23]
	v_cvt_pk_bf16_f32 v82, v82, v83
	v_mfma_f32_16x16x32_bf16 v[90:93], v[70:73], v[58:61], 0
	v_cvt_pk_bf16_f32 v83, v84, v85
	v_mov_b32_e32 v84, v1
	v_mov_b32_e32 v85, v1
	v_mfma_f32_16x16x32_bf16 v[42:45], v[34:37], v[58:61], 0
	ds_read2_b64 v[58:61], v128 offset0:16 offset1:20
	v_mfma_f32_16x16x32_bf16 v[66:69], v[66:69], v[46:49], 0
	v_mfma_f32_16x16x32_bf16 v[54:57], v[54:57], v[46:49], 0
	s_waitcnt lgkmcnt(0)
; #define LAS __attribute__((address_space(3)))
; __device__ __forceinline__ unsigned pk2(float lo, float hi) { const f32x2_ v = {lo, hi}; return __builtin_bit_cast(unsigned, __builtin_convertvector(v, bf16x2_)); }
; #define WSYNC() asm volatile("s_waitcnt lgkmcnt(0)" ::: "memory")
; #define MFMA16(a, b, c) __builtin_amdgcn_mfma_f32_16x16x32_bf16((a), (b), (c), 0, 0, 0)
; __device__ __forceinline__ void gla_out_unit(int u, const bf16* proj, const float* wg, const float* bg, const float* gn, const float* SP, bf16* MIXO, LAS unsigned char* wl, int lane) {
;     ...
;     for (int ks = 0; ks < 2; ++ks)
; #pragma unroll
;         for (int vb = 0; vb < 4; ++vb) { const LAS bf16* p = VT + (vb * 16 + fr) * 68 + ks * 32 + quad * 4; const bf16x8 vf = mk_frag(*(const LAS u32x2*)p, *(const LAS u32x2*)(p + 16));
; #pragma unroll
;             for (int qb = 0; qb < 4; ++qb) { if (qb >= 2 * ks) o[qb][vb] = MFMA16(pf[qb][ks], vf, o[qb][vb]); } }
;     WSYNC();
;     { LAS bf16* SPT = Kd;
; #pragma unroll
;       for (int d = 0; d < 32; ++d) SPT[lane * 40 + d] = (bf16)(pk2(spv[d], 0.f) & 0xffffu);
;       WSYNC();
; #pragma unroll
;       for (int vb = 0; vb < 4; ++vb) { const bf16x8 sf = *(const LAS bf16x8*)(SPT + (vb * 16 + fr) * 40 + quad * 8);
; #pragma unroll
;           for (int qb = 0; qb < 4; ++qb) o[qb][vb] = MFMA16(qf[qb], sf, o[qb][vb]); } }
;     float gnv[4];
; #pragma unroll
;     for (int vb = 0; vb < 4; ++vb) gnv[vb] = gn[vb * 16 + fr];
;     WSYNC();
;     LAS bf16* OT = (LAS bf16*)wl;
; #pragma unroll
;     for (int qb = 0; qb < 4; ++qb)
; #pragma unroll
;         for (int j = 0; j < 4; ++j) { float ss = 0.f;
; #pragma unroll
;             for (int vb = 0; vb < 4; ++vb) ss += o[qb][vb][j] * o[qb][vb][j];
;             ss += __shfl_xor(ss, 1); ss += __shfl_xor(ss, 2); ss += __shfl_xor(ss, 4); ss += __shfl_xor(ss, 8);
;             const float rstd = rsqrtf(ss * (1.f / 64.f) + EPS);
; #pragma unroll
;             for (int vb = 0; vb < 4; ++vb) OT[(qb * 16 + quad * 4 + j) * 72 + vb * 16 + fr] = (bf16)(pk2(o[qb][vb][j] * rstd * gnv[vb], 0.f) & 0xffffu); }
	v_mfma_f32_16x16x32_bf16 v[98:101], v[38:41], v[58:61], 0
	s_nop 4
	v_cndmask_b32_e64 v67, 0, v67, s[18:19]
	v_cndmask_b32_e64 v68, v68, 0, s[20:21]
	v_cndmask_b32_e64 v69, v69, 0, s[22:23]
	v_mfma_f32_16x16x32_bf16 v[152:155], v[38:41], v[110:113], 0
	v_cvt_pk_bf16_f32 v54, v54, v55
	v_cvt_pk_bf16_f32 v55, v56, v57
	v_cvt_pk_bf16_f32 v57, v68, v69
	v_mfma_f32_16x16x32_bf16 v[218:221], v[38:41], v[200:203], 0
	v_mov_b32_e32 v38, s35
	v_cndmask_b32_e64 v38, v66, v38, s[16:17]
	v_cndmask_b32_e64 v66, v38, v66, s[18:19]
	v_mfma_f32_16x16x32_bf16 v[102:105], v[50:53], v[58:61], 0
	v_cvt_pk_bf16_f32 v56, v66, v67
	v_mfma_f32_16x16x32_bf16 v[156:159], v[50:53], v[110:113], 0
	v_mfma_f32_16x16x32_bf16 v[222:225], v[50:53], v[200:203], 0
	ds_read2_b64 v[50:53], v126 offset0:8 offset1:12
	v_mfma_f32_16x16x32_bf16 v[106:109], v[70:73], v[58:61], 0
	v_mfma_f32_16x16x32_bf16 v[196:199], v[70:73], v[110:113], 0
	v_mfma_f32_16x16x32_bf16 v[38:41], v[70:73], v[200:203], 0
	s_waitcnt lgkmcnt(0)
	v_mfma_f32_16x16x32_bf16 v[70:73], v[82:85], v[50:53], v[90:93]
	v_mfma_f32_16x16x32_bf16 v[42:45], v[54:57], v[50:53], v[42:45]
	ds_read2_b64 v[50:53], v128 offset0:24 offset1:28
	v_mfma_f32_16x16x32_bf16 v[58:61], v[34:37], v[58:61], 0
	v_mfma_f32_16x16x32_bf16 v[110:113], v[34:37], v[110:113], 0
	v_mfma_f32_16x16x32_bf16 v[34:37], v[34:37], v[200:203], 0
	s_waitcnt lgkmcnt(0)
	v_mfma_f32_16x16x32_bf16 v[106:109], v[82:85], v[50:53], v[106:109]
	v_mfma_f32_16x16x32_bf16 v[200:203], v[54:57], v[50:53], v[58:61]
	ds_read2_b64 v[50:53], v130 offset0:40 offset1:44
	s_waitcnt lgkmcnt(0)
	v_mfma_f32_16x16x32_bf16 v[196:199], v[82:85], v[50:53], v[196:199]
	v_mfma_f32_16x16x32_bf16 v[110:113], v[54:57], v[50:53], v[110:113]
	ds_read2_b64 v[50:53], v124 offset0:8 offset1:12
	s_waitcnt lgkmcnt(0)
	s_waitcnt lgkmcnt(0)
	v_mfma_f32_16x16x32_bf16 v[234:237], v[54:57], v[50:53], v[34:37]
	s_nop 2
	v_cvt_pk_bf16_f32 v37, v194, v211
	v_cvt_pk_bf16_f32 v36, v186, v189
	v_cvt_pk_bf16_f32 v35, v178, v181
	v_cvt_pk_bf16_f32 v34, v171, v173
	ds_write_b128 v166, v[34:37] offset:5120
	v_cvt_pk_bf16_f32 v37, v191, v195
	v_cvt_pk_bf16_f32 v36, v183, v187
	v_cvt_pk_bf16_f32 v35, v175, v179
	v_cvt_pk_bf16_f32 v34, v170, v172
	ds_write_b128 v166, v[34:37] offset:5136
	v_cvt_pk_bf16_f32 v37, v213, v215
	v_cvt_pk_bf16_f32 v36, v192, v210
	v_cvt_pk_bf16_f32 v35, v184, v188
	v_cvt_pk_bf16_f32 v34, v176, v180
	ds_write_b128 v166, v[34:37] offset:5152
	v_cvt_pk_bf16_f32 v37, v212, v214
	v_cvt_pk_bf16_f32 v36, v190, v193
	v_cvt_pk_bf16_f32 v35, v182, v185
	v_cvt_pk_bf16_f32 v34, v174, v177
	ds_write_b128 v166, v[34:37] offset:5168
	s_waitcnt lgkmcnt(0)
	v_mfma_f32_16x16x32_bf16 v[226:229], v[82:85], v[50:53], v[38:41]
	ds_read_b128 v[34:37], v167 offset:5120
	s_nop 1
	ds_read_b128 v[38:41], v167 offset:6400
	s_waitcnt lgkmcnt(0)
	v_mfma_f32_16x16x32_bf16 v[90:93], v[94:97], v[38:41], v[98:101]
	s_nop 2
	global_load_dword v100, v[116:117], off
	v_xor_b32_e32 v98, 1, v241
	s_nop 2
	v_mov_b32_e32 v99, v90
	v_mfma_f32_16x16x32_bf16 v[82:85], v[94:97], v[34:37], v[86:89]
	v_mfma_f32_16x16x32_bf16 v[66:69], v[78:81], v[34:37], v[74:77]
	v_mfma_f32_16x16x32_bf16 v[50:53], v[62:65], v[34:37], v[70:73]
	v_mfma_f32_16x16x32_bf16 v[34:37], v[46:49], v[34:37], v[42:45]
	s_nop 2
	ds_read_b128 v[42:45], v167 offset:7680
	v_mfma_f32_16x16x32_bf16 v[74:77], v[78:81], v[38:41], v[102:105]
	s_nop 2
	global_load_dword v103, v[116:117], off offset:64
	s_waitcnt lgkmcnt(0)
	v_mfma_f32_16x16x32_bf16 v[86:89], v[94:97], v[42:45], v[152:155]
	s_nop 2
	ds_read_b128 v[152:155], v168 offset:5120
	global_load_dword v102, v[116:117], off offset:128
	global_load_dword v101, v[118:119], off
	s_waitcnt lgkmcnt(0)
	v_mfma_f32_16x16x32_bf16 v[94:97], v[94:97], v[152:155], v[218:221]
	v_mov_b32_e32 v104, v86
	s_waitcnt lgkmcnt(0)
	s_nop 6
	v_mov_b32_e32 v105, v94
	v_mfma_f32_16x16x32_bf16 v[70:73], v[78:81], v[42:45], v[156:159]
	v_mul_f32_e64 v104, v104, v104
	v_mul_f32_e64 v105, v105, v105
	v_mfma_f32_16x16x32_bf16 v[54:57], v[62:65], v[42:45], v[196:199]
	v_mfma_f32_16x16x32_bf16 v[42:45], v[46:49], v[42:45], v[110:113]
	s_nop 2
	v_add_u32_e32 v112, 64, v0
	v_cmp_lt_i32_e32 vcc, v98, v112
	v_mfma_f32_16x16x32_bf16 v[58:61], v[62:65], v[38:41], v[106:109]
	v_mov_b32_e32 v113, v93
	v_cndmask_b32_e32 v0, v241, v98, vcc
	v_mov_b32_e32 v98, v82
	v_mov_b32_e32 v106, v83
	v_mov_b32_e32 v107, v91
	v_pk_mul_f32 v[98:99], v[98:99], v[98:99]
	v_pk_mul_f32 v[106:107], v[106:107], v[106:107]
	v_mov_b32_e32 v108, v87
	v_mov_b32_e32 v109, v95
	v_pk_mul_f32 v[108:109], v[108:109], v[108:109]
	v_mov_b32_e32 v110, v106
	v_mov_b32_e32 v111, v98
	v_mov_b32_e32 v98, v107
	v_pk_add_f32 v[98:99], v[110:111], v[98:99]
	v_mov_b32_e32 v106, v108
	v_mov_b32_e32 v107, v104
	v_pk_add_f32 v[98:99], v[98:99], v[106:107]
	v_mov_b32_e32 v104, v109
	v_lshlrev_b32_e32 v0, 2, v0
	v_pk_add_f32 v[98:99], v[98:99], v[104:105]
	ds_bpermute_b32 v105, v0, v99
	ds_bpermute_b32 v104, v0, v98
	v_xor_b32_e32 v106, 2, v241
	v_cmp_lt_i32_e32 vcc, v106, v112
	v_mfma_f32_16x16x32_bf16 v[38:41], v[46:49], v[38:41], v[200:203]
	v_mov_b32_e32 v110, v88
	v_cndmask_b32_e32 v106, v241, v106, vcc
	v_lshlrev_b32_e32 v106, 2, v106
	s_waitcnt lgkmcnt(0)
	v_pk_add_f32 v[98:99], v[98:99], v[104:105]
	ds_bpermute_b32 v109, v106, v99
	ds_bpermute_b32 v108, v106, v98
	v_xor_b32_e32 v104, 4, v241
	v_cmp_lt_i32_e32 vcc, v104, v112
	v_mfma_f32_16x16x32_bf16 v[78:81], v[78:81], v[152:155], v[222:225]
	v_mov_b32_e32 v111, v96
	v_cndmask_b32_e32 v104, v241, v104, vcc
	v_lshlrev_b32_e32 v105, 2, v104
	s_waitcnt lgkmcnt(0)
; #define LAS __attribute__((address_space(3)))
; __device__ __forceinline__ unsigned pk2(float lo, float hi) { const f32x2_ v = {lo, hi}; return __builtin_bit_cast(unsigned, __builtin_convertvector(v, bf16x2_)); }
; #define WSYNC() asm volatile("s_waitcnt lgkmcnt(0)" ::: "memory")
; __device__ __forceinline__ void gla_out_unit(int u, const bf16* proj, const float* wg, const float* bg, const float* gn, const float* SP, bf16* MIXO, LAS unsigned char* wl, int lane) {
;     ...
;     LAS bf16* OT = (LAS bf16*)wl;
; #pragma unroll
;     for (int qb = 0; qb < 4; ++qb)
; #pragma unroll
;         for (int j = 0; j < 4; ++j) { float ss = 0.f;
; #pragma unroll
;             for (int vb = 0; vb < 4; ++vb) ss += o[qb][vb][j] * o[qb][vb][j];
;             ss += __shfl_xor(ss, 1); ss += __shfl_xor(ss, 2); ss += __shfl_xor(ss, 4); ss += __shfl_xor(ss, 8);
;             const float rstd = rsqrtf(ss * (1.f / 64.f) + EPS);
; #pragma unroll
;             for (int vb = 0; vb < 4; ++vb) OT[(qb * 16 + quad * 4 + j) * 72 + vb * 16 + fr] = (bf16)(pk2(o[qb][vb][j] * rstd * gnv[vb], 0.f) & 0xffffu); }
;     WSYNC();
	v_pk_add_f32 v[98:99], v[98:99], v[108:109]
	ds_bpermute_b32 v109, v105, v99
	ds_bpermute_b32 v108, v105, v98
	v_xor_b32_e32 v104, 8, v241
	v_cmp_lt_i32_e32 vcc, v104, v112
	v_mov_b32_e32 v112, v85
	v_mfma_f32_16x16x32_bf16 v[62:65], v[62:65], v[152:155], v[226:229]
	v_cndmask_b32_e32 v104, v241, v104, vcc
	v_lshlrev_b32_e32 v104, 2, v104
	s_waitcnt lgkmcnt(0)
	v_pk_add_f32 v[98:99], v[98:99], v[108:109]
	ds_bpermute_b32 v109, v104, v99
	ds_bpermute_b32 v108, v104, v98
	v_mfma_f32_16x16x32_bf16 v[46:49], v[46:49], v[152:155], v[234:237]
	v_mul_f32_e64 v112, v112, v112
	v_mul_f32_e64 v113, v113, v113
	v_mov_b32_e32 v152, v89
	v_mov_b32_e32 v153, v97
	s_waitcnt lgkmcnt(0)
	v_pk_add_f32 v[108:109], v[98:99], v[108:109]
	v_mov_b64_e32 v[98:99], s[2:3]
	v_pk_fma_f32 v[108:109], v[108:109], s[62:63], v[98:99] op_sel_hi:[1,0,0]
	v_pk_mul_f32 v[110:111], v[110:111], v[110:111]
	v_mul_f32_e32 v107, 0x4b800000, v109
	v_cmp_gt_f32_e64 s[26:27], s45, v109
	v_cmp_gt_f32_e32 vcc, s45, v108
	v_pk_mul_f32 v[152:153], v[152:153], v[152:153]
	v_cndmask_b32_e64 v107, v109, v107, s[26:27]
	v_rsq_f32_e32 v107, v107
	v_mov_b32_e32 v154, v112
	v_mov_b32_e32 v112, v152
	v_mul_f32_e32 v109, 0x45800000, v107
	v_cndmask_b32_e64 v107, v107, v109, s[26:27]
	v_mul_f32_e32 v82, v82, v107
	s_waitcnt vmcnt(3)
	v_mul_f32_e32 v82, v100, v82
	v_cvt_pk_bf16_f32 v82, v82, s0
	ds_write_b16 v163, v82
	v_mul_f32_e32 v82, v90, v107
	s_waitcnt vmcnt(2)
	v_mul_f32_e32 v82, v103, v82
	v_cvt_pk_bf16_f32 v82, v82, s0
	ds_write_b16 v163, v82 offset:32
	v_mul_f32_e32 v82, v86, v107
	s_waitcnt vmcnt(1)
	v_mul_f32_e32 v82, v102, v82
	v_cvt_pk_bf16_f32 v82, v82, s0
	ds_write_b16 v163, v82 offset:64
	v_mul_f32_e32 v82, v94, v107
	s_waitcnt vmcnt(0)
	v_mul_f32_e32 v82, v101, v82
	v_cvt_pk_bf16_f32 v82, v82, s0
	ds_write_b16 v163, v82 offset:96
	v_mul_f32_e32 v82, 0x4b800000, v108
	v_cndmask_b32_e32 v82, v108, v82, vcc
	v_mov_b32_e32 v108, v84
	v_mov_b32_e32 v109, v92
	v_pk_mul_f32 v[108:109], v[108:109], v[108:109]
	v_rsq_f32_e32 v82, v82
	v_mov_b32_e32 v155, v108
	v_mov_b32_e32 v108, v113
	v_pk_add_f32 v[108:109], v[154:155], v[108:109]
	v_mov_b32_e32 v113, v110
	v_pk_add_f32 v[108:109], v[108:109], v[112:113]
	v_mov_b32_e32 v110, v153
	v_pk_add_f32 v[108:109], v[108:109], v[110:111]
	ds_bpermute_b32 v111, v0, v109
	ds_bpermute_b32 v110, v0, v108
	v_mul_f32_e32 v86, 0x45800000, v82
	v_cndmask_b32_e32 v94, v82, v86, vcc
	v_mul_f32_e32 v82, v83, v94
	v_mul_f32_e32 v86, v100, v82
	s_waitcnt lgkmcnt(0)
	v_pk_add_f32 v[82:83], v[108:109], v[110:111]
	ds_bpermute_b32 v109, v106, v83
	ds_bpermute_b32 v108, v106, v82
	v_cvt_pk_bf16_f32 v86, v86, s0
	ds_write_b16 v163, v86 offset:144
	v_mul_f32_e32 v86, v91, v94
	v_mul_f32_e32 v86, v103, v86
	s_waitcnt lgkmcnt(1)
	v_pk_add_f32 v[82:83], v[82:83], v[108:109]
	ds_bpermute_b32 v91, v105, v83
	ds_bpermute_b32 v90, v105, v82
	v_cvt_pk_bf16_f32 v86, v86, s0
	ds_write_b16 v163, v86 offset:176
	v_mul_f32_e32 v86, v87, v94
	v_mul_f32_e32 v107, v102, v86
	s_waitcnt lgkmcnt(1)
	v_pk_add_f32 v[82:83], v[82:83], v[90:91]
	ds_bpermute_b32 v87, v104, v83
	ds_bpermute_b32 v86, v104, v82
	v_cvt_pk_bf16_f32 v90, v107, s0
	ds_write_b16 v163, v90 offset:208
	v_mul_f32_e32 v90, v95, v94
	v_mul_f32_e32 v90, v101, v90
	s_waitcnt lgkmcnt(1)
	v_pk_add_f32 v[82:83], v[82:83], v[86:87]
	v_mov_b32_e32 v91, v75
	v_pk_fma_f32 v[82:83], v[82:83], s[62:63], v[98:99] op_sel_hi:[1,0,0]
	v_mov_b32_e32 v87, v78
	v_mul_f32_e32 v86, 0x4b800000, v83
	v_cmp_gt_f32_e64 s[26:27], s45, v83
	v_cmp_gt_f32_e32 vcc, s45, v82
	v_mov_b32_e32 v94, v71
	v_cndmask_b32_e64 v83, v83, v86, s[26:27]
	v_rsq_f32_e32 v83, v83
	v_cvt_pk_bf16_f32 v86, v90, s0
	ds_write_b16 v163, v86 offset:240
	v_mov_b32_e32 v90, v67
	v_mul_f32_e32 v86, 0x45800000, v83
	v_cndmask_b32_e64 v83, v83, v86, s[26:27]
	v_mul_f32_e32 v84, v84, v83
	v_mul_f32_e32 v84, v100, v84
	v_cvt_pk_bf16_f32 v84, v84, s0
	ds_write_b16 v163, v84 offset:288
	v_mul_f32_e32 v84, v92, v83
	v_mul_f32_e32 v84, v103, v84
	v_cvt_pk_bf16_f32 v84, v84, s0
	ds_write_b16 v163, v84 offset:320
	v_mul_f32_e32 v84, v88, v83
	v_mul_f32_e32 v83, v96, v83
	v_mul_f32_e32 v83, v101, v83
	v_cvt_pk_bf16_f32 v83, v83, s0
	v_mul_f32_e32 v84, v102, v84
	ds_write_b16 v163, v83 offset:384
	v_mul_f32_e32 v83, 0x4b800000, v82
	v_cvt_pk_bf16_f32 v84, v84, s0
	v_cndmask_b32_e32 v82, v82, v83, vcc
	ds_write_b16 v163, v84 offset:352
	v_rsq_f32_e32 v84, v82
	v_mov_b32_e32 v82, v66
	v_mov_b32_e32 v83, v74
	v_pk_mul_f32 v[82:83], v[82:83], v[82:83]
	v_mov_b32_e32 v86, v70
	v_pk_mul_f32 v[90:91], v[90:91], v[90:91]
	v_mov_b32_e32 v95, v79
	v_pk_mul_f32 v[86:87], v[86:87], v[86:87]
	v_pk_mul_f32 v[94:95], v[94:95], v[94:95]
	v_mov_b32_e32 v108, v90
	v_mov_b32_e32 v109, v82
	v_mov_b32_e32 v82, v91
	v_pk_add_f32 v[82:83], v[108:109], v[82:83]
	v_mov_b32_e32 v90, v94
	v_mov_b32_e32 v91, v86
	v_pk_add_f32 v[82:83], v[82:83], v[90:91]
	v_mov_b32_e32 v86, v95
	v_pk_add_f32 v[82:83], v[82:83], v[86:87]
	ds_bpermute_b32 v87, v0, v83
	ds_bpermute_b32 v86, v0, v82
	v_mul_f32_e32 v88, 0x45800000, v84
	v_cndmask_b32_e32 v88, v84, v88, vcc
	v_mul_f32_e32 v84, v85, v88
	v_mul_f32_e32 v90, v100, v84
	s_waitcnt lgkmcnt(0)
	v_pk_add_f32 v[82:83], v[82:83], v[86:87]
	ds_bpermute_b32 v85, v106, v83
	ds_bpermute_b32 v84, v106, v82
	v_cvt_pk_bf16_f32 v86, v90, s0
	ds_write_b16 v163, v86 offset:432
	v_mul_f32_e32 v86, v93, v88
	v_mul_f32_e32 v86, v103, v86
	s_waitcnt lgkmcnt(1)
	v_pk_add_f32 v[82:83], v[82:83], v[84:85]
	ds_bpermute_b32 v85, v105, v83
	ds_bpermute_b32 v84, v105, v82
	v_cvt_pk_bf16_f32 v86, v86, s0
	ds_write_b16 v163, v86 offset:464
	v_mul_f32_e32 v86, v89, v88
	v_mul_f32_e32 v86, v102, v86
	s_waitcnt lgkmcnt(1)
; #define LAS __attribute__((address_space(3)))
; __device__ __forceinline__ unsigned pk2(float lo, float hi) { const f32x2_ v = {lo, hi}; return __builtin_bit_cast(unsigned, __builtin_convertvector(v, bf16x2_)); }
; #define WSYNC() asm volatile("s_waitcnt lgkmcnt(0)" ::: "memory")
; __device__ __forceinline__ void gla_out_unit(int u, const bf16* proj, const float* wg, const float* bg, const float* gn, const float* SP, bf16* MIXO, LAS unsigned char* wl, int lane) {
;     ...
;     LAS bf16* OT = (LAS bf16*)wl;
; #pragma unroll
;     for (int qb = 0; qb < 4; ++qb)
; #pragma unroll
;         for (int j = 0; j < 4; ++j) { float ss = 0.f;
; #pragma unroll
;             for (int vb = 0; vb < 4; ++vb) ss += o[qb][vb][j] * o[qb][vb][j];
;             ss += __shfl_xor(ss, 1); ss += __shfl_xor(ss, 2); ss += __shfl_xor(ss, 4); ss += __shfl_xor(ss, 8);
;             const float rstd = rsqrtf(ss * (1.f / 64.f) + EPS);
; #pragma unroll
;             for (int vb = 0; vb < 4; ++vb) OT[(qb * 16 + quad * 4 + j) * 72 + vb * 16 + fr] = (bf16)(pk2(o[qb][vb][j] * rstd * gnv[vb], 0.f) & 0xffffu); }
;     WSYNC();
	v_pk_add_f32 v[82:83], v[82:83], v[84:85]
	ds_bpermute_b32 v85, v104, v83
	ds_bpermute_b32 v84, v104, v82
	v_cvt_pk_bf16_f32 v86, v86, s0
	ds_write_b16 v163, v86 offset:496
	v_mul_f32_e32 v86, v97, v88
	v_mul_f32_e32 v86, v101, v86
	s_waitcnt lgkmcnt(1)
	v_pk_add_f32 v[82:83], v[82:83], v[84:85]
	v_mov_b32_e32 v87, v77
	v_pk_fma_f32 v[82:83], v[82:83], s[62:63], v[98:99] op_sel_hi:[1,0,0]
	v_mov_b32_e32 v85, v80
	v_mul_f32_e32 v84, 0x4b800000, v83
	v_cmp_gt_f32_e64 s[26:27], s45, v83
	v_cmp_gt_f32_e32 vcc, s45, v82
	v_mov_b32_e32 v88, v73
	v_cndmask_b32_e64 v83, v83, v84, s[26:27]
	v_rsq_f32_e32 v83, v83
	v_cvt_pk_bf16_f32 v84, v86, s0
	ds_write_b16 v163, v84 offset:528
	v_mov_b32_e32 v86, v69
	v_mul_f32_e32 v84, 0x45800000, v83
	v_cndmask_b32_e64 v83, v83, v84, s[26:27]
	v_mul_f32_e32 v66, v66, v83
	v_mul_f32_e32 v66, v100, v66
	v_cvt_pk_bf16_f32 v66, v66, s0
	ds_write_b16 v163, v66 offset:2304
	v_mul_f32_e32 v66, v74, v83
	v_mul_f32_e32 v66, v103, v66
	v_cvt_pk_bf16_f32 v66, v66, s0
	ds_write_b16 v163, v66 offset:2336
	v_mul_f32_e32 v66, v70, v83
	v_mul_f32_e32 v66, v102, v66
	v_cvt_pk_bf16_f32 v66, v66, s0
	ds_write_b16 v163, v66 offset:2368
	v_mul_f32_e32 v66, v78, v83
	v_mul_f32_e32 v66, v101, v66
	v_cvt_pk_bf16_f32 v66, v66, s0
	ds_write_b16 v163, v66 offset:2400
	v_mul_f32_e32 v66, 0x4b800000, v82
	v_cndmask_b32_e32 v66, v82, v66, vcc
	v_mov_b32_e32 v82, v68
	v_mov_b32_e32 v83, v76
	v_pk_mul_f32 v[82:83], v[82:83], v[82:83]
	v_mov_b32_e32 v84, v72
	v_pk_mul_f32 v[86:87], v[86:87], v[86:87]
	v_mov_b32_e32 v89, v81
	v_pk_mul_f32 v[84:85], v[84:85], v[84:85]
	v_pk_mul_f32 v[88:89], v[88:89], v[88:89]
	v_mov_b32_e32 v90, v86
	v_mov_b32_e32 v91, v82
	v_mov_b32_e32 v82, v87
	v_pk_add_f32 v[82:83], v[90:91], v[82:83]
	v_mov_b32_e32 v86, v88
	v_mov_b32_e32 v87, v84
	v_rsq_f32_e32 v66, v66
	v_pk_add_f32 v[82:83], v[82:83], v[86:87]
	v_mov_b32_e32 v84, v89
	v_pk_add_f32 v[82:83], v[82:83], v[84:85]
	ds_bpermute_b32 v85, v0, v83
	ds_bpermute_b32 v84, v0, v82
	v_mul_f32_e32 v70, 0x45800000, v66
	v_cndmask_b32_e32 v78, v66, v70, vcc
	v_mul_f32_e32 v66, v67, v78
	v_mul_f32_e32 v70, v100, v66
	s_waitcnt lgkmcnt(0)
	v_pk_add_f32 v[66:67], v[82:83], v[84:85]
	ds_bpermute_b32 v83, v106, v67
	ds_bpermute_b32 v82, v106, v66
	v_cvt_pk_bf16_f32 v70, v70, s0
	ds_write_b16 v163, v70 offset:2448
	v_mul_f32_e32 v70, v75, v78
	v_mul_f32_e32 v70, v103, v70
	s_waitcnt lgkmcnt(1)
	v_pk_add_f32 v[66:67], v[66:67], v[82:83]
	ds_bpermute_b32 v75, v105, v67
	ds_bpermute_b32 v74, v105, v66
	v_cvt_pk_bf16_f32 v70, v70, s0
	ds_write_b16 v163, v70 offset:2480
	v_mul_f32_e32 v70, v71, v78
	v_mul_f32_e32 v82, v102, v70
	s_waitcnt lgkmcnt(1)
	v_pk_add_f32 v[66:67], v[66:67], v[74:75]
	ds_bpermute_b32 v71, v104, v67
	ds_bpermute_b32 v70, v104, v66
	v_cvt_pk_bf16_f32 v74, v82, s0
	ds_write_b16 v163, v74 offset:2512
	v_mul_f32_e32 v74, v79, v78
	v_mul_f32_e32 v74, v101, v74
	s_waitcnt lgkmcnt(1)
	v_pk_add_f32 v[66:67], v[66:67], v[70:71]
	v_mov_b32_e32 v75, v59
	v_pk_fma_f32 v[66:67], v[66:67], s[62:63], v[98:99] op_sel_hi:[1,0,0]
	v_mov_b32_e32 v71, v62
	v_mul_f32_e32 v70, 0x4b800000, v67
	v_cmp_gt_f32_e64 s[26:27], s45, v67
	v_cmp_gt_f32_e32 vcc, s45, v66
	v_mov_b32_e32 v78, v55
	v_cndmask_b32_e64 v67, v67, v70, s[26:27]
	v_rsq_f32_e32 v67, v67
	v_cvt_pk_bf16_f32 v70, v74, s0
	ds_write_b16 v163, v70 offset:2544
	v_mov_b32_e32 v74, v51
	v_mul_f32_e32 v70, 0x45800000, v67
	v_cndmask_b32_e64 v67, v67, v70, s[26:27]
	v_mul_f32_e32 v68, v68, v67
	v_mul_f32_e32 v68, v100, v68
	v_cvt_pk_bf16_f32 v68, v68, s0
	ds_write_b16 v163, v68 offset:2592
	v_mul_f32_e32 v68, v76, v67
	v_mul_f32_e32 v68, v103, v68
	v_cvt_pk_bf16_f32 v68, v68, s0
	ds_write_b16 v163, v68 offset:2624
	v_mul_f32_e32 v68, v72, v67
	v_mul_f32_e32 v67, v80, v67
	v_mul_f32_e32 v67, v101, v67
	v_cvt_pk_bf16_f32 v67, v67, s0
	v_mul_f32_e32 v68, v102, v68
	ds_write_b16 v163, v67 offset:2688
	v_mul_f32_e32 v67, 0x4b800000, v66
	v_cvt_pk_bf16_f32 v68, v68, s0
	v_cndmask_b32_e32 v66, v66, v67, vcc
	ds_write_b16 v163, v68 offset:2656
	v_rsq_f32_e32 v68, v66
	v_mov_b32_e32 v66, v50
	v_mov_b32_e32 v67, v58
	v_pk_mul_f32 v[66:67], v[66:67], v[66:67]
	v_mov_b32_e32 v70, v54
	v_pk_mul_f32 v[74:75], v[74:75], v[74:75]
	v_mov_b32_e32 v79, v63
	v_pk_mul_f32 v[70:71], v[70:71], v[70:71]
	v_pk_mul_f32 v[78:79], v[78:79], v[78:79]
	v_mov_b32_e32 v82, v74
	v_mov_b32_e32 v83, v66
	v_mov_b32_e32 v66, v75
	v_pk_add_f32 v[66:67], v[82:83], v[66:67]
	v_mov_b32_e32 v74, v78
	v_mov_b32_e32 v75, v70
	v_pk_add_f32 v[66:67], v[66:67], v[74:75]
	v_mov_b32_e32 v70, v79
	v_pk_add_f32 v[66:67], v[66:67], v[70:71]
	ds_bpermute_b32 v71, v0, v67
	ds_bpermute_b32 v70, v0, v66
	v_mul_f32_e32 v72, 0x45800000, v68
	v_cndmask_b32_e32 v72, v68, v72, vcc
	v_mul_f32_e32 v68, v69, v72
	v_mul_f32_e32 v74, v100, v68
	s_waitcnt lgkmcnt(0)
	v_pk_add_f32 v[66:67], v[66:67], v[70:71]
	ds_bpermute_b32 v69, v106, v67
	ds_bpermute_b32 v68, v106, v66
	v_cvt_pk_bf16_f32 v70, v74, s0
	ds_write_b16 v163, v70 offset:2736
	v_mul_f32_e32 v70, v77, v72
	v_mul_f32_e32 v70, v103, v70
	s_waitcnt lgkmcnt(1)
	v_pk_add_f32 v[66:67], v[66:67], v[68:69]
	ds_bpermute_b32 v69, v105, v67
	ds_bpermute_b32 v68, v105, v66
	v_cvt_pk_bf16_f32 v70, v70, s0
	ds_write_b16 v163, v70 offset:2768
	v_mul_f32_e32 v70, v73, v72
	v_mul_f32_e32 v70, v102, v70
	s_waitcnt lgkmcnt(1)
	v_pk_add_f32 v[66:67], v[66:67], v[68:69]
	ds_bpermute_b32 v69, v104, v67
	ds_bpermute_b32 v68, v104, v66
	v_cvt_pk_bf16_f32 v70, v70, s0
	ds_write_b16 v163, v70 offset:2800
	v_mul_f32_e32 v70, v81, v72
	v_mul_f32_e32 v70, v101, v70
	s_waitcnt lgkmcnt(1)
; #define LAS __attribute__((address_space(3)))
; __device__ __forceinline__ unsigned pk2(float lo, float hi) { const f32x2_ v = {lo, hi}; return __builtin_bit_cast(unsigned, __builtin_convertvector(v, bf16x2_)); }
; #define WSYNC() asm volatile("s_waitcnt lgkmcnt(0)" ::: "memory")
; __device__ __forceinline__ void gla_out_unit(int u, const bf16* proj, const float* wg, const float* bg, const float* gn, const float* SP, bf16* MIXO, LAS unsigned char* wl, int lane) {
;     ...
;     LAS bf16* OT = (LAS bf16*)wl;
; #pragma unroll
;     for (int qb = 0; qb < 4; ++qb)
; #pragma unroll
;         for (int j = 0; j < 4; ++j) { float ss = 0.f;
; #pragma unroll
;             for (int vb = 0; vb < 4; ++vb) ss += o[qb][vb][j] * o[qb][vb][j];
;             ss += __shfl_xor(ss, 1); ss += __shfl_xor(ss, 2); ss += __shfl_xor(ss, 4); ss += __shfl_xor(ss, 8);
;             const float rstd = rsqrtf(ss * (1.f / 64.f) + EPS);
; #pragma unroll
;             for (int vb = 0; vb < 4; ++vb) OT[(qb * 16 + quad * 4 + j) * 72 + vb * 16 + fr] = (bf16)(pk2(o[qb][vb][j] * rstd * gnv[vb], 0.f) & 0xffffu); }
;     WSYNC();
	v_pk_add_f32 v[66:67], v[66:67], v[68:69]
	v_mov_b32_e32 v71, v61
	v_pk_fma_f32 v[66:67], v[66:67], s[62:63], v[98:99] op_sel_hi:[1,0,0]
	v_mov_b32_e32 v69, v64
	v_mul_f32_e32 v68, 0x4b800000, v67
	v_cmp_gt_f32_e64 s[26:27], s45, v67
	v_cmp_gt_f32_e32 vcc, s45, v66
	v_mov_b32_e32 v72, v57
	v_cndmask_b32_e64 v67, v67, v68, s[26:27]
	v_rsq_f32_e32 v67, v67
	v_cvt_pk_bf16_f32 v68, v70, s0
	ds_write_b16 v163, v68 offset:2832
	v_mov_b32_e32 v70, v53
	v_mul_f32_e32 v68, 0x45800000, v67
	v_cndmask_b32_e64 v67, v67, v68, s[26:27]
	v_mul_f32_e32 v50, v50, v67
	v_mul_f32_e32 v50, v100, v50
	v_cvt_pk_bf16_f32 v50, v50, s0
	ds_write_b16 v163, v50 offset:4608
	v_mul_f32_e32 v50, v58, v67
	v_mul_f32_e32 v50, v103, v50
	v_cvt_pk_bf16_f32 v50, v50, s0
	ds_write_b16 v163, v50 offset:4640
	v_mul_f32_e32 v50, v54, v67
	v_mul_f32_e32 v50, v102, v50
	v_cvt_pk_bf16_f32 v50, v50, s0
	ds_write_b16 v163, v50 offset:4672
	v_mul_f32_e32 v50, v62, v67
	v_mul_f32_e32 v50, v101, v50
	v_cvt_pk_bf16_f32 v50, v50, s0
	ds_write_b16 v163, v50 offset:4704
	v_mul_f32_e32 v50, 0x4b800000, v66
	v_cndmask_b32_e32 v50, v66, v50, vcc
	v_mov_b32_e32 v66, v52
	v_mov_b32_e32 v67, v60
	v_pk_mul_f32 v[66:67], v[66:67], v[66:67]
	v_mov_b32_e32 v68, v56
	v_pk_mul_f32 v[70:71], v[70:71], v[70:71]
	v_mov_b32_e32 v73, v65
	v_pk_mul_f32 v[68:69], v[68:69], v[68:69]
	v_pk_mul_f32 v[72:73], v[72:73], v[72:73]
	v_mov_b32_e32 v74, v70
	v_mov_b32_e32 v75, v66
	v_mov_b32_e32 v66, v71
	v_pk_add_f32 v[66:67], v[74:75], v[66:67]
	v_mov_b32_e32 v70, v72
	v_mov_b32_e32 v71, v68
	v_rsq_f32_e32 v50, v50
	v_pk_add_f32 v[66:67], v[66:67], v[70:71]
	v_mov_b32_e32 v68, v73
	v_pk_add_f32 v[66:67], v[66:67], v[68:69]
	ds_bpermute_b32 v69, v0, v67
	ds_bpermute_b32 v68, v0, v66
	v_mul_f32_e32 v54, 0x45800000, v50
	v_cndmask_b32_e32 v62, v50, v54, vcc
	v_mul_f32_e32 v50, v51, v62
	v_mul_f32_e32 v54, v100, v50
	s_waitcnt lgkmcnt(0)
	v_pk_add_f32 v[50:51], v[66:67], v[68:69]
	ds_bpermute_b32 v67, v106, v51
	ds_bpermute_b32 v66, v106, v50
	v_cvt_pk_bf16_f32 v54, v54, s0
	ds_write_b16 v163, v54 offset:4752
	v_mul_f32_e32 v54, v59, v62
	v_mul_f32_e32 v54, v103, v54
	s_waitcnt lgkmcnt(1)
	v_pk_add_f32 v[50:51], v[50:51], v[66:67]
	ds_bpermute_b32 v59, v105, v51
	ds_bpermute_b32 v58, v105, v50
	v_cvt_pk_bf16_f32 v54, v54, s0
	ds_write_b16 v163, v54 offset:4784
	v_mul_f32_e32 v54, v55, v62
	v_mul_f32_e32 v66, v102, v54
	s_waitcnt lgkmcnt(1)
	v_pk_add_f32 v[50:51], v[50:51], v[58:59]
	ds_bpermute_b32 v55, v104, v51
	ds_bpermute_b32 v54, v104, v50
	v_cvt_pk_bf16_f32 v58, v66, s0
	ds_write_b16 v163, v58 offset:4816
	v_mul_f32_e32 v58, v63, v62
	v_mul_f32_e32 v58, v101, v58
	s_waitcnt lgkmcnt(1)
	v_pk_add_f32 v[50:51], v[50:51], v[54:55]
	v_mov_b32_e32 v59, v39
	v_pk_fma_f32 v[50:51], v[50:51], s[62:63], v[98:99] op_sel_hi:[1,0,0]
	v_mov_b32_e32 v55, v46
	v_mul_f32_e32 v54, 0x4b800000, v51
	v_cmp_gt_f32_e64 s[26:27], s45, v51
	v_cmp_gt_f32_e32 vcc, s45, v50
	v_mov_b32_e32 v62, v43
	v_cndmask_b32_e64 v51, v51, v54, s[26:27]
	v_rsq_f32_e32 v51, v51
	v_cvt_pk_bf16_f32 v54, v58, s0
	ds_write_b16 v163, v54 offset:4848
	v_mov_b32_e32 v58, v35
	v_mul_f32_e32 v54, 0x45800000, v51
	v_cndmask_b32_e64 v51, v51, v54, s[26:27]
	v_mul_f32_e32 v52, v52, v51
	v_mul_f32_e32 v52, v100, v52
	v_cvt_pk_bf16_f32 v52, v52, s0
	ds_write_b16 v163, v52 offset:4896
	v_mul_f32_e32 v52, v60, v51
	v_mul_f32_e32 v52, v103, v52
	v_cvt_pk_bf16_f32 v52, v52, s0
	ds_write_b16 v163, v52 offset:4928
	v_mul_f32_e32 v52, v56, v51
	v_mul_f32_e32 v51, v64, v51
	v_mul_f32_e32 v51, v101, v51
	v_cvt_pk_bf16_f32 v51, v51, s0
	v_mul_f32_e32 v52, v102, v52
	ds_write_b16 v163, v51 offset:4992
	v_mul_f32_e32 v51, 0x4b800000, v50
	v_cvt_pk_bf16_f32 v52, v52, s0
	v_cndmask_b32_e32 v50, v50, v51, vcc
	ds_write_b16 v163, v52 offset:4960
	v_rsq_f32_e32 v52, v50
	v_mov_b32_e32 v50, v34
	v_mov_b32_e32 v51, v38
	v_pk_mul_f32 v[50:51], v[50:51], v[50:51]
	v_mov_b32_e32 v54, v42
	v_pk_mul_f32 v[58:59], v[58:59], v[58:59]
	v_mov_b32_e32 v63, v47
	v_pk_mul_f32 v[54:55], v[54:55], v[54:55]
	v_pk_mul_f32 v[62:63], v[62:63], v[62:63]
	v_mov_b32_e32 v66, v58
	v_mov_b32_e32 v67, v50
	v_mov_b32_e32 v50, v59
	v_pk_add_f32 v[50:51], v[66:67], v[50:51]
	v_mov_b32_e32 v58, v62
	v_mov_b32_e32 v59, v54
	v_pk_add_f32 v[50:51], v[50:51], v[58:59]
	v_mov_b32_e32 v54, v63
	v_pk_add_f32 v[50:51], v[50:51], v[54:55]
	ds_bpermute_b32 v55, v0, v51
	ds_bpermute_b32 v54, v0, v50
	v_mul_f32_e32 v56, 0x45800000, v52
	v_cndmask_b32_e32 v56, v52, v56, vcc
	v_mul_f32_e32 v52, v53, v56
	v_mul_f32_e32 v58, v100, v52
	s_waitcnt lgkmcnt(0)
	v_pk_add_f32 v[50:51], v[50:51], v[54:55]
	ds_bpermute_b32 v53, v106, v51
	ds_bpermute_b32 v52, v106, v50
	v_cvt_pk_bf16_f32 v54, v58, s0
	ds_write_b16 v163, v54 offset:5040
	v_mul_f32_e32 v54, v61, v56
	v_mul_f32_e32 v54, v103, v54
	s_waitcnt lgkmcnt(1)
	v_pk_add_f32 v[50:51], v[50:51], v[52:53]
	ds_bpermute_b32 v53, v105, v51
	ds_bpermute_b32 v52, v105, v50
	v_cvt_pk_bf16_f32 v54, v54, s0
	ds_write_b16 v163, v54 offset:5072
	v_mul_f32_e32 v54, v57, v56
	v_mul_f32_e32 v54, v102, v54
	s_waitcnt lgkmcnt(1)
	v_pk_add_f32 v[50:51], v[50:51], v[52:53]
	ds_bpermute_b32 v53, v104, v51
	ds_bpermute_b32 v52, v104, v50
	v_cvt_pk_bf16_f32 v54, v54, s0
	ds_write_b16 v163, v54 offset:5104
	v_mul_f32_e32 v54, v65, v56
	v_mul_f32_e32 v54, v101, v54
	s_waitcnt lgkmcnt(1)
; #define LAS __attribute__((address_space(3)))
; __device__ __forceinline__ unsigned pk2(float lo, float hi) { const f32x2_ v = {lo, hi}; return __builtin_bit_cast(unsigned, __builtin_convertvector(v, bf16x2_)); }
; __device__ __forceinline__ u32x4 pack8(const float* f) { u32x4 w; w.x = pk2(f[0], f[1]); w.y = pk2(f[2], f[3]); w.z = pk2(f[4], f[5]); w.w = pk2(f[6], f[7]); return w; }
; __device__ __forceinline__ float sigmoidf_(float z) { return 1.f / (1.f + __expf(-z)); }
; #define WSYNC() asm volatile("s_waitcnt lgkmcnt(0)" ::: "memory")
; __device__ __forceinline__ void gla_out_unit(int u, const bf16* proj, const float* wg, const float* bg, const float* gn, const float* SP, bf16* MIXO, LAS unsigned char* wl, int lane) {
;     ...
;         for (int j = 0; j < 4; ++j) { float ss = 0.f;
; #pragma unroll
;             for (int vb = 0; vb < 4; ++vb) ss += o[qb][vb][j] * o[qb][vb][j];
;             ss += __shfl_xor(ss, 1); ss += __shfl_xor(ss, 2); ss += __shfl_xor(ss, 4); ss += __shfl_xor(ss, 8);
;             const float rstd = rsqrtf(ss * (1.f / 64.f) + EPS);
; #pragma unroll
;             for (int vb = 0; vb < 4; ++vb) OT[(qb * 16 + quad * 4 + j) * 72 + vb * 16 + fr] = (bf16)(pk2(o[qb][vb][j] * rstd * gnv[vb], 0.f) & 0xffffu); }
;     WSYNC();
; #pragma unroll
;     for (int v8 = 0; v8 < 8; ++v8) { float og[8], w[8], y[8]; unpack8(ogv[v8], og); unpack8(*(const LAS u32x4*)(OT + lane * 72 + 8 * v8), y);
; #pragma unroll
;         for (int e = 0; e < 8; ++e) { const float z = og[e]; w[e] = y[e] * (z * sigmoidf_(z)); }
;         *(u32x4*)(MIXO + row * DM + h * 64 + 8 * v8) = pack8(w); }
	v_pk_add_f32 v[50:51], v[50:51], v[52:53]
	v_mov_b32_e32 v55, v41
	v_pk_fma_f32 v[50:51], v[50:51], s[62:63], v[98:99] op_sel_hi:[1,0,0]
	v_mov_b32_e32 v53, v48
	v_mul_f32_e32 v52, 0x4b800000, v51
	v_cmp_gt_f32_e64 s[26:27], s45, v51
	v_cmp_gt_f32_e32 vcc, s45, v50
	v_mov_b32_e32 v56, v45
	v_cndmask_b32_e64 v51, v51, v52, s[26:27]
	v_rsq_f32_e32 v51, v51
	v_cvt_pk_bf16_f32 v52, v54, s0
	ds_write_b16 v163, v52 offset:5136
	v_mov_b32_e32 v54, v37
	v_mul_f32_e32 v52, 0x45800000, v51
	v_cndmask_b32_e64 v51, v51, v52, s[26:27]
	v_mul_f32_e32 v34, v34, v51
	v_mul_f32_e32 v34, v100, v34
	v_cvt_pk_bf16_f32 v34, v34, s0
	ds_write_b16 v163, v34 offset:6912
	v_mul_f32_e32 v34, v38, v51
	v_mul_f32_e32 v34, v103, v34
	v_cvt_pk_bf16_f32 v34, v34, s0
	ds_write_b16 v163, v34 offset:6944
	v_mul_f32_e32 v34, v42, v51
	v_mul_f32_e32 v34, v102, v34
	v_cvt_pk_bf16_f32 v34, v34, s0
	ds_write_b16 v163, v34 offset:6976
	v_mul_f32_e32 v34, v46, v51
	v_mul_f32_e32 v34, v101, v34
	v_cvt_pk_bf16_f32 v34, v34, s0
	ds_write_b16 v163, v34 offset:7008
	v_mul_f32_e32 v34, 0x4b800000, v50
	v_cndmask_b32_e32 v34, v50, v34, vcc
	v_mov_b32_e32 v50, v36
	v_mov_b32_e32 v51, v40
	v_pk_mul_f32 v[50:51], v[50:51], v[50:51]
	v_mov_b32_e32 v52, v44
	v_pk_mul_f32 v[54:55], v[54:55], v[54:55]
	v_mov_b32_e32 v57, v49
	v_pk_mul_f32 v[52:53], v[52:53], v[52:53]
	v_pk_mul_f32 v[56:57], v[56:57], v[56:57]
	v_mov_b32_e32 v58, v54
	v_mov_b32_e32 v59, v50
	v_mov_b32_e32 v50, v55
	v_pk_add_f32 v[50:51], v[58:59], v[50:51]
	v_mov_b32_e32 v54, v56
	v_mov_b32_e32 v55, v52
	v_rsq_f32_e32 v34, v34
	v_pk_add_f32 v[50:51], v[50:51], v[54:55]
	v_mov_b32_e32 v52, v57
	v_pk_add_f32 v[50:51], v[50:51], v[52:53]
	ds_bpermute_b32 v53, v0, v51
	ds_bpermute_b32 v52, v0, v50
	v_mul_f32_e32 v0, 0x45800000, v34
	v_cndmask_b32_e32 v0, v34, v0, vcc
	v_mul_f32_e32 v34, v35, v0
	v_mul_f32_e32 v38, v100, v34
	s_waitcnt lgkmcnt(0)
	v_pk_add_f32 v[34:35], v[50:51], v[52:53]
	ds_bpermute_b32 v51, v106, v35
	ds_bpermute_b32 v50, v106, v34
	v_cvt_pk_bf16_f32 v38, v38, s0
	ds_write_b16 v163, v38 offset:7056
	v_mul_f32_e32 v38, v39, v0
	v_mul_f32_e32 v42, v103, v38
	s_waitcnt lgkmcnt(1)
	v_pk_add_f32 v[34:35], v[34:35], v[50:51]
	ds_bpermute_b32 v39, v105, v35
	ds_bpermute_b32 v38, v105, v34
	v_cvt_pk_bf16_f32 v42, v42, s0
	ds_write_b16 v163, v42 offset:7088
	v_mul_f32_e32 v42, v43, v0
	v_mul_f32_e32 v0, v47, v0
	s_waitcnt lgkmcnt(1)
	v_pk_add_f32 v[34:35], v[34:35], v[38:39]
	ds_bpermute_b32 v39, v104, v35
	ds_bpermute_b32 v38, v104, v34
	v_mul_f32_e32 v0, v101, v0
	v_cvt_pk_bf16_f32 v0, v0, s0
	ds_write_b16 v163, v0 offset:7152
	v_lshlrev_b32_e32 v52, 16, v30
	s_waitcnt lgkmcnt(1)
	v_pk_add_f32 v[34:35], v[34:35], v[38:39]
	v_and_b32_e32 v53, 0xffff0000, v30
	v_pk_fma_f32 v[34:35], v[34:35], s[62:63], v[98:99] op_sel_hi:[1,0,0]
	v_mul_f32_e32 v42, v102, v42
	v_mul_f32_e32 v38, 0x4b800000, v35
	v_cmp_gt_f32_e32 vcc, s45, v35
	v_cmp_gt_f32_e64 s[26:27], s45, v34
	v_cvt_pk_bf16_f32 v42, v42, s0
	v_cndmask_b32_e32 v35, v35, v38, vcc
	v_rsq_f32_e32 v35, v35
	ds_write_b16 v163, v42 offset:7120
	v_mul_f32_e32 v0, 0x45800000, v35
	v_cndmask_b32_e32 v0, v35, v0, vcc
	v_mul_f32_e32 v35, v36, v0
	v_mul_f32_e32 v35, v100, v35
	v_cvt_pk_bf16_f32 v35, v35, s0
	ds_write_b16 v163, v35 offset:7200
	v_mul_f32_e32 v35, v40, v0
	v_mul_f32_e32 v35, v103, v35
	v_cvt_pk_bf16_f32 v35, v35, s0
	ds_write_b16 v163, v35 offset:7232
	v_mul_f32_e32 v35, v44, v0
	v_mul_f32_e32 v35, v102, v35
	v_cvt_pk_bf16_f32 v35, v35, s0
	ds_write_b16 v163, v35 offset:7264
	v_mul_f32_e32 v35, 0x4b800000, v34
	v_cndmask_b32_e64 v34, v34, v35, s[26:27]
	v_rsq_f32_e32 v34, v34
	v_mul_f32_e32 v0, v48, v0
	v_mul_f32_e32 v0, v101, v0
	v_cvt_pk_bf16_f32 v0, v0, s0
	ds_write_b16 v163, v0 offset:7296
	v_mul_f32_e32 v0, 0x45800000, v34
	v_cndmask_b32_e64 v0, v34, v0, s[26:27]
	v_mul_f32_e32 v34, v37, v0
	v_mul_f32_e32 v34, v100, v34
	v_cvt_pk_bf16_f32 v34, v34, s0
	ds_write_b16 v163, v34 offset:7344
	v_mul_f32_e32 v34, v41, v0
	v_mul_f32_e32 v34, v103, v34
	v_cvt_pk_bf16_f32 v34, v34, s0
	ds_write_b16 v163, v34 offset:7376
	v_mul_f32_e32 v34, v45, v0
	v_mul_f32_e32 v34, v102, v34
	v_mul_f32_e32 v0, v49, v0
	v_cvt_pk_bf16_f32 v34, v34, s0
	v_mul_f32_e32 v0, v101, v0
	ds_write_b16 v163, v34 offset:7408
	v_cvt_pk_bf16_f32 v0, v0, s0
	v_lshlrev_b64 v[34:35], 11, v[122:123]
	ds_write_b16 v163, v0 offset:7440
	v_lshl_add_u64 v[34:35], s[78:79], 0, v[34:35]
	v_mul_f32_e32 v0, 0xbfb8aa3b, v52
	v_lshl_add_u64 v[46:47], v[34:35], 0, s[34:35]
	v_exp_f32_e32 v34, v0
	v_mul_f32_e32 v0, 0xbfb8aa3b, v53
	v_exp_f32_e32 v35, v0
	s_waitcnt lgkmcnt(0)
	ds_read_b128 v[48:51], v169
	ds_read_b128 v[42:45], v169 offset:16
	ds_read_b128 v[38:41], v169 offset:32
	v_pk_add_f32 v[54:55], v[34:35], 1.0 op_sel_hi:[1,0]
	s_nop 0
	v_div_scale_f32 v0, s[2:3], v55, v55, 1.0
	v_rcp_f32_e32 v30, v0
	s_waitcnt lgkmcnt(2)
; #define LAS __attribute__((address_space(3)))
; __device__ __forceinline__ u32x4 pack8(const float* f) { u32x4 w; w.x = pk2(f[0], f[1]); w.y = pk2(f[2], f[3]); w.z = pk2(f[4], f[5]); w.w = pk2(f[6], f[7]); return w; }
; __device__ __forceinline__ float sigmoidf_(float z) { return 1.f / (1.f + __expf(-z)); }
; __device__ __forceinline__ void gla_out_unit(int u, const bf16* proj, const float* wg, const float* bg, const float* gn, const float* SP, bf16* MIXO, LAS unsigned char* wl, int lane) {
;     ...
; #pragma unroll
;     for (int v8 = 0; v8 < 8; ++v8) { float og[8], w[8], y[8]; unpack8(ogv[v8], og); unpack8(*(const LAS u32x4*)(OT + lane * 72 + 8 * v8), y);
; #pragma unroll
;         for (int e = 0; e < 8; ++e) { const float z = og[e]; w[e] = y[e] * (z * sigmoidf_(z)); }
;         *(u32x4*)(MIXO + row * DM + h * 64 + 8 * v8) = pack8(w); }
	v_lshlrev_b32_e32 v56, 16, v48
	v_and_b32_e32 v57, 0xffff0000, v48
	ds_read_b128 v[34:37], v169 offset:48
	v_fma_f32 v48, -v0, v30, 1.0
	v_fmac_f32_e32 v30, v48, v30
	v_div_scale_f32 v48, vcc, 1.0, v55, 1.0
	v_mul_f32_e32 v58, v48, v30
	v_fma_f32 v59, -v0, v58, v48
	v_fmac_f32_e32 v58, v59, v30
	v_fma_f32 v0, -v0, v58, v48
	v_div_scale_f32 v48, s[2:3], v54, v54, 1.0
	v_rcp_f32_e32 v60, v48
	v_div_fmas_f32 v0, v0, v30, v58
	v_div_fixup_f32 v55, v0, v55, 1.0
	v_fma_f32 v0, -v48, v60, 1.0
	v_fmac_f32_e32 v60, v0, v60
	v_div_scale_f32 v0, vcc, 1.0, v54, 1.0
	v_mul_f32_e32 v61, v0, v60
	v_fma_f32 v30, -v48, v61, v0
	v_fmac_f32_e32 v61, v30, v60
	v_lshlrev_b32_e32 v30, 16, v31
	v_fma_f32 v0, -v48, v61, v0
	v_and_b32_e32 v31, 0xffff0000, v31
	v_mul_f32_e32 v48, 0xbfb8aa3b, v30
	v_exp_f32_e32 v58, v48
	v_mul_f32_e32 v48, 0xbfb8aa3b, v31
	v_exp_f32_e32 v59, v48
	v_div_fmas_f32 v0, v0, v60, v61
	v_div_fixup_f32 v54, v0, v54, 1.0
	v_pk_mul_f32 v[52:53], v[54:55], v[52:53]
	v_pk_add_f32 v[54:55], v[58:59], 1.0 op_sel_hi:[1,0]
	v_pk_mul_f32 v[52:53], v[52:53], v[56:57]
	v_div_scale_f32 v0, s[2:3], v55, v55, 1.0
	v_rcp_f32_e32 v58, v0
	v_lshlrev_b32_e32 v48, 16, v49
	v_and_b32_e32 v49, 0xffff0000, v49
	v_fma_f32 v56, -v0, v58, 1.0
	v_fmac_f32_e32 v58, v56, v58
	v_div_scale_f32 v56, vcc, 1.0, v55, 1.0
	v_mul_f32_e32 v57, v56, v58
	v_fma_f32 v59, -v0, v57, v56
	v_fmac_f32_e32 v57, v59, v58
	v_fma_f32 v0, -v0, v57, v56
	v_div_scale_f32 v56, s[2:3], v54, v54, 1.0
	v_rcp_f32_e32 v60, v56
	v_div_fmas_f32 v0, v0, v58, v57
	v_div_fixup_f32 v55, v0, v55, 1.0
	v_fma_f32 v0, -v56, v60, 1.0
	v_fmac_f32_e32 v60, v0, v60
	v_div_scale_f32 v0, vcc, 1.0, v54, 1.0
	v_mul_f32_e32 v61, v0, v60
	v_fma_f32 v57, -v56, v61, v0
	v_fmac_f32_e32 v61, v57, v60
	v_fma_f32 v0, -v56, v61, v0
	v_lshlrev_b32_e32 v56, 16, v32
	v_and_b32_e32 v57, 0xffff0000, v32
	v_mul_f32_e32 v32, 0xbfb8aa3b, v56
	v_exp_f32_e32 v58, v32
	v_mul_f32_e32 v32, 0xbfb8aa3b, v57
	v_exp_f32_e32 v59, v32
	v_div_fmas_f32 v0, v0, v60, v61
	v_div_fixup_f32 v54, v0, v54, 1.0
	v_pk_mul_f32 v[30:31], v[54:55], v[30:31]
	v_pk_add_f32 v[54:55], v[58:59], 1.0 op_sel_hi:[1,0]
	v_pk_mul_f32 v[48:49], v[30:31], v[48:49]
	v_div_scale_f32 v0, s[2:3], v55, v55, 1.0
	v_rcp_f32_e32 v32, v0
	v_lshlrev_b32_e32 v30, 16, v50
	v_and_b32_e32 v31, 0xffff0000, v50
	v_fma_f32 v50, -v0, v32, 1.0
	v_fmac_f32_e32 v32, v50, v32
	v_div_scale_f32 v50, vcc, 1.0, v55, 1.0
	v_mul_f32_e32 v58, v50, v32
	v_fma_f32 v59, -v0, v58, v50
	v_fmac_f32_e32 v58, v59, v32
	v_fma_f32 v0, -v0, v58, v50
	v_div_scale_f32 v50, s[2:3], v54, v54, 1.0
	v_rcp_f32_e32 v60, v50
	v_div_fmas_f32 v0, v0, v32, v58
	v_div_fixup_f32 v55, v0, v55, 1.0
	v_fma_f32 v0, -v50, v60, 1.0
	v_fmac_f32_e32 v60, v0, v60
	v_div_scale_f32 v0, vcc, 1.0, v54, 1.0
	v_mul_f32_e32 v61, v0, v60
	v_fma_f32 v32, -v50, v61, v0
	v_fmac_f32_e32 v61, v32, v60
	v_lshlrev_b32_e32 v32, 16, v33
	v_fma_f32 v0, -v50, v61, v0
	v_and_b32_e32 v33, 0xffff0000, v33
	v_mul_f32_e32 v50, 0xbfb8aa3b, v32
	v_exp_f32_e32 v58, v50
	v_mul_f32_e32 v50, 0xbfb8aa3b, v33
	v_exp_f32_e32 v59, v50
	v_div_fmas_f32 v0, v0, v60, v61
	v_div_fixup_f32 v54, v0, v54, 1.0
	v_pk_mul_f32 v[54:55], v[54:55], v[56:57]
	v_pk_add_f32 v[56:57], v[58:59], 1.0 op_sel_hi:[1,0]
	v_pk_mul_f32 v[54:55], v[54:55], v[30:31]
	v_div_scale_f32 v0, s[2:3], v57, v57, 1.0
	v_rcp_f32_e32 v50, v0
	v_lshlrev_b32_e32 v30, 16, v51
	v_and_b32_e32 v31, 0xffff0000, v51
	v_fma_f32 v51, -v0, v50, 1.0
	v_fmac_f32_e32 v50, v51, v50
	v_div_scale_f32 v51, vcc, 1.0, v57, 1.0
	v_mul_f32_e32 v58, v51, v50
	v_fma_f32 v59, -v0, v58, v51
	v_fmac_f32_e32 v58, v59, v50
	v_div_scale_f32 v59, s[2:3], v56, v56, 1.0
	v_rcp_f32_e32 v60, v59
	v_fma_f32 v0, -v0, v58, v51
	v_div_fmas_f32 v0, v0, v50, v58
	v_div_fixup_f32 v51, v0, v57, 1.0
	v_fma_f32 v0, -v59, v60, 1.0
	v_fmac_f32_e32 v60, v0, v60
	v_div_scale_f32 v0, vcc, 1.0, v56, 1.0
	v_mul_f32_e32 v50, v0, v60
	v_fma_f32 v57, -v59, v50, v0
	v_fmac_f32_e32 v50, v57, v60
	v_fma_f32 v0, -v59, v50, v0
	v_div_fmas_f32 v0, v0, v60, v50
	v_div_fixup_f32 v50, v0, v56, 1.0
	v_pk_mul_f32 v[32:33], v[50:51], v[32:33]
	s_nop 0
	v_pk_mul_f32 v[50:51], v[32:33], v[30:31]
	v_cvt_pk_bf16_f32 v30, v52, v53
	v_lshlrev_b32_e32 v52, 16, v26
	v_and_b32_e32 v53, 0xffff0000, v26
	v_mul_f32_e32 v0, 0xbfb8aa3b, v52
	v_exp_f32_e32 v56, v0
	v_mul_f32_e32 v0, 0xbfb8aa3b, v53
	v_exp_f32_e32 v57, v0
	v_cvt_pk_bf16_f32 v31, v48, v49
	v_cvt_pk_bf16_f32 v32, v54, v55
	v_cvt_pk_bf16_f32 v33, v50, v51
	v_pk_add_f32 v[48:49], v[56:57], 1.0 op_sel_hi:[1,0]
	global_store_dwordx4 v[46:47], v[30:33], off
	v_div_scale_f32 v0, s[2:3], v49, v49, 1.0
	v_rcp_f32_e32 v26, v0
	s_waitcnt lgkmcnt(2)
; #define LAS __attribute__((address_space(3)))
; __device__ __forceinline__ u32x4 pack8(const float* f) { u32x4 w; w.x = pk2(f[0], f[1]); w.y = pk2(f[2], f[3]); w.z = pk2(f[4], f[5]); w.w = pk2(f[6], f[7]); return w; }
; __device__ __forceinline__ float sigmoidf_(float z) { return 1.f / (1.f + __expf(-z)); }
; __device__ __forceinline__ void gla_out_unit(int u, const bf16* proj, const float* wg, const float* bg, const float* gn, const float* SP, bf16* MIXO, LAS unsigned char* wl, int lane) {
;     ...
; #pragma unroll
;     for (int v8 = 0; v8 < 8; ++v8) { float og[8], w[8], y[8]; unpack8(ogv[v8], og); unpack8(*(const LAS u32x4*)(OT + lane * 72 + 8 * v8), y);
; #pragma unroll
;         for (int e = 0; e < 8; ++e) { const float z = og[e]; w[e] = y[e] * (z * sigmoidf_(z)); }
;         *(u32x4*)(MIXO + row * DM + h * 64 + 8 * v8) = pack8(w); }
	v_lshlrev_b32_e32 v30, 16, v42
	v_and_b32_e32 v31, 0xffff0000, v42
	v_fma_f32 v32, -v0, v26, 1.0
	v_fmac_f32_e32 v26, v32, v26
	v_div_scale_f32 v32, vcc, 1.0, v49, 1.0
	v_mul_f32_e32 v33, v32, v26
	v_fma_f32 v42, -v0, v33, v32
	v_fmac_f32_e32 v33, v42, v26
	v_fma_f32 v0, -v0, v33, v32
	v_div_scale_f32 v32, s[2:3], v48, v48, 1.0
	v_rcp_f32_e32 v42, v32
	v_div_fmas_f32 v0, v0, v26, v33
	v_div_fixup_f32 v33, v0, v49, 1.0
	v_fma_f32 v0, -v32, v42, 1.0
	v_fmac_f32_e32 v42, v0, v42
	v_div_scale_f32 v0, vcc, 1.0, v48, 1.0
	v_mul_f32_e32 v49, v0, v42
	v_fma_f32 v26, -v32, v49, v0
	v_fmac_f32_e32 v49, v26, v42
	v_lshlrev_b32_e32 v26, 16, v27
	v_fma_f32 v0, -v32, v49, v0
	v_and_b32_e32 v27, 0xffff0000, v27
	v_mul_f32_e32 v32, 0xbfb8aa3b, v26
	v_exp_f32_e32 v50, v32
	v_mul_f32_e32 v32, 0xbfb8aa3b, v27
	v_exp_f32_e32 v51, v32
	v_div_fmas_f32 v0, v0, v42, v49
	v_div_fixup_f32 v32, v0, v48, 1.0
	v_pk_mul_f32 v[32:33], v[32:33], v[52:53]
	v_pk_add_f32 v[48:49], v[50:51], 1.0 op_sel_hi:[1,0]
	v_pk_mul_f32 v[30:31], v[32:33], v[30:31]
	v_div_scale_f32 v0, s[2:3], v49, v49, 1.0
	v_rcp_f32_e32 v42, v0
	v_lshlrev_b32_e32 v32, 16, v43
	v_and_b32_e32 v33, 0xffff0000, v43
	v_fma_f32 v43, -v0, v42, 1.0
	v_fmac_f32_e32 v42, v43, v42
	v_div_scale_f32 v43, vcc, 1.0, v49, 1.0
	v_mul_f32_e32 v50, v43, v42
	v_fma_f32 v51, -v0, v50, v43
	v_fmac_f32_e32 v50, v51, v42
	v_div_scale_f32 v51, s[2:3], v48, v48, 1.0
	v_rcp_f32_e32 v54, v51
	v_fma_f32 v0, -v0, v50, v43
	v_div_fmas_f32 v0, v0, v42, v50
	v_div_fixup_f32 v43, v0, v49, 1.0
	v_fma_f32 v0, -v51, v54, 1.0
	v_fmac_f32_e32 v54, v0, v54
	v_div_scale_f32 v0, vcc, 1.0, v48, 1.0
	v_mul_f32_e32 v42, v0, v54
	v_fma_f32 v49, -v51, v42, v0
	v_fmac_f32_e32 v42, v49, v54
	v_lshlrev_b32_e32 v50, 16, v28
	v_fma_f32 v0, -v51, v42, v0
	v_and_b32_e32 v51, 0xffff0000, v28
	v_mul_f32_e32 v28, 0xbfb8aa3b, v50
	v_exp_f32_e32 v52, v28
	v_mul_f32_e32 v28, 0xbfb8aa3b, v51
	v_exp_f32_e32 v53, v28
	v_div_fmas_f32 v0, v0, v54, v42
	v_div_fixup_f32 v42, v0, v48, 1.0
	v_pk_mul_f32 v[26:27], v[42:43], v[26:27]
	v_pk_add_f32 v[42:43], v[52:53], 1.0 op_sel_hi:[1,0]
	v_pk_mul_f32 v[32:33], v[26:27], v[32:33]
	v_div_scale_f32 v0, s[2:3], v43, v43, 1.0
	v_rcp_f32_e32 v28, v0
	v_lshlrev_b32_e32 v26, 16, v44
	v_and_b32_e32 v27, 0xffff0000, v44
	v_fma_f32 v44, -v0, v28, 1.0
	v_fmac_f32_e32 v28, v44, v28
	v_div_scale_f32 v44, vcc, 1.0, v43, 1.0
	v_mul_f32_e32 v48, v44, v28
	v_fma_f32 v49, -v0, v48, v44
	v_fmac_f32_e32 v48, v49, v28
	v_fma_f32 v0, -v0, v48, v44
	v_div_scale_f32 v44, s[2:3], v42, v42, 1.0
	v_rcp_f32_e32 v52, v44
	v_div_fmas_f32 v0, v0, v28, v48
	v_div_fixup_f32 v43, v0, v43, 1.0
	v_fma_f32 v0, -v44, v52, 1.0
	v_fmac_f32_e32 v52, v0, v52
	v_div_scale_f32 v0, vcc, 1.0, v42, 1.0
	v_mul_f32_e32 v53, v0, v52
	v_fma_f32 v28, -v44, v53, v0
	v_fmac_f32_e32 v53, v28, v52
	v_lshlrev_b32_e32 v28, 16, v29
	v_fma_f32 v0, -v44, v53, v0
	v_and_b32_e32 v29, 0xffff0000, v29
	v_mul_f32_e32 v44, 0xbfb8aa3b, v28
	v_exp_f32_e32 v48, v44
	v_mul_f32_e32 v44, 0xbfb8aa3b, v29
	v_exp_f32_e32 v49, v44
	v_div_fmas_f32 v0, v0, v52, v53
	v_div_fixup_f32 v42, v0, v42, 1.0
	v_pk_mul_f32 v[42:43], v[42:43], v[50:51]
	v_pk_add_f32 v[48:49], v[48:49], 1.0 op_sel_hi:[1,0]
	v_pk_mul_f32 v[42:43], v[42:43], v[26:27]
	v_div_scale_f32 v0, s[2:3], v49, v49, 1.0
	v_rcp_f32_e32 v44, v0
	v_lshlrev_b32_e32 v26, 16, v45
	v_and_b32_e32 v27, 0xffff0000, v45
	v_fma_f32 v45, -v0, v44, 1.0
	v_fmac_f32_e32 v44, v45, v44
	v_div_scale_f32 v45, vcc, 1.0, v49, 1.0
	v_mul_f32_e32 v50, v45, v44
	v_fma_f32 v51, -v0, v50, v45
	v_fmac_f32_e32 v50, v51, v44
	v_div_scale_f32 v51, s[2:3], v48, v48, 1.0
	v_rcp_f32_e32 v52, v51
	v_fma_f32 v0, -v0, v50, v45
	v_div_fmas_f32 v0, v0, v44, v50
	v_div_fixup_f32 v45, v0, v49, 1.0
	v_fma_f32 v0, -v51, v52, 1.0
	v_fmac_f32_e32 v52, v0, v52
	v_div_scale_f32 v0, vcc, 1.0, v48, 1.0
	v_mul_f32_e32 v44, v0, v52
	v_fma_f32 v49, -v51, v44, v0
	v_fmac_f32_e32 v44, v49, v52
	v_fma_f32 v0, -v51, v44, v0
	v_div_fmas_f32 v0, v0, v52, v44
	v_div_fixup_f32 v44, v0, v48, 1.0
	v_pk_mul_f32 v[28:29], v[44:45], v[28:29]
	s_nop 0
	v_pk_mul_f32 v[44:45], v[28:29], v[26:27]
	v_cvt_pk_bf16_f32 v26, v30, v31
	v_lshlrev_b32_e32 v30, 16, v22
	v_and_b32_e32 v31, 0xffff0000, v22
	v_mul_f32_e32 v0, 0xbfb8aa3b, v30
	v_exp_f32_e32 v48, v0
	v_mul_f32_e32 v0, 0xbfb8aa3b, v31
	v_exp_f32_e32 v49, v0
	v_cvt_pk_bf16_f32 v27, v32, v33
	v_cvt_pk_bf16_f32 v28, v42, v43
	v_cvt_pk_bf16_f32 v29, v44, v45
	v_pk_add_f32 v[32:33], v[48:49], 1.0 op_sel_hi:[1,0]
	global_store_dwordx4 v[46:47], v[26:29], off offset:16
	v_div_scale_f32 v0, s[2:3], v33, v33, 1.0
	v_rcp_f32_e32 v22, v0
	s_waitcnt lgkmcnt(1)
; #define LAS __attribute__((address_space(3)))
; __device__ __forceinline__ u32x4 pack8(const float* f) { u32x4 w; w.x = pk2(f[0], f[1]); w.y = pk2(f[2], f[3]); w.z = pk2(f[4], f[5]); w.w = pk2(f[6], f[7]); return w; }
; __device__ __forceinline__ float sigmoidf_(float z) { return 1.f / (1.f + __expf(-z)); }
; __device__ __forceinline__ void gla_out_unit(int u, const bf16* proj, const float* wg, const float* bg, const float* gn, const float* SP, bf16* MIXO, LAS unsigned char* wl, int lane) {
;     ...
; #pragma unroll
;     for (int v8 = 0; v8 < 8; ++v8) { float og[8], w[8], y[8]; unpack8(ogv[v8], og); unpack8(*(const LAS u32x4*)(OT + lane * 72 + 8 * v8), y);
; #pragma unroll
;         for (int e = 0; e < 8; ++e) { const float z = og[e]; w[e] = y[e] * (z * sigmoidf_(z)); }
;         *(u32x4*)(MIXO + row * DM + h * 64 + 8 * v8) = pack8(w); }
	v_lshlrev_b32_e32 v26, 16, v38
	v_and_b32_e32 v27, 0xffff0000, v38
	v_fma_f32 v28, -v0, v22, 1.0
	v_fmac_f32_e32 v22, v28, v22
	v_div_scale_f32 v28, vcc, 1.0, v33, 1.0
	v_mul_f32_e32 v29, v28, v22
	v_fma_f32 v38, -v0, v29, v28
	v_fmac_f32_e32 v29, v38, v22
	v_fma_f32 v0, -v0, v29, v28
	v_div_scale_f32 v28, s[2:3], v32, v32, 1.0
	v_rcp_f32_e32 v38, v28
	v_div_fmas_f32 v0, v0, v22, v29
	v_div_fixup_f32 v29, v0, v33, 1.0
	v_fma_f32 v0, -v28, v38, 1.0
	v_fmac_f32_e32 v38, v0, v38
	v_div_scale_f32 v0, vcc, 1.0, v32, 1.0
	v_mul_f32_e32 v33, v0, v38
	v_fma_f32 v22, -v28, v33, v0
	v_fmac_f32_e32 v33, v22, v38
	v_lshlrev_b32_e32 v22, 16, v23
	v_fma_f32 v0, -v28, v33, v0
	v_and_b32_e32 v23, 0xffff0000, v23
	v_mul_f32_e32 v28, 0xbfb8aa3b, v22
	v_exp_f32_e32 v42, v28
	v_mul_f32_e32 v28, 0xbfb8aa3b, v23
	v_exp_f32_e32 v43, v28
	v_div_fmas_f32 v0, v0, v38, v33
	v_div_fixup_f32 v28, v0, v32, 1.0
	v_pk_mul_f32 v[28:29], v[28:29], v[30:31]
	v_pk_add_f32 v[30:31], v[42:43], 1.0 op_sel_hi:[1,0]
	v_pk_mul_f32 v[26:27], v[28:29], v[26:27]
	v_div_scale_f32 v0, s[2:3], v31, v31, 1.0
	v_rcp_f32_e32 v32, v0
	v_lshlrev_b32_e32 v28, 16, v39
	v_and_b32_e32 v29, 0xffff0000, v39
	v_fma_f32 v33, -v0, v32, 1.0
	v_fmac_f32_e32 v32, v33, v32
	v_div_scale_f32 v33, vcc, 1.0, v31, 1.0
	v_mul_f32_e32 v38, v33, v32
	v_fma_f32 v39, -v0, v38, v33
	v_fmac_f32_e32 v38, v39, v32
	v_fma_f32 v0, -v0, v38, v33
	v_div_scale_f32 v33, s[2:3], v30, v30, 1.0
	v_rcp_f32_e32 v42, v33
	v_div_fmas_f32 v0, v0, v32, v38
	v_div_fixup_f32 v31, v0, v31, 1.0
	v_fma_f32 v0, -v33, v42, 1.0
	v_fmac_f32_e32 v42, v0, v42
	v_div_scale_f32 v0, vcc, 1.0, v30, 1.0
	v_mul_f32_e32 v43, v0, v42
	v_fma_f32 v32, -v33, v43, v0
	v_fmac_f32_e32 v43, v32, v42
	v_lshlrev_b32_e32 v32, 16, v24
	v_fma_f32 v0, -v33, v43, v0
	v_and_b32_e32 v33, 0xffff0000, v24
	v_mul_f32_e32 v24, 0xbfb8aa3b, v32
	v_exp_f32_e32 v38, v24
	v_mul_f32_e32 v24, 0xbfb8aa3b, v33
	v_exp_f32_e32 v39, v24
	v_div_fmas_f32 v0, v0, v42, v43
	v_div_fixup_f32 v30, v0, v30, 1.0
	v_pk_mul_f32 v[22:23], v[30:31], v[22:23]
	v_pk_add_f32 v[30:31], v[38:39], 1.0 op_sel_hi:[1,0]
	v_pk_mul_f32 v[28:29], v[22:23], v[28:29]
	v_div_scale_f32 v0, s[2:3], v31, v31, 1.0
	v_rcp_f32_e32 v24, v0
	v_lshlrev_b32_e32 v22, 16, v40
	v_and_b32_e32 v23, 0xffff0000, v40
	v_fma_f32 v38, -v0, v24, 1.0
	v_fmac_f32_e32 v24, v38, v24
	v_div_scale_f32 v38, vcc, 1.0, v31, 1.0
	v_mul_f32_e32 v39, v38, v24
	v_fma_f32 v40, -v0, v39, v38
	v_fmac_f32_e32 v39, v40, v24
	v_fma_f32 v0, -v0, v39, v38
	v_div_scale_f32 v38, s[2:3], v30, v30, 1.0
	v_rcp_f32_e32 v40, v38
	v_div_fmas_f32 v0, v0, v24, v39
	v_div_fixup_f32 v31, v0, v31, 1.0
	v_fma_f32 v0, -v38, v40, 1.0
	v_fmac_f32_e32 v40, v0, v40
	v_div_scale_f32 v0, vcc, 1.0, v30, 1.0
	v_mul_f32_e32 v42, v0, v40
	v_fma_f32 v24, -v38, v42, v0
	v_fmac_f32_e32 v42, v24, v40
	v_lshlrev_b32_e32 v24, 16, v25
	v_and_b32_e32 v25, 0xffff0000, v25
	v_fma_f32 v0, -v38, v42, v0
	v_mul_f32_e32 v38, 0xbfb8aa3b, v24
	v_mul_f32_e32 v39, 0xbfb8aa3b, v25
	v_exp_f32_e32 v38, v38
	v_exp_f32_e32 v39, v39
	v_div_fmas_f32 v0, v0, v40, v42
	v_div_fixup_f32 v30, v0, v30, 1.0
	v_pk_mul_f32 v[30:31], v[30:31], v[32:33]
	v_pk_add_f32 v[32:33], v[38:39], 1.0 op_sel_hi:[1,0]
	v_pk_mul_f32 v[30:31], v[30:31], v[22:23]
	v_div_scale_f32 v0, s[2:3], v33, v33, 1.0
	v_rcp_f32_e32 v38, v0
	v_lshlrev_b32_e32 v22, 16, v41
	v_and_b32_e32 v23, 0xffff0000, v41
	v_fma_f32 v39, -v0, v38, 1.0
	v_fmac_f32_e32 v38, v39, v38
	v_div_scale_f32 v39, vcc, 1.0, v33, 1.0
	v_mul_f32_e32 v40, v39, v38
	v_fma_f32 v41, -v0, v40, v39
	v_fmac_f32_e32 v40, v41, v38
	v_fma_f32 v0, -v0, v40, v39
	v_div_scale_f32 v39, s[2:3], v32, v32, 1.0
	v_rcp_f32_e32 v41, v39
	v_div_fmas_f32 v0, v0, v38, v40
	v_div_fixup_f32 v33, v0, v33, 1.0
	v_fma_f32 v0, -v39, v41, 1.0
	v_fmac_f32_e32 v41, v0, v41
	v_div_scale_f32 v0, vcc, 1.0, v32, 1.0
	v_mul_f32_e32 v38, v0, v41
	v_fma_f32 v40, -v39, v38, v0
	v_fmac_f32_e32 v38, v40, v41
	v_fma_f32 v0, -v39, v38, v0
	v_div_fmas_f32 v0, v0, v41, v38
	v_div_fixup_f32 v32, v0, v32, 1.0
	v_pk_mul_f32 v[24:25], v[32:33], v[24:25]
	s_nop 0
	v_pk_mul_f32 v[32:33], v[24:25], v[22:23]
	v_cvt_pk_bf16_f32 v22, v26, v27
	v_lshlrev_b32_e32 v26, 16, v18
	v_and_b32_e32 v27, 0xffff0000, v18
	v_mul_f32_e32 v0, 0xbfb8aa3b, v26
	v_exp_f32_e32 v38, v0
	v_mul_f32_e32 v0, 0xbfb8aa3b, v27
	v_exp_f32_e32 v39, v0
	v_cvt_pk_bf16_f32 v23, v28, v29
	v_cvt_pk_bf16_f32 v24, v30, v31
	v_cvt_pk_bf16_f32 v25, v32, v33
	v_pk_add_f32 v[28:29], v[38:39], 1.0 op_sel_hi:[1,0]
	global_store_dwordx4 v[46:47], v[22:25], off offset:32
	v_div_scale_f32 v0, s[2:3], v29, v29, 1.0
	v_rcp_f32_e32 v18, v0
	s_waitcnt lgkmcnt(0)
; #define LAS __attribute__((address_space(3)))
; __device__ __forceinline__ u32x4 pack8(const float* f) { u32x4 w; w.x = pk2(f[0], f[1]); w.y = pk2(f[2], f[3]); w.z = pk2(f[4], f[5]); w.w = pk2(f[6], f[7]); return w; }
; __device__ __forceinline__ float sigmoidf_(float z) { return 1.f / (1.f + __expf(-z)); }
; __device__ __forceinline__ void gla_out_unit(int u, const bf16* proj, const float* wg, const float* bg, const float* gn, const float* SP, bf16* MIXO, LAS unsigned char* wl, int lane) {
;     ...
; #pragma unroll
;     for (int v8 = 0; v8 < 8; ++v8) { float og[8], w[8], y[8]; unpack8(ogv[v8], og); unpack8(*(const LAS u32x4*)(OT + lane * 72 + 8 * v8), y);
; #pragma unroll
;         for (int e = 0; e < 8; ++e) { const float z = og[e]; w[e] = y[e] * (z * sigmoidf_(z)); }
;         *(u32x4*)(MIXO + row * DM + h * 64 + 8 * v8) = pack8(w); }
	v_lshlrev_b32_e32 v22, 16, v34
	v_and_b32_e32 v23, 0xffff0000, v34
	v_fma_f32 v24, -v0, v18, 1.0
	v_fmac_f32_e32 v18, v24, v18
	v_div_scale_f32 v24, vcc, 1.0, v29, 1.0
	v_mul_f32_e32 v25, v24, v18
	v_fma_f32 v30, -v0, v25, v24
	v_fmac_f32_e32 v25, v30, v18
	v_fma_f32 v0, -v0, v25, v24
	v_div_scale_f32 v24, s[2:3], v28, v28, 1.0
	v_rcp_f32_e32 v32, v24
	v_div_fmas_f32 v0, v0, v18, v25
	v_div_fixup_f32 v25, v0, v29, 1.0
	v_fma_f32 v0, -v24, v32, 1.0
	v_fmac_f32_e32 v32, v0, v32
	v_div_scale_f32 v0, vcc, 1.0, v28, 1.0
	v_mul_f32_e32 v29, v0, v32
	v_fma_f32 v18, -v24, v29, v0
	v_fmac_f32_e32 v29, v18, v32
	v_lshlrev_b32_e32 v18, 16, v19
	v_fma_f32 v0, -v24, v29, v0
	v_and_b32_e32 v19, 0xffff0000, v19
	v_mul_f32_e32 v24, 0xbfb8aa3b, v18
	v_exp_f32_e32 v30, v24
	v_mul_f32_e32 v24, 0xbfb8aa3b, v19
	v_exp_f32_e32 v31, v24
	v_div_fmas_f32 v0, v0, v32, v29
	v_div_fixup_f32 v24, v0, v28, 1.0
	v_pk_mul_f32 v[24:25], v[24:25], v[26:27]
	v_pk_add_f32 v[26:27], v[30:31], 1.0 op_sel_hi:[1,0]
	v_pk_mul_f32 v[22:23], v[24:25], v[22:23]
	v_div_scale_f32 v0, s[2:3], v27, v27, 1.0
	v_rcp_f32_e32 v28, v0
	v_lshlrev_b32_e32 v24, 16, v35
	v_and_b32_e32 v25, 0xffff0000, v35
	v_fma_f32 v29, -v0, v28, 1.0
	v_fmac_f32_e32 v28, v29, v28
	v_div_scale_f32 v29, vcc, 1.0, v27, 1.0
	v_mul_f32_e32 v30, v29, v28
	v_fma_f32 v31, -v0, v30, v29
	v_fmac_f32_e32 v30, v31, v28
	v_fma_f32 v0, -v0, v30, v29
	v_div_scale_f32 v29, s[2:3], v26, v26, 1.0
	v_rcp_f32_e32 v32, v29
	v_div_fmas_f32 v0, v0, v28, v30
	v_div_fixup_f32 v27, v0, v27, 1.0
	v_fma_f32 v0, -v29, v32, 1.0
	v_fmac_f32_e32 v32, v0, v32
	v_div_scale_f32 v0, vcc, 1.0, v26, 1.0
	v_mul_f32_e32 v33, v0, v32
	v_fma_f32 v28, -v29, v33, v0
	v_fmac_f32_e32 v33, v28, v32
	v_lshlrev_b32_e32 v28, 16, v20
	v_fma_f32 v0, -v29, v33, v0
	v_and_b32_e32 v29, 0xffff0000, v20
	v_mul_f32_e32 v20, 0xbfb8aa3b, v28
	v_exp_f32_e32 v30, v20
	v_mul_f32_e32 v20, 0xbfb8aa3b, v29
	v_exp_f32_e32 v31, v20
	v_div_fmas_f32 v0, v0, v32, v33
	v_div_fixup_f32 v26, v0, v26, 1.0
	v_pk_mul_f32 v[18:19], v[26:27], v[18:19]
	v_pk_add_f32 v[26:27], v[30:31], 1.0 op_sel_hi:[1,0]
	v_pk_mul_f32 v[24:25], v[18:19], v[24:25]
	v_div_scale_f32 v0, s[2:3], v27, v27, 1.0
	v_rcp_f32_e32 v20, v0
	v_lshlrev_b32_e32 v18, 16, v36
	v_and_b32_e32 v19, 0xffff0000, v36
	v_fma_f32 v30, -v0, v20, 1.0
	v_fmac_f32_e32 v20, v30, v20
	v_div_scale_f32 v30, vcc, 1.0, v27, 1.0
	v_mul_f32_e32 v31, v30, v20
	v_fma_f32 v32, -v0, v31, v30
	v_fmac_f32_e32 v31, v32, v20
	v_fma_f32 v0, -v0, v31, v30
	v_div_scale_f32 v30, s[2:3], v26, v26, 1.0
	v_rcp_f32_e32 v32, v30
	v_div_fmas_f32 v0, v0, v20, v31
	v_div_fixup_f32 v27, v0, v27, 1.0
	v_fma_f32 v0, -v30, v32, 1.0
	v_fmac_f32_e32 v32, v0, v32
	v_div_scale_f32 v0, vcc, 1.0, v26, 1.0
	v_mul_f32_e32 v33, v0, v32
	v_fma_f32 v20, -v30, v33, v0
	v_fmac_f32_e32 v33, v20, v32
	v_lshlrev_b32_e32 v20, 16, v21
	v_and_b32_e32 v21, 0xffff0000, v21
	v_fma_f32 v0, -v30, v33, v0
	v_mul_f32_e32 v30, 0xbfb8aa3b, v20
	v_mul_f32_e32 v31, 0xbfb8aa3b, v21
	v_exp_f32_e32 v30, v30
	v_exp_f32_e32 v31, v31
	v_div_fmas_f32 v0, v0, v32, v33
	v_div_fixup_f32 v26, v0, v26, 1.0
	v_pk_mul_f32 v[26:27], v[26:27], v[28:29]
	v_pk_add_f32 v[28:29], v[30:31], 1.0 op_sel_hi:[1,0]
	v_pk_mul_f32 v[26:27], v[26:27], v[18:19]
	v_div_scale_f32 v0, s[2:3], v29, v29, 1.0
	v_rcp_f32_e32 v30, v0
	v_lshlrev_b32_e32 v18, 16, v37
	v_and_b32_e32 v19, 0xffff0000, v37
	v_fma_f32 v31, -v0, v30, 1.0
	v_fmac_f32_e32 v30, v31, v30
	v_div_scale_f32 v31, vcc, 1.0, v29, 1.0
	v_mul_f32_e32 v32, v31, v30
	v_fma_f32 v33, -v0, v32, v31
	v_fmac_f32_e32 v32, v33, v30
	v_fma_f32 v0, -v0, v32, v31
	v_div_scale_f32 v31, s[2:3], v28, v28, 1.0
	v_rcp_f32_e32 v33, v31
	v_div_fmas_f32 v0, v0, v30, v32
	v_div_fixup_f32 v29, v0, v29, 1.0
	v_fma_f32 v0, -v31, v33, 1.0
	v_fmac_f32_e32 v33, v0, v33
	v_div_scale_f32 v0, vcc, 1.0, v28, 1.0
	v_mul_f32_e32 v30, v0, v33
	v_fma_f32 v32, -v31, v30, v0
	v_fmac_f32_e32 v30, v32, v33
	v_fma_f32 v0, -v31, v30, v0
	v_div_fmas_f32 v0, v0, v33, v30
	v_lshlrev_b32_e32 v30, 16, v14
	v_div_fixup_f32 v28, v0, v28, 1.0
	v_and_b32_e32 v31, 0xffff0000, v14
	v_mul_f32_e32 v0, 0xbfb8aa3b, v30
	v_exp_f32_e32 v32, v0
	v_mul_f32_e32 v0, 0xbfb8aa3b, v31
	v_exp_f32_e32 v33, v0
	v_pk_mul_f32 v[20:21], v[28:29], v[20:21]
	s_nop 0
	v_pk_mul_f32 v[28:29], v[20:21], v[18:19]
	v_cvt_pk_bf16_f32 v20, v26, v27
	v_pk_add_f32 v[26:27], v[32:33], 1.0 op_sel_hi:[1,0]
	v_cvt_pk_bf16_f32 v18, v22, v23
	v_div_scale_f32 v0, s[2:3], v27, v27, 1.0
	v_rcp_f32_e32 v14, v0
	v_cvt_pk_bf16_f32 v19, v24, v25
	ds_read_b128 v[22:25], v169 offset:64
	v_cvt_pk_bf16_f32 v21, v28, v29
	global_store_dwordx4 v[46:47], v[18:21], off offset:48
	s_nop 1
	v_fma_f32 v20, -v0, v14, 1.0
	v_fmac_f32_e32 v14, v20, v14
	v_div_scale_f32 v20, vcc, 1.0, v27, 1.0
	v_mul_f32_e32 v21, v20, v14
	s_waitcnt lgkmcnt(0)
; #define LAS __attribute__((address_space(3)))
; __device__ __forceinline__ u32x4 pack8(const float* f) { u32x4 w; w.x = pk2(f[0], f[1]); w.y = pk2(f[2], f[3]); w.z = pk2(f[4], f[5]); w.w = pk2(f[6], f[7]); return w; }
; __device__ __forceinline__ float sigmoidf_(float z) { return 1.f / (1.f + __expf(-z)); }
; __device__ __forceinline__ void gla_out_unit(int u, const bf16* proj, const float* wg, const float* bg, const float* gn, const float* SP, bf16* MIXO, LAS unsigned char* wl, int lane) {
;     ...
; #pragma unroll
;     for (int v8 = 0; v8 < 8; ++v8) { float og[8], w[8], y[8]; unpack8(ogv[v8], og); unpack8(*(const LAS u32x4*)(OT + lane * 72 + 8 * v8), y);
; #pragma unroll
;         for (int e = 0; e < 8; ++e) { const float z = og[e]; w[e] = y[e] * (z * sigmoidf_(z)); }
;         *(u32x4*)(MIXO + row * DM + h * 64 + 8 * v8) = pack8(w); }
	v_lshlrev_b32_e32 v18, 16, v22
	v_and_b32_e32 v19, 0xffff0000, v22
	v_fma_f32 v22, -v0, v21, v20
	v_fmac_f32_e32 v21, v22, v14
	v_fma_f32 v0, -v0, v21, v20
	v_div_scale_f32 v20, s[2:3], v26, v26, 1.0
	v_rcp_f32_e32 v22, v20
	v_div_fmas_f32 v0, v0, v14, v21
	v_div_fixup_f32 v21, v0, v27, 1.0
	v_fma_f32 v0, -v20, v22, 1.0
	v_fmac_f32_e32 v22, v0, v22
	v_div_scale_f32 v0, vcc, 1.0, v26, 1.0
	v_mul_f32_e32 v27, v0, v22
	v_fma_f32 v14, -v20, v27, v0
	v_fmac_f32_e32 v27, v14, v22
	v_lshlrev_b32_e32 v14, 16, v15
	v_fma_f32 v0, -v20, v27, v0
	v_and_b32_e32 v15, 0xffff0000, v15
	v_mul_f32_e32 v20, 0xbfb8aa3b, v14
	v_exp_f32_e32 v28, v20
	v_mul_f32_e32 v20, 0xbfb8aa3b, v15
	v_exp_f32_e32 v29, v20
	v_div_fmas_f32 v0, v0, v22, v27
	v_div_fixup_f32 v20, v0, v26, 1.0
	v_pk_mul_f32 v[20:21], v[20:21], v[30:31]
	v_pk_add_f32 v[26:27], v[28:29], 1.0 op_sel_hi:[1,0]
	v_pk_mul_f32 v[18:19], v[20:21], v[18:19]
	v_div_scale_f32 v0, s[2:3], v27, v27, 1.0
	v_rcp_f32_e32 v22, v0
	v_lshlrev_b32_e32 v20, 16, v23
	v_and_b32_e32 v21, 0xffff0000, v23
	v_fma_f32 v23, -v0, v22, 1.0
	v_fmac_f32_e32 v22, v23, v22
	v_div_scale_f32 v23, vcc, 1.0, v27, 1.0
	v_mul_f32_e32 v28, v23, v22
	v_fma_f32 v29, -v0, v28, v23
	v_fmac_f32_e32 v28, v29, v22
	v_div_scale_f32 v29, s[2:3], v26, v26, 1.0
	v_rcp_f32_e32 v32, v29
	v_fma_f32 v0, -v0, v28, v23
	v_div_fmas_f32 v0, v0, v22, v28
	v_div_fixup_f32 v23, v0, v27, 1.0
	v_fma_f32 v0, -v29, v32, 1.0
	v_fmac_f32_e32 v32, v0, v32
	v_div_scale_f32 v0, vcc, 1.0, v26, 1.0
	v_mul_f32_e32 v22, v0, v32
	v_fma_f32 v27, -v29, v22, v0
	v_fmac_f32_e32 v22, v27, v32
	v_lshlrev_b32_e32 v28, 16, v16
	v_fma_f32 v0, -v29, v22, v0
	v_and_b32_e32 v29, 0xffff0000, v16
	v_mul_f32_e32 v16, 0xbfb8aa3b, v28
	v_exp_f32_e32 v30, v16
	v_mul_f32_e32 v16, 0xbfb8aa3b, v29
	v_exp_f32_e32 v31, v16
	v_div_fmas_f32 v0, v0, v32, v22
	v_div_fixup_f32 v22, v0, v26, 1.0
	v_pk_mul_f32 v[14:15], v[22:23], v[14:15]
	v_pk_add_f32 v[22:23], v[30:31], 1.0 op_sel_hi:[1,0]
	v_pk_mul_f32 v[20:21], v[14:15], v[20:21]
	v_div_scale_f32 v0, s[2:3], v23, v23, 1.0
	v_rcp_f32_e32 v16, v0
	v_lshlrev_b32_e32 v14, 16, v24
	v_and_b32_e32 v15, 0xffff0000, v24
	v_fma_f32 v24, -v0, v16, 1.0
	v_fmac_f32_e32 v16, v24, v16
	v_div_scale_f32 v24, vcc, 1.0, v23, 1.0
	v_mul_f32_e32 v26, v24, v16
	v_fma_f32 v27, -v0, v26, v24
	v_fmac_f32_e32 v26, v27, v16
	v_fma_f32 v0, -v0, v26, v24
	v_div_scale_f32 v24, s[2:3], v22, v22, 1.0
	v_rcp_f32_e32 v30, v24
	v_div_fmas_f32 v0, v0, v16, v26
	v_div_fixup_f32 v23, v0, v23, 1.0
	v_fma_f32 v0, -v24, v30, 1.0
	v_fmac_f32_e32 v30, v0, v30
	v_div_scale_f32 v0, vcc, 1.0, v22, 1.0
	v_mul_f32_e32 v31, v0, v30
	v_fma_f32 v16, -v24, v31, v0
	v_fmac_f32_e32 v31, v16, v30
	v_lshlrev_b32_e32 v16, 16, v17
	v_fma_f32 v0, -v24, v31, v0
	v_and_b32_e32 v17, 0xffff0000, v17
	v_mul_f32_e32 v24, 0xbfb8aa3b, v16
	v_exp_f32_e32 v26, v24
	v_mul_f32_e32 v24, 0xbfb8aa3b, v17
	v_exp_f32_e32 v27, v24
	v_div_fmas_f32 v0, v0, v30, v31
	v_div_fixup_f32 v22, v0, v22, 1.0
	v_pk_mul_f32 v[22:23], v[22:23], v[28:29]
	v_pk_add_f32 v[26:27], v[26:27], 1.0 op_sel_hi:[1,0]
	v_pk_mul_f32 v[28:29], v[22:23], v[14:15]
	v_div_scale_f32 v0, s[2:3], v27, v27, 1.0
	v_rcp_f32_e32 v24, v0
	v_lshlrev_b32_e32 v14, 16, v25
	v_and_b32_e32 v15, 0xffff0000, v25
	v_fma_f32 v22, -v0, v24, 1.0
	v_fmac_f32_e32 v24, v22, v24
	v_div_scale_f32 v22, vcc, 1.0, v27, 1.0
	v_mul_f32_e32 v23, v22, v24
	v_fma_f32 v25, -v0, v23, v22
	v_fmac_f32_e32 v23, v25, v24
	v_fma_f32 v0, -v0, v23, v22
	v_div_scale_f32 v22, s[2:3], v26, v26, 1.0
	v_rcp_f32_e32 v25, v22
	v_div_fmas_f32 v0, v0, v24, v23
	v_div_fixup_f32 v23, v0, v27, 1.0
	v_fma_f32 v0, -v22, v25, 1.0
	v_fmac_f32_e32 v25, v0, v25
	v_div_scale_f32 v0, vcc, 1.0, v26, 1.0
	v_mul_f32_e32 v24, v0, v25
	v_fma_f32 v27, -v22, v24, v0
	v_fmac_f32_e32 v24, v27, v25
	v_fma_f32 v0, -v22, v24, v0
	v_div_fmas_f32 v0, v0, v25, v24
	v_div_fixup_f32 v22, v0, v26, 1.0
	v_pk_mul_f32 v[16:17], v[22:23], v[16:17]
	v_lshlrev_b32_e32 v22, 16, v10
	v_and_b32_e32 v23, 0xffff0000, v10
	v_mul_f32_e32 v0, 0xbfb8aa3b, v22
	v_exp_f32_e32 v24, v0
	v_mul_f32_e32 v0, 0xbfb8aa3b, v23
	v_exp_f32_e32 v25, v0
	v_pk_mul_f32 v[26:27], v[16:17], v[14:15]
	v_cvt_pk_bf16_f32 v14, v18, v19
	v_cvt_pk_bf16_f32 v15, v20, v21
	v_pk_add_f32 v[24:25], v[24:25], 1.0 op_sel_hi:[1,0]
	ds_read_b128 v[18:21], v169 offset:80
	v_div_scale_f32 v0, s[2:3], v25, v25, 1.0
	v_rcp_f32_e32 v10, v0
	v_cvt_pk_bf16_f32 v16, v28, v29
	v_cvt_pk_bf16_f32 v17, v26, v27
	global_store_dwordx4 v[46:47], v[14:17], off offset:64
	s_nop 1
	v_fma_f32 v16, -v0, v10, 1.0
	v_fmac_f32_e32 v10, v16, v10
	v_div_scale_f32 v16, vcc, 1.0, v25, 1.0
	v_mul_f32_e32 v17, v16, v10
	s_waitcnt lgkmcnt(0)
; #define LAS __attribute__((address_space(3)))
; __device__ __forceinline__ u32x4 pack8(const float* f) { u32x4 w; w.x = pk2(f[0], f[1]); w.y = pk2(f[2], f[3]); w.z = pk2(f[4], f[5]); w.w = pk2(f[6], f[7]); return w; }
; __device__ __forceinline__ float sigmoidf_(float z) { return 1.f / (1.f + __expf(-z)); }
; __device__ __forceinline__ void gla_out_unit(int u, const bf16* proj, const float* wg, const float* bg, const float* gn, const float* SP, bf16* MIXO, LAS unsigned char* wl, int lane) {
;     ...
; #pragma unroll
;     for (int v8 = 0; v8 < 8; ++v8) { float og[8], w[8], y[8]; unpack8(ogv[v8], og); unpack8(*(const LAS u32x4*)(OT + lane * 72 + 8 * v8), y);
; #pragma unroll
;         for (int e = 0; e < 8; ++e) { const float z = og[e]; w[e] = y[e] * (z * sigmoidf_(z)); }
;         *(u32x4*)(MIXO + row * DM + h * 64 + 8 * v8) = pack8(w); }
	v_lshlrev_b32_e32 v14, 16, v18
	v_and_b32_e32 v15, 0xffff0000, v18
	v_fma_f32 v18, -v0, v17, v16
	v_fmac_f32_e32 v17, v18, v10
	v_fma_f32 v0, -v0, v17, v16
	v_div_scale_f32 v16, s[2:3], v24, v24, 1.0
	v_rcp_f32_e32 v18, v16
	v_div_fmas_f32 v0, v0, v10, v17
	v_div_fixup_f32 v17, v0, v25, 1.0
	v_fma_f32 v0, -v16, v18, 1.0
	v_fmac_f32_e32 v18, v0, v18
	v_div_scale_f32 v0, vcc, 1.0, v24, 1.0
	v_mul_f32_e32 v25, v0, v18
	v_fma_f32 v10, -v16, v25, v0
	v_fmac_f32_e32 v25, v10, v18
	v_lshlrev_b32_e32 v10, 16, v11
	v_fma_f32 v0, -v16, v25, v0
	v_and_b32_e32 v11, 0xffff0000, v11
	v_mul_f32_e32 v16, 0xbfb8aa3b, v10
	v_exp_f32_e32 v26, v16
	v_mul_f32_e32 v16, 0xbfb8aa3b, v11
	v_exp_f32_e32 v27, v16
	v_div_fmas_f32 v0, v0, v18, v25
	v_div_fixup_f32 v16, v0, v24, 1.0
	v_pk_mul_f32 v[16:17], v[16:17], v[22:23]
	v_pk_add_f32 v[22:23], v[26:27], 1.0 op_sel_hi:[1,0]
	v_pk_mul_f32 v[14:15], v[16:17], v[14:15]
	v_div_scale_f32 v0, s[2:3], v23, v23, 1.0
	v_rcp_f32_e32 v18, v0
	v_lshlrev_b32_e32 v16, 16, v19
	v_and_b32_e32 v17, 0xffff0000, v19
	v_fma_f32 v19, -v0, v18, 1.0
	v_fmac_f32_e32 v18, v19, v18
	v_div_scale_f32 v19, vcc, 1.0, v23, 1.0
	v_mul_f32_e32 v24, v19, v18
	v_fma_f32 v25, -v0, v24, v19
	v_fmac_f32_e32 v24, v25, v18
	v_div_scale_f32 v25, s[2:3], v22, v22, 1.0
	v_rcp_f32_e32 v28, v25
	v_fma_f32 v0, -v0, v24, v19
	v_div_fmas_f32 v0, v0, v18, v24
	v_div_fixup_f32 v19, v0, v23, 1.0
	v_fma_f32 v0, -v25, v28, 1.0
	v_fmac_f32_e32 v28, v0, v28
	v_div_scale_f32 v0, vcc, 1.0, v22, 1.0
	v_mul_f32_e32 v18, v0, v28
	v_fma_f32 v23, -v25, v18, v0
	v_fmac_f32_e32 v18, v23, v28
	v_lshlrev_b32_e32 v24, 16, v12
	v_fma_f32 v0, -v25, v18, v0
	v_and_b32_e32 v25, 0xffff0000, v12
	v_mul_f32_e32 v12, 0xbfb8aa3b, v24
	v_exp_f32_e32 v26, v12
	v_mul_f32_e32 v12, 0xbfb8aa3b, v25
	v_exp_f32_e32 v27, v12
	v_div_fmas_f32 v0, v0, v28, v18
	v_div_fixup_f32 v18, v0, v22, 1.0
	v_pk_mul_f32 v[10:11], v[18:19], v[10:11]
	v_pk_add_f32 v[18:19], v[26:27], 1.0 op_sel_hi:[1,0]
	v_pk_mul_f32 v[16:17], v[10:11], v[16:17]
	v_div_scale_f32 v0, s[2:3], v19, v19, 1.0
	v_rcp_f32_e32 v12, v0
	v_lshlrev_b32_e32 v10, 16, v20
	v_and_b32_e32 v11, 0xffff0000, v20
	v_fma_f32 v20, -v0, v12, 1.0
	v_fmac_f32_e32 v12, v20, v12
	v_div_scale_f32 v20, vcc, 1.0, v19, 1.0
	v_mul_f32_e32 v22, v20, v12
	v_fma_f32 v23, -v0, v22, v20
	v_fmac_f32_e32 v22, v23, v12
	v_fma_f32 v0, -v0, v22, v20
	v_div_scale_f32 v20, s[2:3], v18, v18, 1.0
	v_rcp_f32_e32 v26, v20
	v_div_fmas_f32 v0, v0, v12, v22
	v_div_fixup_f32 v19, v0, v19, 1.0
	v_fma_f32 v0, -v20, v26, 1.0
	v_fmac_f32_e32 v26, v0, v26
	v_div_scale_f32 v0, vcc, 1.0, v18, 1.0
	v_mul_f32_e32 v27, v0, v26
	v_fma_f32 v12, -v20, v27, v0
	v_fmac_f32_e32 v27, v12, v26
	v_lshlrev_b32_e32 v12, 16, v13
	v_fma_f32 v0, -v20, v27, v0
	v_and_b32_e32 v13, 0xffff0000, v13
	v_mul_f32_e32 v20, 0xbfb8aa3b, v12
	v_exp_f32_e32 v22, v20
	v_mul_f32_e32 v20, 0xbfb8aa3b, v13
	v_exp_f32_e32 v23, v20
	v_div_fmas_f32 v0, v0, v26, v27
	v_div_fixup_f32 v18, v0, v18, 1.0
	v_pk_mul_f32 v[18:19], v[18:19], v[24:25]
	v_pk_add_f32 v[22:23], v[22:23], 1.0 op_sel_hi:[1,0]
	v_pk_mul_f32 v[18:19], v[18:19], v[10:11]
	v_div_scale_f32 v0, s[2:3], v23, v23, 1.0
	v_rcp_f32_e32 v20, v0
	v_lshlrev_b32_e32 v10, 16, v21
	v_and_b32_e32 v11, 0xffff0000, v21
	v_fma_f32 v21, -v0, v20, 1.0
	v_fmac_f32_e32 v20, v21, v20
	v_div_scale_f32 v21, vcc, 1.0, v23, 1.0
	v_mul_f32_e32 v24, v21, v20
	v_fma_f32 v25, -v0, v24, v21
	v_fmac_f32_e32 v24, v25, v20
	v_div_scale_f32 v25, s[2:3], v22, v22, 1.0
	v_rcp_f32_e32 v26, v25
	v_fma_f32 v0, -v0, v24, v21
	v_div_fmas_f32 v0, v0, v20, v24
	v_div_fixup_f32 v21, v0, v23, 1.0
	v_fma_f32 v0, -v25, v26, 1.0
	v_fmac_f32_e32 v26, v0, v26
	v_div_scale_f32 v0, vcc, 1.0, v22, 1.0
	v_mul_f32_e32 v20, v0, v26
	v_fma_f32 v23, -v25, v20, v0
	v_fmac_f32_e32 v20, v23, v26
	v_fma_f32 v0, -v25, v20, v0
	v_div_fmas_f32 v0, v0, v26, v20
	v_div_fixup_f32 v20, v0, v22, 1.0
	v_lshlrev_b32_e32 v22, 16, v6
	v_and_b32_e32 v23, 0xffff0000, v6
	v_mul_f32_e32 v0, 0xbfb8aa3b, v22
	v_exp_f32_e32 v24, v0
	v_mul_f32_e32 v0, 0xbfb8aa3b, v23
	v_exp_f32_e32 v25, v0
	v_pk_mul_f32 v[12:13], v[20:21], v[12:13]
	s_nop 0
	v_pk_mul_f32 v[20:21], v[12:13], v[10:11]
	v_cvt_pk_bf16_f32 v12, v18, v19
	v_pk_add_f32 v[18:19], v[24:25], 1.0 op_sel_hi:[1,0]
	v_cvt_pk_bf16_f32 v10, v14, v15
	v_div_scale_f32 v0, s[2:3], v19, v19, 1.0
	v_rcp_f32_e32 v6, v0
	v_cvt_pk_bf16_f32 v11, v16, v17
	ds_read_b128 v[14:17], v169 offset:96
	v_cvt_pk_bf16_f32 v13, v20, v21
	global_store_dwordx4 v[46:47], v[10:13], off offset:80
	s_nop 1
	v_fma_f32 v12, -v0, v6, 1.0
	v_fmac_f32_e32 v6, v12, v6
	v_div_scale_f32 v12, vcc, 1.0, v19, 1.0
	v_mul_f32_e32 v13, v12, v6
	s_waitcnt lgkmcnt(0)
; #define LAS __attribute__((address_space(3)))
; __device__ __forceinline__ u32x4 pack8(const float* f) { u32x4 w; w.x = pk2(f[0], f[1]); w.y = pk2(f[2], f[3]); w.z = pk2(f[4], f[5]); w.w = pk2(f[6], f[7]); return w; }
; __device__ __forceinline__ float sigmoidf_(float z) { return 1.f / (1.f + __expf(-z)); }
; __device__ __forceinline__ void gla_out_unit(int u, const bf16* proj, const float* wg, const float* bg, const float* gn, const float* SP, bf16* MIXO, LAS unsigned char* wl, int lane) {
;     ...
; #pragma unroll
;     for (int v8 = 0; v8 < 8; ++v8) { float og[8], w[8], y[8]; unpack8(ogv[v8], og); unpack8(*(const LAS u32x4*)(OT + lane * 72 + 8 * v8), y);
; #pragma unroll
;         for (int e = 0; e < 8; ++e) { const float z = og[e]; w[e] = y[e] * (z * sigmoidf_(z)); }
;         *(u32x4*)(MIXO + row * DM + h * 64 + 8 * v8) = pack8(w); }
	v_lshlrev_b32_e32 v10, 16, v14
	v_and_b32_e32 v11, 0xffff0000, v14
	v_fma_f32 v14, -v0, v13, v12
	v_fmac_f32_e32 v13, v14, v6
	v_fma_f32 v0, -v0, v13, v12
	v_div_scale_f32 v12, s[2:3], v18, v18, 1.0
	v_rcp_f32_e32 v14, v12
	v_div_fmas_f32 v0, v0, v6, v13
	v_div_fixup_f32 v13, v0, v19, 1.0
	v_fma_f32 v0, -v12, v14, 1.0
	v_fmac_f32_e32 v14, v0, v14
	v_div_scale_f32 v0, vcc, 1.0, v18, 1.0
	v_mul_f32_e32 v19, v0, v14
	v_fma_f32 v6, -v12, v19, v0
	v_fmac_f32_e32 v19, v6, v14
	v_lshlrev_b32_e32 v6, 16, v7
	v_fma_f32 v0, -v12, v19, v0
	v_and_b32_e32 v7, 0xffff0000, v7
	v_mul_f32_e32 v12, 0xbfb8aa3b, v6
	v_exp_f32_e32 v20, v12
	v_mul_f32_e32 v12, 0xbfb8aa3b, v7
	v_exp_f32_e32 v21, v12
	v_div_fmas_f32 v0, v0, v14, v19
	v_div_fixup_f32 v12, v0, v18, 1.0
	v_pk_mul_f32 v[12:13], v[12:13], v[22:23]
	v_pk_add_f32 v[18:19], v[20:21], 1.0 op_sel_hi:[1,0]
	v_pk_mul_f32 v[10:11], v[12:13], v[10:11]
	v_div_scale_f32 v0, s[2:3], v19, v19, 1.0
	v_rcp_f32_e32 v14, v0
	v_lshlrev_b32_e32 v12, 16, v15
	v_and_b32_e32 v13, 0xffff0000, v15
	v_fma_f32 v15, -v0, v14, 1.0
	v_fmac_f32_e32 v14, v15, v14
	v_div_scale_f32 v15, vcc, 1.0, v19, 1.0
	v_mul_f32_e32 v20, v15, v14
	v_fma_f32 v21, -v0, v20, v15
	v_fmac_f32_e32 v20, v21, v14
	v_div_scale_f32 v21, s[2:3], v18, v18, 1.0
	v_rcp_f32_e32 v24, v21
	v_fma_f32 v0, -v0, v20, v15
	v_div_fmas_f32 v0, v0, v14, v20
	v_div_fixup_f32 v15, v0, v19, 1.0
	v_fma_f32 v0, -v21, v24, 1.0
	v_fmac_f32_e32 v24, v0, v24
	v_div_scale_f32 v0, vcc, 1.0, v18, 1.0
	v_mul_f32_e32 v14, v0, v24
	v_fma_f32 v19, -v21, v14, v0
	v_fmac_f32_e32 v14, v19, v24
	v_lshlrev_b32_e32 v20, 16, v8
	v_fma_f32 v0, -v21, v14, v0
	v_and_b32_e32 v21, 0xffff0000, v8
	v_mul_f32_e32 v8, 0xbfb8aa3b, v20
	v_exp_f32_e32 v22, v8
	v_mul_f32_e32 v8, 0xbfb8aa3b, v21
	v_exp_f32_e32 v23, v8
	v_div_fmas_f32 v0, v0, v24, v14
	v_div_fixup_f32 v14, v0, v18, 1.0
	v_pk_mul_f32 v[6:7], v[14:15], v[6:7]
	v_pk_add_f32 v[14:15], v[22:23], 1.0 op_sel_hi:[1,0]
	v_pk_mul_f32 v[12:13], v[6:7], v[12:13]
	v_div_scale_f32 v0, s[2:3], v15, v15, 1.0
	v_rcp_f32_e32 v8, v0
	v_lshlrev_b32_e32 v6, 16, v16
	v_and_b32_e32 v7, 0xffff0000, v16
	v_fma_f32 v16, -v0, v8, 1.0
	v_fmac_f32_e32 v8, v16, v8
	v_div_scale_f32 v16, vcc, 1.0, v15, 1.0
	v_mul_f32_e32 v18, v16, v8
	v_fma_f32 v19, -v0, v18, v16
	v_fmac_f32_e32 v18, v19, v8
	v_fma_f32 v0, -v0, v18, v16
	v_div_scale_f32 v16, s[2:3], v14, v14, 1.0
	v_rcp_f32_e32 v22, v16
	v_div_fmas_f32 v0, v0, v8, v18
	v_div_fixup_f32 v15, v0, v15, 1.0
	v_fma_f32 v0, -v16, v22, 1.0
	v_fmac_f32_e32 v22, v0, v22
	v_div_scale_f32 v0, vcc, 1.0, v14, 1.0
	v_mul_f32_e32 v23, v0, v22
	v_fma_f32 v8, -v16, v23, v0
	v_fmac_f32_e32 v23, v8, v22
	v_lshlrev_b32_e32 v8, 16, v9
	v_fma_f32 v0, -v16, v23, v0
	v_and_b32_e32 v9, 0xffff0000, v9
	v_mul_f32_e32 v16, 0xbfb8aa3b, v8
	v_exp_f32_e32 v18, v16
	v_mul_f32_e32 v16, 0xbfb8aa3b, v9
	v_exp_f32_e32 v19, v16
	v_div_fmas_f32 v0, v0, v22, v23
	v_div_fixup_f32 v14, v0, v14, 1.0
	v_pk_mul_f32 v[14:15], v[14:15], v[20:21]
	v_pk_add_f32 v[18:19], v[18:19], 1.0 op_sel_hi:[1,0]
	v_pk_mul_f32 v[20:21], v[14:15], v[6:7]
	v_div_scale_f32 v0, s[2:3], v19, v19, 1.0
	v_rcp_f32_e32 v16, v0
	v_lshlrev_b32_e32 v6, 16, v17
	v_and_b32_e32 v7, 0xffff0000, v17
	v_fma_f32 v14, -v0, v16, 1.0
	v_fmac_f32_e32 v16, v14, v16
	v_div_scale_f32 v14, vcc, 1.0, v19, 1.0
	v_mul_f32_e32 v15, v14, v16
	v_fma_f32 v17, -v0, v15, v14
	v_fmac_f32_e32 v15, v17, v16
	v_fma_f32 v0, -v0, v15, v14
	v_div_scale_f32 v14, s[2:3], v18, v18, 1.0
	v_rcp_f32_e32 v17, v14
	v_div_fmas_f32 v0, v0, v16, v15
	v_div_fixup_f32 v15, v0, v19, 1.0
	v_fma_f32 v0, -v14, v17, 1.0
	v_fmac_f32_e32 v17, v0, v17
	v_div_scale_f32 v0, vcc, 1.0, v18, 1.0
	v_mul_f32_e32 v16, v0, v17
	v_fma_f32 v19, -v14, v16, v0
	v_fmac_f32_e32 v16, v19, v17
	v_fma_f32 v0, -v14, v16, v0
	v_div_fmas_f32 v0, v0, v17, v16
	v_div_fixup_f32 v14, v0, v18, 1.0
	v_pk_mul_f32 v[8:9], v[14:15], v[8:9]
	v_lshlrev_b32_e32 v14, 16, v2
	v_and_b32_e32 v15, 0xffff0000, v2
	v_mul_f32_e32 v0, 0xbfb8aa3b, v14
	v_exp_f32_e32 v16, v0
	v_mul_f32_e32 v0, 0xbfb8aa3b, v15
	v_exp_f32_e32 v17, v0
	v_pk_mul_f32 v[18:19], v[8:9], v[6:7]
	v_cvt_pk_bf16_f32 v6, v10, v11
	v_cvt_pk_bf16_f32 v7, v12, v13
	v_pk_add_f32 v[16:17], v[16:17], 1.0 op_sel_hi:[1,0]
	ds_read_b128 v[10:13], v169 offset:112
	v_div_scale_f32 v0, s[2:3], v17, v17, 1.0
	v_rcp_f32_e32 v2, v0
	v_cvt_pk_bf16_f32 v8, v20, v21
	v_cvt_pk_bf16_f32 v9, v18, v19
	global_store_dwordx4 v[46:47], v[6:9], off offset:96
	s_nop 1
	v_fma_f32 v8, -v0, v2, 1.0
	v_fmac_f32_e32 v2, v8, v2
	v_div_scale_f32 v8, vcc, 1.0, v17, 1.0
	v_mul_f32_e32 v9, v8, v2
	s_waitcnt lgkmcnt(0)
; #define LAS __attribute__((address_space(3)))
; __device__ __forceinline__ u32x4 pack8(const float* f) { u32x4 w; w.x = pk2(f[0], f[1]); w.y = pk2(f[2], f[3]); w.z = pk2(f[4], f[5]); w.w = pk2(f[6], f[7]); return w; }
; __device__ __forceinline__ float sigmoidf_(float z) { return 1.f / (1.f + __expf(-z)); }
; __device__ __forceinline__ void gla_out_unit(int u, const bf16* proj, const float* wg, const float* bg, const float* gn, const float* SP, bf16* MIXO, LAS unsigned char* wl, int lane) {
;     const int b = u >> 8, h = (u >> 6) & 3, n = u & 63; const size_t row = (size_t)b * SEQ + n * 64 + lane; const bf16* prow = proj + row * PP;
;     LAS bf16* Qd = (LAS bf16*)wl; LAS bf16* Kd = (LAS bf16*)(wl + 5120); LAS bf16* VT = (LAS bf16*)(wl + 10240);
;     float spv[32]; { const float* sp = SP + (size_t)u * 2048;
; #pragma unroll
;       for (int d = 0; d < 32; ++d) spv[d] = sp[d * 64 + lane]; }
;     ...
; #pragma unroll
;     for (int v8 = 0; v8 < 8; ++v8) { float og[8], w[8], y[8]; unpack8(ogv[v8], og); unpack8(*(const LAS u32x4*)(OT + lane * 72 + 8 * v8), y);
; #pragma unroll
;         for (int e = 0; e < 8; ++e) { const float z = og[e]; w[e] = y[e] * (z * sigmoidf_(z)); }
;         *(u32x4*)(MIXO + row * DM + h * 64 + 8 * v8) = pack8(w); }
	v_lshlrev_b32_e32 v6, 16, v10
	v_and_b32_e32 v7, 0xffff0000, v10
	v_fma_f32 v10, -v0, v9, v8
	v_fmac_f32_e32 v9, v10, v2
	v_fma_f32 v0, -v0, v9, v8
	v_div_scale_f32 v8, s[2:3], v16, v16, 1.0
	v_rcp_f32_e32 v10, v8
	v_div_fmas_f32 v0, v0, v2, v9
	v_div_fixup_f32 v9, v0, v17, 1.0
	v_fma_f32 v0, -v8, v10, 1.0
	v_fmac_f32_e32 v10, v0, v10
	v_div_scale_f32 v0, vcc, 1.0, v16, 1.0
	v_mul_f32_e32 v17, v0, v10
	v_fma_f32 v2, -v8, v17, v0
	v_fmac_f32_e32 v17, v2, v10
	v_lshlrev_b32_e32 v2, 16, v3
	v_fma_f32 v0, -v8, v17, v0
	v_and_b32_e32 v3, 0xffff0000, v3
	v_mul_f32_e32 v8, 0xbfb8aa3b, v2
	v_exp_f32_e32 v18, v8
	v_mul_f32_e32 v8, 0xbfb8aa3b, v3
	v_exp_f32_e32 v19, v8
	v_div_fmas_f32 v0, v0, v10, v17
	v_div_fixup_f32 v8, v0, v16, 1.0
	v_pk_mul_f32 v[8:9], v[8:9], v[14:15]
	v_pk_add_f32 v[14:15], v[18:19], 1.0 op_sel_hi:[1,0]
	v_pk_mul_f32 v[6:7], v[8:9], v[6:7]
	v_div_scale_f32 v0, s[2:3], v15, v15, 1.0
	v_rcp_f32_e32 v10, v0
	v_lshlrev_b32_e32 v8, 16, v11
	v_and_b32_e32 v9, 0xffff0000, v11
	v_fma_f32 v11, -v0, v10, 1.0
	v_fmac_f32_e32 v10, v11, v10
	v_div_scale_f32 v11, vcc, 1.0, v15, 1.0
	v_mul_f32_e32 v16, v11, v10
	v_fma_f32 v17, -v0, v16, v11
	v_fmac_f32_e32 v16, v17, v10
	v_div_scale_f32 v17, s[2:3], v14, v14, 1.0
	v_rcp_f32_e32 v20, v17
	v_fma_f32 v0, -v0, v16, v11
	v_div_fmas_f32 v0, v0, v10, v16
	v_div_fixup_f32 v11, v0, v15, 1.0
	v_fma_f32 v0, -v17, v20, 1.0
	v_fmac_f32_e32 v20, v0, v20
	v_div_scale_f32 v0, vcc, 1.0, v14, 1.0
	v_mul_f32_e32 v10, v0, v20
	v_fma_f32 v15, -v17, v10, v0
	v_fmac_f32_e32 v10, v15, v20
	v_lshlrev_b32_e32 v16, 16, v4
	v_fma_f32 v0, -v17, v10, v0
	v_and_b32_e32 v17, 0xffff0000, v4
	v_mul_f32_e32 v4, 0xbfb8aa3b, v16
	v_exp_f32_e32 v18, v4
	v_mul_f32_e32 v4, 0xbfb8aa3b, v17
	v_exp_f32_e32 v19, v4
	v_div_fmas_f32 v0, v0, v20, v10
	v_div_fixup_f32 v10, v0, v14, 1.0
	v_pk_mul_f32 v[2:3], v[10:11], v[2:3]
	v_pk_add_f32 v[10:11], v[18:19], 1.0 op_sel_hi:[1,0]
	v_pk_mul_f32 v[8:9], v[2:3], v[8:9]
	v_div_scale_f32 v0, s[2:3], v11, v11, 1.0
	v_rcp_f32_e32 v4, v0
	v_lshlrev_b32_e32 v2, 16, v12
	v_and_b32_e32 v3, 0xffff0000, v12
	v_fma_f32 v12, -v0, v4, 1.0
	v_fmac_f32_e32 v4, v12, v4
	v_div_scale_f32 v12, vcc, 1.0, v11, 1.0
	v_mul_f32_e32 v14, v12, v4
	v_fma_f32 v15, -v0, v14, v12
	v_fmac_f32_e32 v14, v15, v4
	v_fma_f32 v0, -v0, v14, v12
	v_div_scale_f32 v12, s[2:3], v10, v10, 1.0
	v_rcp_f32_e32 v18, v12
	v_div_fmas_f32 v0, v0, v4, v14
	v_div_fixup_f32 v11, v0, v11, 1.0
	v_fma_f32 v0, -v12, v18, 1.0
	v_fmac_f32_e32 v18, v0, v18
	v_div_scale_f32 v0, vcc, 1.0, v10, 1.0
	v_mul_f32_e32 v19, v0, v18
	v_fma_f32 v4, -v12, v19, v0
	v_fmac_f32_e32 v19, v4, v18
	v_lshlrev_b32_e32 v4, 16, v5
	v_fma_f32 v0, -v12, v19, v0
	v_and_b32_e32 v5, 0xffff0000, v5
	v_mul_f32_e32 v12, 0xbfb8aa3b, v4
	v_exp_f32_e32 v14, v12
	v_mul_f32_e32 v12, 0xbfb8aa3b, v5
	v_exp_f32_e32 v15, v12
	v_div_fmas_f32 v0, v0, v18, v19
	v_div_fixup_f32 v10, v0, v10, 1.0
	v_pk_mul_f32 v[10:11], v[10:11], v[16:17]
	v_pk_add_f32 v[14:15], v[14:15], 1.0 op_sel_hi:[1,0]
	v_pk_mul_f32 v[10:11], v[10:11], v[2:3]
	v_div_scale_f32 v0, s[2:3], v15, v15, 1.0
	v_rcp_f32_e32 v12, v0
	v_lshlrev_b32_e32 v2, 16, v13
	v_and_b32_e32 v3, 0xffff0000, v13
	v_fma_f32 v13, -v0, v12, 1.0
	v_fmac_f32_e32 v12, v13, v12
	v_div_scale_f32 v13, vcc, 1.0, v15, 1.0
	v_mul_f32_e32 v16, v13, v12
	v_fma_f32 v17, -v0, v16, v13
	v_fmac_f32_e32 v16, v17, v12
	v_div_scale_f32 v17, s[2:3], v14, v14, 1.0
	v_rcp_f32_e32 v18, v17
	v_fma_f32 v0, -v0, v16, v13
	v_div_fmas_f32 v0, v0, v12, v16
	v_div_fixup_f32 v13, v0, v15, 1.0
	v_fma_f32 v0, -v17, v18, 1.0
	v_fmac_f32_e32 v18, v0, v18
	v_div_scale_f32 v0, vcc, 1.0, v14, 1.0
	v_mul_f32_e32 v12, v0, v18
	v_fma_f32 v15, -v17, v12, v0
	v_fmac_f32_e32 v12, v15, v18
	v_fma_f32 v0, -v17, v12, v0
	v_div_fmas_f32 v0, v0, v18, v12
	v_div_fixup_f32 v12, v0, v14, 1.0
	v_pk_mul_f32 v[4:5], v[12:13], v[4:5]
	s_nop 0
	v_pk_mul_f32 v[12:13], v[4:5], v[2:3]
	v_cvt_pk_bf16_f32 v2, v6, v7
	v_cvt_pk_bf16_f32 v3, v8, v9
	v_cvt_pk_bf16_f32 v4, v10, v11
	v_cvt_pk_bf16_f32 v5, v12, v13
	global_store_dwordx4 v[46:47], v[2:5], off offset:112
	s_waitcnt lgkmcnt(0)
	s_cbranch_scc1 .LBB0_721
.LBB0_719:
	s_ashr_i32 s2, s59, 8
	s_ashr_i32 s3, s2, 31
	s_lshl_b64 s[2:3], s[2:3], 12
	s_and_b32 s24, s84, 0xfc0
	v_add_co_u32_e32 v2, vcc, s42, v120
	s_or_b32 s2, s2, s24
	s_nop 0
	v_addc_co_u32_e32 v3, vcc, 0, v121, vcc
	v_or_b32_e32 v122, s2, v114
	global_load_dword v171, v[120:121], off
	global_load_dword v173, v[120:121], off offset:256
	global_load_dword v178, v[120:121], off offset:512
	global_load_dword v181, v[120:121], off offset:768
	global_load_dword v186, v[120:121], off offset:1024
	global_load_dword v189, v[120:121], off offset:1280
	global_load_dword v194, v[120:121], off offset:1536
	global_load_dword v211, v[120:121], off offset:1792
	global_load_dword v170, v[120:121], off offset:2048
	global_load_dword v172, v[120:121], off offset:2304
	global_load_dword v175, v[120:121], off offset:2560
	global_load_dword v179, v[120:121], off offset:2816
	global_load_dword v183, v[120:121], off offset:3072
	global_load_dword v187, v[120:121], off offset:3328
	global_load_dword v191, v[120:121], off offset:3584
	global_load_dword v195, v[120:121], off offset:3840
	global_load_dword v176, v[2:3], off
	global_load_dword v180, v[2:3], off offset:256
	global_load_dword v184, v[2:3], off offset:512
	global_load_dword v188, v[2:3], off offset:768
	global_load_dword v192, v[2:3], off offset:1024
	global_load_dword v210, v[2:3], off offset:1280
	global_load_dword v213, v[2:3], off offset:1536
	global_load_dword v215, v[2:3], off offset:1792
	global_load_dword v174, v[2:3], off offset:2048
; __device__ __forceinline__ void gla_gates(const bf16* prow, const float* wg, const float* bg, int h, int lane, float (&bc)[32], LAS float* Wst) {
;     ...
;     for (int r = 0; r < 8; ++r) { const int i = r * 64 + lane; Wst[i] = wg[(i >> 5) * 128 + h * 32 + (i & 31)]; }
;     if (lane < 32) Wst[512 + lane] = bg[h * 32 + lane];
;     float glr[16]; unpack8(*(const u32x4*)(prow + C_GLR), glr); unpack8(*(const u32x4*)(prow + C_GLR + 8), glr + 8);
; __device__ __forceinline__ void gla_out_unit(int u, const bf16* proj, const float* wg, const float* bg, const float* gn, const float* SP, bf16* MIXO, LAS unsigned char* wl, int lane) {
;     ...
;     float spv[32]; { const float* sp = SP + (size_t)u * 2048;
; #pragma unroll
;       for (int d = 0; d < 32; ++d) spv[d] = sp[d * 64 + lane]; }
;     u32x4 ogv[8];
; #pragma unroll
;     for (int v8 = 0; v8 < 8; ++v8) ogv[v8] = *(const u32x4*)(prow + C_GOG + h * 64 + 8 * v8);
;     u32x4 kraw[4], qraw[4], vraw[8];
; #pragma unroll
;     for (int i = 0; i < 4; ++i) { kraw[i] = *(const u32x4*)(prow + C_GK + h * 32 + 8 * i); qraw[i] = *(const u32x4*)(prow + C_GQ + h * 32 + 8 * i); }
; #pragma unroll
;     for (int i = 0; i < 8; ++i) vraw[i] = *(const u32x4*)(prow + C_GV + h * 64 + 8 * i);
	global_load_dword v177, v[2:3], off offset:2304
	global_load_dword v182, v[2:3], off offset:2560
	global_load_dword v185, v[2:3], off offset:2816
	global_load_dword v190, v[2:3], off offset:3072
	global_load_dword v193, v[2:3], off offset:3328
	global_load_dword v212, v[2:3], off offset:3584
	global_load_dword v214, v[2:3], off offset:3840
	v_mov_b64_e32 v[2:3], s[74:75]
	s_bfe_u32 s26, s59, 0x20006
	v_mad_u64_u32 v[98:99], s[24:25], v122, s88, v[2:3]
	v_mov_b32_e32 v0, 0x1400
	v_mov_b32_e32 v123, s3
	v_mad_i32_i24 v99, s3, v0, v99
	s_lshl_b32 s2, s26, 7
	s_mov_b32 s3, s35
	v_lshl_add_u64 v[34:35], v[98:99], 0, s[2:3]
	s_lshl_b32 s2, s26, 5
	v_or_b32_e32 v0, s2, v115
	s_lshl_b32 s34, s26, 6
	v_or_b32_e32 v100, v0, v125
	v_or_b32_e32 v101, v0, v129
	v_lshl_add_u64 v[36:37], v[98:99], 0, s[34:35]
	v_lshlrev_b32_e32 v100, 2, v100
	v_lshlrev_b32_e32 v101, 2, v101
	global_load_dwordx4 v[18:21], v[34:35], off offset:1072
	global_load_dwordx4 v[22:25], v[34:35], off offset:1056
	global_load_dwordx4 v[26:29], v[34:35], off offset:1040
	global_load_dwordx4 v[30:33], v[34:35], off offset:1024
	global_load_dwordx4 v[2:5], v[34:35], off offset:1136
	global_load_dwordx4 v[6:9], v[34:35], off offset:1120
	global_load_dwordx4 v[10:13], v[34:35], off offset:1104
	global_load_dwordx4 v[14:17], v[34:35], off offset:1088
	global_load_dwordx4 v[66:69], v[36:37], off offset:304
	global_load_dwordx4 v[74:77], v[36:37], off offset:288
	global_load_dwordx4 v[82:85], v[36:37], off offset:272
	global_load_dwordx4 v[90:93], v[36:37], off offset:256
	global_load_dwordx4 v[70:73], v[36:37], off offset:48
	global_load_dwordx4 v[78:81], v[36:37], off offset:32
	global_load_dwordx4 v[86:89], v[36:37], off offset:16
	global_load_dwordx4 v[94:97], v[36:37], off
	global_load_dwordx4 v[62:65], v[34:35], off offset:512
	global_load_dwordx4 v[58:61], v[34:35], off offset:528
	global_load_dwordx4 v[54:57], v[34:35], off offset:544
	global_load_dwordx4 v[50:53], v[34:35], off offset:560
	global_load_dwordx4 v[46:49], v[34:35], off offset:576
	global_load_dwordx4 v[42:45], v[34:35], off offset:592
	global_load_dwordx4 v[38:41], v[34:35], off offset:608
	s_nop 0
	global_load_dwordx4 v[34:37], v[34:35], off offset:624
	s_nop 0
	global_load_dword v100, v100, s[76:77]
	s_nop 0
	global_load_dword v101, v101, s[76:77]
	v_or_b32_e32 v196, v0, v131
	v_or_b32_e32 v197, v0, v133
	v_or_b32_e32 v198, v0, v135
	v_or_b32_e32 v199, v0, v137
	v_or_b32_e32 v200, v0, v139
	v_or_b32_e32 v201, v0, v141
	v_lshlrev_b32_e32 v196, 2, v196
	v_lshlrev_b32_e32 v197, 2, v197
	v_lshlrev_b32_e32 v198, 2, v198
	v_lshlrev_b32_e32 v199, 2, v199
	v_lshlrev_b32_e32 v200, 2, v200
	v_lshlrev_b32_e32 v201, 2, v201
	s_nop 0
	global_load_dword v196, v196, s[76:77]
	s_nop 0
	global_load_dword v197, v197, s[76:77]
	s_nop 0
	global_load_dword v198, v198, s[76:77]
	s_nop 0
	global_load_dword v199, v199, s[76:77]
	s_nop 0
	global_load_dword v200, v200, s[76:77]
	s_nop 0
	global_load_dword v201, v201, s[76:77]
	v_lshl_add_u64 v[218:219], v[98:99], 0, s[48:49]
	v_add_co_u32_e32 v220, vcc, s42, v98
	s_nop 1
	v_addc_co_u32_e32 v221, vcc, 0, v99, vcc
	global_load_dwordx4 v[110:113], v[218:219], off offset:16
	global_load_dwordx4 v[154:157], v[220:221], off offset:512
	s_and_saveexec_b64 s[26:27], s[4:5]
	v_or_b32_e32 v202, s2, v114
	v_lshlrev_b32_e32 v202, 2, v202
	global_load_dword v202, v202, s[80:81]
	s_or_b64 exec, exec, s[26:27]
	s_waitcnt vmcnt(0)
	ds_write2st64_b32 v127, v100, v101 offset0:40 offset1:41
	ds_write2st64_b32 v127, v196, v197 offset0:42 offset1:43
	ds_write2st64_b32 v127, v198, v199 offset0:44 offset1:45
	ds_write2st64_b32 v127, v200, v201 offset0:46 offset1:47
	s_and_saveexec_b64 s[26:27], s[4:5]
	ds_write_b32 v127, v202 offset:12288
	s_branch .LBB0_718
; __device__ __forceinline__ void phase_lru_diff_out(int l, KIn in, const bf16* __restrict__ proj, const bf16* __restrict__ LH, const bf16* __restrict__ CP, const float* __restrict__ HIN, ...
;     float s1 = 0.f, s2 = 0.f;
;     for (int i = 0; i < 32; ++i) { s1 += in[10][l * 32 + i] * in[11][l * 32 + i]; s2 += in[12][l * 32 + i] * in[13][l * 32 + i]; }
;     const float lam_init = 0.8f - 0.6f * expf(-0.3f * (float)l), lam = expf(s1) - expf(s2) + lam_init, osc = 1.f - lam_init;
;     const float* dn = in[14] + l * 64;
; #pragma unroll 2
;     for (int idx = gid; idx < T * 32; idx += gsz) {
;         const int row = idx >> 5;
;         const int c8 = (idx & 31) * 8, b = row >> 12, ch = (row & (SEQ - 1)) >> 6, h = (idx >> 3) & 3, v8 = (idx & 7) * 8;
.LBB0_721:
	v_mov_b32_e32 v0, v216
	s_mov_b64 s[28:29], s[0:1]
	s_mov_b32 s24, s56
	s_mov_b32 s25, s55
	s_cmp_lt_u32 s55, 0x80
	s_cselect_b32 s100, 0, 0x50000
	s_mov_b32 s101, 0xfffff
	s_cselect_b32 s101, 0x5ffff, s101
	s_mov_b32 s2, 0x100000
	v_lshl_add_u32 v34, s25, 9, v0
	v_add_u32_e32 v34, s100, v34
	s_lshl_b32 s100, s100, 3
	v_cmp_gt_i32_e32 vcc, s2, v34
	s_and_saveexec_b64 s[12:13], vcc
	s_mov_b32 s30, 0xfffff
	s_cbranch_execz .LBB0_724
	s_load_dwordx2 s[14:15], s[28:29], 0x118
	s_mov_b32 s2, 0x10000
	v_cvt_f32_u32_e32 v2, s66
	s_load_dwordx8 s[4:11], s[28:29], 0x50
	s_nop 0
	s_load_dwordx2 s[28:29], s[28:29], 0x70
	s_mov_b32 s3, 0x3fb8aa3b
	s_waitcnt lgkmcnt(0)
	s_add_u32 s16, s14, 0x1b800000
	s_addc_u32 s17, s15, 0
	s_add_u32 s18, s14, 0x1c800000
	s_addc_u32 s19, s15, 0
	s_add_u32 s20, s14, 0x380000
	s_addc_u32 s21, s15, 0
	v_mul_f32_e32 v2, 0xbe99999a, v2
	s_add_u32 s22, s14, 0x1d800000
	v_mul_f32_e32 v3, 0x3fb8aa3b, v2
	s_addc_u32 s23, s15, 0
	v_fma_f32 v4, v2, s3, -v3
	v_rndne_f32_e32 v5, v3
	s_add_u32 s26, s14, 0x17800000
	v_fmac_f32_e32 v4, 0x32a5705f, v2
	v_sub_f32_e32 v3, v3, v5
	s_addc_u32 s27, s15, 0
	v_add_f32_e32 v3, v3, v4
	s_lshl_b64 s[38:39], s[70:71], 2
	v_exp_f32_e32 v3, v3
	v_cvt_i32_f32_e32 v4, v5
	s_add_u32 s28, s28, s38
	s_addc_u32 s29, s29, s39
	s_lshl_b32 s34, s66, 5
	s_lshl_b64 s[70:71], s[34:35], 2
	s_mov_b32 s33, 0xc2ce8ed0
	s_add_u32 s4, s4, s70
	v_ldexp_f32 v3, v3, v4
	v_cmp_ngt_f32_e32 vcc, s33, v2
	s_mov_b32 s40, 0x42b17218
	s_addc_u32 s5, s5, s71
	v_cndmask_b32_e32 v3, 0, v3, vcc
	v_cmp_nlt_f32_e32 vcc, s40, v2
	v_mov_b32_e32 v39, 0x7f800000
	s_add_u32 s6, s6, s70
	v_cndmask_b32_e32 v2, v39, v3, vcc
	v_mov_b32_e32 v3, 0x3f4ccccd
	s_addc_u32 s7, s7, s71
	v_fmamk_f32 v36, v2, 0xbf19999a, v3
	global_load_dwordx4 v[2:5], v1, s[4:5] offset:48
	global_load_dwordx4 v[6:9], v1, s[4:5] offset:32
	global_load_dwordx4 v[10:13], v1, s[4:5] offset:16
	global_load_dwordx4 v[14:17], v1, s[4:5]
	global_load_dwordx4 v[18:21], v1, s[6:7] offset:48
	global_load_dwordx4 v[22:25], v1, s[6:7] offset:32
	global_load_dwordx4 v[26:29], v1, s[6:7] offset:16
	global_load_dwordx4 v[30:33], v1, s[6:7]
	global_load_dwordx4 v[52:55], v1, s[4:5] offset:112
	global_load_dwordx4 v[56:59], v1, s[4:5] offset:96
	global_load_dwordx4 v[60:63], v1, s[4:5] offset:80
	global_load_dwordx4 v[64:67], v1, s[4:5] offset:64
	global_load_dwordx4 v[68:71], v1, s[6:7] offset:112
	global_load_dwordx4 v[72:75], v1, s[6:7] offset:96
	global_load_dwordx4 v[76:79], v1, s[6:7] offset:80
	global_load_dwordx4 v[80:83], v1, s[6:7] offset:64
	s_add_u32 s6, s8, s70
	s_addc_u32 s7, s9, s71
	s_add_u32 s4, s10, s70
	s_addc_u32 s5, s11, s71
	global_load_dwordx4 v[96:99], v1, s[6:7] offset:48
	global_load_dwordx4 v[100:103], v1, s[6:7] offset:32
	global_load_dwordx4 v[104:107], v1, s[6:7] offset:16
	global_load_dwordx4 v[108:111], v1, s[6:7]
	global_load_dwordx4 v[112:115], v1, s[4:5] offset:48
	global_load_dwordx4 v[116:119], v1, s[4:5] offset:32
	global_load_dwordx4 v[120:123], v1, s[4:5] offset:16
	global_load_dwordx4 v[124:127], v1, s[4:5]
	global_load_dwordx4 v[128:131], v1, s[6:7] offset:112
	global_load_dwordx4 v[136:139], v1, s[6:7] offset:96
	global_load_dwordx4 v[144:147], v1, s[6:7] offset:80
	global_load_dwordx4 v[154:157], v1, s[6:7] offset:64
	global_load_dwordx4 v[132:135], v1, s[4:5] offset:112
	global_load_dwordx4 v[140:143], v1, s[4:5] offset:96
	global_load_dwordx4 v[148:151], v1, s[4:5] offset:80
	global_load_dwordx4 v[158:161], v1, s[4:5] offset:64
	v_lshlrev_b32_e32 v0, 3, v0
	v_sub_f32_e32 v35, 1.0, v36
	s_waitcnt vmcnt(24)
	v_fma_f32 v37, v14, v30, 0
	v_fmac_f32_e32 v37, v15, v31
	v_fmac_f32_e32 v37, v16, v32
	v_fmac_f32_e32 v37, v17, v33
	v_fmac_f32_e32 v37, v10, v26
	v_fmac_f32_e32 v37, v11, v27
	v_fmac_f32_e32 v37, v12, v28
	v_fmac_f32_e32 v37, v13, v29
	v_fmac_f32_e32 v37, v6, v22
	v_fmac_f32_e32 v37, v7, v23
	v_fmac_f32_e32 v37, v8, v24
	v_fmac_f32_e32 v37, v9, v25
	v_fmac_f32_e32 v37, v2, v18
	v_fmac_f32_e32 v37, v3, v19
	v_fmac_f32_e32 v37, v4, v20
	v_fmac_f32_e32 v37, v5, v21
	s_waitcnt vmcnt(16)
	v_fmac_f32_e32 v37, v64, v80
	v_fmac_f32_e32 v37, v65, v81
	v_fmac_f32_e32 v37, v66, v82
	v_fmac_f32_e32 v37, v67, v83
	v_fmac_f32_e32 v37, v60, v76
	v_fmac_f32_e32 v37, v61, v77
	v_fmac_f32_e32 v37, v62, v78
	v_fmac_f32_e32 v37, v63, v79
	v_fmac_f32_e32 v37, v56, v72
	v_fmac_f32_e32 v37, v57, v73
	v_fmac_f32_e32 v37, v58, v74
	v_fmac_f32_e32 v37, v59, v75
	v_fmac_f32_e32 v37, v52, v68
	v_fmac_f32_e32 v37, v53, v69
	v_fmac_f32_e32 v37, v54, v70
	v_fmac_f32_e32 v37, v55, v71
	v_mul_f32_e32 v2, 0x3fb8aa3b, v37
	v_fma_f32 v3, v37, s3, -v2
	v_rndne_f32_e32 v4, v2
	v_fmac_f32_e32 v3, 0x32a5705f, v37
	v_sub_f32_e32 v2, v2, v4
	v_add_f32_e32 v2, v2, v3
	v_exp_f32_e32 v2, v2
	v_cvt_i32_f32_e32 v3, v4
	v_cmp_ngt_f32_e32 vcc, s33, v37
	v_ldexp_f32 v2, v2, v3
	s_nop 0
	v_cndmask_b32_e32 v2, 0, v2, vcc
	v_cmp_nlt_f32_e32 vcc, s40, v37
	s_nop 1
	v_cndmask_b32_e32 v37, v39, v2, vcc
	s_waitcnt vmcnt(8)
	v_fma_f32 v38, v108, v124, 0
	v_fmac_f32_e32 v38, v109, v125
	v_fmac_f32_e32 v38, v110, v126
	v_fmac_f32_e32 v38, v111, v127
	v_fmac_f32_e32 v38, v104, v120
	v_fmac_f32_e32 v38, v105, v121
	v_fmac_f32_e32 v38, v106, v122
	v_fmac_f32_e32 v38, v107, v123
	v_fmac_f32_e32 v38, v100, v116
	v_fmac_f32_e32 v38, v101, v117
	v_fmac_f32_e32 v38, v102, v118
	v_fmac_f32_e32 v38, v103, v119
	v_fmac_f32_e32 v38, v96, v112
	v_fmac_f32_e32 v38, v97, v113
	v_fmac_f32_e32 v38, v98, v114
	v_fmac_f32_e32 v38, v99, v115
	s_mov_b32 s6, 0x80000
	s_mov_b64 s[4:5], 0
	s_waitcnt vmcnt(0)
	v_fmac_f32_e32 v38, v154, v158
	v_fmac_f32_e32 v38, v155, v159
	v_fmac_f32_e32 v38, v156, v160
	v_fmac_f32_e32 v38, v157, v161
	v_fmac_f32_e32 v38, v144, v148
	v_fmac_f32_e32 v38, v145, v149
	v_fmac_f32_e32 v38, v146, v150
	v_fmac_f32_e32 v38, v147, v151
	v_fmac_f32_e32 v38, v136, v140
	v_fmac_f32_e32 v38, v137, v141
	v_fmac_f32_e32 v38, v138, v142
	v_fmac_f32_e32 v38, v139, v143
	v_fmac_f32_e32 v38, v128, v132
	v_fmac_f32_e32 v38, v129, v133
	v_fmac_f32_e32 v38, v130, v134
	v_fmac_f32_e32 v38, v131, v135
	v_mul_f32_e32 v2, 0x3fb8aa3b, v38
	v_fma_f32 v3, v38, s3, -v2
	v_rndne_f32_e32 v4, v2
	v_fmac_f32_e32 v3, 0x32a5705f, v38
	v_sub_f32_e32 v2, v2, v4
	v_add_f32_e32 v2, v2, v3
	v_exp_f32_e32 v2, v2
	v_cvt_i32_f32_e32 v3, v4
	v_cmp_ngt_f32_e32 vcc, s33, v38
	v_lshl_add_u32 v29, s25, 12, v0
	v_add_u32_e32 v29, s100, v29
	v_ldexp_f32 v2, v2, v3
	v_cndmask_b32_e32 v2, 0, v2, vcc
	v_cmp_nlt_f32_e32 vcc, s40, v38
	v_and_b32_e32 v3, 64, v241
	v_add_u32_e32 v3, 64, v3
	v_cndmask_b32_e32 v2, v39, v2, vcc
	v_sub_f32_e32 v2, v37, v2
	v_add_f32_e32 v18, v36, v2
	v_xor_b32_e32 v2, 1, v241
	v_cmp_lt_i32_e32 vcc, v2, v3
	v_mov_b32_e32 v19, v18
	s_nop 0
	v_cndmask_b32_e32 v2, v241, v2, vcc
	v_lshlrev_b32_e32 v26, 2, v2
	v_xor_b32_e32 v2, 2, v241
	v_cmp_lt_i32_e32 vcc, v2, v3
	s_nop 1
	v_cndmask_b32_e32 v2, v241, v2, vcc
	v_lshlrev_b32_e32 v27, 2, v2
	v_xor_b32_e32 v2, 4, v241
	v_cmp_lt_i32_e32 vcc, v2, v3
	s_nop 1
	v_cndmask_b32_e32 v2, v241, v2, vcc
	v_lshlrev_b32_e32 v28, 2, v2
